# v19 + GEMM K-loops: second iteration peeled and steady loop unrolled by two (half the taken back-branches)
# baseline (speedup 1.0000x reference)
; #define PG8_STAGE(bufoff, gbase, voff) do { _Pragma("unroll") for (int _i = 0; _i < 2; ++_i) \
;         __builtin_amdgcn_global_load_lds((const unsigned*)((const char*)(gbase) + (voff)[_i]), (PG8_LAS unsigned*)(lds + (bufoff) + ldsw + _i * 8192), 16, 0, 0); } while (0)
; #define PG8_LDA(dst, b, h) do { _Pragma("unroll") for (int m = 0; m < 4; ++m) _Pragma("unroll") for (int k = 0; k < 2; ++k) dst[m][k] = *(const PG8_LAS bf16x8*)(lds + PG8_SA(b, h) + aoff + m * 2048 + k * 1024); } while (0)
; #define PG8_LDB(dst, b, h) do { _Pragma("unroll") for (int n = 0; n < 2; ++n) _Pragma("unroll") for (int k = 0; k < 2; ++k) dst[n][k] = *(const PG8_LAS bf16x8*)(lds + PG8_SB(b, h) + boff + n * 2048 + k * 1024); } while (0)
; #define PG8_WAIT_V(n) asm volatile("s_waitcnt vmcnt(" #n ")" ::: "memory")
; #define PG8_BAR __builtin_amdgcn_s_barrier()
; template <class Epi, class Sched, bool ALIGN_EPI = false>
; __device__ __forceinline__ void gemm_phase8(PG8_LAS unsigned char* lds, const Gemm g, const Sched& S, const Epi& E) {
;     ...
;     for (;;) {
;         const bool has_next = S.next(ui + 1, nxt);
;         const size_t nko = (has_next && nxt.kp > 0) ? (size_t)nxt.kp * g.kpiece : 0;
;         const char* nA = has_next ? (const char*)g.A + (size_t)nxt.pm * tstepA + (size_t)nxt.pn * astep + nko : cA; const char* nB = has_next ? (const char*)g.Bt + (size_t)nxt.pn * tstepB + nko : cB;
;         const int nt = (cur.kp < 0 ? g.K : g.kpiece) / 128;
;         for (int t = 0; t < nt; t += 2) {
;             const bool last = (t == nt - 2);
;             const char* a1 = cA + (size_t)(t + 1) * kstep;
;             const char* a2 = last ? nA : cA + (size_t)(t + 2) * kstep; const char* b2 = last ? nB : cB + (size_t)(t + 2) * kstep;
;             const char* a3 = a2 + kstep; const char* b3 = b2 + kstep;
;             if (last && has_next) S.a_ready(nxt);
;             PG8_LDB(B0, 0, 0); PG8_LDB(B1, 0, 1); PG8_SCHED; PG8_LDA(At, 0, 0); PG8_STAGE(PG8_SA(1, 1), a1 + hstepA, voffA);
;             PG8_WAIT_V(8); PG8_WAIT_L(0); PG8_BAR; PG8_MMA(0, 0, At, B0); PG8_MMA(0, 1, At, B1); PG8_BAR; PG8_SCHED;
;             PG8_LDA(At, 0, 1); PG8_STAGE(PG8_SB(0, 0), b2, voffB); PG8_STAGE(PG8_SB(0, 1), b2 + hstepB, voffB); PG8_STAGE(PG8_SA(0, 0), a2, voffA);
;             PG8_WAIT_V(8); PG8_WAIT_L(0); PG8_BAR; PG8_MMA(1, 0, At, B0); PG8_MMA(1, 1, At, B1); PG8_BAR; PG8_SCHED;
.LBB0_324:
	s_ashr_i32 s15, s14, 31
	s_lshl_b64 s[16:17], s[14:15], 19
	s_add_u32 s16, s28, s16
	s_addc_u32 s17, s29, s17
	s_and_b64 s[18:19], s[2:3], exec
	s_cselect_b32 s15, s17, s23
	s_cselect_b32 s61, s16, s22
	s_ashr_i32 s13, s12, 31
	s_lshl_b64 s[18:19], s[12:13], 19
	s_add_u32 s18, s4, s18
	s_addc_u32 s19, s5, s19
	s_and_b64 s[26:27], s[2:3], exec
	s_cselect_b32 s13, s19, s25
	s_cselect_b32 s62, s18, s24
	s_add_u32 s22, s22, 0x40080
	s_addc_u32 s23, s23, 0
	s_add_u32 s63, s24, 0x100
	s_addc_u32 s64, s25, 0
	s_mov_b32 s65, -2
	ds_read_b128 v[18:21], v191
	ds_read_b128 v[26:29], v191 offset:2048
	ds_read_b128 v[22:25], v192
	ds_read_b128 v[30:33], v192 offset:2048
	ds_read_b128 v[2:5], v193
	ds_read_b128 v[10:13], v193 offset:2048
	ds_read_b128 v[6:9], v194
	ds_read_b128 v[14:17], v194 offset:2048
	s_add_u32 s24, s22, 0xfffc0080
	s_addc_u32 s25, s23, -1
	s_cmp_eq_u32 s65, 12
	s_cselect_b32 s27, s15, s25
	s_cselect_b32 s26, s61, s24
	s_cselect_b32 s25, s13, s64
	s_cselect_b32 s24, s62, s63
	s_add_i32 m0, s21, 0xc000
	ds_read_b128 v[178:181], v195
	ds_read_b128 v[198:201], v195 offset:2048
	ds_read_b128 v[182:185], v196
	ds_read_b128 v[202:205], v196 offset:2048
	ds_read_b128 v[206:209], v195 offset:4096
	ds_read_b128 v[214:217], v195 offset:6144
	ds_read_b128 v[210:213], v196 offset:4096
	ds_read_b128 v[218:221], v196 offset:6144
	global_load_lds_dwordx4 v170, s[22:23]
	s_add_i32 m0, s21, 0xe000
	s_nop 0
	global_load_lds_dwordx4 v172, s[22:23]
	s_waitcnt vmcnt(8)
	s_waitcnt lgkmcnt(0)
	s_barrier
	s_setprio 1
	s_waitcnt lgkmcnt(0)
	v_mfma_scale_f32_16x16x128_f8f6f4 v[158:161], v[18:25], v[178:185], 0, v1, v186 op_sel_hi:[0,0,0]
	v_mfma_scale_f32_16x16x128_f8f6f4 v[150:153], v[26:33], v[178:185], 0, v1, v186 op_sel_hi:[0,0,0]
	v_mfma_scale_f32_16x16x128_f8f6f4 v[142:145], v[18:25], v[198:205], 0, v1, v186 op_sel_hi:[0,0,0]
	v_mfma_scale_f32_16x16x128_f8f6f4 v[134:137], v[26:33], v[198:205], 0, v1, v186 op_sel_hi:[0,0,0]
	v_mfma_scale_f32_16x16x128_f8f6f4 v[126:129], v[18:25], v[206:213], 0, v1, v186 op_sel_hi:[0,0,0]
	v_mfma_scale_f32_16x16x128_f8f6f4 v[118:121], v[26:33], v[206:213], 0, v1, v186 op_sel_hi:[0,0,0]
	v_mfma_scale_f32_16x16x128_f8f6f4 v[110:113], v[18:25], v[214:221], 0, v1, v186 op_sel_hi:[0,0,0]
	v_mfma_scale_f32_16x16x128_f8f6f4 v[102:105], v[26:33], v[214:221], 0, v1, v186 op_sel_hi:[0,0,0]
	s_setprio 0
	s_setprio 1
	v_mfma_scale_f32_16x16x128_f8f6f4 v[154:157], v[2:9], v[178:185], 0, v1, v186 op_sel_hi:[0,0,0]
	v_mfma_scale_f32_16x16x128_f8f6f4 v[146:149], v[10:17], v[178:185], 0, v1, v186 op_sel_hi:[0,0,0]
	v_mfma_scale_f32_16x16x128_f8f6f4 v[138:141], v[2:9], v[198:205], 0, v1, v186 op_sel_hi:[0,0,0]
	v_mfma_scale_f32_16x16x128_f8f6f4 v[130:133], v[10:17], v[198:205], 0, v1, v186 op_sel_hi:[0,0,0]
	v_mfma_scale_f32_16x16x128_f8f6f4 v[122:125], v[2:9], v[206:213], 0, v1, v186 op_sel_hi:[0,0,0]
	v_mfma_scale_f32_16x16x128_f8f6f4 v[114:117], v[10:17], v[206:213], 0, v1, v186 op_sel_hi:[0,0,0]
	v_mfma_scale_f32_16x16x128_f8f6f4 v[106:109], v[2:9], v[214:221], 0, v1, v186 op_sel_hi:[0,0,0]
	v_mfma_scale_f32_16x16x128_f8f6f4 v[98:101], v[10:17], v[214:221], 0, v1, v186 op_sel_hi:[0,0,0]
	s_setprio 0
	s_barrier
	s_add_i32 s66, s57, s30
	s_mov_b32 m0, s66
	ds_read_b128 v[198:201], v195 offset:16384
	ds_read_b128 v[206:209], v195 offset:18432
	ds_read_b128 v[202:205], v196 offset:16384
	ds_read_b128 v[210:213], v196 offset:18432
	ds_read_b128 v[214:217], v195 offset:20480
	ds_read_b128 v[222:225], v195 offset:22528
	ds_read_b128 v[218:221], v196 offset:20480
	ds_read_b128 v[226:229], v196 offset:22528
	global_load_lds_dwordx4 v164, s[24:25]
	s_add_i32 m0, s66, 0x2000
	s_add_u32 s66, s24, 0x40000
	s_addc_u32 s67, s25, 0
	s_add_i32 s72, s58, s30
	global_load_lds_dwordx4 v168, s[24:25]
	s_mov_b32 m0, s72
	s_nop 0
	global_load_lds_dwordx4 v164, s[66:67]
	s_add_i32 m0, s72, 0x2000
	s_nop 0
	global_load_lds_dwordx4 v168, s[66:67]
	s_mov_b32 m0, s21
	s_nop 0
	global_load_lds_dwordx4 v162, s[26:27]
	s_mov_b32 m0, s34
	s_nop 0
	global_load_lds_dwordx4 v166, s[26:27]
	s_waitcnt vmcnt(8)
	s_waitcnt lgkmcnt(0)
	s_barrier
	s_setprio 1
	s_waitcnt lgkmcnt(0)
	v_mfma_scale_f32_16x16x128_f8f6f4 v[94:97], v[18:25], v[198:205], 0, v1, v186 op_sel_hi:[0,0,0]
	v_mfma_scale_f32_16x16x128_f8f6f4 v[86:89], v[26:33], v[198:205], 0, v1, v186 op_sel_hi:[0,0,0]
	v_mfma_scale_f32_16x16x128_f8f6f4 v[78:81], v[18:25], v[206:213], 0, v1, v186 op_sel_hi:[0,0,0]
	v_mfma_scale_f32_16x16x128_f8f6f4 v[70:73], v[26:33], v[206:213], 0, v1, v186 op_sel_hi:[0,0,0]
	v_mfma_scale_f32_16x16x128_f8f6f4 v[62:65], v[18:25], v[214:221], 0, v1, v186 op_sel_hi:[0,0,0]
	v_mfma_scale_f32_16x16x128_f8f6f4 v[54:57], v[26:33], v[214:221], 0, v1, v186 op_sel_hi:[0,0,0]
	v_mfma_scale_f32_16x16x128_f8f6f4 v[46:49], v[18:25], v[222:229], 0, v1, v186 op_sel_hi:[0,0,0]
	v_mfma_scale_f32_16x16x128_f8f6f4 v[38:41], v[26:33], v[222:229], 0, v1, v186 op_sel_hi:[0,0,0]
	s_setprio 0
	s_setprio 1
	v_mfma_scale_f32_16x16x128_f8f6f4 v[90:93], v[2:9], v[198:205], 0, v1, v186 op_sel_hi:[0,0,0]
	v_mfma_scale_f32_16x16x128_f8f6f4 v[82:85], v[10:17], v[198:205], 0, v1, v186 op_sel_hi:[0,0,0]
	v_mfma_scale_f32_16x16x128_f8f6f4 v[74:77], v[2:9], v[206:213], 0, v1, v186 op_sel_hi:[0,0,0]
	v_mfma_scale_f32_16x16x128_f8f6f4 v[66:69], v[10:17], v[206:213], 0, v1, v186 op_sel_hi:[0,0,0]
	v_mfma_scale_f32_16x16x128_f8f6f4 v[58:61], v[2:9], v[214:221], 0, v1, v186 op_sel_hi:[0,0,0]
	v_mfma_scale_f32_16x16x128_f8f6f4 v[50:53], v[10:17], v[214:221], 0, v1, v186 op_sel_hi:[0,0,0]
	v_mfma_scale_f32_16x16x128_f8f6f4 v[42:45], v[2:9], v[222:229], 0, v1, v186 op_sel_hi:[0,0,0]
	v_mfma_scale_f32_16x16x128_f8f6f4 v[34:37], v[10:17], v[222:229], 0, v1, v186 op_sel_hi:[0,0,0]
	s_setprio 0
	s_barrier
; #define PG8_STAGE(bufoff, gbase, voff) do { _Pragma("unroll") for (int _i = 0; _i < 2; ++_i) \
;         __builtin_amdgcn_global_load_lds((const unsigned*)((const char*)(gbase) + (voff)[_i]), (PG8_LAS unsigned*)(lds + (bufoff) + ldsw + _i * 8192), 16, 0, 0); } while (0)
; #define PG8_LDA(dst, b, h) do { _Pragma("unroll") for (int m = 0; m < 4; ++m) _Pragma("unroll") for (int k = 0; k < 2; ++k) dst[m][k] = *(const PG8_LAS bf16x8*)(lds + PG8_SA(b, h) + aoff + m * 2048 + k * 1024); } while (0)
; #define PG8_LDB(dst, b, h) do { _Pragma("unroll") for (int n = 0; n < 2; ++n) _Pragma("unroll") for (int k = 0; k < 2; ++k) dst[n][k] = *(const PG8_LAS bf16x8*)(lds + PG8_SB(b, h) + boff + n * 2048 + k * 1024); } while (0)
; #define PG8_MMA(ai, bj, At, Bt) do { __builtin_amdgcn_s_setprio(1); _Pragma("unroll") for (int m = 0; m < 4; ++m) _Pragma("unroll") for (int n = 0; n < 2; ++n) _Pragma("unroll") for (int k = 0; k < 2; ++k) \
;         acc[ai][bj][m][n] = __builtin_amdgcn_mfma_f32_16x16x32_bf16(Bt[n][k], At[m][k], acc[ai][bj][m][n], 0, 0, 0); __builtin_amdgcn_s_setprio(0); } while (0)
; #define PG8_WAIT_V(n) asm volatile("s_waitcnt vmcnt(" #n ")" ::: "memory")
; #define PG8_WAIT_L(n) asm volatile("s_waitcnt lgkmcnt(" #n ")" ::: "memory")
; #define PG8_BAR __builtin_amdgcn_s_barrier()
; #define PG8_SCHED __builtin_amdgcn_sched_barrier(0)
; #define PG8_STAGE(bufoff, gbase, voff) do { _Pragma("unroll") for (int _i = 0; _i < 2; ++_i) \
;         __builtin_amdgcn_global_load_lds((const unsigned*)((const char*)(gbase) + (voff)[_i]), (PG8_LAS unsigned*)(lds + (bufoff) + ldsw + _i * 8192), 16, 0, 0); } while (0)
; #define PG8_WAIT_V(n) asm volatile("s_waitcnt vmcnt(" #n ")" ::: "memory")
; template <class Epi, class Sched, bool ALIGN_EPI = false>
; __device__ __forceinline__ void gemm_phase8(PG8_LAS unsigned char* lds, const Gemm g, const Sched& S, const Epi& E) {
;     ...
;             PG8_LDB(B0, 1, 0); PG8_LDB(B1, 1, 1); PG8_SCHED; PG8_LDA(At, 1, 0); PG8_STAGE(PG8_SA(0, 1), a2 + hstepA, voffA);
;             PG8_WAIT_V(8); PG8_WAIT_L(0); PG8_BAR; PG8_MMA(0, 0, At, B0); PG8_MMA(0, 1, At, B1); PG8_BAR; PG8_SCHED;
;             PG8_LDA(At, 1, 1); PG8_STAGE(PG8_SB(1, 0), b3, voffB); PG8_STAGE(PG8_SB(1, 1), b3 + hstepB, voffB); PG8_STAGE(PG8_SA(1, 0), a3, voffA);
;             PG8_WAIT_V(8); PG8_WAIT_L(0); PG8_BAR; PG8_MMA(1, 0, At, B0); PG8_MMA(1, 1, At, B1); PG8_BAR; PG8_SCHED;
	s_add_i32 s66, 0, 0x18000
	s_add_i32 s67, 0, 0x1c000
	v_add_u32_e32 v6, s66, v187
	v_add_u32_e32 v14, s66, v188
	v_add_u32_e32 v22, s67, v187
	v_add_u32_e32 v30, s67, v188
	ds_read_b128 v[2:5], v6
	ds_read_b128 v[10:13], v6 offset:2048
	ds_read_b128 v[6:9], v14
	ds_read_b128 v[14:17], v14 offset:2048
	ds_read_b128 v[18:21], v22
	ds_read_b128 v[26:29], v22 offset:2048
	ds_read_b128 v[22:25], v30
	ds_read_b128 v[30:33], v30 offset:2048
	s_add_u32 s26, s26, 0x40000
	s_addc_u32 s27, s27, 0
	s_mov_b32 m0, s35
	ds_read_b128 v[198:201], v195 offset:32768
	ds_read_b128 v[206:209], v195 offset:34816
	ds_read_b128 v[202:205], v196 offset:32768
	ds_read_b128 v[210:213], v196 offset:34816
	ds_read_b128 v[214:217], v195 offset:36864
	ds_read_b128 v[222:225], v195 offset:38912
	ds_read_b128 v[218:221], v196 offset:36864
	ds_read_b128 v[226:229], v196 offset:38912
	global_load_lds_dwordx4 v162, s[26:27]
	s_mov_b32 m0, s52
	s_nop 0
	global_load_lds_dwordx4 v166, s[26:27]
	s_waitcnt vmcnt(8)
	s_waitcnt lgkmcnt(0)
	s_barrier
	s_setprio 1
	s_waitcnt lgkmcnt(0)
	v_mfma_scale_f32_16x16x128_f8f6f4 v[158:161], v[2:9], v[198:205], v[158:161], v1, v186 op_sel_hi:[0,0,0]
	v_mfma_scale_f32_16x16x128_f8f6f4 v[150:153], v[10:17], v[198:205], v[150:153], v1, v186 op_sel_hi:[0,0,0]
	v_mfma_scale_f32_16x16x128_f8f6f4 v[142:145], v[2:9], v[206:213], v[142:145], v1, v186 op_sel_hi:[0,0,0]
	v_mfma_scale_f32_16x16x128_f8f6f4 v[134:137], v[10:17], v[206:213], v[134:137], v1, v186 op_sel_hi:[0,0,0]
	v_mfma_scale_f32_16x16x128_f8f6f4 v[126:129], v[2:9], v[214:221], v[126:129], v1, v186 op_sel_hi:[0,0,0]
	v_mfma_scale_f32_16x16x128_f8f6f4 v[118:121], v[10:17], v[214:221], v[118:121], v1, v186 op_sel_hi:[0,0,0]
	v_mfma_scale_f32_16x16x128_f8f6f4 v[110:113], v[2:9], v[222:229], v[110:113], v1, v186 op_sel_hi:[0,0,0]
	v_mfma_scale_f32_16x16x128_f8f6f4 v[102:105], v[10:17], v[222:229], v[102:105], v1, v186 op_sel_hi:[0,0,0]
	s_setprio 0
	s_setprio 1
	v_mfma_scale_f32_16x16x128_f8f6f4 v[154:157], v[18:25], v[198:205], v[154:157], v1, v186 op_sel_hi:[0,0,0]
	v_mfma_scale_f32_16x16x128_f8f6f4 v[146:149], v[26:33], v[198:205], v[146:149], v1, v186 op_sel_hi:[0,0,0]
	v_mfma_scale_f32_16x16x128_f8f6f4 v[138:141], v[18:25], v[206:213], v[138:141], v1, v186 op_sel_hi:[0,0,0]
	v_mfma_scale_f32_16x16x128_f8f6f4 v[130:133], v[26:33], v[206:213], v[130:133], v1, v186 op_sel_hi:[0,0,0]
	v_mfma_scale_f32_16x16x128_f8f6f4 v[122:125], v[18:25], v[214:221], v[122:125], v1, v186 op_sel_hi:[0,0,0]
	v_mfma_scale_f32_16x16x128_f8f6f4 v[114:117], v[26:33], v[214:221], v[114:117], v1, v186 op_sel_hi:[0,0,0]
	v_mfma_scale_f32_16x16x128_f8f6f4 v[106:109], v[18:25], v[222:229], v[106:109], v1, v186 op_sel_hi:[0,0,0]
	v_mfma_scale_f32_16x16x128_f8f6f4 v[98:101], v[26:33], v[222:229], v[98:101], v1, v186 op_sel_hi:[0,0,0]
	s_setprio 0
	s_barrier
	s_add_i32 s101, s66, s30
	s_add_u32 s98, s24, s8
	s_addc_u32 s99, s25, s9
	s_mov_b32 m0, s101
	ds_read_b128 v[198:201], v195 offset:49152
	ds_read_b128 v[206:209], v195 offset:51200
	ds_read_b128 v[202:205], v196 offset:49152
	ds_read_b128 v[210:213], v196 offset:51200
	ds_read_b128 v[214:217], v195 offset:53248
	ds_read_b128 v[222:225], v195 offset:55296
	ds_read_b128 v[218:221], v196 offset:53248
	ds_read_b128 v[226:229], v196 offset:55296
	global_load_lds_dwordx4 v164, s[98:99]
	s_add_i32 m0, s101, 0x2000
	s_add_u32 s24, s24, 0x40080
	s_addc_u32 s25, s25, 0
	s_add_i32 s101, s67, s30
	global_load_lds_dwordx4 v168, s[98:99]
	s_add_u32 s98, s26, s8
	s_addc_u32 s99, s27, s9
	s_sub_u32 s98, s98, 0x40000
	s_subb_u32 s99, s99, 0
	s_mov_b32 m0, s101
	s_nop 0
	global_load_lds_dwordx4 v164, s[24:25]
	s_add_i32 m0, s101, 0x2000
	s_nop 0
	global_load_lds_dwordx4 v168, s[24:25]
	s_mov_b32 m0, s55
	s_nop 0
	global_load_lds_dwordx4 v162, s[98:99]
	s_mov_b32 m0, s56
	s_nop 0
	global_load_lds_dwordx4 v166, s[98:99]
	s_waitcnt vmcnt(8)
	s_waitcnt lgkmcnt(0)
	s_barrier
	s_setprio 1
	s_waitcnt lgkmcnt(0)
	v_mfma_scale_f32_16x16x128_f8f6f4 v[94:97], v[2:9], v[198:205], v[94:97], v1, v186 op_sel_hi:[0,0,0]
	v_mfma_scale_f32_16x16x128_f8f6f4 v[86:89], v[10:17], v[198:205], v[86:89], v1, v186 op_sel_hi:[0,0,0]
	v_mfma_scale_f32_16x16x128_f8f6f4 v[78:81], v[2:9], v[206:213], v[78:81], v1, v186 op_sel_hi:[0,0,0]
	v_mfma_scale_f32_16x16x128_f8f6f4 v[70:73], v[10:17], v[206:213], v[70:73], v1, v186 op_sel_hi:[0,0,0]
	v_mfma_scale_f32_16x16x128_f8f6f4 v[62:65], v[2:9], v[214:221], v[62:65], v1, v186 op_sel_hi:[0,0,0]
	v_mfma_scale_f32_16x16x128_f8f6f4 v[54:57], v[10:17], v[214:221], v[54:57], v1, v186 op_sel_hi:[0,0,0]
	v_mfma_scale_f32_16x16x128_f8f6f4 v[46:49], v[2:9], v[222:229], v[46:49], v1, v186 op_sel_hi:[0,0,0]
	v_mfma_scale_f32_16x16x128_f8f6f4 v[38:41], v[10:17], v[222:229], v[38:41], v1, v186 op_sel_hi:[0,0,0]
	s_setprio 0
	s_setprio 1
	v_mfma_scale_f32_16x16x128_f8f6f4 v[90:93], v[18:25], v[198:205], v[90:93], v1, v186 op_sel_hi:[0,0,0]
	v_mfma_scale_f32_16x16x128_f8f6f4 v[82:85], v[26:33], v[198:205], v[82:85], v1, v186 op_sel_hi:[0,0,0]
	v_mfma_scale_f32_16x16x128_f8f6f4 v[74:77], v[18:25], v[206:213], v[74:77], v1, v186 op_sel_hi:[0,0,0]
	v_mfma_scale_f32_16x16x128_f8f6f4 v[66:69], v[26:33], v[206:213], v[66:69], v1, v186 op_sel_hi:[0,0,0]
	v_mfma_scale_f32_16x16x128_f8f6f4 v[58:61], v[18:25], v[214:221], v[58:61], v1, v186 op_sel_hi:[0,0,0]
	v_mfma_scale_f32_16x16x128_f8f6f4 v[50:53], v[26:33], v[214:221], v[50:53], v1, v186 op_sel_hi:[0,0,0]
	v_mfma_scale_f32_16x16x128_f8f6f4 v[42:45], v[18:25], v[222:229], v[42:45], v1, v186 op_sel_hi:[0,0,0]
	v_mfma_scale_f32_16x16x128_f8f6f4 v[34:37], v[26:33], v[222:229], v[34:37], v1, v186 op_sel_hi:[0,0,0]
	s_setprio 0
	s_barrier
; #define PG8_STAGE(bufoff, gbase, voff) do { _Pragma("unroll") for (int _i = 0; _i < 2; ++_i) \
;         __builtin_amdgcn_global_load_lds((const unsigned*)((const char*)(gbase) + (voff)[_i]), (PG8_LAS unsigned*)(lds + (bufoff) + ldsw + _i * 8192), 16, 0, 0); } while (0)
; #define PG8_LDA(dst, b, h) do { _Pragma("unroll") for (int m = 0; m < 4; ++m) _Pragma("unroll") for (int k = 0; k < 2; ++k) dst[m][k] = *(const PG8_LAS bf16x8*)(lds + PG8_SA(b, h) + aoff + m * 2048 + k * 1024); } while (0)
; #define PG8_LDB(dst, b, h) do { _Pragma("unroll") for (int n = 0; n < 2; ++n) _Pragma("unroll") for (int k = 0; k < 2; ++k) dst[n][k] = *(const PG8_LAS bf16x8*)(lds + PG8_SB(b, h) + boff + n * 2048 + k * 1024); } while (0)
; #define PG8_MMA(ai, bj, At, Bt) do { __builtin_amdgcn_s_setprio(1); _Pragma("unroll") for (int m = 0; m < 4; ++m) _Pragma("unroll") for (int n = 0; n < 2; ++n) _Pragma("unroll") for (int k = 0; k < 2; ++k) \
;         acc[ai][bj][m][n] = __builtin_amdgcn_mfma_f32_16x16x32_bf16(Bt[n][k], At[m][k], acc[ai][bj][m][n], 0, 0, 0); __builtin_amdgcn_s_setprio(0); } while (0)
; #define PG8_WAIT_V(n) asm volatile("s_waitcnt vmcnt(" #n ")" ::: "memory")
; #define PG8_WAIT_L(n) asm volatile("s_waitcnt lgkmcnt(" #n ")" ::: "memory")
; template <class Epi, class Sched, bool ALIGN_EPI = false>
; __device__ __forceinline__ void gemm_phase8(PG8_LAS unsigned char* lds, const Gemm g, const Sched& S, const Epi& E) {
;     ...
;         for (int t = 0; t < nt; t += 2) {
;             const bool last = (t == nt - 2);
;             const char* a1 = cA + (size_t)(t + 1) * kstep;
;             const char* a2 = last ? nA : cA + (size_t)(t + 2) * kstep; const char* b2 = last ? nB : cB + (size_t)(t + 2) * kstep;
;             const char* a3 = a2 + kstep; const char* b3 = b2 + kstep;
;             if (last && has_next) S.a_ready(nxt);
;             PG8_LDB(B0, 0, 0); PG8_LDB(B1, 0, 1); PG8_SCHED; PG8_LDA(At, 0, 0); PG8_STAGE(PG8_SA(1, 1), a1 + hstepA, voffA);
;             PG8_WAIT_V(8); PG8_WAIT_L(0); PG8_BAR; PG8_MMA(0, 0, At, B0); PG8_MMA(0, 1, At, B1); PG8_BAR; PG8_SCHED;
;             PG8_LDA(At, 0, 1); PG8_STAGE(PG8_SB(0, 0), b2, voffB); PG8_STAGE(PG8_SB(0, 1), b2 + hstepB, voffB); PG8_STAGE(PG8_SA(0, 0), a2, voffA);
;             PG8_WAIT_V(8); PG8_WAIT_L(0); PG8_BAR; PG8_MMA(1, 0, At, B0); PG8_MMA(1, 1, At, B1); PG8_BAR; PG8_SCHED;
	s_add_i32 s65, s65, 2
	s_add_u32 s22, s22, 0x100
	s_addc_u32 s23, s23, 0
	s_add_u32 s63, s63, 0x100
	s_addc_u32 s64, s64, 0
	s_cmp_gt_u32 s65, 13
	ds_read_b128 v[18:21], v191
	ds_read_b128 v[26:29], v191 offset:2048
	ds_read_b128 v[22:25], v192
	ds_read_b128 v[30:33], v192 offset:2048
	ds_read_b128 v[2:5], v193
	ds_read_b128 v[10:13], v193 offset:2048
	ds_read_b128 v[6:9], v194
	ds_read_b128 v[14:17], v194 offset:2048
	s_add_u32 s24, s22, 0xfffc0080
	s_addc_u32 s25, s23, -1
	s_cmp_eq_u32 s65, 12
	s_cselect_b32 s27, s15, s25
	s_cselect_b32 s26, s61, s24
	s_cselect_b32 s25, s13, s64
	s_cselect_b32 s24, s62, s63
	s_add_i32 m0, s21, 0xc000
	ds_read_b128 v[178:181], v195
	ds_read_b128 v[198:201], v195 offset:2048
	ds_read_b128 v[182:185], v196
	ds_read_b128 v[202:205], v196 offset:2048
	ds_read_b128 v[206:209], v195 offset:4096
	ds_read_b128 v[214:217], v195 offset:6144
	ds_read_b128 v[210:213], v196 offset:4096
	ds_read_b128 v[218:221], v196 offset:6144
	global_load_lds_dwordx4 v170, s[22:23]
	s_add_i32 m0, s21, 0xe000
	s_nop 0
	global_load_lds_dwordx4 v172, s[22:23]
	s_waitcnt vmcnt(8)
	s_waitcnt lgkmcnt(0)
	s_barrier
	s_setprio 1
	s_waitcnt lgkmcnt(0)
	v_mfma_scale_f32_16x16x128_f8f6f4 v[158:161], v[18:25], v[178:185], v[158:161], v1, v186 op_sel_hi:[0,0,0]
	v_mfma_scale_f32_16x16x128_f8f6f4 v[150:153], v[26:33], v[178:185], v[150:153], v1, v186 op_sel_hi:[0,0,0]
	v_mfma_scale_f32_16x16x128_f8f6f4 v[142:145], v[18:25], v[198:205], v[142:145], v1, v186 op_sel_hi:[0,0,0]
	v_mfma_scale_f32_16x16x128_f8f6f4 v[134:137], v[26:33], v[198:205], v[134:137], v1, v186 op_sel_hi:[0,0,0]
	v_mfma_scale_f32_16x16x128_f8f6f4 v[126:129], v[18:25], v[206:213], v[126:129], v1, v186 op_sel_hi:[0,0,0]
	v_mfma_scale_f32_16x16x128_f8f6f4 v[118:121], v[26:33], v[206:213], v[118:121], v1, v186 op_sel_hi:[0,0,0]
	v_mfma_scale_f32_16x16x128_f8f6f4 v[110:113], v[18:25], v[214:221], v[110:113], v1, v186 op_sel_hi:[0,0,0]
	v_mfma_scale_f32_16x16x128_f8f6f4 v[102:105], v[26:33], v[214:221], v[102:105], v1, v186 op_sel_hi:[0,0,0]
	s_setprio 0
	s_setprio 1
	v_mfma_scale_f32_16x16x128_f8f6f4 v[154:157], v[2:9], v[178:185], v[154:157], v1, v186 op_sel_hi:[0,0,0]
	v_mfma_scale_f32_16x16x128_f8f6f4 v[146:149], v[10:17], v[178:185], v[146:149], v1, v186 op_sel_hi:[0,0,0]
	v_mfma_scale_f32_16x16x128_f8f6f4 v[138:141], v[2:9], v[198:205], v[138:141], v1, v186 op_sel_hi:[0,0,0]
	v_mfma_scale_f32_16x16x128_f8f6f4 v[130:133], v[10:17], v[198:205], v[130:133], v1, v186 op_sel_hi:[0,0,0]
	v_mfma_scale_f32_16x16x128_f8f6f4 v[122:125], v[2:9], v[206:213], v[122:125], v1, v186 op_sel_hi:[0,0,0]
	v_mfma_scale_f32_16x16x128_f8f6f4 v[114:117], v[10:17], v[206:213], v[114:117], v1, v186 op_sel_hi:[0,0,0]
	v_mfma_scale_f32_16x16x128_f8f6f4 v[106:109], v[2:9], v[214:221], v[106:109], v1, v186 op_sel_hi:[0,0,0]
	v_mfma_scale_f32_16x16x128_f8f6f4 v[98:101], v[10:17], v[214:221], v[98:101], v1, v186 op_sel_hi:[0,0,0]
	s_setprio 0
	s_barrier
	s_add_i32 s66, s57, s30
	s_mov_b32 m0, s66
	ds_read_b128 v[198:201], v195 offset:16384
	ds_read_b128 v[206:209], v195 offset:18432
	ds_read_b128 v[202:205], v196 offset:16384
	ds_read_b128 v[210:213], v196 offset:18432
	ds_read_b128 v[214:217], v195 offset:20480
	ds_read_b128 v[222:225], v195 offset:22528
	ds_read_b128 v[218:221], v196 offset:20480
	ds_read_b128 v[226:229], v196 offset:22528
	global_load_lds_dwordx4 v164, s[24:25]
	s_add_i32 m0, s66, 0x2000
	s_add_u32 s66, s24, 0x40000
	s_addc_u32 s67, s25, 0
	s_add_i32 s72, s58, s30
	global_load_lds_dwordx4 v168, s[24:25]
	s_mov_b32 m0, s72
	s_nop 0
	global_load_lds_dwordx4 v164, s[66:67]
	s_add_i32 m0, s72, 0x2000
	s_nop 0
	global_load_lds_dwordx4 v168, s[66:67]
	s_mov_b32 m0, s21
	s_nop 0
	global_load_lds_dwordx4 v162, s[26:27]
	s_mov_b32 m0, s34
	s_nop 0
	global_load_lds_dwordx4 v166, s[26:27]
	s_waitcnt vmcnt(8)
	s_waitcnt lgkmcnt(0)
	s_barrier
	s_setprio 1
	s_waitcnt lgkmcnt(0)
	v_mfma_scale_f32_16x16x128_f8f6f4 v[94:97], v[18:25], v[198:205], v[94:97], v1, v186 op_sel_hi:[0,0,0]
	v_mfma_scale_f32_16x16x128_f8f6f4 v[86:89], v[26:33], v[198:205], v[86:89], v1, v186 op_sel_hi:[0,0,0]
	v_mfma_scale_f32_16x16x128_f8f6f4 v[78:81], v[18:25], v[206:213], v[78:81], v1, v186 op_sel_hi:[0,0,0]
	v_mfma_scale_f32_16x16x128_f8f6f4 v[70:73], v[26:33], v[206:213], v[70:73], v1, v186 op_sel_hi:[0,0,0]
	v_mfma_scale_f32_16x16x128_f8f6f4 v[62:65], v[18:25], v[214:221], v[62:65], v1, v186 op_sel_hi:[0,0,0]
	v_mfma_scale_f32_16x16x128_f8f6f4 v[54:57], v[26:33], v[214:221], v[54:57], v1, v186 op_sel_hi:[0,0,0]
	v_mfma_scale_f32_16x16x128_f8f6f4 v[46:49], v[18:25], v[222:229], v[46:49], v1, v186 op_sel_hi:[0,0,0]
	v_mfma_scale_f32_16x16x128_f8f6f4 v[38:41], v[26:33], v[222:229], v[38:41], v1, v186 op_sel_hi:[0,0,0]
	s_setprio 0
	s_setprio 1
	v_mfma_scale_f32_16x16x128_f8f6f4 v[90:93], v[2:9], v[198:205], v[90:93], v1, v186 op_sel_hi:[0,0,0]
	v_mfma_scale_f32_16x16x128_f8f6f4 v[82:85], v[10:17], v[198:205], v[82:85], v1, v186 op_sel_hi:[0,0,0]
	v_mfma_scale_f32_16x16x128_f8f6f4 v[74:77], v[2:9], v[206:213], v[74:77], v1, v186 op_sel_hi:[0,0,0]
	v_mfma_scale_f32_16x16x128_f8f6f4 v[66:69], v[10:17], v[206:213], v[66:69], v1, v186 op_sel_hi:[0,0,0]
	v_mfma_scale_f32_16x16x128_f8f6f4 v[58:61], v[2:9], v[214:221], v[58:61], v1, v186 op_sel_hi:[0,0,0]
	v_mfma_scale_f32_16x16x128_f8f6f4 v[50:53], v[10:17], v[214:221], v[50:53], v1, v186 op_sel_hi:[0,0,0]
	v_mfma_scale_f32_16x16x128_f8f6f4 v[42:45], v[2:9], v[222:229], v[42:45], v1, v186 op_sel_hi:[0,0,0]
	v_mfma_scale_f32_16x16x128_f8f6f4 v[34:37], v[10:17], v[222:229], v[34:37], v1, v186 op_sel_hi:[0,0,0]
	s_setprio 0
	s_barrier
; #define PG8_STAGE(bufoff, gbase, voff) do { _Pragma("unroll") for (int _i = 0; _i < 2; ++_i) \
;         __builtin_amdgcn_global_load_lds((const unsigned*)((const char*)(gbase) + (voff)[_i]), (PG8_LAS unsigned*)(lds + (bufoff) + ldsw + _i * 8192), 16, 0, 0); } while (0)
; #define PG8_LDA(dst, b, h) do { _Pragma("unroll") for (int m = 0; m < 4; ++m) _Pragma("unroll") for (int k = 0; k < 2; ++k) dst[m][k] = *(const PG8_LAS bf16x8*)(lds + PG8_SA(b, h) + aoff + m * 2048 + k * 1024); } while (0)
; #define PG8_LDB(dst, b, h) do { _Pragma("unroll") for (int n = 0; n < 2; ++n) _Pragma("unroll") for (int k = 0; k < 2; ++k) dst[n][k] = *(const PG8_LAS bf16x8*)(lds + PG8_SB(b, h) + boff + n * 2048 + k * 1024); } while (0)
; #define PG8_MMA(ai, bj, At, Bt) do { __builtin_amdgcn_s_setprio(1); _Pragma("unroll") for (int m = 0; m < 4; ++m) _Pragma("unroll") for (int n = 0; n < 2; ++n) _Pragma("unroll") for (int k = 0; k < 2; ++k) \
;         acc[ai][bj][m][n] = __builtin_amdgcn_mfma_f32_16x16x32_bf16(Bt[n][k], At[m][k], acc[ai][bj][m][n], 0, 0, 0); __builtin_amdgcn_s_setprio(0); } while (0)
; #define PG8_WAIT_V(n) asm volatile("s_waitcnt vmcnt(" #n ")" ::: "memory")
; #define PG8_WAIT_L(n) asm volatile("s_waitcnt lgkmcnt(" #n ")" ::: "memory")
; #define PG8_BAR __builtin_amdgcn_s_barrier()
; #define PG8_SCHED __builtin_amdgcn_sched_barrier(0)
; #define PG8_STAGE(bufoff, gbase, voff) do { _Pragma("unroll") for (int _i = 0; _i < 2; ++_i) \
;         __builtin_amdgcn_global_load_lds((const unsigned*)((const char*)(gbase) + (voff)[_i]), (PG8_LAS unsigned*)(lds + (bufoff) + ldsw + _i * 8192), 16, 0, 0); } while (0)
; #define PG8_BAR __builtin_amdgcn_s_barrier()
; template <class Epi, class Sched, bool ALIGN_EPI = false>
; __device__ __forceinline__ void gemm_phase8(PG8_LAS unsigned char* lds, const Gemm g, const Sched& S, const Epi& E) {
;     ...
;             PG8_LDB(B0, 1, 0); PG8_LDB(B1, 1, 1); PG8_SCHED; PG8_LDA(At, 1, 0); PG8_STAGE(PG8_SA(0, 1), a2 + hstepA, voffA);
;             PG8_WAIT_V(8); PG8_WAIT_L(0); PG8_BAR; PG8_MMA(0, 0, At, B0); PG8_MMA(0, 1, At, B1); PG8_BAR; PG8_SCHED;
;             PG8_LDA(At, 1, 1); PG8_STAGE(PG8_SB(1, 0), b3, voffB); PG8_STAGE(PG8_SB(1, 1), b3 + hstepB, voffB); PG8_STAGE(PG8_SA(1, 0), a3, voffA);
;             PG8_WAIT_V(8); PG8_WAIT_L(0); PG8_BAR; PG8_MMA(1, 0, At, B0); PG8_MMA(1, 1, At, B1); PG8_BAR; PG8_SCHED;
;         }
	s_add_i32 s66, 0, 0x18000
	s_add_i32 s67, 0, 0x1c000
	v_add_u32_e32 v6, s66, v187
	v_add_u32_e32 v14, s66, v188
	v_add_u32_e32 v22, s67, v187
	v_add_u32_e32 v30, s67, v188
	ds_read_b128 v[2:5], v6
	ds_read_b128 v[10:13], v6 offset:2048
	ds_read_b128 v[6:9], v14
	ds_read_b128 v[14:17], v14 offset:2048
	ds_read_b128 v[18:21], v22
	ds_read_b128 v[26:29], v22 offset:2048
	ds_read_b128 v[22:25], v30
	ds_read_b128 v[30:33], v30 offset:2048
	s_add_u32 s26, s26, 0x40000
	s_addc_u32 s27, s27, 0
	s_mov_b32 m0, s35
	ds_read_b128 v[198:201], v195 offset:32768
	ds_read_b128 v[206:209], v195 offset:34816
	ds_read_b128 v[202:205], v196 offset:32768
	ds_read_b128 v[210:213], v196 offset:34816
	ds_read_b128 v[214:217], v195 offset:36864
	ds_read_b128 v[222:225], v195 offset:38912
	ds_read_b128 v[218:221], v196 offset:36864
	ds_read_b128 v[226:229], v196 offset:38912
	global_load_lds_dwordx4 v162, s[26:27]
	s_mov_b32 m0, s52
	s_nop 0
	global_load_lds_dwordx4 v166, s[26:27]
	s_waitcnt vmcnt(8)
	s_waitcnt lgkmcnt(0)
	s_barrier
	s_setprio 1
	s_waitcnt lgkmcnt(0)
	v_mfma_scale_f32_16x16x128_f8f6f4 v[158:161], v[2:9], v[198:205], v[158:161], v1, v186 op_sel_hi:[0,0,0]
	v_mfma_scale_f32_16x16x128_f8f6f4 v[150:153], v[10:17], v[198:205], v[150:153], v1, v186 op_sel_hi:[0,0,0]
	v_mfma_scale_f32_16x16x128_f8f6f4 v[142:145], v[2:9], v[206:213], v[142:145], v1, v186 op_sel_hi:[0,0,0]
	v_mfma_scale_f32_16x16x128_f8f6f4 v[134:137], v[10:17], v[206:213], v[134:137], v1, v186 op_sel_hi:[0,0,0]
	v_mfma_scale_f32_16x16x128_f8f6f4 v[126:129], v[2:9], v[214:221], v[126:129], v1, v186 op_sel_hi:[0,0,0]
	v_mfma_scale_f32_16x16x128_f8f6f4 v[118:121], v[10:17], v[214:221], v[118:121], v1, v186 op_sel_hi:[0,0,0]
	v_mfma_scale_f32_16x16x128_f8f6f4 v[110:113], v[2:9], v[222:229], v[110:113], v1, v186 op_sel_hi:[0,0,0]
	v_mfma_scale_f32_16x16x128_f8f6f4 v[102:105], v[10:17], v[222:229], v[102:105], v1, v186 op_sel_hi:[0,0,0]
	s_setprio 0
	s_setprio 1
	v_mfma_scale_f32_16x16x128_f8f6f4 v[154:157], v[18:25], v[198:205], v[154:157], v1, v186 op_sel_hi:[0,0,0]
	v_mfma_scale_f32_16x16x128_f8f6f4 v[146:149], v[26:33], v[198:205], v[146:149], v1, v186 op_sel_hi:[0,0,0]
	v_mfma_scale_f32_16x16x128_f8f6f4 v[138:141], v[18:25], v[206:213], v[138:141], v1, v186 op_sel_hi:[0,0,0]
	v_mfma_scale_f32_16x16x128_f8f6f4 v[130:133], v[26:33], v[206:213], v[130:133], v1, v186 op_sel_hi:[0,0,0]
	v_mfma_scale_f32_16x16x128_f8f6f4 v[122:125], v[18:25], v[214:221], v[122:125], v1, v186 op_sel_hi:[0,0,0]
	v_mfma_scale_f32_16x16x128_f8f6f4 v[114:117], v[26:33], v[214:221], v[114:117], v1, v186 op_sel_hi:[0,0,0]
	v_mfma_scale_f32_16x16x128_f8f6f4 v[106:109], v[18:25], v[222:229], v[106:109], v1, v186 op_sel_hi:[0,0,0]
	v_mfma_scale_f32_16x16x128_f8f6f4 v[98:101], v[26:33], v[222:229], v[98:101], v1, v186 op_sel_hi:[0,0,0]
	s_setprio 0
	s_barrier
	s_add_i32 s101, s66, s30
	s_add_u32 s98, s24, s8
	s_addc_u32 s99, s25, s9
	s_mov_b32 m0, s101
	ds_read_b128 v[198:201], v195 offset:49152
	ds_read_b128 v[206:209], v195 offset:51200
	ds_read_b128 v[202:205], v196 offset:49152
	ds_read_b128 v[210:213], v196 offset:51200
	ds_read_b128 v[214:217], v195 offset:53248
	ds_read_b128 v[222:225], v195 offset:55296
	ds_read_b128 v[218:221], v196 offset:53248
	ds_read_b128 v[226:229], v196 offset:55296
	global_load_lds_dwordx4 v164, s[98:99]
	s_add_i32 m0, s101, 0x2000
	s_add_u32 s24, s24, 0x40080
	s_addc_u32 s25, s25, 0
	s_add_i32 s101, s67, s30
	global_load_lds_dwordx4 v168, s[98:99]
	s_add_u32 s98, s26, s8
	s_addc_u32 s99, s27, s9
	s_sub_u32 s98, s98, 0x40000
	s_subb_u32 s99, s99, 0
	s_mov_b32 m0, s101
	s_nop 0
	global_load_lds_dwordx4 v164, s[24:25]
	s_add_i32 m0, s101, 0x2000
	s_nop 0
	global_load_lds_dwordx4 v168, s[24:25]
	s_mov_b32 m0, s55
	s_nop 0
	global_load_lds_dwordx4 v162, s[98:99]
	s_mov_b32 m0, s56
	s_nop 0
	global_load_lds_dwordx4 v166, s[98:99]
	s_waitcnt vmcnt(8)
	s_waitcnt lgkmcnt(0)
	s_barrier
	s_setprio 1
	s_waitcnt lgkmcnt(0)
	v_mfma_scale_f32_16x16x128_f8f6f4 v[94:97], v[2:9], v[198:205], v[94:97], v1, v186 op_sel_hi:[0,0,0]
	v_mfma_scale_f32_16x16x128_f8f6f4 v[86:89], v[10:17], v[198:205], v[86:89], v1, v186 op_sel_hi:[0,0,0]
	v_mfma_scale_f32_16x16x128_f8f6f4 v[78:81], v[2:9], v[206:213], v[78:81], v1, v186 op_sel_hi:[0,0,0]
	v_mfma_scale_f32_16x16x128_f8f6f4 v[70:73], v[10:17], v[206:213], v[70:73], v1, v186 op_sel_hi:[0,0,0]
	v_mfma_scale_f32_16x16x128_f8f6f4 v[62:65], v[2:9], v[214:221], v[62:65], v1, v186 op_sel_hi:[0,0,0]
	v_mfma_scale_f32_16x16x128_f8f6f4 v[54:57], v[10:17], v[214:221], v[54:57], v1, v186 op_sel_hi:[0,0,0]
	v_mfma_scale_f32_16x16x128_f8f6f4 v[46:49], v[2:9], v[222:229], v[46:49], v1, v186 op_sel_hi:[0,0,0]
	v_mfma_scale_f32_16x16x128_f8f6f4 v[38:41], v[10:17], v[222:229], v[38:41], v1, v186 op_sel_hi:[0,0,0]
	s_setprio 0
	s_setprio 1
	v_mfma_scale_f32_16x16x128_f8f6f4 v[90:93], v[18:25], v[198:205], v[90:93], v1, v186 op_sel_hi:[0,0,0]
	v_mfma_scale_f32_16x16x128_f8f6f4 v[82:85], v[26:33], v[198:205], v[82:85], v1, v186 op_sel_hi:[0,0,0]
	v_mfma_scale_f32_16x16x128_f8f6f4 v[74:77], v[18:25], v[206:213], v[74:77], v1, v186 op_sel_hi:[0,0,0]
	v_mfma_scale_f32_16x16x128_f8f6f4 v[66:69], v[26:33], v[206:213], v[66:69], v1, v186 op_sel_hi:[0,0,0]
	v_mfma_scale_f32_16x16x128_f8f6f4 v[58:61], v[18:25], v[214:221], v[58:61], v1, v186 op_sel_hi:[0,0,0]
	v_mfma_scale_f32_16x16x128_f8f6f4 v[50:53], v[26:33], v[214:221], v[50:53], v1, v186 op_sel_hi:[0,0,0]
	v_mfma_scale_f32_16x16x128_f8f6f4 v[42:45], v[18:25], v[222:229], v[42:45], v1, v186 op_sel_hi:[0,0,0]
	v_mfma_scale_f32_16x16x128_f8f6f4 v[34:37], v[26:33], v[222:229], v[34:37], v1, v186 op_sel_hi:[0,0,0]
	s_setprio 0
	s_barrier
	s_add_i32 s65, s65, 2
	s_add_u32 s22, s22, 0x100
	s_addc_u32 s23, s23, 0
	s_add_u32 s63, s63, 0x100
	s_addc_u32 s64, s64, 0
	s_cmp_gt_u32 s65, 13
	s_cbranch_scc1 .Lpx_0
; #define PG8_STAGE(bufoff, gbase, voff) do { _Pragma("unroll") for (int _i = 0; _i < 2; ++_i) \
;         __builtin_amdgcn_global_load_lds((const unsigned*)((const char*)(gbase) + (voff)[_i]), (PG8_LAS unsigned*)(lds + (bufoff) + ldsw + _i * 8192), 16, 0, 0); } while (0)
; #define PG8_LDA(dst, b, h) do { _Pragma("unroll") for (int m = 0; m < 4; ++m) _Pragma("unroll") for (int k = 0; k < 2; ++k) dst[m][k] = *(const PG8_LAS bf16x8*)(lds + PG8_SA(b, h) + aoff + m * 2048 + k * 1024); } while (0)
; #define PG8_LDB(dst, b, h) do { _Pragma("unroll") for (int n = 0; n < 2; ++n) _Pragma("unroll") for (int k = 0; k < 2; ++k) dst[n][k] = *(const PG8_LAS bf16x8*)(lds + PG8_SB(b, h) + boff + n * 2048 + k * 1024); } while (0)
; #define PG8_MMA(ai, bj, At, Bt) do { __builtin_amdgcn_s_setprio(1); _Pragma("unroll") for (int m = 0; m < 4; ++m) _Pragma("unroll") for (int n = 0; n < 2; ++n) _Pragma("unroll") for (int k = 0; k < 2; ++k) \
;         acc[ai][bj][m][n] = __builtin_amdgcn_mfma_f32_16x16x32_bf16(Bt[n][k], At[m][k], acc[ai][bj][m][n], 0, 0, 0); __builtin_amdgcn_s_setprio(0); } while (0)
; #define PG8_WAIT_V(n) asm volatile("s_waitcnt vmcnt(" #n ")" ::: "memory")
; #define PG8_WAIT_L(n) asm volatile("s_waitcnt lgkmcnt(" #n ")" ::: "memory")
; template <class Epi, class Sched, bool ALIGN_EPI = false>
; __device__ __forceinline__ void gemm_phase8(PG8_LAS unsigned char* lds, const Gemm g, const Sched& S, const Epi& E) {
;     ...
;         for (int t = 0; t < nt; t += 2) {
;             const bool last = (t == nt - 2);
;             const char* a1 = cA + (size_t)(t + 1) * kstep;
;             const char* a2 = last ? nA : cA + (size_t)(t + 2) * kstep; const char* b2 = last ? nB : cB + (size_t)(t + 2) * kstep;
;             const char* a3 = a2 + kstep; const char* b3 = b2 + kstep;
;             if (last && has_next) S.a_ready(nxt);
;             PG8_LDB(B0, 0, 0); PG8_LDB(B1, 0, 1); PG8_SCHED; PG8_LDA(At, 0, 0); PG8_STAGE(PG8_SA(1, 1), a1 + hstepA, voffA);
;             PG8_WAIT_V(8); PG8_WAIT_L(0); PG8_BAR; PG8_MMA(0, 0, At, B0); PG8_MMA(0, 1, At, B1); PG8_BAR; PG8_SCHED;
;             PG8_LDA(At, 0, 1); PG8_STAGE(PG8_SB(0, 0), b2, voffB); PG8_STAGE(PG8_SB(0, 1), b2 + hstepB, voffB); PG8_STAGE(PG8_SA(0, 0), a2, voffA);
;             PG8_WAIT_V(8); PG8_WAIT_L(0); PG8_BAR; PG8_MMA(1, 0, At, B0); PG8_MMA(1, 1, At, B1); PG8_BAR; PG8_SCHED;
.LBB0_325:
	ds_read_b128 v[18:21], v191
	ds_read_b128 v[26:29], v191 offset:2048
	ds_read_b128 v[22:25], v192
	ds_read_b128 v[30:33], v192 offset:2048
	ds_read_b128 v[2:5], v193
	ds_read_b128 v[10:13], v193 offset:2048
	ds_read_b128 v[6:9], v194
	ds_read_b128 v[14:17], v194 offset:2048
	s_add_u32 s24, s22, 0xfffc0080
	s_addc_u32 s25, s23, -1
	s_cmp_eq_u32 s65, 12
	s_cselect_b32 s27, s15, s25
	s_cselect_b32 s26, s61, s24
	s_cselect_b32 s25, s13, s64
	s_cselect_b32 s24, s62, s63
	s_add_i32 m0, s21, 0xc000
	ds_read_b128 v[178:181], v195
	ds_read_b128 v[198:201], v195 offset:2048
	ds_read_b128 v[182:185], v196
	ds_read_b128 v[202:205], v196 offset:2048
	ds_read_b128 v[206:209], v195 offset:4096
	ds_read_b128 v[214:217], v195 offset:6144
	ds_read_b128 v[210:213], v196 offset:4096
	ds_read_b128 v[218:221], v196 offset:6144
	global_load_lds_dwordx4 v170, s[22:23]
	s_add_i32 m0, s21, 0xe000
	s_nop 0
	global_load_lds_dwordx4 v172, s[22:23]
	s_waitcnt vmcnt(8)
	s_waitcnt lgkmcnt(0)
	s_barrier
	s_setprio 1
	s_waitcnt lgkmcnt(0)
	v_mfma_scale_f32_16x16x128_f8f6f4 v[158:161], v[18:25], v[178:185], v[158:161], v1, v186 op_sel_hi:[0,0,0]
	v_mfma_scale_f32_16x16x128_f8f6f4 v[150:153], v[26:33], v[178:185], v[150:153], v1, v186 op_sel_hi:[0,0,0]
	v_mfma_scale_f32_16x16x128_f8f6f4 v[142:145], v[18:25], v[198:205], v[142:145], v1, v186 op_sel_hi:[0,0,0]
	v_mfma_scale_f32_16x16x128_f8f6f4 v[134:137], v[26:33], v[198:205], v[134:137], v1, v186 op_sel_hi:[0,0,0]
	v_mfma_scale_f32_16x16x128_f8f6f4 v[126:129], v[18:25], v[206:213], v[126:129], v1, v186 op_sel_hi:[0,0,0]
	v_mfma_scale_f32_16x16x128_f8f6f4 v[118:121], v[26:33], v[206:213], v[118:121], v1, v186 op_sel_hi:[0,0,0]
	v_mfma_scale_f32_16x16x128_f8f6f4 v[110:113], v[18:25], v[214:221], v[110:113], v1, v186 op_sel_hi:[0,0,0]
	v_mfma_scale_f32_16x16x128_f8f6f4 v[102:105], v[26:33], v[214:221], v[102:105], v1, v186 op_sel_hi:[0,0,0]
	s_setprio 0
	s_setprio 1
	v_mfma_scale_f32_16x16x128_f8f6f4 v[154:157], v[2:9], v[178:185], v[154:157], v1, v186 op_sel_hi:[0,0,0]
	v_mfma_scale_f32_16x16x128_f8f6f4 v[146:149], v[10:17], v[178:185], v[146:149], v1, v186 op_sel_hi:[0,0,0]
	v_mfma_scale_f32_16x16x128_f8f6f4 v[138:141], v[2:9], v[198:205], v[138:141], v1, v186 op_sel_hi:[0,0,0]
	v_mfma_scale_f32_16x16x128_f8f6f4 v[130:133], v[10:17], v[198:205], v[130:133], v1, v186 op_sel_hi:[0,0,0]
	v_mfma_scale_f32_16x16x128_f8f6f4 v[122:125], v[2:9], v[206:213], v[122:125], v1, v186 op_sel_hi:[0,0,0]
	v_mfma_scale_f32_16x16x128_f8f6f4 v[114:117], v[10:17], v[206:213], v[114:117], v1, v186 op_sel_hi:[0,0,0]
	v_mfma_scale_f32_16x16x128_f8f6f4 v[106:109], v[2:9], v[214:221], v[106:109], v1, v186 op_sel_hi:[0,0,0]
	v_mfma_scale_f32_16x16x128_f8f6f4 v[98:101], v[10:17], v[214:221], v[98:101], v1, v186 op_sel_hi:[0,0,0]
	s_setprio 0
	s_barrier
	s_add_i32 s66, s57, s30
	s_mov_b32 m0, s66
	ds_read_b128 v[198:201], v195 offset:16384
	ds_read_b128 v[206:209], v195 offset:18432
	ds_read_b128 v[202:205], v196 offset:16384
	ds_read_b128 v[210:213], v196 offset:18432
	ds_read_b128 v[214:217], v195 offset:20480
	ds_read_b128 v[222:225], v195 offset:22528
	ds_read_b128 v[218:221], v196 offset:20480
	ds_read_b128 v[226:229], v196 offset:22528
	global_load_lds_dwordx4 v164, s[24:25]
	s_add_i32 m0, s66, 0x2000
	s_add_u32 s66, s24, 0x40000
	s_addc_u32 s67, s25, 0
	s_add_i32 s72, s58, s30
	global_load_lds_dwordx4 v168, s[24:25]
	s_mov_b32 m0, s72
	s_nop 0
	global_load_lds_dwordx4 v164, s[66:67]
	s_add_i32 m0, s72, 0x2000
	s_nop 0
	global_load_lds_dwordx4 v168, s[66:67]
	s_mov_b32 m0, s21
	s_nop 0
	global_load_lds_dwordx4 v162, s[26:27]
	s_mov_b32 m0, s34
	s_nop 0
	global_load_lds_dwordx4 v166, s[26:27]
	s_waitcnt vmcnt(8)
	s_waitcnt lgkmcnt(0)
	s_barrier
	s_setprio 1
	s_waitcnt lgkmcnt(0)
	v_mfma_scale_f32_16x16x128_f8f6f4 v[94:97], v[18:25], v[198:205], v[94:97], v1, v186 op_sel_hi:[0,0,0]
	v_mfma_scale_f32_16x16x128_f8f6f4 v[86:89], v[26:33], v[198:205], v[86:89], v1, v186 op_sel_hi:[0,0,0]
	v_mfma_scale_f32_16x16x128_f8f6f4 v[78:81], v[18:25], v[206:213], v[78:81], v1, v186 op_sel_hi:[0,0,0]
	v_mfma_scale_f32_16x16x128_f8f6f4 v[70:73], v[26:33], v[206:213], v[70:73], v1, v186 op_sel_hi:[0,0,0]
	v_mfma_scale_f32_16x16x128_f8f6f4 v[62:65], v[18:25], v[214:221], v[62:65], v1, v186 op_sel_hi:[0,0,0]
	v_mfma_scale_f32_16x16x128_f8f6f4 v[54:57], v[26:33], v[214:221], v[54:57], v1, v186 op_sel_hi:[0,0,0]
	v_mfma_scale_f32_16x16x128_f8f6f4 v[46:49], v[18:25], v[222:229], v[46:49], v1, v186 op_sel_hi:[0,0,0]
	v_mfma_scale_f32_16x16x128_f8f6f4 v[38:41], v[26:33], v[222:229], v[38:41], v1, v186 op_sel_hi:[0,0,0]
	s_setprio 0
	s_setprio 1
	v_mfma_scale_f32_16x16x128_f8f6f4 v[90:93], v[2:9], v[198:205], v[90:93], v1, v186 op_sel_hi:[0,0,0]
	v_mfma_scale_f32_16x16x128_f8f6f4 v[82:85], v[10:17], v[198:205], v[82:85], v1, v186 op_sel_hi:[0,0,0]
	v_mfma_scale_f32_16x16x128_f8f6f4 v[74:77], v[2:9], v[206:213], v[74:77], v1, v186 op_sel_hi:[0,0,0]
	v_mfma_scale_f32_16x16x128_f8f6f4 v[66:69], v[10:17], v[206:213], v[66:69], v1, v186 op_sel_hi:[0,0,0]
	v_mfma_scale_f32_16x16x128_f8f6f4 v[58:61], v[2:9], v[214:221], v[58:61], v1, v186 op_sel_hi:[0,0,0]
	v_mfma_scale_f32_16x16x128_f8f6f4 v[50:53], v[10:17], v[214:221], v[50:53], v1, v186 op_sel_hi:[0,0,0]
	v_mfma_scale_f32_16x16x128_f8f6f4 v[42:45], v[2:9], v[222:229], v[42:45], v1, v186 op_sel_hi:[0,0,0]
	v_mfma_scale_f32_16x16x128_f8f6f4 v[34:37], v[10:17], v[222:229], v[34:37], v1, v186 op_sel_hi:[0,0,0]
	s_setprio 0
	s_barrier
; #define PG8_STAGE(bufoff, gbase, voff) do { _Pragma("unroll") for (int _i = 0; _i < 2; ++_i) \
;         __builtin_amdgcn_global_load_lds((const unsigned*)((const char*)(gbase) + (voff)[_i]), (PG8_LAS unsigned*)(lds + (bufoff) + ldsw + _i * 8192), 16, 0, 0); } while (0)
; #define PG8_LDA(dst, b, h) do { _Pragma("unroll") for (int m = 0; m < 4; ++m) _Pragma("unroll") for (int k = 0; k < 2; ++k) dst[m][k] = *(const PG8_LAS bf16x8*)(lds + PG8_SA(b, h) + aoff + m * 2048 + k * 1024); } while (0)
; #define PG8_LDB(dst, b, h) do { _Pragma("unroll") for (int n = 0; n < 2; ++n) _Pragma("unroll") for (int k = 0; k < 2; ++k) dst[n][k] = *(const PG8_LAS bf16x8*)(lds + PG8_SB(b, h) + boff + n * 2048 + k * 1024); } while (0)
; #define PG8_MMA(ai, bj, At, Bt) do { __builtin_amdgcn_s_setprio(1); _Pragma("unroll") for (int m = 0; m < 4; ++m) _Pragma("unroll") for (int n = 0; n < 2; ++n) _Pragma("unroll") for (int k = 0; k < 2; ++k) \
;         acc[ai][bj][m][n] = __builtin_amdgcn_mfma_f32_16x16x32_bf16(Bt[n][k], At[m][k], acc[ai][bj][m][n], 0, 0, 0); __builtin_amdgcn_s_setprio(0); } while (0)
; #define PG8_WAIT_V(n) asm volatile("s_waitcnt vmcnt(" #n ")" ::: "memory")
; #define PG8_WAIT_L(n) asm volatile("s_waitcnt lgkmcnt(" #n ")" ::: "memory")
; #define PG8_BAR __builtin_amdgcn_s_barrier()
; #define PG8_SCHED __builtin_amdgcn_sched_barrier(0)
; #define PG8_STAGE(bufoff, gbase, voff) do { _Pragma("unroll") for (int _i = 0; _i < 2; ++_i) \
;         __builtin_amdgcn_global_load_lds((const unsigned*)((const char*)(gbase) + (voff)[_i]), (PG8_LAS unsigned*)(lds + (bufoff) + ldsw + _i * 8192), 16, 0, 0); } while (0)
; #define PG8_WAIT_V(n) asm volatile("s_waitcnt vmcnt(" #n ")" ::: "memory")
; template <class Epi, class Sched, bool ALIGN_EPI = false>
; __device__ __forceinline__ void gemm_phase8(PG8_LAS unsigned char* lds, const Gemm g, const Sched& S, const Epi& E) {
;     ...
;             PG8_LDB(B0, 1, 0); PG8_LDB(B1, 1, 1); PG8_SCHED; PG8_LDA(At, 1, 0); PG8_STAGE(PG8_SA(0, 1), a2 + hstepA, voffA);
;             PG8_WAIT_V(8); PG8_WAIT_L(0); PG8_BAR; PG8_MMA(0, 0, At, B0); PG8_MMA(0, 1, At, B1); PG8_BAR; PG8_SCHED;
;             PG8_LDA(At, 1, 1); PG8_STAGE(PG8_SB(1, 0), b3, voffB); PG8_STAGE(PG8_SB(1, 1), b3 + hstepB, voffB); PG8_STAGE(PG8_SA(1, 0), a3, voffA);
;             PG8_WAIT_V(8); PG8_WAIT_L(0); PG8_BAR; PG8_MMA(1, 0, At, B0); PG8_MMA(1, 1, At, B1); PG8_BAR; PG8_SCHED;
	s_add_i32 s66, 0, 0x18000
	s_add_i32 s67, 0, 0x1c000
	v_add_u32_e32 v6, s66, v187
	v_add_u32_e32 v14, s66, v188
	v_add_u32_e32 v22, s67, v187
	v_add_u32_e32 v30, s67, v188
	ds_read_b128 v[2:5], v6
	ds_read_b128 v[10:13], v6 offset:2048
	ds_read_b128 v[6:9], v14
	ds_read_b128 v[14:17], v14 offset:2048
	ds_read_b128 v[18:21], v22
	ds_read_b128 v[26:29], v22 offset:2048
	ds_read_b128 v[22:25], v30
	ds_read_b128 v[30:33], v30 offset:2048
	s_add_u32 s26, s26, 0x40000
	s_addc_u32 s27, s27, 0
	s_mov_b32 m0, s35
	ds_read_b128 v[198:201], v195 offset:32768
	ds_read_b128 v[206:209], v195 offset:34816
	ds_read_b128 v[202:205], v196 offset:32768
	ds_read_b128 v[210:213], v196 offset:34816
	ds_read_b128 v[214:217], v195 offset:36864
	ds_read_b128 v[222:225], v195 offset:38912
	ds_read_b128 v[218:221], v196 offset:36864
	ds_read_b128 v[226:229], v196 offset:38912
	global_load_lds_dwordx4 v162, s[26:27]
	s_mov_b32 m0, s52
	s_nop 0
	global_load_lds_dwordx4 v166, s[26:27]
	s_waitcnt vmcnt(8)
	s_waitcnt lgkmcnt(0)
	s_barrier
	s_setprio 1
	s_waitcnt lgkmcnt(0)
	v_mfma_scale_f32_16x16x128_f8f6f4 v[158:161], v[2:9], v[198:205], v[158:161], v1, v186 op_sel_hi:[0,0,0]
	v_mfma_scale_f32_16x16x128_f8f6f4 v[150:153], v[10:17], v[198:205], v[150:153], v1, v186 op_sel_hi:[0,0,0]
	v_mfma_scale_f32_16x16x128_f8f6f4 v[142:145], v[2:9], v[206:213], v[142:145], v1, v186 op_sel_hi:[0,0,0]
	v_mfma_scale_f32_16x16x128_f8f6f4 v[134:137], v[10:17], v[206:213], v[134:137], v1, v186 op_sel_hi:[0,0,0]
	v_mfma_scale_f32_16x16x128_f8f6f4 v[126:129], v[2:9], v[214:221], v[126:129], v1, v186 op_sel_hi:[0,0,0]
	v_mfma_scale_f32_16x16x128_f8f6f4 v[118:121], v[10:17], v[214:221], v[118:121], v1, v186 op_sel_hi:[0,0,0]
	v_mfma_scale_f32_16x16x128_f8f6f4 v[110:113], v[2:9], v[222:229], v[110:113], v1, v186 op_sel_hi:[0,0,0]
	v_mfma_scale_f32_16x16x128_f8f6f4 v[102:105], v[10:17], v[222:229], v[102:105], v1, v186 op_sel_hi:[0,0,0]
	s_setprio 0
	s_setprio 1
	v_mfma_scale_f32_16x16x128_f8f6f4 v[154:157], v[18:25], v[198:205], v[154:157], v1, v186 op_sel_hi:[0,0,0]
	v_mfma_scale_f32_16x16x128_f8f6f4 v[146:149], v[26:33], v[198:205], v[146:149], v1, v186 op_sel_hi:[0,0,0]
	v_mfma_scale_f32_16x16x128_f8f6f4 v[138:141], v[18:25], v[206:213], v[138:141], v1, v186 op_sel_hi:[0,0,0]
	v_mfma_scale_f32_16x16x128_f8f6f4 v[130:133], v[26:33], v[206:213], v[130:133], v1, v186 op_sel_hi:[0,0,0]
	v_mfma_scale_f32_16x16x128_f8f6f4 v[122:125], v[18:25], v[214:221], v[122:125], v1, v186 op_sel_hi:[0,0,0]
	v_mfma_scale_f32_16x16x128_f8f6f4 v[114:117], v[26:33], v[214:221], v[114:117], v1, v186 op_sel_hi:[0,0,0]
	v_mfma_scale_f32_16x16x128_f8f6f4 v[106:109], v[18:25], v[222:229], v[106:109], v1, v186 op_sel_hi:[0,0,0]
	v_mfma_scale_f32_16x16x128_f8f6f4 v[98:101], v[26:33], v[222:229], v[98:101], v1, v186 op_sel_hi:[0,0,0]
	s_setprio 0
	s_barrier
	s_add_i32 s101, s66, s30
	s_add_u32 s98, s24, s8
	s_addc_u32 s99, s25, s9
	s_mov_b32 m0, s101
	ds_read_b128 v[198:201], v195 offset:49152
	ds_read_b128 v[206:209], v195 offset:51200
	ds_read_b128 v[202:205], v196 offset:49152
	ds_read_b128 v[210:213], v196 offset:51200
	ds_read_b128 v[214:217], v195 offset:53248
	ds_read_b128 v[222:225], v195 offset:55296
	ds_read_b128 v[218:221], v196 offset:53248
	ds_read_b128 v[226:229], v196 offset:55296
	global_load_lds_dwordx4 v164, s[98:99]
	s_add_i32 m0, s101, 0x2000
	s_add_u32 s24, s24, 0x40080
	s_addc_u32 s25, s25, 0
	s_add_i32 s101, s67, s30
	global_load_lds_dwordx4 v168, s[98:99]
	s_add_u32 s98, s26, s8
	s_addc_u32 s99, s27, s9
	s_sub_u32 s98, s98, 0x40000
	s_subb_u32 s99, s99, 0
	s_mov_b32 m0, s101
	s_nop 0
	global_load_lds_dwordx4 v164, s[24:25]
	s_add_i32 m0, s101, 0x2000
	s_nop 0
	global_load_lds_dwordx4 v168, s[24:25]
	s_mov_b32 m0, s55
	s_nop 0
	global_load_lds_dwordx4 v162, s[98:99]
	s_mov_b32 m0, s56
	s_nop 0
	global_load_lds_dwordx4 v166, s[98:99]
	s_waitcnt vmcnt(8)
	s_waitcnt lgkmcnt(0)
	s_barrier
	s_setprio 1
	s_waitcnt lgkmcnt(0)
	v_mfma_scale_f32_16x16x128_f8f6f4 v[94:97], v[2:9], v[198:205], v[94:97], v1, v186 op_sel_hi:[0,0,0]
	v_mfma_scale_f32_16x16x128_f8f6f4 v[86:89], v[10:17], v[198:205], v[86:89], v1, v186 op_sel_hi:[0,0,0]
	v_mfma_scale_f32_16x16x128_f8f6f4 v[78:81], v[2:9], v[206:213], v[78:81], v1, v186 op_sel_hi:[0,0,0]
	v_mfma_scale_f32_16x16x128_f8f6f4 v[70:73], v[10:17], v[206:213], v[70:73], v1, v186 op_sel_hi:[0,0,0]
	v_mfma_scale_f32_16x16x128_f8f6f4 v[62:65], v[2:9], v[214:221], v[62:65], v1, v186 op_sel_hi:[0,0,0]
	v_mfma_scale_f32_16x16x128_f8f6f4 v[54:57], v[10:17], v[214:221], v[54:57], v1, v186 op_sel_hi:[0,0,0]
	v_mfma_scale_f32_16x16x128_f8f6f4 v[46:49], v[2:9], v[222:229], v[46:49], v1, v186 op_sel_hi:[0,0,0]
	v_mfma_scale_f32_16x16x128_f8f6f4 v[38:41], v[10:17], v[222:229], v[38:41], v1, v186 op_sel_hi:[0,0,0]
	s_setprio 0
	s_setprio 1
	v_mfma_scale_f32_16x16x128_f8f6f4 v[90:93], v[18:25], v[198:205], v[90:93], v1, v186 op_sel_hi:[0,0,0]
	v_mfma_scale_f32_16x16x128_f8f6f4 v[82:85], v[26:33], v[198:205], v[82:85], v1, v186 op_sel_hi:[0,0,0]
	v_mfma_scale_f32_16x16x128_f8f6f4 v[74:77], v[18:25], v[206:213], v[74:77], v1, v186 op_sel_hi:[0,0,0]
	v_mfma_scale_f32_16x16x128_f8f6f4 v[66:69], v[26:33], v[206:213], v[66:69], v1, v186 op_sel_hi:[0,0,0]
	v_mfma_scale_f32_16x16x128_f8f6f4 v[58:61], v[18:25], v[214:221], v[58:61], v1, v186 op_sel_hi:[0,0,0]
	v_mfma_scale_f32_16x16x128_f8f6f4 v[50:53], v[26:33], v[214:221], v[50:53], v1, v186 op_sel_hi:[0,0,0]
	v_mfma_scale_f32_16x16x128_f8f6f4 v[42:45], v[18:25], v[222:229], v[42:45], v1, v186 op_sel_hi:[0,0,0]
	v_mfma_scale_f32_16x16x128_f8f6f4 v[34:37], v[26:33], v[222:229], v[34:37], v1, v186 op_sel_hi:[0,0,0]
	s_setprio 0
	s_barrier
; #define PG8_STAGE(bufoff, gbase, voff) do { _Pragma("unroll") for (int _i = 0; _i < 2; ++_i) \
;         __builtin_amdgcn_global_load_lds((const unsigned*)((const char*)(gbase) + (voff)[_i]), (PG8_LAS unsigned*)(lds + (bufoff) + ldsw + _i * 8192), 16, 0, 0); } while (0)
; #define PG8_LDA(dst, b, h) do { _Pragma("unroll") for (int m = 0; m < 4; ++m) _Pragma("unroll") for (int k = 0; k < 2; ++k) dst[m][k] = *(const PG8_LAS bf16x8*)(lds + PG8_SA(b, h) + aoff + m * 2048 + k * 1024); } while (0)
; #define PG8_LDB(dst, b, h) do { _Pragma("unroll") for (int n = 0; n < 2; ++n) _Pragma("unroll") for (int k = 0; k < 2; ++k) dst[n][k] = *(const PG8_LAS bf16x8*)(lds + PG8_SB(b, h) + boff + n * 2048 + k * 1024); } while (0)
; #define PG8_MMA(ai, bj, At, Bt) do { __builtin_amdgcn_s_setprio(1); _Pragma("unroll") for (int m = 0; m < 4; ++m) _Pragma("unroll") for (int n = 0; n < 2; ++n) _Pragma("unroll") for (int k = 0; k < 2; ++k) \
;         acc[ai][bj][m][n] = __builtin_amdgcn_mfma_f32_16x16x32_bf16(Bt[n][k], At[m][k], acc[ai][bj][m][n], 0, 0, 0); __builtin_amdgcn_s_setprio(0); } while (0)
; #define PG8_WAIT_V(n) asm volatile("s_waitcnt vmcnt(" #n ")" ::: "memory")
; #define PG8_WAIT_L(n) asm volatile("s_waitcnt lgkmcnt(" #n ")" ::: "memory")
; template <class Epi, class Sched, bool ALIGN_EPI = false>
; __device__ __forceinline__ void gemm_phase8(PG8_LAS unsigned char* lds, const Gemm g, const Sched& S, const Epi& E) {
;     ...
;         for (int t = 0; t < nt; t += 2) {
;             const bool last = (t == nt - 2);
;             const char* a1 = cA + (size_t)(t + 1) * kstep;
;             const char* a2 = last ? nA : cA + (size_t)(t + 2) * kstep; const char* b2 = last ? nB : cB + (size_t)(t + 2) * kstep;
;             const char* a3 = a2 + kstep; const char* b3 = b2 + kstep;
;             if (last && has_next) S.a_ready(nxt);
;             PG8_LDB(B0, 0, 0); PG8_LDB(B1, 0, 1); PG8_SCHED; PG8_LDA(At, 0, 0); PG8_STAGE(PG8_SA(1, 1), a1 + hstepA, voffA);
;             PG8_WAIT_V(8); PG8_WAIT_L(0); PG8_BAR; PG8_MMA(0, 0, At, B0); PG8_MMA(0, 1, At, B1); PG8_BAR; PG8_SCHED;
;             PG8_LDA(At, 0, 1); PG8_STAGE(PG8_SB(0, 0), b2, voffB); PG8_STAGE(PG8_SB(0, 1), b2 + hstepB, voffB); PG8_STAGE(PG8_SA(0, 0), a2, voffA);
;             PG8_WAIT_V(8); PG8_WAIT_L(0); PG8_BAR; PG8_MMA(1, 0, At, B0); PG8_MMA(1, 1, At, B1); PG8_BAR; PG8_SCHED;
	s_add_i32 s65, s65, 2
	s_add_u32 s22, s22, 0x100
	s_addc_u32 s23, s23, 0
	s_add_u32 s63, s63, 0x100
	s_addc_u32 s64, s64, 0
	s_cmp_gt_u32 s65, 13
	ds_read_b128 v[18:21], v191
	ds_read_b128 v[26:29], v191 offset:2048
	ds_read_b128 v[22:25], v192
	ds_read_b128 v[30:33], v192 offset:2048
	ds_read_b128 v[2:5], v193
	ds_read_b128 v[10:13], v193 offset:2048
	ds_read_b128 v[6:9], v194
	ds_read_b128 v[14:17], v194 offset:2048
	s_add_u32 s24, s22, 0xfffc0080
	s_addc_u32 s25, s23, -1
	s_cmp_eq_u32 s65, 12
	s_cselect_b32 s27, s15, s25
	s_cselect_b32 s26, s61, s24
	s_cselect_b32 s25, s13, s64
	s_cselect_b32 s24, s62, s63
	s_add_i32 m0, s21, 0xc000
	ds_read_b128 v[178:181], v195
	ds_read_b128 v[198:201], v195 offset:2048
	ds_read_b128 v[182:185], v196
	ds_read_b128 v[202:205], v196 offset:2048
	ds_read_b128 v[206:209], v195 offset:4096
	ds_read_b128 v[214:217], v195 offset:6144
	ds_read_b128 v[210:213], v196 offset:4096
	ds_read_b128 v[218:221], v196 offset:6144
	global_load_lds_dwordx4 v170, s[22:23]
	s_add_i32 m0, s21, 0xe000
	s_nop 0
	global_load_lds_dwordx4 v172, s[22:23]
	s_waitcnt vmcnt(8)
	s_waitcnt lgkmcnt(0)
	s_barrier
	s_setprio 1
	s_waitcnt lgkmcnt(0)
	v_mfma_scale_f32_16x16x128_f8f6f4 v[158:161], v[18:25], v[178:185], v[158:161], v1, v186 op_sel_hi:[0,0,0]
	v_mfma_scale_f32_16x16x128_f8f6f4 v[150:153], v[26:33], v[178:185], v[150:153], v1, v186 op_sel_hi:[0,0,0]
	v_mfma_scale_f32_16x16x128_f8f6f4 v[142:145], v[18:25], v[198:205], v[142:145], v1, v186 op_sel_hi:[0,0,0]
	v_mfma_scale_f32_16x16x128_f8f6f4 v[134:137], v[26:33], v[198:205], v[134:137], v1, v186 op_sel_hi:[0,0,0]
	v_mfma_scale_f32_16x16x128_f8f6f4 v[126:129], v[18:25], v[206:213], v[126:129], v1, v186 op_sel_hi:[0,0,0]
	v_mfma_scale_f32_16x16x128_f8f6f4 v[118:121], v[26:33], v[206:213], v[118:121], v1, v186 op_sel_hi:[0,0,0]
	v_mfma_scale_f32_16x16x128_f8f6f4 v[110:113], v[18:25], v[214:221], v[110:113], v1, v186 op_sel_hi:[0,0,0]
	v_mfma_scale_f32_16x16x128_f8f6f4 v[102:105], v[26:33], v[214:221], v[102:105], v1, v186 op_sel_hi:[0,0,0]
	s_setprio 0
	s_setprio 1
	v_mfma_scale_f32_16x16x128_f8f6f4 v[154:157], v[2:9], v[178:185], v[154:157], v1, v186 op_sel_hi:[0,0,0]
	v_mfma_scale_f32_16x16x128_f8f6f4 v[146:149], v[10:17], v[178:185], v[146:149], v1, v186 op_sel_hi:[0,0,0]
	v_mfma_scale_f32_16x16x128_f8f6f4 v[138:141], v[2:9], v[198:205], v[138:141], v1, v186 op_sel_hi:[0,0,0]
	v_mfma_scale_f32_16x16x128_f8f6f4 v[130:133], v[10:17], v[198:205], v[130:133], v1, v186 op_sel_hi:[0,0,0]
	v_mfma_scale_f32_16x16x128_f8f6f4 v[122:125], v[2:9], v[206:213], v[122:125], v1, v186 op_sel_hi:[0,0,0]
	v_mfma_scale_f32_16x16x128_f8f6f4 v[114:117], v[10:17], v[206:213], v[114:117], v1, v186 op_sel_hi:[0,0,0]
	v_mfma_scale_f32_16x16x128_f8f6f4 v[106:109], v[2:9], v[214:221], v[106:109], v1, v186 op_sel_hi:[0,0,0]
	v_mfma_scale_f32_16x16x128_f8f6f4 v[98:101], v[10:17], v[214:221], v[98:101], v1, v186 op_sel_hi:[0,0,0]
	s_setprio 0
	s_barrier
	s_add_i32 s66, s57, s30
	s_mov_b32 m0, s66
	ds_read_b128 v[198:201], v195 offset:16384
	ds_read_b128 v[206:209], v195 offset:18432
	ds_read_b128 v[202:205], v196 offset:16384
	ds_read_b128 v[210:213], v196 offset:18432
	ds_read_b128 v[214:217], v195 offset:20480
	ds_read_b128 v[222:225], v195 offset:22528
	ds_read_b128 v[218:221], v196 offset:20480
	ds_read_b128 v[226:229], v196 offset:22528
	global_load_lds_dwordx4 v164, s[24:25]
	s_add_i32 m0, s66, 0x2000
	s_add_u32 s66, s24, 0x40000
	s_addc_u32 s67, s25, 0
	s_add_i32 s72, s58, s30
	global_load_lds_dwordx4 v168, s[24:25]
	s_mov_b32 m0, s72
	s_nop 0
	global_load_lds_dwordx4 v164, s[66:67]
	s_add_i32 m0, s72, 0x2000
	s_nop 0
	global_load_lds_dwordx4 v168, s[66:67]
	s_mov_b32 m0, s21
	s_nop 0
	global_load_lds_dwordx4 v162, s[26:27]
	s_mov_b32 m0, s34
	s_nop 0
	global_load_lds_dwordx4 v166, s[26:27]
	s_waitcnt vmcnt(8)
	s_waitcnt lgkmcnt(0)
	s_barrier
	s_setprio 1
	s_waitcnt lgkmcnt(0)
	v_mfma_scale_f32_16x16x128_f8f6f4 v[94:97], v[18:25], v[198:205], v[94:97], v1, v186 op_sel_hi:[0,0,0]
	v_mfma_scale_f32_16x16x128_f8f6f4 v[86:89], v[26:33], v[198:205], v[86:89], v1, v186 op_sel_hi:[0,0,0]
	v_mfma_scale_f32_16x16x128_f8f6f4 v[78:81], v[18:25], v[206:213], v[78:81], v1, v186 op_sel_hi:[0,0,0]
	v_mfma_scale_f32_16x16x128_f8f6f4 v[70:73], v[26:33], v[206:213], v[70:73], v1, v186 op_sel_hi:[0,0,0]
	v_mfma_scale_f32_16x16x128_f8f6f4 v[62:65], v[18:25], v[214:221], v[62:65], v1, v186 op_sel_hi:[0,0,0]
	v_mfma_scale_f32_16x16x128_f8f6f4 v[54:57], v[26:33], v[214:221], v[54:57], v1, v186 op_sel_hi:[0,0,0]
	v_mfma_scale_f32_16x16x128_f8f6f4 v[46:49], v[18:25], v[222:229], v[46:49], v1, v186 op_sel_hi:[0,0,0]
	v_mfma_scale_f32_16x16x128_f8f6f4 v[38:41], v[26:33], v[222:229], v[38:41], v1, v186 op_sel_hi:[0,0,0]
	s_setprio 0
	s_setprio 1
	v_mfma_scale_f32_16x16x128_f8f6f4 v[90:93], v[2:9], v[198:205], v[90:93], v1, v186 op_sel_hi:[0,0,0]
	v_mfma_scale_f32_16x16x128_f8f6f4 v[82:85], v[10:17], v[198:205], v[82:85], v1, v186 op_sel_hi:[0,0,0]
	v_mfma_scale_f32_16x16x128_f8f6f4 v[74:77], v[2:9], v[206:213], v[74:77], v1, v186 op_sel_hi:[0,0,0]
	v_mfma_scale_f32_16x16x128_f8f6f4 v[66:69], v[10:17], v[206:213], v[66:69], v1, v186 op_sel_hi:[0,0,0]
	v_mfma_scale_f32_16x16x128_f8f6f4 v[58:61], v[2:9], v[214:221], v[58:61], v1, v186 op_sel_hi:[0,0,0]
	v_mfma_scale_f32_16x16x128_f8f6f4 v[50:53], v[10:17], v[214:221], v[50:53], v1, v186 op_sel_hi:[0,0,0]
	v_mfma_scale_f32_16x16x128_f8f6f4 v[42:45], v[2:9], v[222:229], v[42:45], v1, v186 op_sel_hi:[0,0,0]
	v_mfma_scale_f32_16x16x128_f8f6f4 v[34:37], v[10:17], v[222:229], v[34:37], v1, v186 op_sel_hi:[0,0,0]
	s_setprio 0
	s_barrier
; #define PG8_STAGE(bufoff, gbase, voff) do { _Pragma("unroll") for (int _i = 0; _i < 2; ++_i) \
;         __builtin_amdgcn_global_load_lds((const unsigned*)((const char*)(gbase) + (voff)[_i]), (PG8_LAS unsigned*)(lds + (bufoff) + ldsw + _i * 8192), 16, 0, 0); } while (0)
; #define PG8_LDA(dst, b, h) do { _Pragma("unroll") for (int m = 0; m < 4; ++m) _Pragma("unroll") for (int k = 0; k < 2; ++k) dst[m][k] = *(const PG8_LAS bf16x8*)(lds + PG8_SA(b, h) + aoff + m * 2048 + k * 1024); } while (0)
; #define PG8_LDB(dst, b, h) do { _Pragma("unroll") for (int n = 0; n < 2; ++n) _Pragma("unroll") for (int k = 0; k < 2; ++k) dst[n][k] = *(const PG8_LAS bf16x8*)(lds + PG8_SB(b, h) + boff + n * 2048 + k * 1024); } while (0)
; #define PG8_MMA(ai, bj, At, Bt) do { __builtin_amdgcn_s_setprio(1); _Pragma("unroll") for (int m = 0; m < 4; ++m) _Pragma("unroll") for (int n = 0; n < 2; ++n) _Pragma("unroll") for (int k = 0; k < 2; ++k) \
;         acc[ai][bj][m][n] = __builtin_amdgcn_mfma_f32_16x16x32_bf16(Bt[n][k], At[m][k], acc[ai][bj][m][n], 0, 0, 0); __builtin_amdgcn_s_setprio(0); } while (0)
; #define PG8_WAIT_V(n) asm volatile("s_waitcnt vmcnt(" #n ")" ::: "memory")
; #define PG8_WAIT_L(n) asm volatile("s_waitcnt lgkmcnt(" #n ")" ::: "memory")
; #define PG8_BAR __builtin_amdgcn_s_barrier()
; #define PG8_SCHED __builtin_amdgcn_sched_barrier(0)
; #define PG8_STAGE(bufoff, gbase, voff) do { _Pragma("unroll") for (int _i = 0; _i < 2; ++_i) \
;         __builtin_amdgcn_global_load_lds((const unsigned*)((const char*)(gbase) + (voff)[_i]), (PG8_LAS unsigned*)(lds + (bufoff) + ldsw + _i * 8192), 16, 0, 0); } while (0)
; template <class Epi, class Sched, bool ALIGN_EPI = false>
; __device__ __forceinline__ void gemm_phase8(PG8_LAS unsigned char* lds, const Gemm g, const Sched& S, const Epi& E) {
;     ...
;             PG8_LDB(B0, 1, 0); PG8_LDB(B1, 1, 1); PG8_SCHED; PG8_LDA(At, 1, 0); PG8_STAGE(PG8_SA(0, 1), a2 + hstepA, voffA);
;             PG8_WAIT_V(8); PG8_WAIT_L(0); PG8_BAR; PG8_MMA(0, 0, At, B0); PG8_MMA(0, 1, At, B1); PG8_BAR; PG8_SCHED;
;             PG8_LDA(At, 1, 1); PG8_STAGE(PG8_SB(1, 0), b3, voffB); PG8_STAGE(PG8_SB(1, 1), b3 + hstepB, voffB); PG8_STAGE(PG8_SA(1, 0), a3, voffA);
;             PG8_WAIT_V(8); PG8_WAIT_L(0); PG8_BAR; PG8_MMA(1, 0, At, B0); PG8_MMA(1, 1, At, B1); PG8_BAR; PG8_SCHED;
;         }
;         if constexpr (ALIGN_EPI) { if (wr == 0) PG8_BAR; }
	s_add_i32 s66, 0, 0x18000
	s_add_i32 s67, 0, 0x1c000
	v_add_u32_e32 v6, s66, v187
	v_add_u32_e32 v14, s66, v188
	v_add_u32_e32 v22, s67, v187
	v_add_u32_e32 v30, s67, v188
	ds_read_b128 v[2:5], v6
	ds_read_b128 v[10:13], v6 offset:2048
	ds_read_b128 v[6:9], v14
	ds_read_b128 v[14:17], v14 offset:2048
	ds_read_b128 v[18:21], v22
	ds_read_b128 v[26:29], v22 offset:2048
	ds_read_b128 v[22:25], v30
	ds_read_b128 v[30:33], v30 offset:2048
	s_add_u32 s26, s26, 0x40000
	s_addc_u32 s27, s27, 0
	s_mov_b32 m0, s35
	ds_read_b128 v[198:201], v195 offset:32768
	ds_read_b128 v[206:209], v195 offset:34816
	ds_read_b128 v[202:205], v196 offset:32768
	ds_read_b128 v[210:213], v196 offset:34816
	ds_read_b128 v[214:217], v195 offset:36864
	ds_read_b128 v[222:225], v195 offset:38912
	ds_read_b128 v[218:221], v196 offset:36864
	ds_read_b128 v[226:229], v196 offset:38912
	global_load_lds_dwordx4 v162, s[26:27]
	s_mov_b32 m0, s52
	s_nop 0
	global_load_lds_dwordx4 v166, s[26:27]
	s_waitcnt vmcnt(8)
	s_waitcnt lgkmcnt(0)
	s_barrier
	s_setprio 1
	s_waitcnt lgkmcnt(0)
	v_mfma_scale_f32_16x16x128_f8f6f4 v[158:161], v[2:9], v[198:205], v[158:161], v1, v186 op_sel_hi:[0,0,0]
	v_mfma_scale_f32_16x16x128_f8f6f4 v[150:153], v[10:17], v[198:205], v[150:153], v1, v186 op_sel_hi:[0,0,0]
	v_mfma_scale_f32_16x16x128_f8f6f4 v[142:145], v[2:9], v[206:213], v[142:145], v1, v186 op_sel_hi:[0,0,0]
	v_mfma_scale_f32_16x16x128_f8f6f4 v[134:137], v[10:17], v[206:213], v[134:137], v1, v186 op_sel_hi:[0,0,0]
	v_mfma_scale_f32_16x16x128_f8f6f4 v[126:129], v[2:9], v[214:221], v[126:129], v1, v186 op_sel_hi:[0,0,0]
	v_mfma_scale_f32_16x16x128_f8f6f4 v[118:121], v[10:17], v[214:221], v[118:121], v1, v186 op_sel_hi:[0,0,0]
	v_mfma_scale_f32_16x16x128_f8f6f4 v[110:113], v[2:9], v[222:229], v[110:113], v1, v186 op_sel_hi:[0,0,0]
	v_mfma_scale_f32_16x16x128_f8f6f4 v[102:105], v[10:17], v[222:229], v[102:105], v1, v186 op_sel_hi:[0,0,0]
	s_setprio 0
	s_setprio 1
	v_mfma_scale_f32_16x16x128_f8f6f4 v[154:157], v[18:25], v[198:205], v[154:157], v1, v186 op_sel_hi:[0,0,0]
	v_mfma_scale_f32_16x16x128_f8f6f4 v[146:149], v[26:33], v[198:205], v[146:149], v1, v186 op_sel_hi:[0,0,0]
	v_mfma_scale_f32_16x16x128_f8f6f4 v[138:141], v[18:25], v[206:213], v[138:141], v1, v186 op_sel_hi:[0,0,0]
	v_mfma_scale_f32_16x16x128_f8f6f4 v[130:133], v[26:33], v[206:213], v[130:133], v1, v186 op_sel_hi:[0,0,0]
	v_mfma_scale_f32_16x16x128_f8f6f4 v[122:125], v[18:25], v[214:221], v[122:125], v1, v186 op_sel_hi:[0,0,0]
	v_mfma_scale_f32_16x16x128_f8f6f4 v[114:117], v[26:33], v[214:221], v[114:117], v1, v186 op_sel_hi:[0,0,0]
	v_mfma_scale_f32_16x16x128_f8f6f4 v[106:109], v[18:25], v[222:229], v[106:109], v1, v186 op_sel_hi:[0,0,0]
	v_mfma_scale_f32_16x16x128_f8f6f4 v[98:101], v[26:33], v[222:229], v[98:101], v1, v186 op_sel_hi:[0,0,0]
	s_setprio 0
	s_barrier
	s_add_i32 s101, s66, s30
	s_add_u32 s98, s24, s8
	s_addc_u32 s99, s25, s9
	s_mov_b32 m0, s101
	ds_read_b128 v[198:201], v195 offset:49152
	ds_read_b128 v[206:209], v195 offset:51200
	ds_read_b128 v[202:205], v196 offset:49152
	ds_read_b128 v[210:213], v196 offset:51200
	ds_read_b128 v[214:217], v195 offset:53248
	ds_read_b128 v[222:225], v195 offset:55296
	ds_read_b128 v[218:221], v196 offset:53248
	ds_read_b128 v[226:229], v196 offset:55296
	global_load_lds_dwordx4 v164, s[98:99]
	s_add_i32 m0, s101, 0x2000
	s_add_u32 s24, s24, 0x40080
	s_addc_u32 s25, s25, 0
	s_add_i32 s101, s67, s30
	global_load_lds_dwordx4 v168, s[98:99]
	s_add_u32 s98, s26, s8
	s_addc_u32 s99, s27, s9
	s_sub_u32 s98, s98, 0x40000
	s_subb_u32 s99, s99, 0
	s_mov_b32 m0, s101
	s_nop 0
	global_load_lds_dwordx4 v164, s[24:25]
	s_add_i32 m0, s101, 0x2000
	s_nop 0
	global_load_lds_dwordx4 v168, s[24:25]
	s_mov_b32 m0, s55
	s_nop 0
	global_load_lds_dwordx4 v162, s[98:99]
	s_mov_b32 m0, s56
	s_nop 0
	global_load_lds_dwordx4 v166, s[98:99]
	s_waitcnt vmcnt(8)
	s_waitcnt lgkmcnt(0)
	s_barrier
	s_setprio 1
	s_waitcnt lgkmcnt(0)
	v_mfma_scale_f32_16x16x128_f8f6f4 v[94:97], v[2:9], v[198:205], v[94:97], v1, v186 op_sel_hi:[0,0,0]
	v_mfma_scale_f32_16x16x128_f8f6f4 v[86:89], v[10:17], v[198:205], v[86:89], v1, v186 op_sel_hi:[0,0,0]
	v_mfma_scale_f32_16x16x128_f8f6f4 v[78:81], v[2:9], v[206:213], v[78:81], v1, v186 op_sel_hi:[0,0,0]
	v_mfma_scale_f32_16x16x128_f8f6f4 v[70:73], v[10:17], v[206:213], v[70:73], v1, v186 op_sel_hi:[0,0,0]
	v_mfma_scale_f32_16x16x128_f8f6f4 v[62:65], v[2:9], v[214:221], v[62:65], v1, v186 op_sel_hi:[0,0,0]
	v_mfma_scale_f32_16x16x128_f8f6f4 v[54:57], v[10:17], v[214:221], v[54:57], v1, v186 op_sel_hi:[0,0,0]
	v_mfma_scale_f32_16x16x128_f8f6f4 v[46:49], v[2:9], v[222:229], v[46:49], v1, v186 op_sel_hi:[0,0,0]
	v_mfma_scale_f32_16x16x128_f8f6f4 v[38:41], v[10:17], v[222:229], v[38:41], v1, v186 op_sel_hi:[0,0,0]
	s_setprio 0
	s_setprio 1
	v_mfma_scale_f32_16x16x128_f8f6f4 v[90:93], v[18:25], v[198:205], v[90:93], v1, v186 op_sel_hi:[0,0,0]
	v_mfma_scale_f32_16x16x128_f8f6f4 v[82:85], v[26:33], v[198:205], v[82:85], v1, v186 op_sel_hi:[0,0,0]
	v_mfma_scale_f32_16x16x128_f8f6f4 v[74:77], v[18:25], v[206:213], v[74:77], v1, v186 op_sel_hi:[0,0,0]
	v_mfma_scale_f32_16x16x128_f8f6f4 v[66:69], v[26:33], v[206:213], v[66:69], v1, v186 op_sel_hi:[0,0,0]
	v_mfma_scale_f32_16x16x128_f8f6f4 v[58:61], v[18:25], v[214:221], v[58:61], v1, v186 op_sel_hi:[0,0,0]
	v_mfma_scale_f32_16x16x128_f8f6f4 v[50:53], v[26:33], v[214:221], v[50:53], v1, v186 op_sel_hi:[0,0,0]
	v_mfma_scale_f32_16x16x128_f8f6f4 v[42:45], v[18:25], v[222:229], v[42:45], v1, v186 op_sel_hi:[0,0,0]
	v_mfma_scale_f32_16x16x128_f8f6f4 v[34:37], v[26:33], v[222:229], v[34:37], v1, v186 op_sel_hi:[0,0,0]
	s_setprio 0
	s_barrier
	s_add_i32 s65, s65, 2
	s_add_u32 s22, s22, 0x100
	s_addc_u32 s23, s23, 0
	s_add_u32 s63, s63, 0x100
	s_addc_u32 s64, s64, 0
	s_cmp_gt_u32 s65, 13
	s_cbranch_scc0 .LBB0_325
.Lpx_0:
	s_and_b64 vcc, exec, s[10:11]
	s_cbranch_vccz .LBB0_328
	s_barrier

; #define PG8_STAGE(bufoff, gbase, voff) do { _Pragma("unroll") for (int _i = 0; _i < 2; ++_i) \
;         __builtin_amdgcn_global_load_lds((const unsigned*)((const char*)(gbase) + (voff)[_i]), (PG8_LAS unsigned*)(lds + (bufoff) + ldsw + _i * 8192), 16, 0, 0); } while (0)
; #define PG8_LDA(dst, b, h) do { _Pragma("unroll") for (int m = 0; m < 4; ++m) _Pragma("unroll") for (int k = 0; k < 2; ++k) dst[m][k] = *(const PG8_LAS bf16x8*)(lds + PG8_SA(b, h) + aoff + m * 2048 + k * 1024); } while (0)
; #define PG8_LDB(dst, b, h) do { _Pragma("unroll") for (int n = 0; n < 2; ++n) _Pragma("unroll") for (int k = 0; k < 2; ++k) dst[n][k] = *(const PG8_LAS bf16x8*)(lds + PG8_SB(b, h) + boff + n * 2048 + k * 1024); } while (0)
; #define PG8_WAIT_V(n) asm volatile("s_waitcnt vmcnt(" #n ")" ::: "memory")
; #define PG8_WAIT_L(n) asm volatile("s_waitcnt lgkmcnt(" #n ")" ::: "memory")
; #define PG8_BAR __builtin_amdgcn_s_barrier()
; template <class Epi, class Sched, bool ALIGN_EPI = false>
; __device__ __forceinline__ void gemm_phase8(PG8_LAS unsigned char* lds, const Gemm g, const Sched& S, const Epi& E) {
;     ...
;         const size_t nko = (has_next && nxt.kp > 0) ? (size_t)nxt.kp * g.kpiece : 0;
;         const char* nA = has_next ? (const char*)g.A + (size_t)nxt.pm * tstepA + (size_t)nxt.pn * astep + nko : cA; const char* nB = has_next ? (const char*)g.Bt + (size_t)nxt.pn * tstepB + nko : cB;
;         const int nt = (cur.kp < 0 ? g.K : g.kpiece) / 128;
;         for (int t = 0; t < nt; t += 2) {
;             const bool last = (t == nt - 2);
;             const char* a1 = cA + (size_t)(t + 1) * kstep;
;             const char* a2 = last ? nA : cA + (size_t)(t + 2) * kstep; const char* b2 = last ? nB : cB + (size_t)(t + 2) * kstep;
;             const char* a3 = a2 + kstep; const char* b3 = b2 + kstep;
;             if (last && has_next) S.a_ready(nxt);
;             PG8_LDB(B0, 0, 0); PG8_LDB(B1, 0, 1); PG8_SCHED; PG8_LDA(At, 0, 0); PG8_STAGE(PG8_SA(1, 1), a1 + hstepA, voffA);
;             PG8_WAIT_V(8); PG8_WAIT_L(0); PG8_BAR; PG8_MMA(0, 0, At, B0); PG8_MMA(0, 1, At, B1); PG8_BAR; PG8_SCHED;
;             PG8_LDA(At, 0, 1); PG8_STAGE(PG8_SB(0, 0), b2, voffB); PG8_STAGE(PG8_SB(0, 1), b2 + hstepB, voffB); PG8_STAGE(PG8_SA(0, 0), a2, voffA);
;             PG8_WAIT_V(8); PG8_WAIT_L(0); PG8_BAR; PG8_MMA(1, 0, At, B0); PG8_MMA(1, 1, At, B1); PG8_BAR; PG8_SCHED;
.LBB0_501:
	s_cmp_gt_i32 s24, -1
	s_cselect_b64 s[26:27], -1, 0
	s_cmp_lt_i32 s24, 0
	s_cselect_b32 s25, 44, 4
	s_add_i32 s81, s25, -2
	s_add_u32 s28, s28, 0xb0080
	s_addc_u32 s29, s29, 0
	s_add_u32 s82, s30, 0x100
	s_mov_b32 s34, 0
	s_addc_u32 s83, s31, 0
	ds_read_b128 v[18:21], v187
	ds_read_b128 v[26:29], v187 offset:2048
	ds_read_b128 v[22:25], v188
	ds_read_b128 v[30:33], v188 offset:2048
	ds_read_b128 v[2:5], v189
	ds_read_b128 v[10:13], v189 offset:2048
	ds_read_b128 v[6:9], v190
	ds_read_b128 v[14:17], v190 offset:2048
	s_add_i32 s84, s34, 2
	s_add_u32 s30, s28, 0xfff50080
	s_addc_u32 s31, s29, -1
	s_cmp_eq_u32 s81, s34
	s_cselect_b32 s34, s20, s30
	s_cselect_b32 s35, s21, s31
	s_cselect_b32 s31, s23, s83
	s_cselect_b32 s30, s22, s82
	s_add_i32 m0, s54, 0xc000
	ds_read_b128 v[174:177], v191
	ds_read_b128 v[194:197], v191 offset:2048
	ds_read_b128 v[178:181], v192
	ds_read_b128 v[198:201], v192 offset:2048
	ds_read_b128 v[202:205], v191 offset:4096
	ds_read_b128 v[210:213], v191 offset:6144
	ds_read_b128 v[206:209], v192 offset:4096
	ds_read_b128 v[214:217], v192 offset:6144
	global_load_lds_dwordx4 v170, s[28:29]
	s_add_i32 m0, s54, 0xe000
	s_nop 0
	global_load_lds_dwordx4 v172, s[28:29]
	s_waitcnt vmcnt(8)
	s_waitcnt lgkmcnt(0)
	s_barrier
	s_setprio 1
	s_waitcnt lgkmcnt(0)
	v_mfma_scale_f32_16x16x128_f8f6f4 v[158:161], v[18:25], v[174:181], 0, v1, v182 op_sel_hi:[0,0,0]
	v_mfma_scale_f32_16x16x128_f8f6f4 v[154:157], v[26:33], v[174:181], 0, v1, v182 op_sel_hi:[0,0,0]
	v_mfma_scale_f32_16x16x128_f8f6f4 v[142:145], v[18:25], v[194:201], 0, v1, v182 op_sel_hi:[0,0,0]
	v_mfma_scale_f32_16x16x128_f8f6f4 v[138:141], v[26:33], v[194:201], 0, v1, v182 op_sel_hi:[0,0,0]
	v_mfma_scale_f32_16x16x128_f8f6f4 v[126:129], v[18:25], v[202:209], 0, v1, v182 op_sel_hi:[0,0,0]
	v_mfma_scale_f32_16x16x128_f8f6f4 v[122:125], v[26:33], v[202:209], 0, v1, v182 op_sel_hi:[0,0,0]
	v_mfma_scale_f32_16x16x128_f8f6f4 v[110:113], v[18:25], v[210:217], 0, v1, v182 op_sel_hi:[0,0,0]
	v_mfma_scale_f32_16x16x128_f8f6f4 v[106:109], v[26:33], v[210:217], 0, v1, v182 op_sel_hi:[0,0,0]
	s_setprio 0
	s_setprio 1
	v_mfma_scale_f32_16x16x128_f8f6f4 v[150:153], v[2:9], v[174:181], 0, v1, v182 op_sel_hi:[0,0,0]
	v_mfma_scale_f32_16x16x128_f8f6f4 v[146:149], v[10:17], v[174:181], 0, v1, v182 op_sel_hi:[0,0,0]
	v_mfma_scale_f32_16x16x128_f8f6f4 v[134:137], v[2:9], v[194:201], 0, v1, v182 op_sel_hi:[0,0,0]
	v_mfma_scale_f32_16x16x128_f8f6f4 v[130:133], v[10:17], v[194:201], 0, v1, v182 op_sel_hi:[0,0,0]
	v_mfma_scale_f32_16x16x128_f8f6f4 v[118:121], v[2:9], v[202:209], 0, v1, v182 op_sel_hi:[0,0,0]
	v_mfma_scale_f32_16x16x128_f8f6f4 v[114:117], v[10:17], v[202:209], 0, v1, v182 op_sel_hi:[0,0,0]
	v_mfma_scale_f32_16x16x128_f8f6f4 v[102:105], v[2:9], v[210:217], 0, v1, v182 op_sel_hi:[0,0,0]
	v_mfma_scale_f32_16x16x128_f8f6f4 v[98:101], v[10:17], v[210:217], 0, v1, v182 op_sel_hi:[0,0,0]
	s_setprio 0
	s_barrier
	s_add_i32 s85, s65, s53
	s_mov_b32 m0, s85
	ds_read_b128 v[194:197], v191 offset:16384
	ds_read_b128 v[202:205], v191 offset:18432
	ds_read_b128 v[198:201], v192 offset:16384
	ds_read_b128 v[206:209], v192 offset:18432
	ds_read_b128 v[210:213], v191 offset:20480
	ds_read_b128 v[218:221], v191 offset:22528
	ds_read_b128 v[214:217], v192 offset:20480
	ds_read_b128 v[222:225], v192 offset:22528
	global_load_lds_dwordx4 v164, s[30:31]
	s_add_i32 m0, s85, 0x2000
	s_add_u32 s88, s30, 0xb0000
	s_addc_u32 s89, s31, 0
	s_add_i32 s85, s66, s53
	global_load_lds_dwordx4 v168, s[30:31]
	s_mov_b32 m0, s85
	s_nop 0
	global_load_lds_dwordx4 v164, s[88:89]
	s_add_i32 m0, s85, 0x2000
	s_nop 0
	global_load_lds_dwordx4 v168, s[88:89]
	s_mov_b32 m0, s54
	s_nop 0
	global_load_lds_dwordx4 v162, s[34:35]
	s_mov_b32 m0, s55
	s_nop 0
	global_load_lds_dwordx4 v166, s[34:35]
	s_waitcnt vmcnt(8)
	s_waitcnt lgkmcnt(0)
	s_barrier
	s_setprio 1
	s_waitcnt lgkmcnt(0)
	v_mfma_scale_f32_16x16x128_f8f6f4 v[94:97], v[18:25], v[194:201], 0, v1, v182 op_sel_hi:[0,0,0]
	v_mfma_scale_f32_16x16x128_f8f6f4 v[90:93], v[26:33], v[194:201], 0, v1, v182 op_sel_hi:[0,0,0]
	v_mfma_scale_f32_16x16x128_f8f6f4 v[78:81], v[18:25], v[202:209], 0, v1, v182 op_sel_hi:[0,0,0]
	v_mfma_scale_f32_16x16x128_f8f6f4 v[74:77], v[26:33], v[202:209], 0, v1, v182 op_sel_hi:[0,0,0]
	v_mfma_scale_f32_16x16x128_f8f6f4 v[62:65], v[18:25], v[210:217], 0, v1, v182 op_sel_hi:[0,0,0]
	v_mfma_scale_f32_16x16x128_f8f6f4 v[58:61], v[26:33], v[210:217], 0, v1, v182 op_sel_hi:[0,0,0]
	v_mfma_scale_f32_16x16x128_f8f6f4 v[46:49], v[18:25], v[218:225], 0, v1, v182 op_sel_hi:[0,0,0]
	v_mfma_scale_f32_16x16x128_f8f6f4 v[42:45], v[26:33], v[218:225], 0, v1, v182 op_sel_hi:[0,0,0]
	s_setprio 0
	s_setprio 1
	v_mfma_scale_f32_16x16x128_f8f6f4 v[86:89], v[2:9], v[194:201], 0, v1, v182 op_sel_hi:[0,0,0]
	v_mfma_scale_f32_16x16x128_f8f6f4 v[82:85], v[10:17], v[194:201], 0, v1, v182 op_sel_hi:[0,0,0]
	v_mfma_scale_f32_16x16x128_f8f6f4 v[70:73], v[2:9], v[202:209], 0, v1, v182 op_sel_hi:[0,0,0]
	v_mfma_scale_f32_16x16x128_f8f6f4 v[66:69], v[10:17], v[202:209], 0, v1, v182 op_sel_hi:[0,0,0]
	v_mfma_scale_f32_16x16x128_f8f6f4 v[54:57], v[2:9], v[210:217], 0, v1, v182 op_sel_hi:[0,0,0]
	v_mfma_scale_f32_16x16x128_f8f6f4 v[50:53], v[10:17], v[210:217], 0, v1, v182 op_sel_hi:[0,0,0]
	v_mfma_scale_f32_16x16x128_f8f6f4 v[38:41], v[2:9], v[218:225], 0, v1, v182 op_sel_hi:[0,0,0]
	v_mfma_scale_f32_16x16x128_f8f6f4 v[34:37], v[10:17], v[218:225], 0, v1, v182 op_sel_hi:[0,0,0]
	s_setprio 0
	s_barrier
; #define PG8_STAGE(bufoff, gbase, voff) do { _Pragma("unroll") for (int _i = 0; _i < 2; ++_i) \
;         __builtin_amdgcn_global_load_lds((const unsigned*)((const char*)(gbase) + (voff)[_i]), (PG8_LAS unsigned*)(lds + (bufoff) + ldsw + _i * 8192), 16, 0, 0); } while (0)
; #define PG8_LDA(dst, b, h) do { _Pragma("unroll") for (int m = 0; m < 4; ++m) _Pragma("unroll") for (int k = 0; k < 2; ++k) dst[m][k] = *(const PG8_LAS bf16x8*)(lds + PG8_SA(b, h) + aoff + m * 2048 + k * 1024); } while (0)
; #define PG8_LDB(dst, b, h) do { _Pragma("unroll") for (int n = 0; n < 2; ++n) _Pragma("unroll") for (int k = 0; k < 2; ++k) dst[n][k] = *(const PG8_LAS bf16x8*)(lds + PG8_SB(b, h) + boff + n * 2048 + k * 1024); } while (0)
; #define PG8_MMA(ai, bj, At, Bt) do { __builtin_amdgcn_s_setprio(1); _Pragma("unroll") for (int m = 0; m < 4; ++m) _Pragma("unroll") for (int n = 0; n < 2; ++n) _Pragma("unroll") for (int k = 0; k < 2; ++k) \
;         acc[ai][bj][m][n] = __builtin_amdgcn_mfma_f32_16x16x32_bf16(Bt[n][k], At[m][k], acc[ai][bj][m][n], 0, 0, 0); __builtin_amdgcn_s_setprio(0); } while (0)
; #define PG8_WAIT_V(n) asm volatile("s_waitcnt vmcnt(" #n ")" ::: "memory")
; #define PG8_WAIT_L(n) asm volatile("s_waitcnt lgkmcnt(" #n ")" ::: "memory")
; #define PG8_BAR __builtin_amdgcn_s_barrier()
; #define PG8_SCHED __builtin_amdgcn_sched_barrier(0)
; #define PG8_STAGE(bufoff, gbase, voff) do { _Pragma("unroll") for (int _i = 0; _i < 2; ++_i) \
;         __builtin_amdgcn_global_load_lds((const unsigned*)((const char*)(gbase) + (voff)[_i]), (PG8_LAS unsigned*)(lds + (bufoff) + ldsw + _i * 8192), 16, 0, 0); } while (0)
; #define PG8_WAIT_V(n) asm volatile("s_waitcnt vmcnt(" #n ")" ::: "memory")
; template <class Epi, class Sched, bool ALIGN_EPI = false>
; __device__ __forceinline__ void gemm_phase8(PG8_LAS unsigned char* lds, const Gemm g, const Sched& S, const Epi& E) {
;     ...
;             PG8_LDB(B0, 1, 0); PG8_LDB(B1, 1, 1); PG8_SCHED; PG8_LDA(At, 1, 0); PG8_STAGE(PG8_SA(0, 1), a2 + hstepA, voffA);
;             PG8_WAIT_V(8); PG8_WAIT_L(0); PG8_BAR; PG8_MMA(0, 0, At, B0); PG8_MMA(0, 1, At, B1); PG8_BAR; PG8_SCHED;
;             PG8_LDA(At, 1, 1); PG8_STAGE(PG8_SB(1, 0), b3, voffB); PG8_STAGE(PG8_SB(1, 1), b3 + hstepB, voffB); PG8_STAGE(PG8_SA(1, 0), a3, voffA);
;             PG8_WAIT_V(8); PG8_WAIT_L(0); PG8_BAR; PG8_MMA(1, 0, At, B0); PG8_MMA(1, 1, At, B1); PG8_BAR; PG8_SCHED;
	s_add_i32 s85, 0, 0x18000
	s_add_i32 s88, 0, 0x1c000
	v_add_u32_e32 v6, s85, v184
	v_add_u32_e32 v14, s85, v185
	v_add_u32_e32 v22, s88, v184
	v_add_u32_e32 v30, s88, v185
	ds_read_b128 v[2:5], v6
	ds_read_b128 v[10:13], v6 offset:2048
	ds_read_b128 v[6:9], v14
	ds_read_b128 v[14:17], v14 offset:2048
	ds_read_b128 v[18:21], v22
	ds_read_b128 v[26:29], v22 offset:2048
	ds_read_b128 v[22:25], v30
	ds_read_b128 v[30:33], v30 offset:2048
	s_add_u32 s34, s34, 0xb0000
	s_addc_u32 s35, s35, 0
	s_mov_b32 m0, s56
	ds_read_b128 v[194:197], v191 offset:32768
	ds_read_b128 v[202:205], v191 offset:34816
	ds_read_b128 v[198:201], v192 offset:32768
	ds_read_b128 v[206:209], v192 offset:34816
	ds_read_b128 v[210:213], v191 offset:36864
	ds_read_b128 v[218:221], v191 offset:38912
	ds_read_b128 v[214:217], v192 offset:36864
	ds_read_b128 v[222:225], v192 offset:38912
	global_load_lds_dwordx4 v162, s[34:35]
	s_mov_b32 m0, s57
	s_nop 0
	global_load_lds_dwordx4 v166, s[34:35]
	s_waitcnt vmcnt(8)
	s_waitcnt lgkmcnt(0)
	s_barrier
	s_setprio 1
	s_waitcnt lgkmcnt(0)
	v_mfma_scale_f32_16x16x128_f8f6f4 v[158:161], v[2:9], v[194:201], v[158:161], v1, v182 op_sel_hi:[0,0,0]
	v_mfma_scale_f32_16x16x128_f8f6f4 v[154:157], v[10:17], v[194:201], v[154:157], v1, v182 op_sel_hi:[0,0,0]
	v_mfma_scale_f32_16x16x128_f8f6f4 v[142:145], v[2:9], v[202:209], v[142:145], v1, v182 op_sel_hi:[0,0,0]
	v_mfma_scale_f32_16x16x128_f8f6f4 v[138:141], v[10:17], v[202:209], v[138:141], v1, v182 op_sel_hi:[0,0,0]
	v_mfma_scale_f32_16x16x128_f8f6f4 v[126:129], v[2:9], v[210:217], v[126:129], v1, v182 op_sel_hi:[0,0,0]
	v_mfma_scale_f32_16x16x128_f8f6f4 v[122:125], v[10:17], v[210:217], v[122:125], v1, v182 op_sel_hi:[0,0,0]
	v_mfma_scale_f32_16x16x128_f8f6f4 v[110:113], v[2:9], v[218:225], v[110:113], v1, v182 op_sel_hi:[0,0,0]
	v_mfma_scale_f32_16x16x128_f8f6f4 v[106:109], v[10:17], v[218:225], v[106:109], v1, v182 op_sel_hi:[0,0,0]
	s_setprio 0
	s_setprio 1
	v_mfma_scale_f32_16x16x128_f8f6f4 v[150:153], v[18:25], v[194:201], v[150:153], v1, v182 op_sel_hi:[0,0,0]
	v_mfma_scale_f32_16x16x128_f8f6f4 v[146:149], v[26:33], v[194:201], v[146:149], v1, v182 op_sel_hi:[0,0,0]
	v_mfma_scale_f32_16x16x128_f8f6f4 v[134:137], v[18:25], v[202:209], v[134:137], v1, v182 op_sel_hi:[0,0,0]
	v_mfma_scale_f32_16x16x128_f8f6f4 v[130:133], v[26:33], v[202:209], v[130:133], v1, v182 op_sel_hi:[0,0,0]
	v_mfma_scale_f32_16x16x128_f8f6f4 v[118:121], v[18:25], v[210:217], v[118:121], v1, v182 op_sel_hi:[0,0,0]
	v_mfma_scale_f32_16x16x128_f8f6f4 v[114:117], v[26:33], v[210:217], v[114:117], v1, v182 op_sel_hi:[0,0,0]
	v_mfma_scale_f32_16x16x128_f8f6f4 v[102:105], v[18:25], v[218:225], v[102:105], v1, v182 op_sel_hi:[0,0,0]
	v_mfma_scale_f32_16x16x128_f8f6f4 v[98:101], v[26:33], v[218:225], v[98:101], v1, v182 op_sel_hi:[0,0,0]
	s_setprio 0
	s_barrier
	s_add_i32 s101, s85, s53
	s_add_u32 s98, s30, s12
	s_addc_u32 s99, s31, s13
	s_mov_b32 m0, s101
	ds_read_b128 v[194:197], v191 offset:49152
	ds_read_b128 v[202:205], v191 offset:51200
	ds_read_b128 v[198:201], v192 offset:49152
	ds_read_b128 v[206:209], v192 offset:51200
	ds_read_b128 v[210:213], v191 offset:53248
	ds_read_b128 v[218:221], v191 offset:55296
	ds_read_b128 v[214:217], v192 offset:53248
	ds_read_b128 v[222:225], v192 offset:55296
	global_load_lds_dwordx4 v164, s[98:99]
	s_add_i32 m0, s101, 0x2000
	s_add_u32 s30, s30, 0xb0080
	s_addc_u32 s31, s31, 0
	s_add_i32 s101, s88, s53
	global_load_lds_dwordx4 v168, s[98:99]
	s_add_u32 s98, s34, s12
	s_addc_u32 s99, s35, s13
	s_sub_u32 s98, s98, 0xb0000
	s_subb_u32 s99, s99, 0
	s_mov_b32 m0, s101
	s_nop 0
	global_load_lds_dwordx4 v164, s[30:31]
	s_add_i32 m0, s101, 0x2000
	s_nop 0
	global_load_lds_dwordx4 v168, s[30:31]
	s_mov_b32 m0, s63
	s_nop 0
	global_load_lds_dwordx4 v162, s[98:99]
	s_mov_b32 m0, s64
	s_nop 0
	global_load_lds_dwordx4 v166, s[98:99]
	s_waitcnt vmcnt(8)
	s_waitcnt lgkmcnt(0)
	s_barrier
	s_setprio 1
	s_waitcnt lgkmcnt(0)
	v_mfma_scale_f32_16x16x128_f8f6f4 v[94:97], v[2:9], v[194:201], v[94:97], v1, v182 op_sel_hi:[0,0,0]
	v_mfma_scale_f32_16x16x128_f8f6f4 v[90:93], v[10:17], v[194:201], v[90:93], v1, v182 op_sel_hi:[0,0,0]
	v_mfma_scale_f32_16x16x128_f8f6f4 v[78:81], v[2:9], v[202:209], v[78:81], v1, v182 op_sel_hi:[0,0,0]
	v_mfma_scale_f32_16x16x128_f8f6f4 v[74:77], v[10:17], v[202:209], v[74:77], v1, v182 op_sel_hi:[0,0,0]
	v_mfma_scale_f32_16x16x128_f8f6f4 v[62:65], v[2:9], v[210:217], v[62:65], v1, v182 op_sel_hi:[0,0,0]
	v_mfma_scale_f32_16x16x128_f8f6f4 v[58:61], v[10:17], v[210:217], v[58:61], v1, v182 op_sel_hi:[0,0,0]
	v_mfma_scale_f32_16x16x128_f8f6f4 v[46:49], v[2:9], v[218:225], v[46:49], v1, v182 op_sel_hi:[0,0,0]
	v_mfma_scale_f32_16x16x128_f8f6f4 v[42:45], v[10:17], v[218:225], v[42:45], v1, v182 op_sel_hi:[0,0,0]
	s_setprio 0
	s_setprio 1
	v_mfma_scale_f32_16x16x128_f8f6f4 v[86:89], v[18:25], v[194:201], v[86:89], v1, v182 op_sel_hi:[0,0,0]
	v_mfma_scale_f32_16x16x128_f8f6f4 v[82:85], v[26:33], v[194:201], v[82:85], v1, v182 op_sel_hi:[0,0,0]
	v_mfma_scale_f32_16x16x128_f8f6f4 v[70:73], v[18:25], v[202:209], v[70:73], v1, v182 op_sel_hi:[0,0,0]
	v_mfma_scale_f32_16x16x128_f8f6f4 v[66:69], v[26:33], v[202:209], v[66:69], v1, v182 op_sel_hi:[0,0,0]
	v_mfma_scale_f32_16x16x128_f8f6f4 v[54:57], v[18:25], v[210:217], v[54:57], v1, v182 op_sel_hi:[0,0,0]
	v_mfma_scale_f32_16x16x128_f8f6f4 v[50:53], v[26:33], v[210:217], v[50:53], v1, v182 op_sel_hi:[0,0,0]
	v_mfma_scale_f32_16x16x128_f8f6f4 v[38:41], v[18:25], v[218:225], v[38:41], v1, v182 op_sel_hi:[0,0,0]
	v_mfma_scale_f32_16x16x128_f8f6f4 v[34:37], v[26:33], v[218:225], v[34:37], v1, v182 op_sel_hi:[0,0,0]
	s_setprio 0
	s_barrier
; #define PG8_STAGE(bufoff, gbase, voff) do { _Pragma("unroll") for (int _i = 0; _i < 2; ++_i) \
;         __builtin_amdgcn_global_load_lds((const unsigned*)((const char*)(gbase) + (voff)[_i]), (PG8_LAS unsigned*)(lds + (bufoff) + ldsw + _i * 8192), 16, 0, 0); } while (0)
; #define PG8_LDA(dst, b, h) do { _Pragma("unroll") for (int m = 0; m < 4; ++m) _Pragma("unroll") for (int k = 0; k < 2; ++k) dst[m][k] = *(const PG8_LAS bf16x8*)(lds + PG8_SA(b, h) + aoff + m * 2048 + k * 1024); } while (0)
; #define PG8_LDB(dst, b, h) do { _Pragma("unroll") for (int n = 0; n < 2; ++n) _Pragma("unroll") for (int k = 0; k < 2; ++k) dst[n][k] = *(const PG8_LAS bf16x8*)(lds + PG8_SB(b, h) + boff + n * 2048 + k * 1024); } while (0)
; #define PG8_MMA(ai, bj, At, Bt) do { __builtin_amdgcn_s_setprio(1); _Pragma("unroll") for (int m = 0; m < 4; ++m) _Pragma("unroll") for (int n = 0; n < 2; ++n) _Pragma("unroll") for (int k = 0; k < 2; ++k) \
;         acc[ai][bj][m][n] = __builtin_amdgcn_mfma_f32_16x16x32_bf16(Bt[n][k], At[m][k], acc[ai][bj][m][n], 0, 0, 0); __builtin_amdgcn_s_setprio(0); } while (0)
; #define PG8_WAIT_V(n) asm volatile("s_waitcnt vmcnt(" #n ")" ::: "memory")
; #define PG8_WAIT_L(n) asm volatile("s_waitcnt lgkmcnt(" #n ")" ::: "memory")
; template <class Epi, class Sched, bool ALIGN_EPI = false>
; __device__ __forceinline__ void gemm_phase8(PG8_LAS unsigned char* lds, const Gemm g, const Sched& S, const Epi& E) {
;     ...
;         for (int t = 0; t < nt; t += 2) {
;             const bool last = (t == nt - 2);
;             const char* a1 = cA + (size_t)(t + 1) * kstep;
;             const char* a2 = last ? nA : cA + (size_t)(t + 2) * kstep; const char* b2 = last ? nB : cB + (size_t)(t + 2) * kstep;
;             const char* a3 = a2 + kstep; const char* b3 = b2 + kstep;
;             if (last && has_next) S.a_ready(nxt);
;             PG8_LDB(B0, 0, 0); PG8_LDB(B1, 0, 1); PG8_SCHED; PG8_LDA(At, 0, 0); PG8_STAGE(PG8_SA(1, 1), a1 + hstepA, voffA);
;             PG8_WAIT_V(8); PG8_WAIT_L(0); PG8_BAR; PG8_MMA(0, 0, At, B0); PG8_MMA(0, 1, At, B1); PG8_BAR; PG8_SCHED;
;             PG8_LDA(At, 0, 1); PG8_STAGE(PG8_SB(0, 0), b2, voffB); PG8_STAGE(PG8_SB(0, 1), b2 + hstepB, voffB); PG8_STAGE(PG8_SA(0, 0), a2, voffA);
;             PG8_WAIT_V(8); PG8_WAIT_L(0); PG8_BAR; PG8_MMA(1, 0, At, B0); PG8_MMA(1, 1, At, B1); PG8_BAR; PG8_SCHED;
	s_add_u32 s28, s28, 0x100
	s_addc_u32 s29, s29, 0
	s_add_u32 s82, s82, 0x100
	s_addc_u32 s83, s83, 0
	s_cmp_ge_u32 s84, s25
	s_mov_b32 s34, s84
	ds_read_b128 v[18:21], v187
	ds_read_b128 v[26:29], v187 offset:2048
	ds_read_b128 v[22:25], v188
	ds_read_b128 v[30:33], v188 offset:2048
	ds_read_b128 v[2:5], v189
	ds_read_b128 v[10:13], v189 offset:2048
	ds_read_b128 v[6:9], v190
	ds_read_b128 v[14:17], v190 offset:2048
	s_add_i32 s84, s34, 2
	s_add_u32 s30, s28, 0xfff50080
	s_addc_u32 s31, s29, -1
	s_cmp_eq_u32 s81, s34
	s_cselect_b32 s34, s20, s30
	s_cselect_b32 s35, s21, s31
	s_cselect_b32 s31, s23, s83
	s_cselect_b32 s30, s22, s82
	s_add_i32 m0, s54, 0xc000
	ds_read_b128 v[174:177], v191
	ds_read_b128 v[194:197], v191 offset:2048
	ds_read_b128 v[178:181], v192
	ds_read_b128 v[198:201], v192 offset:2048
	ds_read_b128 v[202:205], v191 offset:4096
	ds_read_b128 v[210:213], v191 offset:6144
	ds_read_b128 v[206:209], v192 offset:4096
	ds_read_b128 v[214:217], v192 offset:6144
	global_load_lds_dwordx4 v170, s[28:29]
	s_add_i32 m0, s54, 0xe000
	s_nop 0
	global_load_lds_dwordx4 v172, s[28:29]
	s_waitcnt vmcnt(8)
	s_waitcnt lgkmcnt(0)
	s_barrier
	s_setprio 1
	s_waitcnt lgkmcnt(0)
	v_mfma_scale_f32_16x16x128_f8f6f4 v[158:161], v[18:25], v[174:181], v[158:161], v1, v182 op_sel_hi:[0,0,0]
	v_mfma_scale_f32_16x16x128_f8f6f4 v[154:157], v[26:33], v[174:181], v[154:157], v1, v182 op_sel_hi:[0,0,0]
	v_mfma_scale_f32_16x16x128_f8f6f4 v[142:145], v[18:25], v[194:201], v[142:145], v1, v182 op_sel_hi:[0,0,0]
	v_mfma_scale_f32_16x16x128_f8f6f4 v[138:141], v[26:33], v[194:201], v[138:141], v1, v182 op_sel_hi:[0,0,0]
	v_mfma_scale_f32_16x16x128_f8f6f4 v[126:129], v[18:25], v[202:209], v[126:129], v1, v182 op_sel_hi:[0,0,0]
	v_mfma_scale_f32_16x16x128_f8f6f4 v[122:125], v[26:33], v[202:209], v[122:125], v1, v182 op_sel_hi:[0,0,0]
	v_mfma_scale_f32_16x16x128_f8f6f4 v[110:113], v[18:25], v[210:217], v[110:113], v1, v182 op_sel_hi:[0,0,0]
	v_mfma_scale_f32_16x16x128_f8f6f4 v[106:109], v[26:33], v[210:217], v[106:109], v1, v182 op_sel_hi:[0,0,0]
	s_setprio 0
	s_setprio 1
	v_mfma_scale_f32_16x16x128_f8f6f4 v[150:153], v[2:9], v[174:181], v[150:153], v1, v182 op_sel_hi:[0,0,0]
	v_mfma_scale_f32_16x16x128_f8f6f4 v[146:149], v[10:17], v[174:181], v[146:149], v1, v182 op_sel_hi:[0,0,0]
	v_mfma_scale_f32_16x16x128_f8f6f4 v[134:137], v[2:9], v[194:201], v[134:137], v1, v182 op_sel_hi:[0,0,0]
	v_mfma_scale_f32_16x16x128_f8f6f4 v[130:133], v[10:17], v[194:201], v[130:133], v1, v182 op_sel_hi:[0,0,0]
	v_mfma_scale_f32_16x16x128_f8f6f4 v[118:121], v[2:9], v[202:209], v[118:121], v1, v182 op_sel_hi:[0,0,0]
	v_mfma_scale_f32_16x16x128_f8f6f4 v[114:117], v[10:17], v[202:209], v[114:117], v1, v182 op_sel_hi:[0,0,0]
	v_mfma_scale_f32_16x16x128_f8f6f4 v[102:105], v[2:9], v[210:217], v[102:105], v1, v182 op_sel_hi:[0,0,0]
	v_mfma_scale_f32_16x16x128_f8f6f4 v[98:101], v[10:17], v[210:217], v[98:101], v1, v182 op_sel_hi:[0,0,0]
	s_setprio 0
	s_barrier
	s_add_i32 s85, s65, s53
	s_mov_b32 m0, s85
	ds_read_b128 v[194:197], v191 offset:16384
	ds_read_b128 v[202:205], v191 offset:18432
	ds_read_b128 v[198:201], v192 offset:16384
	ds_read_b128 v[206:209], v192 offset:18432
	ds_read_b128 v[210:213], v191 offset:20480
	ds_read_b128 v[218:221], v191 offset:22528
	ds_read_b128 v[214:217], v192 offset:20480
	ds_read_b128 v[222:225], v192 offset:22528
	global_load_lds_dwordx4 v164, s[30:31]
	s_add_i32 m0, s85, 0x2000
	s_add_u32 s88, s30, 0xb0000
	s_addc_u32 s89, s31, 0
	s_add_i32 s85, s66, s53
	global_load_lds_dwordx4 v168, s[30:31]
	s_mov_b32 m0, s85
	s_nop 0
	global_load_lds_dwordx4 v164, s[88:89]
	s_add_i32 m0, s85, 0x2000
	s_nop 0
	global_load_lds_dwordx4 v168, s[88:89]
	s_mov_b32 m0, s54
	s_nop 0
	global_load_lds_dwordx4 v162, s[34:35]
	s_mov_b32 m0, s55
	s_nop 0
	global_load_lds_dwordx4 v166, s[34:35]
	s_waitcnt vmcnt(8)
	s_waitcnt lgkmcnt(0)
	s_barrier
	s_setprio 1
	s_waitcnt lgkmcnt(0)
	v_mfma_scale_f32_16x16x128_f8f6f4 v[94:97], v[18:25], v[194:201], v[94:97], v1, v182 op_sel_hi:[0,0,0]
	v_mfma_scale_f32_16x16x128_f8f6f4 v[90:93], v[26:33], v[194:201], v[90:93], v1, v182 op_sel_hi:[0,0,0]
	v_mfma_scale_f32_16x16x128_f8f6f4 v[78:81], v[18:25], v[202:209], v[78:81], v1, v182 op_sel_hi:[0,0,0]
	v_mfma_scale_f32_16x16x128_f8f6f4 v[74:77], v[26:33], v[202:209], v[74:77], v1, v182 op_sel_hi:[0,0,0]
	v_mfma_scale_f32_16x16x128_f8f6f4 v[62:65], v[18:25], v[210:217], v[62:65], v1, v182 op_sel_hi:[0,0,0]
	v_mfma_scale_f32_16x16x128_f8f6f4 v[58:61], v[26:33], v[210:217], v[58:61], v1, v182 op_sel_hi:[0,0,0]
	v_mfma_scale_f32_16x16x128_f8f6f4 v[46:49], v[18:25], v[218:225], v[46:49], v1, v182 op_sel_hi:[0,0,0]
	v_mfma_scale_f32_16x16x128_f8f6f4 v[42:45], v[26:33], v[218:225], v[42:45], v1, v182 op_sel_hi:[0,0,0]
	s_setprio 0
	s_setprio 1
	v_mfma_scale_f32_16x16x128_f8f6f4 v[86:89], v[2:9], v[194:201], v[86:89], v1, v182 op_sel_hi:[0,0,0]
	v_mfma_scale_f32_16x16x128_f8f6f4 v[82:85], v[10:17], v[194:201], v[82:85], v1, v182 op_sel_hi:[0,0,0]
	v_mfma_scale_f32_16x16x128_f8f6f4 v[70:73], v[2:9], v[202:209], v[70:73], v1, v182 op_sel_hi:[0,0,0]
	v_mfma_scale_f32_16x16x128_f8f6f4 v[66:69], v[10:17], v[202:209], v[66:69], v1, v182 op_sel_hi:[0,0,0]
	v_mfma_scale_f32_16x16x128_f8f6f4 v[54:57], v[2:9], v[210:217], v[54:57], v1, v182 op_sel_hi:[0,0,0]
	v_mfma_scale_f32_16x16x128_f8f6f4 v[50:53], v[10:17], v[210:217], v[50:53], v1, v182 op_sel_hi:[0,0,0]
	v_mfma_scale_f32_16x16x128_f8f6f4 v[38:41], v[2:9], v[218:225], v[38:41], v1, v182 op_sel_hi:[0,0,0]
	v_mfma_scale_f32_16x16x128_f8f6f4 v[34:37], v[10:17], v[218:225], v[34:37], v1, v182 op_sel_hi:[0,0,0]
	s_setprio 0
	s_barrier
; #define PG8_STAGE(bufoff, gbase, voff) do { _Pragma("unroll") for (int _i = 0; _i < 2; ++_i) \
;         __builtin_amdgcn_global_load_lds((const unsigned*)((const char*)(gbase) + (voff)[_i]), (PG8_LAS unsigned*)(lds + (bufoff) + ldsw + _i * 8192), 16, 0, 0); } while (0)
; #define PG8_LDA(dst, b, h) do { _Pragma("unroll") for (int m = 0; m < 4; ++m) _Pragma("unroll") for (int k = 0; k < 2; ++k) dst[m][k] = *(const PG8_LAS bf16x8*)(lds + PG8_SA(b, h) + aoff + m * 2048 + k * 1024); } while (0)
; #define PG8_LDB(dst, b, h) do { _Pragma("unroll") for (int n = 0; n < 2; ++n) _Pragma("unroll") for (int k = 0; k < 2; ++k) dst[n][k] = *(const PG8_LAS bf16x8*)(lds + PG8_SB(b, h) + boff + n * 2048 + k * 1024); } while (0)
; #define PG8_MMA(ai, bj, At, Bt) do { __builtin_amdgcn_s_setprio(1); _Pragma("unroll") for (int m = 0; m < 4; ++m) _Pragma("unroll") for (int n = 0; n < 2; ++n) _Pragma("unroll") for (int k = 0; k < 2; ++k) \
;         acc[ai][bj][m][n] = __builtin_amdgcn_mfma_f32_16x16x32_bf16(Bt[n][k], At[m][k], acc[ai][bj][m][n], 0, 0, 0); __builtin_amdgcn_s_setprio(0); } while (0)
; #define PG8_WAIT_V(n) asm volatile("s_waitcnt vmcnt(" #n ")" ::: "memory")
; #define PG8_WAIT_L(n) asm volatile("s_waitcnt lgkmcnt(" #n ")" ::: "memory")
; #define PG8_BAR __builtin_amdgcn_s_barrier()
; #define PG8_SCHED __builtin_amdgcn_sched_barrier(0)
; #define PG8_STAGE(bufoff, gbase, voff) do { _Pragma("unroll") for (int _i = 0; _i < 2; ++_i) \
;         __builtin_amdgcn_global_load_lds((const unsigned*)((const char*)(gbase) + (voff)[_i]), (PG8_LAS unsigned*)(lds + (bufoff) + ldsw + _i * 8192), 16, 0, 0); } while (0)
; #define PG8_BAR __builtin_amdgcn_s_barrier()
; template <class Epi, class Sched, bool ALIGN_EPI = false>
; __device__ __forceinline__ void gemm_phase8(PG8_LAS unsigned char* lds, const Gemm g, const Sched& S, const Epi& E) {
;     ...
;             PG8_LDB(B0, 1, 0); PG8_LDB(B1, 1, 1); PG8_SCHED; PG8_LDA(At, 1, 0); PG8_STAGE(PG8_SA(0, 1), a2 + hstepA, voffA);
;             PG8_WAIT_V(8); PG8_WAIT_L(0); PG8_BAR; PG8_MMA(0, 0, At, B0); PG8_MMA(0, 1, At, B1); PG8_BAR; PG8_SCHED;
;             PG8_LDA(At, 1, 1); PG8_STAGE(PG8_SB(1, 0), b3, voffB); PG8_STAGE(PG8_SB(1, 1), b3 + hstepB, voffB); PG8_STAGE(PG8_SA(1, 0), a3, voffA);
;             PG8_WAIT_V(8); PG8_WAIT_L(0); PG8_BAR; PG8_MMA(1, 0, At, B0); PG8_MMA(1, 1, At, B1); PG8_BAR; PG8_SCHED;
;         }
	s_add_i32 s85, 0, 0x18000
	s_add_i32 s88, 0, 0x1c000
	v_add_u32_e32 v6, s85, v184
	v_add_u32_e32 v14, s85, v185
	v_add_u32_e32 v22, s88, v184
	v_add_u32_e32 v30, s88, v185
	ds_read_b128 v[2:5], v6
	ds_read_b128 v[10:13], v6 offset:2048
	ds_read_b128 v[6:9], v14
	ds_read_b128 v[14:17], v14 offset:2048
	ds_read_b128 v[18:21], v22
	ds_read_b128 v[26:29], v22 offset:2048
	ds_read_b128 v[22:25], v30
	ds_read_b128 v[30:33], v30 offset:2048
	s_add_u32 s34, s34, 0xb0000
	s_addc_u32 s35, s35, 0
	s_mov_b32 m0, s56
	ds_read_b128 v[194:197], v191 offset:32768
	ds_read_b128 v[202:205], v191 offset:34816
	ds_read_b128 v[198:201], v192 offset:32768
	ds_read_b128 v[206:209], v192 offset:34816
	ds_read_b128 v[210:213], v191 offset:36864
	ds_read_b128 v[218:221], v191 offset:38912
	ds_read_b128 v[214:217], v192 offset:36864
	ds_read_b128 v[222:225], v192 offset:38912
	global_load_lds_dwordx4 v162, s[34:35]
	s_mov_b32 m0, s57
	s_nop 0
	global_load_lds_dwordx4 v166, s[34:35]
	s_waitcnt vmcnt(8)
	s_waitcnt lgkmcnt(0)
	s_barrier
	s_setprio 1
	s_waitcnt lgkmcnt(0)
	v_mfma_scale_f32_16x16x128_f8f6f4 v[158:161], v[2:9], v[194:201], v[158:161], v1, v182 op_sel_hi:[0,0,0]
	v_mfma_scale_f32_16x16x128_f8f6f4 v[154:157], v[10:17], v[194:201], v[154:157], v1, v182 op_sel_hi:[0,0,0]
	v_mfma_scale_f32_16x16x128_f8f6f4 v[142:145], v[2:9], v[202:209], v[142:145], v1, v182 op_sel_hi:[0,0,0]
	v_mfma_scale_f32_16x16x128_f8f6f4 v[138:141], v[10:17], v[202:209], v[138:141], v1, v182 op_sel_hi:[0,0,0]
	v_mfma_scale_f32_16x16x128_f8f6f4 v[126:129], v[2:9], v[210:217], v[126:129], v1, v182 op_sel_hi:[0,0,0]
	v_mfma_scale_f32_16x16x128_f8f6f4 v[122:125], v[10:17], v[210:217], v[122:125], v1, v182 op_sel_hi:[0,0,0]
	v_mfma_scale_f32_16x16x128_f8f6f4 v[110:113], v[2:9], v[218:225], v[110:113], v1, v182 op_sel_hi:[0,0,0]
	v_mfma_scale_f32_16x16x128_f8f6f4 v[106:109], v[10:17], v[218:225], v[106:109], v1, v182 op_sel_hi:[0,0,0]
	s_setprio 0
	s_setprio 1
	v_mfma_scale_f32_16x16x128_f8f6f4 v[150:153], v[18:25], v[194:201], v[150:153], v1, v182 op_sel_hi:[0,0,0]
	v_mfma_scale_f32_16x16x128_f8f6f4 v[146:149], v[26:33], v[194:201], v[146:149], v1, v182 op_sel_hi:[0,0,0]
	v_mfma_scale_f32_16x16x128_f8f6f4 v[134:137], v[18:25], v[202:209], v[134:137], v1, v182 op_sel_hi:[0,0,0]
	v_mfma_scale_f32_16x16x128_f8f6f4 v[130:133], v[26:33], v[202:209], v[130:133], v1, v182 op_sel_hi:[0,0,0]
	v_mfma_scale_f32_16x16x128_f8f6f4 v[118:121], v[18:25], v[210:217], v[118:121], v1, v182 op_sel_hi:[0,0,0]
	v_mfma_scale_f32_16x16x128_f8f6f4 v[114:117], v[26:33], v[210:217], v[114:117], v1, v182 op_sel_hi:[0,0,0]
	v_mfma_scale_f32_16x16x128_f8f6f4 v[102:105], v[18:25], v[218:225], v[102:105], v1, v182 op_sel_hi:[0,0,0]
	v_mfma_scale_f32_16x16x128_f8f6f4 v[98:101], v[26:33], v[218:225], v[98:101], v1, v182 op_sel_hi:[0,0,0]
	s_setprio 0
	s_barrier
	s_add_i32 s101, s85, s53
	s_add_u32 s98, s30, s12
	s_addc_u32 s99, s31, s13
	s_mov_b32 m0, s101
	ds_read_b128 v[194:197], v191 offset:49152
	ds_read_b128 v[202:205], v191 offset:51200
	ds_read_b128 v[198:201], v192 offset:49152
	ds_read_b128 v[206:209], v192 offset:51200
	ds_read_b128 v[210:213], v191 offset:53248
	ds_read_b128 v[218:221], v191 offset:55296
	ds_read_b128 v[214:217], v192 offset:53248
	ds_read_b128 v[222:225], v192 offset:55296
	global_load_lds_dwordx4 v164, s[98:99]
	s_add_i32 m0, s101, 0x2000
	s_add_u32 s30, s30, 0xb0080
	s_addc_u32 s31, s31, 0
	s_add_i32 s101, s88, s53
	global_load_lds_dwordx4 v168, s[98:99]
	s_add_u32 s98, s34, s12
	s_addc_u32 s99, s35, s13
	s_sub_u32 s98, s98, 0xb0000
	s_subb_u32 s99, s99, 0
	s_mov_b32 m0, s101
	s_nop 0
	global_load_lds_dwordx4 v164, s[30:31]
	s_add_i32 m0, s101, 0x2000
	s_nop 0
	global_load_lds_dwordx4 v168, s[30:31]
	s_mov_b32 m0, s63
	s_nop 0
	global_load_lds_dwordx4 v162, s[98:99]
	s_mov_b32 m0, s64
	s_nop 0
	global_load_lds_dwordx4 v166, s[98:99]
	s_waitcnt vmcnt(8)
	s_waitcnt lgkmcnt(0)
	s_barrier
	s_setprio 1
	s_waitcnt lgkmcnt(0)
	v_mfma_scale_f32_16x16x128_f8f6f4 v[94:97], v[2:9], v[194:201], v[94:97], v1, v182 op_sel_hi:[0,0,0]
	v_mfma_scale_f32_16x16x128_f8f6f4 v[90:93], v[10:17], v[194:201], v[90:93], v1, v182 op_sel_hi:[0,0,0]
	v_mfma_scale_f32_16x16x128_f8f6f4 v[78:81], v[2:9], v[202:209], v[78:81], v1, v182 op_sel_hi:[0,0,0]
	v_mfma_scale_f32_16x16x128_f8f6f4 v[74:77], v[10:17], v[202:209], v[74:77], v1, v182 op_sel_hi:[0,0,0]
	v_mfma_scale_f32_16x16x128_f8f6f4 v[62:65], v[2:9], v[210:217], v[62:65], v1, v182 op_sel_hi:[0,0,0]
	v_mfma_scale_f32_16x16x128_f8f6f4 v[58:61], v[10:17], v[210:217], v[58:61], v1, v182 op_sel_hi:[0,0,0]
	v_mfma_scale_f32_16x16x128_f8f6f4 v[46:49], v[2:9], v[218:225], v[46:49], v1, v182 op_sel_hi:[0,0,0]
	v_mfma_scale_f32_16x16x128_f8f6f4 v[42:45], v[10:17], v[218:225], v[42:45], v1, v182 op_sel_hi:[0,0,0]
	s_setprio 0
	s_setprio 1
	v_mfma_scale_f32_16x16x128_f8f6f4 v[86:89], v[18:25], v[194:201], v[86:89], v1, v182 op_sel_hi:[0,0,0]
	v_mfma_scale_f32_16x16x128_f8f6f4 v[82:85], v[26:33], v[194:201], v[82:85], v1, v182 op_sel_hi:[0,0,0]
	v_mfma_scale_f32_16x16x128_f8f6f4 v[70:73], v[18:25], v[202:209], v[70:73], v1, v182 op_sel_hi:[0,0,0]
	v_mfma_scale_f32_16x16x128_f8f6f4 v[66:69], v[26:33], v[202:209], v[66:69], v1, v182 op_sel_hi:[0,0,0]
	v_mfma_scale_f32_16x16x128_f8f6f4 v[54:57], v[18:25], v[210:217], v[54:57], v1, v182 op_sel_hi:[0,0,0]
	v_mfma_scale_f32_16x16x128_f8f6f4 v[50:53], v[26:33], v[210:217], v[50:53], v1, v182 op_sel_hi:[0,0,0]
	v_mfma_scale_f32_16x16x128_f8f6f4 v[38:41], v[18:25], v[218:225], v[38:41], v1, v182 op_sel_hi:[0,0,0]
	v_mfma_scale_f32_16x16x128_f8f6f4 v[34:37], v[26:33], v[218:225], v[34:37], v1, v182 op_sel_hi:[0,0,0]
	s_setprio 0
	s_barrier
	s_add_u32 s28, s28, 0x100
	s_addc_u32 s29, s29, 0
	s_add_u32 s82, s82, 0x100
	s_addc_u32 s83, s83, 0
	s_cmp_ge_u32 s84, s25
	s_mov_b32 s34, s84
	s_cbranch_scc1 .Lpx_1
; #define PG8_STAGE(bufoff, gbase, voff) do { _Pragma("unroll") for (int _i = 0; _i < 2; ++_i) \
;         __builtin_amdgcn_global_load_lds((const unsigned*)((const char*)(gbase) + (voff)[_i]), (PG8_LAS unsigned*)(lds + (bufoff) + ldsw + _i * 8192), 16, 0, 0); } while (0)
; #define PG8_LDA(dst, b, h) do { _Pragma("unroll") for (int m = 0; m < 4; ++m) _Pragma("unroll") for (int k = 0; k < 2; ++k) dst[m][k] = *(const PG8_LAS bf16x8*)(lds + PG8_SA(b, h) + aoff + m * 2048 + k * 1024); } while (0)
; #define PG8_LDB(dst, b, h) do { _Pragma("unroll") for (int n = 0; n < 2; ++n) _Pragma("unroll") for (int k = 0; k < 2; ++k) dst[n][k] = *(const PG8_LAS bf16x8*)(lds + PG8_SB(b, h) + boff + n * 2048 + k * 1024); } while (0)
; #define PG8_MMA(ai, bj, At, Bt) do { __builtin_amdgcn_s_setprio(1); _Pragma("unroll") for (int m = 0; m < 4; ++m) _Pragma("unroll") for (int n = 0; n < 2; ++n) _Pragma("unroll") for (int k = 0; k < 2; ++k) \
;         acc[ai][bj][m][n] = __builtin_amdgcn_mfma_f32_16x16x32_bf16(Bt[n][k], At[m][k], acc[ai][bj][m][n], 0, 0, 0); __builtin_amdgcn_s_setprio(0); } while (0)
; #define PG8_WAIT_V(n) asm volatile("s_waitcnt vmcnt(" #n ")" ::: "memory")
; #define PG8_WAIT_L(n) asm volatile("s_waitcnt lgkmcnt(" #n ")" ::: "memory")
; template <class Epi, class Sched, bool ALIGN_EPI = false>
; __device__ __forceinline__ void gemm_phase8(PG8_LAS unsigned char* lds, const Gemm g, const Sched& S, const Epi& E) {
;     ...
;         for (int t = 0; t < nt; t += 2) {
;             const bool last = (t == nt - 2);
;             const char* a1 = cA + (size_t)(t + 1) * kstep;
;             const char* a2 = last ? nA : cA + (size_t)(t + 2) * kstep; const char* b2 = last ? nB : cB + (size_t)(t + 2) * kstep;
;             const char* a3 = a2 + kstep; const char* b3 = b2 + kstep;
;             if (last && has_next) S.a_ready(nxt);
;             PG8_LDB(B0, 0, 0); PG8_LDB(B1, 0, 1); PG8_SCHED; PG8_LDA(At, 0, 0); PG8_STAGE(PG8_SA(1, 1), a1 + hstepA, voffA);
;             PG8_WAIT_V(8); PG8_WAIT_L(0); PG8_BAR; PG8_MMA(0, 0, At, B0); PG8_MMA(0, 1, At, B1); PG8_BAR; PG8_SCHED;
;             PG8_LDA(At, 0, 1); PG8_STAGE(PG8_SB(0, 0), b2, voffB); PG8_STAGE(PG8_SB(0, 1), b2 + hstepB, voffB); PG8_STAGE(PG8_SA(0, 0), a2, voffA);
;             PG8_WAIT_V(8); PG8_WAIT_L(0); PG8_BAR; PG8_MMA(1, 0, At, B0); PG8_MMA(1, 1, At, B1); PG8_BAR; PG8_SCHED;
.LBB0_502:
	ds_read_b128 v[18:21], v187
	ds_read_b128 v[26:29], v187 offset:2048
	ds_read_b128 v[22:25], v188
	ds_read_b128 v[30:33], v188 offset:2048
	ds_read_b128 v[2:5], v189
	ds_read_b128 v[10:13], v189 offset:2048
	ds_read_b128 v[6:9], v190
	ds_read_b128 v[14:17], v190 offset:2048
	s_add_i32 s84, s34, 2
	s_add_u32 s30, s28, 0xfff50080
	s_addc_u32 s31, s29, -1
	s_cmp_eq_u32 s81, s34
	s_cselect_b32 s34, s20, s30
	s_cselect_b32 s35, s21, s31
	s_cselect_b32 s31, s23, s83
	s_cselect_b32 s30, s22, s82
	s_add_i32 m0, s54, 0xc000
	ds_read_b128 v[174:177], v191
	ds_read_b128 v[194:197], v191 offset:2048
	ds_read_b128 v[178:181], v192
	ds_read_b128 v[198:201], v192 offset:2048
	ds_read_b128 v[202:205], v191 offset:4096
	ds_read_b128 v[210:213], v191 offset:6144
	ds_read_b128 v[206:209], v192 offset:4096
	ds_read_b128 v[214:217], v192 offset:6144
	global_load_lds_dwordx4 v170, s[28:29]
	s_add_i32 m0, s54, 0xe000
	s_nop 0
	global_load_lds_dwordx4 v172, s[28:29]
	s_waitcnt vmcnt(8)
	s_waitcnt lgkmcnt(0)
	s_barrier
	s_setprio 1
	s_waitcnt lgkmcnt(0)
	v_mfma_scale_f32_16x16x128_f8f6f4 v[158:161], v[18:25], v[174:181], v[158:161], v1, v182 op_sel_hi:[0,0,0]
	v_mfma_scale_f32_16x16x128_f8f6f4 v[154:157], v[26:33], v[174:181], v[154:157], v1, v182 op_sel_hi:[0,0,0]
	v_mfma_scale_f32_16x16x128_f8f6f4 v[142:145], v[18:25], v[194:201], v[142:145], v1, v182 op_sel_hi:[0,0,0]
	v_mfma_scale_f32_16x16x128_f8f6f4 v[138:141], v[26:33], v[194:201], v[138:141], v1, v182 op_sel_hi:[0,0,0]
	v_mfma_scale_f32_16x16x128_f8f6f4 v[126:129], v[18:25], v[202:209], v[126:129], v1, v182 op_sel_hi:[0,0,0]
	v_mfma_scale_f32_16x16x128_f8f6f4 v[122:125], v[26:33], v[202:209], v[122:125], v1, v182 op_sel_hi:[0,0,0]
	v_mfma_scale_f32_16x16x128_f8f6f4 v[110:113], v[18:25], v[210:217], v[110:113], v1, v182 op_sel_hi:[0,0,0]
	v_mfma_scale_f32_16x16x128_f8f6f4 v[106:109], v[26:33], v[210:217], v[106:109], v1, v182 op_sel_hi:[0,0,0]
	s_setprio 0
	s_setprio 1
	v_mfma_scale_f32_16x16x128_f8f6f4 v[150:153], v[2:9], v[174:181], v[150:153], v1, v182 op_sel_hi:[0,0,0]
	v_mfma_scale_f32_16x16x128_f8f6f4 v[146:149], v[10:17], v[174:181], v[146:149], v1, v182 op_sel_hi:[0,0,0]
	v_mfma_scale_f32_16x16x128_f8f6f4 v[134:137], v[2:9], v[194:201], v[134:137], v1, v182 op_sel_hi:[0,0,0]
	v_mfma_scale_f32_16x16x128_f8f6f4 v[130:133], v[10:17], v[194:201], v[130:133], v1, v182 op_sel_hi:[0,0,0]
	v_mfma_scale_f32_16x16x128_f8f6f4 v[118:121], v[2:9], v[202:209], v[118:121], v1, v182 op_sel_hi:[0,0,0]
	v_mfma_scale_f32_16x16x128_f8f6f4 v[114:117], v[10:17], v[202:209], v[114:117], v1, v182 op_sel_hi:[0,0,0]
	v_mfma_scale_f32_16x16x128_f8f6f4 v[102:105], v[2:9], v[210:217], v[102:105], v1, v182 op_sel_hi:[0,0,0]
	v_mfma_scale_f32_16x16x128_f8f6f4 v[98:101], v[10:17], v[210:217], v[98:101], v1, v182 op_sel_hi:[0,0,0]
	s_setprio 0
	s_barrier
	s_add_i32 s85, s65, s53
	s_mov_b32 m0, s85
	ds_read_b128 v[194:197], v191 offset:16384
	ds_read_b128 v[202:205], v191 offset:18432
	ds_read_b128 v[198:201], v192 offset:16384
	ds_read_b128 v[206:209], v192 offset:18432
	ds_read_b128 v[210:213], v191 offset:20480
	ds_read_b128 v[218:221], v191 offset:22528
	ds_read_b128 v[214:217], v192 offset:20480
	ds_read_b128 v[222:225], v192 offset:22528
	global_load_lds_dwordx4 v164, s[30:31]
	s_add_i32 m0, s85, 0x2000
	s_add_u32 s88, s30, 0xb0000
	s_addc_u32 s89, s31, 0
	s_add_i32 s85, s66, s53
	global_load_lds_dwordx4 v168, s[30:31]
	s_mov_b32 m0, s85
	s_nop 0
	global_load_lds_dwordx4 v164, s[88:89]
	s_add_i32 m0, s85, 0x2000
	s_nop 0
	global_load_lds_dwordx4 v168, s[88:89]
	s_mov_b32 m0, s54
	s_nop 0
	global_load_lds_dwordx4 v162, s[34:35]
	s_mov_b32 m0, s55
	s_nop 0
	global_load_lds_dwordx4 v166, s[34:35]
	s_waitcnt vmcnt(8)
	s_waitcnt lgkmcnt(0)
	s_barrier
	s_setprio 1
	s_waitcnt lgkmcnt(0)
	v_mfma_scale_f32_16x16x128_f8f6f4 v[94:97], v[18:25], v[194:201], v[94:97], v1, v182 op_sel_hi:[0,0,0]
	v_mfma_scale_f32_16x16x128_f8f6f4 v[90:93], v[26:33], v[194:201], v[90:93], v1, v182 op_sel_hi:[0,0,0]
	v_mfma_scale_f32_16x16x128_f8f6f4 v[78:81], v[18:25], v[202:209], v[78:81], v1, v182 op_sel_hi:[0,0,0]
	v_mfma_scale_f32_16x16x128_f8f6f4 v[74:77], v[26:33], v[202:209], v[74:77], v1, v182 op_sel_hi:[0,0,0]
	v_mfma_scale_f32_16x16x128_f8f6f4 v[62:65], v[18:25], v[210:217], v[62:65], v1, v182 op_sel_hi:[0,0,0]
	v_mfma_scale_f32_16x16x128_f8f6f4 v[58:61], v[26:33], v[210:217], v[58:61], v1, v182 op_sel_hi:[0,0,0]
	v_mfma_scale_f32_16x16x128_f8f6f4 v[46:49], v[18:25], v[218:225], v[46:49], v1, v182 op_sel_hi:[0,0,0]
	v_mfma_scale_f32_16x16x128_f8f6f4 v[42:45], v[26:33], v[218:225], v[42:45], v1, v182 op_sel_hi:[0,0,0]
	s_setprio 0
	s_setprio 1
	v_mfma_scale_f32_16x16x128_f8f6f4 v[86:89], v[2:9], v[194:201], v[86:89], v1, v182 op_sel_hi:[0,0,0]
	v_mfma_scale_f32_16x16x128_f8f6f4 v[82:85], v[10:17], v[194:201], v[82:85], v1, v182 op_sel_hi:[0,0,0]
	v_mfma_scale_f32_16x16x128_f8f6f4 v[70:73], v[2:9], v[202:209], v[70:73], v1, v182 op_sel_hi:[0,0,0]
	v_mfma_scale_f32_16x16x128_f8f6f4 v[66:69], v[10:17], v[202:209], v[66:69], v1, v182 op_sel_hi:[0,0,0]
	v_mfma_scale_f32_16x16x128_f8f6f4 v[54:57], v[2:9], v[210:217], v[54:57], v1, v182 op_sel_hi:[0,0,0]
	v_mfma_scale_f32_16x16x128_f8f6f4 v[50:53], v[10:17], v[210:217], v[50:53], v1, v182 op_sel_hi:[0,0,0]
	v_mfma_scale_f32_16x16x128_f8f6f4 v[38:41], v[2:9], v[218:225], v[38:41], v1, v182 op_sel_hi:[0,0,0]
	v_mfma_scale_f32_16x16x128_f8f6f4 v[34:37], v[10:17], v[218:225], v[34:37], v1, v182 op_sel_hi:[0,0,0]
	s_setprio 0
	s_barrier
; #define PG8_STAGE(bufoff, gbase, voff) do { _Pragma("unroll") for (int _i = 0; _i < 2; ++_i) \
;         __builtin_amdgcn_global_load_lds((const unsigned*)((const char*)(gbase) + (voff)[_i]), (PG8_LAS unsigned*)(lds + (bufoff) + ldsw + _i * 8192), 16, 0, 0); } while (0)
; #define PG8_LDA(dst, b, h) do { _Pragma("unroll") for (int m = 0; m < 4; ++m) _Pragma("unroll") for (int k = 0; k < 2; ++k) dst[m][k] = *(const PG8_LAS bf16x8*)(lds + PG8_SA(b, h) + aoff + m * 2048 + k * 1024); } while (0)
; #define PG8_LDB(dst, b, h) do { _Pragma("unroll") for (int n = 0; n < 2; ++n) _Pragma("unroll") for (int k = 0; k < 2; ++k) dst[n][k] = *(const PG8_LAS bf16x8*)(lds + PG8_SB(b, h) + boff + n * 2048 + k * 1024); } while (0)
; #define PG8_MMA(ai, bj, At, Bt) do { __builtin_amdgcn_s_setprio(1); _Pragma("unroll") for (int m = 0; m < 4; ++m) _Pragma("unroll") for (int n = 0; n < 2; ++n) _Pragma("unroll") for (int k = 0; k < 2; ++k) \
;         acc[ai][bj][m][n] = __builtin_amdgcn_mfma_f32_16x16x32_bf16(Bt[n][k], At[m][k], acc[ai][bj][m][n], 0, 0, 0); __builtin_amdgcn_s_setprio(0); } while (0)
; #define PG8_WAIT_V(n) asm volatile("s_waitcnt vmcnt(" #n ")" ::: "memory")
; #define PG8_WAIT_L(n) asm volatile("s_waitcnt lgkmcnt(" #n ")" ::: "memory")
; #define PG8_BAR __builtin_amdgcn_s_barrier()
; #define PG8_SCHED __builtin_amdgcn_sched_barrier(0)
; #define PG8_STAGE(bufoff, gbase, voff) do { _Pragma("unroll") for (int _i = 0; _i < 2; ++_i) \
;         __builtin_amdgcn_global_load_lds((const unsigned*)((const char*)(gbase) + (voff)[_i]), (PG8_LAS unsigned*)(lds + (bufoff) + ldsw + _i * 8192), 16, 0, 0); } while (0)
; #define PG8_WAIT_V(n) asm volatile("s_waitcnt vmcnt(" #n ")" ::: "memory")
; template <class Epi, class Sched, bool ALIGN_EPI = false>
; __device__ __forceinline__ void gemm_phase8(PG8_LAS unsigned char* lds, const Gemm g, const Sched& S, const Epi& E) {
;     ...
;             PG8_LDB(B0, 1, 0); PG8_LDB(B1, 1, 1); PG8_SCHED; PG8_LDA(At, 1, 0); PG8_STAGE(PG8_SA(0, 1), a2 + hstepA, voffA);
;             PG8_WAIT_V(8); PG8_WAIT_L(0); PG8_BAR; PG8_MMA(0, 0, At, B0); PG8_MMA(0, 1, At, B1); PG8_BAR; PG8_SCHED;
;             PG8_LDA(At, 1, 1); PG8_STAGE(PG8_SB(1, 0), b3, voffB); PG8_STAGE(PG8_SB(1, 1), b3 + hstepB, voffB); PG8_STAGE(PG8_SA(1, 0), a3, voffA);
;             PG8_WAIT_V(8); PG8_WAIT_L(0); PG8_BAR; PG8_MMA(1, 0, At, B0); PG8_MMA(1, 1, At, B1); PG8_BAR; PG8_SCHED;
	s_add_i32 s85, 0, 0x18000
	s_add_i32 s88, 0, 0x1c000
	v_add_u32_e32 v6, s85, v184
	v_add_u32_e32 v14, s85, v185
	v_add_u32_e32 v22, s88, v184
	v_add_u32_e32 v30, s88, v185
	ds_read_b128 v[2:5], v6
	ds_read_b128 v[10:13], v6 offset:2048
	ds_read_b128 v[6:9], v14
	ds_read_b128 v[14:17], v14 offset:2048
	ds_read_b128 v[18:21], v22
	ds_read_b128 v[26:29], v22 offset:2048
	ds_read_b128 v[22:25], v30
	ds_read_b128 v[30:33], v30 offset:2048
	s_add_u32 s34, s34, 0xb0000
	s_addc_u32 s35, s35, 0
	s_mov_b32 m0, s56
	ds_read_b128 v[194:197], v191 offset:32768
	ds_read_b128 v[202:205], v191 offset:34816
	ds_read_b128 v[198:201], v192 offset:32768
	ds_read_b128 v[206:209], v192 offset:34816
	ds_read_b128 v[210:213], v191 offset:36864
	ds_read_b128 v[218:221], v191 offset:38912
	ds_read_b128 v[214:217], v192 offset:36864
	ds_read_b128 v[222:225], v192 offset:38912
	global_load_lds_dwordx4 v162, s[34:35]
	s_mov_b32 m0, s57
	s_nop 0
	global_load_lds_dwordx4 v166, s[34:35]
	s_waitcnt vmcnt(8)
	s_waitcnt lgkmcnt(0)
	s_barrier
	s_setprio 1
	s_waitcnt lgkmcnt(0)
	v_mfma_scale_f32_16x16x128_f8f6f4 v[158:161], v[2:9], v[194:201], v[158:161], v1, v182 op_sel_hi:[0,0,0]
	v_mfma_scale_f32_16x16x128_f8f6f4 v[154:157], v[10:17], v[194:201], v[154:157], v1, v182 op_sel_hi:[0,0,0]
	v_mfma_scale_f32_16x16x128_f8f6f4 v[142:145], v[2:9], v[202:209], v[142:145], v1, v182 op_sel_hi:[0,0,0]
	v_mfma_scale_f32_16x16x128_f8f6f4 v[138:141], v[10:17], v[202:209], v[138:141], v1, v182 op_sel_hi:[0,0,0]
	v_mfma_scale_f32_16x16x128_f8f6f4 v[126:129], v[2:9], v[210:217], v[126:129], v1, v182 op_sel_hi:[0,0,0]
	v_mfma_scale_f32_16x16x128_f8f6f4 v[122:125], v[10:17], v[210:217], v[122:125], v1, v182 op_sel_hi:[0,0,0]
	v_mfma_scale_f32_16x16x128_f8f6f4 v[110:113], v[2:9], v[218:225], v[110:113], v1, v182 op_sel_hi:[0,0,0]
	v_mfma_scale_f32_16x16x128_f8f6f4 v[106:109], v[10:17], v[218:225], v[106:109], v1, v182 op_sel_hi:[0,0,0]
	s_setprio 0
	s_setprio 1
	v_mfma_scale_f32_16x16x128_f8f6f4 v[150:153], v[18:25], v[194:201], v[150:153], v1, v182 op_sel_hi:[0,0,0]
	v_mfma_scale_f32_16x16x128_f8f6f4 v[146:149], v[26:33], v[194:201], v[146:149], v1, v182 op_sel_hi:[0,0,0]
	v_mfma_scale_f32_16x16x128_f8f6f4 v[134:137], v[18:25], v[202:209], v[134:137], v1, v182 op_sel_hi:[0,0,0]
	v_mfma_scale_f32_16x16x128_f8f6f4 v[130:133], v[26:33], v[202:209], v[130:133], v1, v182 op_sel_hi:[0,0,0]
	v_mfma_scale_f32_16x16x128_f8f6f4 v[118:121], v[18:25], v[210:217], v[118:121], v1, v182 op_sel_hi:[0,0,0]
	v_mfma_scale_f32_16x16x128_f8f6f4 v[114:117], v[26:33], v[210:217], v[114:117], v1, v182 op_sel_hi:[0,0,0]
	v_mfma_scale_f32_16x16x128_f8f6f4 v[102:105], v[18:25], v[218:225], v[102:105], v1, v182 op_sel_hi:[0,0,0]
	v_mfma_scale_f32_16x16x128_f8f6f4 v[98:101], v[26:33], v[218:225], v[98:101], v1, v182 op_sel_hi:[0,0,0]
	s_setprio 0
	s_barrier
	s_add_i32 s101, s85, s53
	s_add_u32 s98, s30, s12
	s_addc_u32 s99, s31, s13
	s_mov_b32 m0, s101
	ds_read_b128 v[194:197], v191 offset:49152
	ds_read_b128 v[202:205], v191 offset:51200
	ds_read_b128 v[198:201], v192 offset:49152
	ds_read_b128 v[206:209], v192 offset:51200
	ds_read_b128 v[210:213], v191 offset:53248
	ds_read_b128 v[218:221], v191 offset:55296
	ds_read_b128 v[214:217], v192 offset:53248
	ds_read_b128 v[222:225], v192 offset:55296
	global_load_lds_dwordx4 v164, s[98:99]
	s_add_i32 m0, s101, 0x2000
	s_add_u32 s30, s30, 0xb0080
	s_addc_u32 s31, s31, 0
	s_add_i32 s101, s88, s53
	global_load_lds_dwordx4 v168, s[98:99]
	s_add_u32 s98, s34, s12
	s_addc_u32 s99, s35, s13
	s_sub_u32 s98, s98, 0xb0000
	s_subb_u32 s99, s99, 0
	s_mov_b32 m0, s101
	s_nop 0
	global_load_lds_dwordx4 v164, s[30:31]
	s_add_i32 m0, s101, 0x2000
	s_nop 0
	global_load_lds_dwordx4 v168, s[30:31]
	s_mov_b32 m0, s63
	s_nop 0
	global_load_lds_dwordx4 v162, s[98:99]
	s_mov_b32 m0, s64
	s_nop 0
	global_load_lds_dwordx4 v166, s[98:99]
	s_waitcnt vmcnt(8)
	s_waitcnt lgkmcnt(0)
	s_barrier
	s_setprio 1
	s_waitcnt lgkmcnt(0)
	v_mfma_scale_f32_16x16x128_f8f6f4 v[94:97], v[2:9], v[194:201], v[94:97], v1, v182 op_sel_hi:[0,0,0]
	v_mfma_scale_f32_16x16x128_f8f6f4 v[90:93], v[10:17], v[194:201], v[90:93], v1, v182 op_sel_hi:[0,0,0]
	v_mfma_scale_f32_16x16x128_f8f6f4 v[78:81], v[2:9], v[202:209], v[78:81], v1, v182 op_sel_hi:[0,0,0]
	v_mfma_scale_f32_16x16x128_f8f6f4 v[74:77], v[10:17], v[202:209], v[74:77], v1, v182 op_sel_hi:[0,0,0]
	v_mfma_scale_f32_16x16x128_f8f6f4 v[62:65], v[2:9], v[210:217], v[62:65], v1, v182 op_sel_hi:[0,0,0]
	v_mfma_scale_f32_16x16x128_f8f6f4 v[58:61], v[10:17], v[210:217], v[58:61], v1, v182 op_sel_hi:[0,0,0]
	v_mfma_scale_f32_16x16x128_f8f6f4 v[46:49], v[2:9], v[218:225], v[46:49], v1, v182 op_sel_hi:[0,0,0]
	v_mfma_scale_f32_16x16x128_f8f6f4 v[42:45], v[10:17], v[218:225], v[42:45], v1, v182 op_sel_hi:[0,0,0]
	s_setprio 0
	s_setprio 1
	v_mfma_scale_f32_16x16x128_f8f6f4 v[86:89], v[18:25], v[194:201], v[86:89], v1, v182 op_sel_hi:[0,0,0]
	v_mfma_scale_f32_16x16x128_f8f6f4 v[82:85], v[26:33], v[194:201], v[82:85], v1, v182 op_sel_hi:[0,0,0]
	v_mfma_scale_f32_16x16x128_f8f6f4 v[70:73], v[18:25], v[202:209], v[70:73], v1, v182 op_sel_hi:[0,0,0]
	v_mfma_scale_f32_16x16x128_f8f6f4 v[66:69], v[26:33], v[202:209], v[66:69], v1, v182 op_sel_hi:[0,0,0]
	v_mfma_scale_f32_16x16x128_f8f6f4 v[54:57], v[18:25], v[210:217], v[54:57], v1, v182 op_sel_hi:[0,0,0]
	v_mfma_scale_f32_16x16x128_f8f6f4 v[50:53], v[26:33], v[210:217], v[50:53], v1, v182 op_sel_hi:[0,0,0]
	v_mfma_scale_f32_16x16x128_f8f6f4 v[38:41], v[18:25], v[218:225], v[38:41], v1, v182 op_sel_hi:[0,0,0]
	v_mfma_scale_f32_16x16x128_f8f6f4 v[34:37], v[26:33], v[218:225], v[34:37], v1, v182 op_sel_hi:[0,0,0]
	s_setprio 0
	s_barrier
; #define PG8_STAGE(bufoff, gbase, voff) do { _Pragma("unroll") for (int _i = 0; _i < 2; ++_i) \
;         __builtin_amdgcn_global_load_lds((const unsigned*)((const char*)(gbase) + (voff)[_i]), (PG8_LAS unsigned*)(lds + (bufoff) + ldsw + _i * 8192), 16, 0, 0); } while (0)
; #define PG8_LDA(dst, b, h) do { _Pragma("unroll") for (int m = 0; m < 4; ++m) _Pragma("unroll") for (int k = 0; k < 2; ++k) dst[m][k] = *(const PG8_LAS bf16x8*)(lds + PG8_SA(b, h) + aoff + m * 2048 + k * 1024); } while (0)
; #define PG8_LDB(dst, b, h) do { _Pragma("unroll") for (int n = 0; n < 2; ++n) _Pragma("unroll") for (int k = 0; k < 2; ++k) dst[n][k] = *(const PG8_LAS bf16x8*)(lds + PG8_SB(b, h) + boff + n * 2048 + k * 1024); } while (0)
; #define PG8_BAR __builtin_amdgcn_s_barrier()
; template <class Epi, class Sched, bool ALIGN_EPI = false>
; __device__ __forceinline__ void gemm_phase8(PG8_LAS unsigned char* lds, const Gemm g, const Sched& S, const Epi& E) {
;     ...
;         for (int t = 0; t < nt; t += 2) {
;             const bool last = (t == nt - 2);
;             const char* a1 = cA + (size_t)(t + 1) * kstep;
;             const char* a2 = last ? nA : cA + (size_t)(t + 2) * kstep; const char* b2 = last ? nB : cB + (size_t)(t + 2) * kstep;
;             const char* a3 = a2 + kstep; const char* b3 = b2 + kstep;
;             if (last && has_next) S.a_ready(nxt);
;             PG8_LDB(B0, 0, 0); PG8_LDB(B1, 0, 1); PG8_SCHED; PG8_LDA(At, 0, 0); PG8_STAGE(PG8_SA(1, 1), a1 + hstepA, voffA);
;             PG8_WAIT_V(8); PG8_WAIT_L(0); PG8_BAR; PG8_MMA(0, 0, At, B0); PG8_MMA(0, 1, At, B1); PG8_BAR; PG8_SCHED;
;             PG8_LDA(At, 0, 1); PG8_STAGE(PG8_SB(0, 0), b2, voffB); PG8_STAGE(PG8_SB(0, 1), b2 + hstepB, voffB); PG8_STAGE(PG8_SA(0, 0), a2, voffA);
;             PG8_WAIT_V(8); PG8_WAIT_L(0); PG8_BAR; PG8_MMA(1, 0, At, B0); PG8_MMA(1, 1, At, B1); PG8_BAR; PG8_SCHED;
;             PG8_LDB(B0, 1, 0); PG8_LDB(B1, 1, 1); PG8_SCHED; PG8_LDA(At, 1, 0); PG8_STAGE(PG8_SA(0, 1), a2 + hstepA, voffA);
;             PG8_WAIT_V(8); PG8_WAIT_L(0); PG8_BAR; PG8_MMA(0, 0, At, B0); PG8_MMA(0, 1, At, B1); PG8_BAR; PG8_SCHED;
;             PG8_LDA(At, 1, 1); PG8_STAGE(PG8_SB(1, 0), b3, voffB); PG8_STAGE(PG8_SB(1, 1), b3 + hstepB, voffB); PG8_STAGE(PG8_SA(1, 0), a3, voffA);
;             PG8_WAIT_V(8); PG8_WAIT_L(0); PG8_BAR; PG8_MMA(1, 0, At, B0); PG8_MMA(1, 1, At, B1); PG8_BAR; PG8_SCHED;
	s_add_u32 s28, s28, 0x100
	s_addc_u32 s29, s29, 0
	s_add_u32 s82, s82, 0x100
	s_addc_u32 s83, s83, 0
	s_cmp_ge_u32 s84, s25
	s_mov_b32 s34, s84
	ds_read_b128 v[18:21], v187
	ds_read_b128 v[26:29], v187 offset:2048
	ds_read_b128 v[22:25], v188
	ds_read_b128 v[30:33], v188 offset:2048
	ds_read_b128 v[2:5], v189
	ds_read_b128 v[10:13], v189 offset:2048
	ds_read_b128 v[6:9], v190
	ds_read_b128 v[14:17], v190 offset:2048
	s_add_i32 s84, s34, 2
	s_add_u32 s30, s28, 0xfff50080
	s_addc_u32 s31, s29, -1
	s_cmp_eq_u32 s81, s34
	s_cselect_b32 s34, s20, s30
	s_cselect_b32 s35, s21, s31
	s_cselect_b32 s31, s23, s83
	s_cselect_b32 s30, s22, s82
	s_add_i32 m0, s54, 0xc000
	ds_read_b128 v[174:177], v191
	ds_read_b128 v[194:197], v191 offset:2048
	ds_read_b128 v[178:181], v192
	ds_read_b128 v[198:201], v192 offset:2048
	ds_read_b128 v[202:205], v191 offset:4096
	ds_read_b128 v[210:213], v191 offset:6144
	ds_read_b128 v[206:209], v192 offset:4096
	ds_read_b128 v[214:217], v192 offset:6144
	global_load_lds_dwordx4 v170, s[28:29]
	s_add_i32 m0, s54, 0xe000
	s_nop 0
	global_load_lds_dwordx4 v172, s[28:29]
	s_waitcnt vmcnt(8)
	s_waitcnt lgkmcnt(0)
	s_barrier
	s_setprio 1
	s_waitcnt lgkmcnt(0)
	v_mfma_scale_f32_16x16x128_f8f6f4 v[158:161], v[18:25], v[174:181], v[158:161], v1, v182 op_sel_hi:[0,0,0]
	v_mfma_scale_f32_16x16x128_f8f6f4 v[154:157], v[26:33], v[174:181], v[154:157], v1, v182 op_sel_hi:[0,0,0]
	v_mfma_scale_f32_16x16x128_f8f6f4 v[142:145], v[18:25], v[194:201], v[142:145], v1, v182 op_sel_hi:[0,0,0]
	v_mfma_scale_f32_16x16x128_f8f6f4 v[138:141], v[26:33], v[194:201], v[138:141], v1, v182 op_sel_hi:[0,0,0]
	v_mfma_scale_f32_16x16x128_f8f6f4 v[126:129], v[18:25], v[202:209], v[126:129], v1, v182 op_sel_hi:[0,0,0]
	v_mfma_scale_f32_16x16x128_f8f6f4 v[122:125], v[26:33], v[202:209], v[122:125], v1, v182 op_sel_hi:[0,0,0]
	v_mfma_scale_f32_16x16x128_f8f6f4 v[110:113], v[18:25], v[210:217], v[110:113], v1, v182 op_sel_hi:[0,0,0]
	v_mfma_scale_f32_16x16x128_f8f6f4 v[106:109], v[26:33], v[210:217], v[106:109], v1, v182 op_sel_hi:[0,0,0]
	s_setprio 0
	s_setprio 1
	v_mfma_scale_f32_16x16x128_f8f6f4 v[150:153], v[2:9], v[174:181], v[150:153], v1, v182 op_sel_hi:[0,0,0]
	v_mfma_scale_f32_16x16x128_f8f6f4 v[146:149], v[10:17], v[174:181], v[146:149], v1, v182 op_sel_hi:[0,0,0]
	v_mfma_scale_f32_16x16x128_f8f6f4 v[134:137], v[2:9], v[194:201], v[134:137], v1, v182 op_sel_hi:[0,0,0]
	v_mfma_scale_f32_16x16x128_f8f6f4 v[130:133], v[10:17], v[194:201], v[130:133], v1, v182 op_sel_hi:[0,0,0]
	v_mfma_scale_f32_16x16x128_f8f6f4 v[118:121], v[2:9], v[202:209], v[118:121], v1, v182 op_sel_hi:[0,0,0]
	v_mfma_scale_f32_16x16x128_f8f6f4 v[114:117], v[10:17], v[202:209], v[114:117], v1, v182 op_sel_hi:[0,0,0]
	v_mfma_scale_f32_16x16x128_f8f6f4 v[102:105], v[2:9], v[210:217], v[102:105], v1, v182 op_sel_hi:[0,0,0]
	v_mfma_scale_f32_16x16x128_f8f6f4 v[98:101], v[10:17], v[210:217], v[98:101], v1, v182 op_sel_hi:[0,0,0]
	s_setprio 0
	s_barrier
	s_add_i32 s85, s65, s53
	s_mov_b32 m0, s85
	ds_read_b128 v[194:197], v191 offset:16384
	ds_read_b128 v[202:205], v191 offset:18432
	ds_read_b128 v[198:201], v192 offset:16384
	ds_read_b128 v[206:209], v192 offset:18432
	ds_read_b128 v[210:213], v191 offset:20480
	ds_read_b128 v[218:221], v191 offset:22528
	ds_read_b128 v[214:217], v192 offset:20480
	ds_read_b128 v[222:225], v192 offset:22528
	global_load_lds_dwordx4 v164, s[30:31]
	s_add_i32 m0, s85, 0x2000
	s_add_u32 s88, s30, 0xb0000
	s_addc_u32 s89, s31, 0
	s_add_i32 s85, s66, s53
	global_load_lds_dwordx4 v168, s[30:31]
	s_mov_b32 m0, s85
	s_nop 0
	global_load_lds_dwordx4 v164, s[88:89]
	s_add_i32 m0, s85, 0x2000
	s_nop 0
	global_load_lds_dwordx4 v168, s[88:89]
	s_mov_b32 m0, s54
	s_nop 0
	global_load_lds_dwordx4 v162, s[34:35]
	s_mov_b32 m0, s55
	s_nop 0
	global_load_lds_dwordx4 v166, s[34:35]
	s_waitcnt vmcnt(8)
	s_waitcnt lgkmcnt(0)
	s_barrier
	s_setprio 1
	s_waitcnt lgkmcnt(0)
	v_mfma_scale_f32_16x16x128_f8f6f4 v[94:97], v[18:25], v[194:201], v[94:97], v1, v182 op_sel_hi:[0,0,0]
	v_mfma_scale_f32_16x16x128_f8f6f4 v[90:93], v[26:33], v[194:201], v[90:93], v1, v182 op_sel_hi:[0,0,0]
	v_mfma_scale_f32_16x16x128_f8f6f4 v[78:81], v[18:25], v[202:209], v[78:81], v1, v182 op_sel_hi:[0,0,0]
	v_mfma_scale_f32_16x16x128_f8f6f4 v[74:77], v[26:33], v[202:209], v[74:77], v1, v182 op_sel_hi:[0,0,0]
	v_mfma_scale_f32_16x16x128_f8f6f4 v[62:65], v[18:25], v[210:217], v[62:65], v1, v182 op_sel_hi:[0,0,0]
	v_mfma_scale_f32_16x16x128_f8f6f4 v[58:61], v[26:33], v[210:217], v[58:61], v1, v182 op_sel_hi:[0,0,0]
	v_mfma_scale_f32_16x16x128_f8f6f4 v[46:49], v[18:25], v[218:225], v[46:49], v1, v182 op_sel_hi:[0,0,0]
	v_mfma_scale_f32_16x16x128_f8f6f4 v[42:45], v[26:33], v[218:225], v[42:45], v1, v182 op_sel_hi:[0,0,0]
	s_setprio 0
	s_setprio 1
	v_mfma_scale_f32_16x16x128_f8f6f4 v[86:89], v[2:9], v[194:201], v[86:89], v1, v182 op_sel_hi:[0,0,0]
	v_mfma_scale_f32_16x16x128_f8f6f4 v[82:85], v[10:17], v[194:201], v[82:85], v1, v182 op_sel_hi:[0,0,0]
	v_mfma_scale_f32_16x16x128_f8f6f4 v[70:73], v[2:9], v[202:209], v[70:73], v1, v182 op_sel_hi:[0,0,0]
	v_mfma_scale_f32_16x16x128_f8f6f4 v[66:69], v[10:17], v[202:209], v[66:69], v1, v182 op_sel_hi:[0,0,0]
	v_mfma_scale_f32_16x16x128_f8f6f4 v[54:57], v[2:9], v[210:217], v[54:57], v1, v182 op_sel_hi:[0,0,0]
	v_mfma_scale_f32_16x16x128_f8f6f4 v[50:53], v[10:17], v[210:217], v[50:53], v1, v182 op_sel_hi:[0,0,0]
	v_mfma_scale_f32_16x16x128_f8f6f4 v[38:41], v[2:9], v[218:225], v[38:41], v1, v182 op_sel_hi:[0,0,0]
	v_mfma_scale_f32_16x16x128_f8f6f4 v[34:37], v[10:17], v[218:225], v[34:37], v1, v182 op_sel_hi:[0,0,0]
	s_setprio 0
	s_barrier
; #define PG8_STAGE(bufoff, gbase, voff) do { _Pragma("unroll") for (int _i = 0; _i < 2; ++_i) \
;         __builtin_amdgcn_global_load_lds((const unsigned*)((const char*)(gbase) + (voff)[_i]), (PG8_LAS unsigned*)(lds + (bufoff) + ldsw + _i * 8192), 16, 0, 0); } while (0)
; #define PG8_LDA(dst, b, h) do { _Pragma("unroll") for (int m = 0; m < 4; ++m) _Pragma("unroll") for (int k = 0; k < 2; ++k) dst[m][k] = *(const PG8_LAS bf16x8*)(lds + PG8_SA(b, h) + aoff + m * 2048 + k * 1024); } while (0)
; #define PG8_LDB(dst, b, h) do { _Pragma("unroll") for (int n = 0; n < 2; ++n) _Pragma("unroll") for (int k = 0; k < 2; ++k) dst[n][k] = *(const PG8_LAS bf16x8*)(lds + PG8_SB(b, h) + boff + n * 2048 + k * 1024); } while (0)
; #define PG8_MMA(ai, bj, At, Bt) do { __builtin_amdgcn_s_setprio(1); _Pragma("unroll") for (int m = 0; m < 4; ++m) _Pragma("unroll") for (int n = 0; n < 2; ++n) _Pragma("unroll") for (int k = 0; k < 2; ++k) \
;         acc[ai][bj][m][n] = __builtin_amdgcn_mfma_f32_16x16x32_bf16(Bt[n][k], At[m][k], acc[ai][bj][m][n], 0, 0, 0); __builtin_amdgcn_s_setprio(0); } while (0)
; #define PG8_WAIT_V(n) asm volatile("s_waitcnt vmcnt(" #n ")" ::: "memory")
; #define PG8_WAIT_L(n) asm volatile("s_waitcnt lgkmcnt(" #n ")" ::: "memory")
; #define PG8_BAR __builtin_amdgcn_s_barrier()
; #define PG8_SCHED __builtin_amdgcn_sched_barrier(0)
; #define PG8_STAGE(bufoff, gbase, voff) do { _Pragma("unroll") for (int _i = 0; _i < 2; ++_i) \
;         __builtin_amdgcn_global_load_lds((const unsigned*)((const char*)(gbase) + (voff)[_i]), (PG8_LAS unsigned*)(lds + (bufoff) + ldsw + _i * 8192), 16, 0, 0); } while (0)
; #define PG8_BAR __builtin_amdgcn_s_barrier()
; template <class Epi, class Sched, bool ALIGN_EPI = false>
; __device__ __forceinline__ void gemm_phase8(PG8_LAS unsigned char* lds, const Gemm g, const Sched& S, const Epi& E) {
;     ...
;             PG8_LDB(B0, 1, 0); PG8_LDB(B1, 1, 1); PG8_SCHED; PG8_LDA(At, 1, 0); PG8_STAGE(PG8_SA(0, 1), a2 + hstepA, voffA);
;             PG8_WAIT_V(8); PG8_WAIT_L(0); PG8_BAR; PG8_MMA(0, 0, At, B0); PG8_MMA(0, 1, At, B1); PG8_BAR; PG8_SCHED;
;             PG8_LDA(At, 1, 1); PG8_STAGE(PG8_SB(1, 0), b3, voffB); PG8_STAGE(PG8_SB(1, 1), b3 + hstepB, voffB); PG8_STAGE(PG8_SA(1, 0), a3, voffA);
;             PG8_WAIT_V(8); PG8_WAIT_L(0); PG8_BAR; PG8_MMA(1, 0, At, B0); PG8_MMA(1, 1, At, B1); PG8_BAR; PG8_SCHED;
;         }
	s_add_i32 s85, 0, 0x18000
	s_add_i32 s88, 0, 0x1c000
	v_add_u32_e32 v6, s85, v184
	v_add_u32_e32 v14, s85, v185
	v_add_u32_e32 v22, s88, v184
	v_add_u32_e32 v30, s88, v185
	ds_read_b128 v[2:5], v6
	ds_read_b128 v[10:13], v6 offset:2048
	ds_read_b128 v[6:9], v14
	ds_read_b128 v[14:17], v14 offset:2048
	ds_read_b128 v[18:21], v22
	ds_read_b128 v[26:29], v22 offset:2048
	ds_read_b128 v[22:25], v30
	ds_read_b128 v[30:33], v30 offset:2048
	s_add_u32 s34, s34, 0xb0000
	s_addc_u32 s35, s35, 0
	s_mov_b32 m0, s56
	ds_read_b128 v[194:197], v191 offset:32768
	ds_read_b128 v[202:205], v191 offset:34816
	ds_read_b128 v[198:201], v192 offset:32768
	ds_read_b128 v[206:209], v192 offset:34816
	ds_read_b128 v[210:213], v191 offset:36864
	ds_read_b128 v[218:221], v191 offset:38912
	ds_read_b128 v[214:217], v192 offset:36864
	ds_read_b128 v[222:225], v192 offset:38912
	global_load_lds_dwordx4 v162, s[34:35]
	s_mov_b32 m0, s57
	s_nop 0
	global_load_lds_dwordx4 v166, s[34:35]
	s_waitcnt vmcnt(8)
	s_waitcnt lgkmcnt(0)
	s_barrier
	s_setprio 1
	s_waitcnt lgkmcnt(0)
	v_mfma_scale_f32_16x16x128_f8f6f4 v[158:161], v[2:9], v[194:201], v[158:161], v1, v182 op_sel_hi:[0,0,0]
	v_mfma_scale_f32_16x16x128_f8f6f4 v[154:157], v[10:17], v[194:201], v[154:157], v1, v182 op_sel_hi:[0,0,0]
	v_mfma_scale_f32_16x16x128_f8f6f4 v[142:145], v[2:9], v[202:209], v[142:145], v1, v182 op_sel_hi:[0,0,0]
	v_mfma_scale_f32_16x16x128_f8f6f4 v[138:141], v[10:17], v[202:209], v[138:141], v1, v182 op_sel_hi:[0,0,0]
	v_mfma_scale_f32_16x16x128_f8f6f4 v[126:129], v[2:9], v[210:217], v[126:129], v1, v182 op_sel_hi:[0,0,0]
	v_mfma_scale_f32_16x16x128_f8f6f4 v[122:125], v[10:17], v[210:217], v[122:125], v1, v182 op_sel_hi:[0,0,0]
	v_mfma_scale_f32_16x16x128_f8f6f4 v[110:113], v[2:9], v[218:225], v[110:113], v1, v182 op_sel_hi:[0,0,0]
	v_mfma_scale_f32_16x16x128_f8f6f4 v[106:109], v[10:17], v[218:225], v[106:109], v1, v182 op_sel_hi:[0,0,0]
	s_setprio 0
	s_setprio 1
	v_mfma_scale_f32_16x16x128_f8f6f4 v[150:153], v[18:25], v[194:201], v[150:153], v1, v182 op_sel_hi:[0,0,0]
	v_mfma_scale_f32_16x16x128_f8f6f4 v[146:149], v[26:33], v[194:201], v[146:149], v1, v182 op_sel_hi:[0,0,0]
	v_mfma_scale_f32_16x16x128_f8f6f4 v[134:137], v[18:25], v[202:209], v[134:137], v1, v182 op_sel_hi:[0,0,0]
	v_mfma_scale_f32_16x16x128_f8f6f4 v[130:133], v[26:33], v[202:209], v[130:133], v1, v182 op_sel_hi:[0,0,0]
	v_mfma_scale_f32_16x16x128_f8f6f4 v[118:121], v[18:25], v[210:217], v[118:121], v1, v182 op_sel_hi:[0,0,0]
	v_mfma_scale_f32_16x16x128_f8f6f4 v[114:117], v[26:33], v[210:217], v[114:117], v1, v182 op_sel_hi:[0,0,0]
	v_mfma_scale_f32_16x16x128_f8f6f4 v[102:105], v[18:25], v[218:225], v[102:105], v1, v182 op_sel_hi:[0,0,0]
	v_mfma_scale_f32_16x16x128_f8f6f4 v[98:101], v[26:33], v[218:225], v[98:101], v1, v182 op_sel_hi:[0,0,0]
	s_setprio 0
	s_barrier
	s_add_i32 s101, s85, s53
	s_add_u32 s98, s30, s12
	s_addc_u32 s99, s31, s13
	s_mov_b32 m0, s101
	ds_read_b128 v[194:197], v191 offset:49152
	ds_read_b128 v[202:205], v191 offset:51200
	ds_read_b128 v[198:201], v192 offset:49152
	ds_read_b128 v[206:209], v192 offset:51200
	ds_read_b128 v[210:213], v191 offset:53248
	ds_read_b128 v[218:221], v191 offset:55296
	ds_read_b128 v[214:217], v192 offset:53248
	ds_read_b128 v[222:225], v192 offset:55296
	global_load_lds_dwordx4 v164, s[98:99]
	s_add_i32 m0, s101, 0x2000
	s_add_u32 s30, s30, 0xb0080
	s_addc_u32 s31, s31, 0
	s_add_i32 s101, s88, s53
	global_load_lds_dwordx4 v168, s[98:99]
	s_add_u32 s98, s34, s12
	s_addc_u32 s99, s35, s13
	s_sub_u32 s98, s98, 0xb0000
	s_subb_u32 s99, s99, 0
	s_mov_b32 m0, s101
	s_nop 0
	global_load_lds_dwordx4 v164, s[30:31]
	s_add_i32 m0, s101, 0x2000
	s_nop 0
	global_load_lds_dwordx4 v168, s[30:31]
	s_mov_b32 m0, s63
	s_nop 0
	global_load_lds_dwordx4 v162, s[98:99]
	s_mov_b32 m0, s64
	s_nop 0
	global_load_lds_dwordx4 v166, s[98:99]
	s_waitcnt vmcnt(8)
	s_waitcnt lgkmcnt(0)
	s_barrier
	s_setprio 1
	s_waitcnt lgkmcnt(0)
	v_mfma_scale_f32_16x16x128_f8f6f4 v[94:97], v[2:9], v[194:201], v[94:97], v1, v182 op_sel_hi:[0,0,0]
	v_mfma_scale_f32_16x16x128_f8f6f4 v[90:93], v[10:17], v[194:201], v[90:93], v1, v182 op_sel_hi:[0,0,0]
	v_mfma_scale_f32_16x16x128_f8f6f4 v[78:81], v[2:9], v[202:209], v[78:81], v1, v182 op_sel_hi:[0,0,0]
	v_mfma_scale_f32_16x16x128_f8f6f4 v[74:77], v[10:17], v[202:209], v[74:77], v1, v182 op_sel_hi:[0,0,0]
	v_mfma_scale_f32_16x16x128_f8f6f4 v[62:65], v[2:9], v[210:217], v[62:65], v1, v182 op_sel_hi:[0,0,0]
	v_mfma_scale_f32_16x16x128_f8f6f4 v[58:61], v[10:17], v[210:217], v[58:61], v1, v182 op_sel_hi:[0,0,0]
	v_mfma_scale_f32_16x16x128_f8f6f4 v[46:49], v[2:9], v[218:225], v[46:49], v1, v182 op_sel_hi:[0,0,0]
	v_mfma_scale_f32_16x16x128_f8f6f4 v[42:45], v[10:17], v[218:225], v[42:45], v1, v182 op_sel_hi:[0,0,0]
	s_setprio 0
	s_setprio 1
	v_mfma_scale_f32_16x16x128_f8f6f4 v[86:89], v[18:25], v[194:201], v[86:89], v1, v182 op_sel_hi:[0,0,0]
	v_mfma_scale_f32_16x16x128_f8f6f4 v[82:85], v[26:33], v[194:201], v[82:85], v1, v182 op_sel_hi:[0,0,0]
	v_mfma_scale_f32_16x16x128_f8f6f4 v[70:73], v[18:25], v[202:209], v[70:73], v1, v182 op_sel_hi:[0,0,0]
	v_mfma_scale_f32_16x16x128_f8f6f4 v[66:69], v[26:33], v[202:209], v[66:69], v1, v182 op_sel_hi:[0,0,0]
	v_mfma_scale_f32_16x16x128_f8f6f4 v[54:57], v[18:25], v[210:217], v[54:57], v1, v182 op_sel_hi:[0,0,0]
	v_mfma_scale_f32_16x16x128_f8f6f4 v[50:53], v[26:33], v[210:217], v[50:53], v1, v182 op_sel_hi:[0,0,0]
	v_mfma_scale_f32_16x16x128_f8f6f4 v[38:41], v[18:25], v[218:225], v[38:41], v1, v182 op_sel_hi:[0,0,0]
	v_mfma_scale_f32_16x16x128_f8f6f4 v[34:37], v[26:33], v[218:225], v[34:37], v1, v182 op_sel_hi:[0,0,0]
	s_setprio 0
	s_barrier
	s_add_u32 s28, s28, 0x100
	s_addc_u32 s29, s29, 0
	s_add_u32 s82, s82, 0x100
	s_addc_u32 s83, s83, 0
	s_cmp_ge_u32 s84, s25
	s_mov_b32 s34, s84
	s_cbranch_scc0 .LBB0_502
.Lpx_1:
	s_and_b64 vcc, exec, s[14:15]
	s_cbranch_vccz .LBB0_505
	s_barrier

; #define PG8_STAGE(bufoff, gbase, voff) do { _Pragma("unroll") for (int _i = 0; _i < 2; ++_i) \
;         __builtin_amdgcn_global_load_lds((const unsigned*)((const char*)(gbase) + (voff)[_i]), (PG8_LAS unsigned*)(lds + (bufoff) + ldsw + _i * 8192), 16, 0, 0); } while (0)
; #define PG8_LDA(dst, b, h) do { _Pragma("unroll") for (int m = 0; m < 4; ++m) _Pragma("unroll") for (int k = 0; k < 2; ++k) dst[m][k] = *(const PG8_LAS bf16x8*)(lds + PG8_SA(b, h) + aoff + m * 2048 + k * 1024); } while (0)
; #define PG8_LDB(dst, b, h) do { _Pragma("unroll") for (int n = 0; n < 2; ++n) _Pragma("unroll") for (int k = 0; k < 2; ++k) dst[n][k] = *(const PG8_LAS bf16x8*)(lds + PG8_SB(b, h) + boff + n * 2048 + k * 1024); } while (0)
; #define PG8_WAIT_V(n) asm volatile("s_waitcnt vmcnt(" #n ")" ::: "memory")
; #define PG8_WAIT_L(n) asm volatile("s_waitcnt lgkmcnt(" #n ")" ::: "memory")
; template <class Epi, class Sched, bool ALIGN_EPI = false>
; __device__ __forceinline__ void gemm_phase(PG8_LAS unsigned char* lds, const Gemm g, const Sched& S, const Epi& E) {
;     ...
;         const bool has_next = S.next(ui + 1, nxt);
;         const size_t nko = (has_next && nxt.kp > 0) ? (size_t)nxt.kp * g.kpiece * 2 : 0;
;         const char* nA = has_next ? (const char*)g.A + (size_t)nxt.pm * tstepA + (size_t)nxt.pn * astep + nko : cA; const char* nB = has_next ? (const char*)g.Bt + (size_t)nxt.pn * tstepB + nko : cB;
;         const int nt = (cur.kp < 0 ? g.K : g.kpiece) / BK;
;         for (int t = 0; t < nt; t += 2) {
;             const bool last = (t == nt - 2);
;             const char* a1 = cA + (size_t)(t + 1) * kstep;
;             const char* a2 = last ? nA : cA + (size_t)(t + 2) * kstep; const char* b2 = last ? nB : cB + (size_t)(t + 2) * kstep;
;             const char* a3 = a2 + kstep; const char* b3 = b2 + kstep;
;             if (last && has_next) S.a_ready(nxt);
;             PG8_LDB(B0, 0, 0); PG8_LDB(B1, 0, 1); PG8_SCHED; PG8_LDA(At, 0, 0); PG8_STAGE(PG8_SA(1, 1), a1 + hstepA, voffA);
;             PG8_WAIT_V(8); PG8_WAIT_L(0); PG8_BAR; PG8_MMA(0, 0, At, B0); PG8_MMA(0, 1, At, B1); PG8_BAR; PG8_SCHED;
;             PG8_LDA(At, 0, 1); PG8_STAGE(PG8_SB(0, 0), b2, voffB); PG8_STAGE(PG8_SB(0, 1), b2 + hstepB, voffB); PG8_STAGE(PG8_SA(0, 0), a2, voffA);
;             PG8_WAIT_V(8); PG8_WAIT_L(0); PG8_BAR; PG8_MMA(1, 0, At, B0); PG8_MMA(1, 1, At, B1); PG8_BAR; PG8_SCHED;
.LBB0_733:
	s_ashr_i32 s27, s26, 31
	s_lshl_b64 s[28:29], s[26:27], 20
	s_add_u32 s28, s56, s28
	s_addc_u32 s29, s57, s29
	s_and_b64 s[30:31], s[2:3], exec
	s_cselect_b32 s13, s29, s53
	s_cselect_b32 s27, s28, s52
	s_ashr_i32 s25, s24, 31
	s_lshl_b64 s[30:31], s[24:25], 20
	s_add_u32 s30, s4, s30
	s_addc_u32 s31, s5, s31
	s_and_b64 s[54:55], s[2:3], exec
	s_cselect_b32 s25, s31, s35
	s_cselect_b32 s82, s30, s34
	s_add_u32 s52, s52, 0x80080
	s_addc_u32 s53, s53, 0
	s_add_u32 s83, s34, 0x100
	s_addc_u32 s84, s35, 0
	s_mov_b32 s85, -2
	ds_read_b128 v[130:133], v165
	ds_read_b128 v[134:137], v165 offset:1024
	ds_read_b128 v[158:161], v165 offset:2048
	ds_read_b128 v[170:173], v165 offset:3072
	ds_read_b128 v[174:177], v166
	ds_read_b128 v[178:181], v166 offset:1024
	ds_read_b128 v[182:185], v166 offset:2048
	ds_read_b128 v[186:189], v166 offset:3072
	s_add_u32 s34, s52, 0xfff80080
	s_addc_u32 s35, s53, -1
	s_cmp_eq_u32 s85, 28
	s_cselect_b32 s55, s13, s35
	s_cselect_b32 s54, s27, s34
	s_cselect_b32 s35, s25, s84
	s_cselect_b32 s34, s82, s83
	s_add_i32 m0, s61, 0xc000
	ds_read_b128 v[190:193], v167
	ds_read_b128 v[194:197], v167 offset:1024
	ds_read_b128 v[198:201], v167 offset:2048
	ds_read_b128 v[202:205], v167 offset:3072
	ds_read_b128 v[206:209], v167 offset:4096
	ds_read_b128 v[210:213], v167 offset:5120
	ds_read_b128 v[214:217], v167 offset:6144
	ds_read_b128 v[218:221], v167 offset:7168
	global_load_lds_dwordx4 v150, s[52:53]
	s_add_i32 m0, s61, 0xe000
	s_nop 0
	global_load_lds_dwordx4 v152, s[52:53]
	s_waitcnt vmcnt(8)
	s_waitcnt lgkmcnt(0)
	s_barrier
	s_waitcnt lgkmcnt(0)
	v_mfma_f32_16x16x32_bf16 v[126:129], v[130:133], v[190:193], 0
	v_mfma_f32_16x16x32_bf16 v[122:125], v[158:161], v[190:193], 0
	v_mfma_f32_16x16x32_bf16 v[114:117], v[130:133], v[198:201], 0
	v_mfma_f32_16x16x32_bf16 v[106:109], v[158:161], v[198:201], 0
	v_mfma_f32_16x16x32_bf16 v[98:101], v[130:133], v[206:209], 0
	v_mfma_f32_16x16x32_bf16 v[90:93], v[158:161], v[206:209], 0
	v_mfma_f32_16x16x32_bf16 v[82:85], v[130:133], v[214:217], 0
	v_mfma_f32_16x16x32_bf16 v[74:77], v[158:161], v[214:217], 0
	v_mfma_f32_16x16x32_bf16 v[126:129], v[134:137], v[194:197], v[126:129]
	v_mfma_f32_16x16x32_bf16 v[122:125], v[170:173], v[194:197], v[122:125]
	v_mfma_f32_16x16x32_bf16 v[114:117], v[134:137], v[202:205], v[114:117]
	v_mfma_f32_16x16x32_bf16 v[106:109], v[170:173], v[202:205], v[106:109]
	v_mfma_f32_16x16x32_bf16 v[98:101], v[134:137], v[210:213], v[98:101]
	v_mfma_f32_16x16x32_bf16 v[90:93], v[170:173], v[210:213], v[90:93]
	v_mfma_f32_16x16x32_bf16 v[82:85], v[134:137], v[218:221], v[82:85]
	v_mfma_f32_16x16x32_bf16 v[74:77], v[170:173], v[218:221], v[74:77]
	v_mfma_f32_16x16x32_bf16 v[118:121], v[174:177], v[190:193], 0
	v_mfma_f32_16x16x32_bf16 v[110:113], v[182:185], v[190:193], 0
	v_mfma_f32_16x16x32_bf16 v[102:105], v[174:177], v[198:201], 0
	v_mfma_f32_16x16x32_bf16 v[94:97], v[182:185], v[198:201], 0
	v_mfma_f32_16x16x32_bf16 v[86:89], v[174:177], v[206:209], 0
	v_mfma_f32_16x16x32_bf16 v[78:81], v[182:185], v[206:209], 0
	v_mfma_f32_16x16x32_bf16 v[70:73], v[174:177], v[214:217], 0
	v_mfma_f32_16x16x32_bf16 v[66:69], v[182:185], v[214:217], 0
	v_mfma_f32_16x16x32_bf16 v[118:121], v[178:181], v[194:197], v[118:121]
	v_mfma_f32_16x16x32_bf16 v[110:113], v[186:189], v[194:197], v[110:113]
	v_mfma_f32_16x16x32_bf16 v[102:105], v[178:181], v[202:205], v[102:105]
	v_mfma_f32_16x16x32_bf16 v[94:97], v[186:189], v[202:205], v[94:97]
	v_mfma_f32_16x16x32_bf16 v[86:89], v[178:181], v[210:213], v[86:89]
	v_mfma_f32_16x16x32_bf16 v[78:81], v[186:189], v[210:213], v[78:81]
	v_mfma_f32_16x16x32_bf16 v[70:73], v[178:181], v[218:221], v[70:73]
	v_mfma_f32_16x16x32_bf16 v[66:69], v[186:189], v[218:221], v[66:69]
	s_barrier
	s_add_i32 s88, s72, s58
	s_mov_b32 m0, s88
	ds_read_b128 v[190:193], v167 offset:16384
	ds_read_b128 v[194:197], v167 offset:17408
	ds_read_b128 v[198:201], v167 offset:18432
	ds_read_b128 v[202:205], v167 offset:19456
	ds_read_b128 v[206:209], v167 offset:20480
	ds_read_b128 v[210:213], v167 offset:21504
	ds_read_b128 v[214:217], v167 offset:22528
	ds_read_b128 v[218:221], v167 offset:23552
	global_load_lds_dwordx4 v140, s[34:35]
	s_add_i32 m0, s88, 0x2000
	s_add_u32 s88, s34, 0x80000
	s_addc_u32 s89, s35, 0
	s_add_i32 s90, s73, s58
	global_load_lds_dwordx4 v144, s[34:35]
	s_mov_b32 m0, s90
	s_nop 0
	global_load_lds_dwordx4 v140, s[88:89]
	s_add_i32 m0, s90, 0x2000
	s_nop 0
	global_load_lds_dwordx4 v144, s[88:89]
	s_mov_b32 m0, s61
	s_nop 0
	global_load_lds_dwordx4 v138, s[54:55]
	s_mov_b32 m0, s62
	s_nop 0
	global_load_lds_dwordx4 v142, s[54:55]
	s_waitcnt vmcnt(8)
	s_waitcnt lgkmcnt(0)
	s_barrier
; #define PG8_STAGE(bufoff, gbase, voff) do { _Pragma("unroll") for (int _i = 0; _i < 2; ++_i) \
;         __builtin_amdgcn_global_load_lds((const unsigned*)((const char*)(gbase) + (voff)[_i]), (PG8_LAS unsigned*)(lds + (bufoff) + ldsw + _i * 8192), 16, 0, 0); } while (0)
; #define PG8_LDA(dst, b, h) do { _Pragma("unroll") for (int m = 0; m < 4; ++m) _Pragma("unroll") for (int k = 0; k < 2; ++k) dst[m][k] = *(const PG8_LAS bf16x8*)(lds + PG8_SA(b, h) + aoff + m * 2048 + k * 1024); } while (0)
; #define PG8_LDB(dst, b, h) do { _Pragma("unroll") for (int n = 0; n < 2; ++n) _Pragma("unroll") for (int k = 0; k < 2; ++k) dst[n][k] = *(const PG8_LAS bf16x8*)(lds + PG8_SB(b, h) + boff + n * 2048 + k * 1024); } while (0)
; #define PG8_MMA(ai, bj, At, Bt) do { __builtin_amdgcn_s_setprio(1); _Pragma("unroll") for (int m = 0; m < 4; ++m) _Pragma("unroll") for (int n = 0; n < 2; ++n) _Pragma("unroll") for (int k = 0; k < 2; ++k) \
;         acc[ai][bj][m][n] = __builtin_amdgcn_mfma_f32_16x16x32_bf16(Bt[n][k], At[m][k], acc[ai][bj][m][n], 0, 0, 0); __builtin_amdgcn_s_setprio(0); } while (0)
; #define PG8_WAIT_V(n) asm volatile("s_waitcnt vmcnt(" #n ")" ::: "memory")
; #define PG8_WAIT_L(n) asm volatile("s_waitcnt lgkmcnt(" #n ")" ::: "memory")
; #define PG8_BAR __builtin_amdgcn_s_barrier()
; #define PG8_SCHED __builtin_amdgcn_sched_barrier(0)
; #define PG8_WAIT_V(n) asm volatile("s_waitcnt vmcnt(" #n ")" ::: "memory")
; #define PG8_WAIT_L(n) asm volatile("s_waitcnt lgkmcnt(" #n ")" ::: "memory")
; #define PG8_BAR __builtin_amdgcn_s_barrier()
; template <class Epi, class Sched, bool ALIGN_EPI = false>
; __device__ __forceinline__ void gemm_phase(PG8_LAS unsigned char* lds, const Gemm g, const Sched& S, const Epi& E) {
;     ...
;             PG8_WAIT_V(8); PG8_WAIT_L(0); PG8_BAR; PG8_MMA(0, 0, At, B0); PG8_MMA(0, 1, At, B1); PG8_BAR; PG8_SCHED;
;             PG8_LDA(At, 0, 1); PG8_STAGE(PG8_SB(0, 0), b2, voffB); PG8_STAGE(PG8_SB(0, 1), b2 + hstepB, voffB); PG8_STAGE(PG8_SA(0, 0), a2, voffA);
;             PG8_WAIT_V(8); PG8_WAIT_L(0); PG8_BAR; PG8_MMA(1, 0, At, B0); PG8_MMA(1, 1, At, B1); PG8_BAR; PG8_SCHED;
;             PG8_LDB(B0, 1, 0); PG8_LDB(B1, 1, 1); PG8_SCHED; PG8_LDA(At, 1, 0); PG8_STAGE(PG8_SA(0, 1), a2 + hstepA, voffA);
;             PG8_WAIT_V(8); PG8_WAIT_L(0); PG8_BAR; PG8_MMA(0, 0, At, B0); PG8_MMA(0, 1, At, B1); PG8_BAR; PG8_SCHED;
	s_waitcnt lgkmcnt(0)
	v_mfma_f32_16x16x32_bf16 v[62:65], v[130:133], v[190:193], 0
	v_mfma_f32_16x16x32_bf16 v[58:61], v[158:161], v[190:193], 0
	v_mfma_f32_16x16x32_bf16 v[54:57], v[130:133], v[198:201], 0
	v_mfma_f32_16x16x32_bf16 v[46:49], v[158:161], v[198:201], 0
	v_mfma_f32_16x16x32_bf16 v[38:41], v[130:133], v[206:209], 0
	v_mfma_f32_16x16x32_bf16 v[30:33], v[158:161], v[206:209], 0
	v_mfma_f32_16x16x32_bf16 v[22:25], v[130:133], v[214:217], 0
	v_mfma_f32_16x16x32_bf16 v[14:17], v[158:161], v[214:217], 0
	v_mfma_f32_16x16x32_bf16 v[62:65], v[134:137], v[194:197], v[62:65]
	v_mfma_f32_16x16x32_bf16 v[58:61], v[170:173], v[194:197], v[58:61]
	v_mfma_f32_16x16x32_bf16 v[54:57], v[134:137], v[202:205], v[54:57]
	v_mfma_f32_16x16x32_bf16 v[46:49], v[170:173], v[202:205], v[46:49]
	v_mfma_f32_16x16x32_bf16 v[38:41], v[134:137], v[210:213], v[38:41]
	v_mfma_f32_16x16x32_bf16 v[30:33], v[170:173], v[210:213], v[30:33]
	v_mfma_f32_16x16x32_bf16 v[22:25], v[134:137], v[218:221], v[22:25]
	v_mfma_f32_16x16x32_bf16 v[14:17], v[170:173], v[218:221], v[14:17]
	v_mfma_f32_16x16x32_bf16 v[50:53], v[174:177], v[190:193], 0
	v_mfma_f32_16x16x32_bf16 v[42:45], v[182:185], v[190:193], 0
	v_mfma_f32_16x16x32_bf16 v[34:37], v[174:177], v[198:201], 0
	v_mfma_f32_16x16x32_bf16 v[26:29], v[182:185], v[198:201], 0
	v_mfma_f32_16x16x32_bf16 v[18:21], v[174:177], v[206:209], 0
	v_mfma_f32_16x16x32_bf16 v[10:13], v[182:185], v[206:209], 0
	v_mfma_f32_16x16x32_bf16 v[6:9], v[174:177], v[214:217], 0
	v_mfma_f32_16x16x32_bf16 v[2:5], v[182:185], v[214:217], 0
	v_mfma_f32_16x16x32_bf16 v[50:53], v[178:181], v[194:197], v[50:53]
	v_mfma_f32_16x16x32_bf16 v[42:45], v[186:189], v[194:197], v[42:45]
	v_mfma_f32_16x16x32_bf16 v[34:37], v[178:181], v[202:205], v[34:37]
	v_mfma_f32_16x16x32_bf16 v[26:29], v[186:189], v[202:205], v[26:29]
	v_mfma_f32_16x16x32_bf16 v[18:21], v[178:181], v[210:213], v[18:21]
	v_mfma_f32_16x16x32_bf16 v[10:13], v[186:189], v[210:213], v[10:13]
	v_mfma_f32_16x16x32_bf16 v[6:9], v[178:181], v[218:221], v[6:9]
	v_mfma_f32_16x16x32_bf16 v[2:5], v[186:189], v[218:221], v[2:5]
	s_barrier
	s_add_i32 s88, 0, 0x18000
	v_add_u32_e32 v146, s88, v164
	s_add_i32 s89, 0, 0x1c000
	ds_read_b128 v[130:133], v146
	ds_read_b128 v[134:137], v146 offset:1024
	ds_read_b128 v[158:161], v146 offset:2048
	ds_read_b128 v[170:173], v146 offset:3072
	v_add_u32_e32 v146, s89, v164
	ds_read_b128 v[174:177], v146
	ds_read_b128 v[178:181], v146 offset:1024
	ds_read_b128 v[182:185], v146 offset:2048
	ds_read_b128 v[186:189], v146 offset:3072
	s_add_u32 s54, s54, 0x80000
	s_addc_u32 s55, s55, 0
	s_mov_b32 m0, s63
	ds_read_b128 v[190:193], v167 offset:32768
	ds_read_b128 v[194:197], v167 offset:33792
	ds_read_b128 v[198:201], v167 offset:34816
	ds_read_b128 v[202:205], v167 offset:35840
	ds_read_b128 v[206:209], v167 offset:36864
	ds_read_b128 v[210:213], v167 offset:37888
	ds_read_b128 v[214:217], v167 offset:38912
	ds_read_b128 v[218:221], v167 offset:39936
	global_load_lds_dwordx4 v138, s[54:55]
	s_mov_b32 m0, s64
	s_nop 0
	global_load_lds_dwordx4 v142, s[54:55]
	s_waitcnt vmcnt(8)
	s_waitcnt lgkmcnt(0)
	s_barrier
	s_waitcnt lgkmcnt(0)
	v_mfma_f32_16x16x32_bf16 v[126:129], v[130:133], v[190:193], v[126:129]
	v_mfma_f32_16x16x32_bf16 v[122:125], v[158:161], v[190:193], v[122:125]
	v_mfma_f32_16x16x32_bf16 v[114:117], v[130:133], v[198:201], v[114:117]
	v_mfma_f32_16x16x32_bf16 v[106:109], v[158:161], v[198:201], v[106:109]
	v_mfma_f32_16x16x32_bf16 v[98:101], v[130:133], v[206:209], v[98:101]
	v_mfma_f32_16x16x32_bf16 v[90:93], v[158:161], v[206:209], v[90:93]
	v_mfma_f32_16x16x32_bf16 v[82:85], v[130:133], v[214:217], v[82:85]
	v_mfma_f32_16x16x32_bf16 v[74:77], v[158:161], v[214:217], v[74:77]
	v_mfma_f32_16x16x32_bf16 v[126:129], v[134:137], v[194:197], v[126:129]
	v_mfma_f32_16x16x32_bf16 v[122:125], v[170:173], v[194:197], v[122:125]
	v_mfma_f32_16x16x32_bf16 v[114:117], v[134:137], v[202:205], v[114:117]
	v_mfma_f32_16x16x32_bf16 v[106:109], v[170:173], v[202:205], v[106:109]
	v_mfma_f32_16x16x32_bf16 v[98:101], v[134:137], v[210:213], v[98:101]
	v_mfma_f32_16x16x32_bf16 v[90:93], v[170:173], v[210:213], v[90:93]
	v_mfma_f32_16x16x32_bf16 v[82:85], v[134:137], v[218:221], v[82:85]
	v_mfma_f32_16x16x32_bf16 v[74:77], v[170:173], v[218:221], v[74:77]
	v_mfma_f32_16x16x32_bf16 v[118:121], v[174:177], v[190:193], v[118:121]
	v_mfma_f32_16x16x32_bf16 v[110:113], v[182:185], v[190:193], v[110:113]
	v_mfma_f32_16x16x32_bf16 v[102:105], v[174:177], v[198:201], v[102:105]
	v_mfma_f32_16x16x32_bf16 v[94:97], v[182:185], v[198:201], v[94:97]
	v_mfma_f32_16x16x32_bf16 v[86:89], v[174:177], v[206:209], v[86:89]
	v_mfma_f32_16x16x32_bf16 v[78:81], v[182:185], v[206:209], v[78:81]
	v_mfma_f32_16x16x32_bf16 v[70:73], v[174:177], v[214:217], v[70:73]
	v_mfma_f32_16x16x32_bf16 v[66:69], v[182:185], v[214:217], v[66:69]
	v_mfma_f32_16x16x32_bf16 v[118:121], v[178:181], v[194:197], v[118:121]
	v_mfma_f32_16x16x32_bf16 v[110:113], v[186:189], v[194:197], v[110:113]
	v_mfma_f32_16x16x32_bf16 v[102:105], v[178:181], v[202:205], v[102:105]
	v_mfma_f32_16x16x32_bf16 v[94:97], v[186:189], v[202:205], v[94:97]
	v_mfma_f32_16x16x32_bf16 v[86:89], v[178:181], v[210:213], v[86:89]
	v_mfma_f32_16x16x32_bf16 v[78:81], v[186:189], v[210:213], v[78:81]
	v_mfma_f32_16x16x32_bf16 v[70:73], v[178:181], v[218:221], v[70:73]
	v_mfma_f32_16x16x32_bf16 v[66:69], v[186:189], v[218:221], v[66:69]
	s_barrier
; #define PG8_STAGE(bufoff, gbase, voff) do { _Pragma("unroll") for (int _i = 0; _i < 2; ++_i) \
;         __builtin_amdgcn_global_load_lds((const unsigned*)((const char*)(gbase) + (voff)[_i]), (PG8_LAS unsigned*)(lds + (bufoff) + ldsw + _i * 8192), 16, 0, 0); } while (0)
; #define PG8_LDA(dst, b, h) do { _Pragma("unroll") for (int m = 0; m < 4; ++m) _Pragma("unroll") for (int k = 0; k < 2; ++k) dst[m][k] = *(const PG8_LAS bf16x8*)(lds + PG8_SA(b, h) + aoff + m * 2048 + k * 1024); } while (0)
; #define PG8_LDB(dst, b, h) do { _Pragma("unroll") for (int n = 0; n < 2; ++n) _Pragma("unroll") for (int k = 0; k < 2; ++k) dst[n][k] = *(const PG8_LAS bf16x8*)(lds + PG8_SB(b, h) + boff + n * 2048 + k * 1024); } while (0)
; #define PG8_MMA(ai, bj, At, Bt) do { __builtin_amdgcn_s_setprio(1); _Pragma("unroll") for (int m = 0; m < 4; ++m) _Pragma("unroll") for (int n = 0; n < 2; ++n) _Pragma("unroll") for (int k = 0; k < 2; ++k) \
;         acc[ai][bj][m][n] = __builtin_amdgcn_mfma_f32_16x16x32_bf16(Bt[n][k], At[m][k], acc[ai][bj][m][n], 0, 0, 0); __builtin_amdgcn_s_setprio(0); } while (0)
; #define PG8_WAIT_V(n) asm volatile("s_waitcnt vmcnt(" #n ")" ::: "memory")
; #define PG8_WAIT_L(n) asm volatile("s_waitcnt lgkmcnt(" #n ")" ::: "memory")
; #define PG8_BAR __builtin_amdgcn_s_barrier()
; #define PG8_SCHED __builtin_amdgcn_sched_barrier(0)
; #define PG8_BAR __builtin_amdgcn_s_barrier()
; template <class Epi, class Sched, bool ALIGN_EPI = false>
; __device__ __forceinline__ void gemm_phase(PG8_LAS unsigned char* lds, const Gemm g, const Sched& S, const Epi& E) {
;     ...
;         for (int t = 0; t < nt; t += 2) {
;             const bool last = (t == nt - 2);
;             const char* a1 = cA + (size_t)(t + 1) * kstep;
;             const char* a2 = last ? nA : cA + (size_t)(t + 2) * kstep; const char* b2 = last ? nB : cB + (size_t)(t + 2) * kstep;
;             const char* a3 = a2 + kstep; const char* b3 = b2 + kstep;
;             if (last && has_next) S.a_ready(nxt);
;             PG8_LDB(B0, 0, 0); PG8_LDB(B1, 0, 1); PG8_SCHED; PG8_LDA(At, 0, 0); PG8_STAGE(PG8_SA(1, 1), a1 + hstepA, voffA);
;     ...
;             PG8_LDA(At, 1, 1); PG8_STAGE(PG8_SB(1, 0), b3, voffB); PG8_STAGE(PG8_SB(1, 1), b3 + hstepB, voffB); PG8_STAGE(PG8_SA(1, 0), a3, voffA);
;             PG8_WAIT_V(8); PG8_WAIT_L(0); PG8_BAR; PG8_MMA(1, 0, At, B0); PG8_MMA(1, 1, At, B1); PG8_BAR; PG8_SCHED;
;         }
	s_add_i32 s101, s88, s58
	s_add_u32 s98, s34, s10
	s_addc_u32 s99, s35, s11
	s_mov_b32 m0, s101
	ds_read_b128 v[190:193], v167 offset:49152
	ds_read_b128 v[194:197], v167 offset:50176
	ds_read_b128 v[198:201], v167 offset:51200
	ds_read_b128 v[202:205], v167 offset:52224
	ds_read_b128 v[206:209], v167 offset:53248
	ds_read_b128 v[210:213], v167 offset:54272
	ds_read_b128 v[214:217], v167 offset:55296
	ds_read_b128 v[218:221], v167 offset:56320
	global_load_lds_dwordx4 v140, s[98:99]
	s_add_i32 m0, s101, 0x2000
	s_add_u32 s34, s34, 0x80080
	s_addc_u32 s35, s35, 0
	s_add_i32 s101, s89, s58
	global_load_lds_dwordx4 v144, s[98:99]
	s_add_u32 s98, s54, s10
	s_addc_u32 s99, s55, s11
	s_sub_u32 s98, s98, 0x80000
	s_subb_u32 s99, s99, 0
	s_mov_b32 m0, s101
	s_nop 0
	global_load_lds_dwordx4 v140, s[34:35]
	s_add_i32 m0, s101, 0x2000
	s_nop 0
	global_load_lds_dwordx4 v144, s[34:35]
	s_mov_b32 m0, s70
	s_nop 0
	global_load_lds_dwordx4 v138, s[98:99]
	s_mov_b32 m0, s71
	s_nop 0
	global_load_lds_dwordx4 v142, s[98:99]
	s_waitcnt vmcnt(8)
	s_waitcnt lgkmcnt(0)
	s_barrier
	s_waitcnt lgkmcnt(0)
	v_mfma_f32_16x16x32_bf16 v[62:65], v[130:133], v[190:193], v[62:65]
	v_mfma_f32_16x16x32_bf16 v[58:61], v[158:161], v[190:193], v[58:61]
	v_mfma_f32_16x16x32_bf16 v[54:57], v[130:133], v[198:201], v[54:57]
	v_mfma_f32_16x16x32_bf16 v[46:49], v[158:161], v[198:201], v[46:49]
	v_mfma_f32_16x16x32_bf16 v[38:41], v[130:133], v[206:209], v[38:41]
	v_mfma_f32_16x16x32_bf16 v[30:33], v[158:161], v[206:209], v[30:33]
	v_mfma_f32_16x16x32_bf16 v[22:25], v[130:133], v[214:217], v[22:25]
	v_mfma_f32_16x16x32_bf16 v[14:17], v[158:161], v[214:217], v[14:17]
	v_mfma_f32_16x16x32_bf16 v[62:65], v[134:137], v[194:197], v[62:65]
	v_mfma_f32_16x16x32_bf16 v[58:61], v[170:173], v[194:197], v[58:61]
	v_mfma_f32_16x16x32_bf16 v[54:57], v[134:137], v[202:205], v[54:57]
	v_mfma_f32_16x16x32_bf16 v[46:49], v[170:173], v[202:205], v[46:49]
	v_mfma_f32_16x16x32_bf16 v[38:41], v[134:137], v[210:213], v[38:41]
	v_mfma_f32_16x16x32_bf16 v[30:33], v[170:173], v[210:213], v[30:33]
	v_mfma_f32_16x16x32_bf16 v[22:25], v[134:137], v[218:221], v[22:25]
	v_mfma_f32_16x16x32_bf16 v[14:17], v[170:173], v[218:221], v[14:17]
	v_mfma_f32_16x16x32_bf16 v[50:53], v[174:177], v[190:193], v[50:53]
	v_mfma_f32_16x16x32_bf16 v[42:45], v[182:185], v[190:193], v[42:45]
	v_mfma_f32_16x16x32_bf16 v[34:37], v[174:177], v[198:201], v[34:37]
	v_mfma_f32_16x16x32_bf16 v[26:29], v[182:185], v[198:201], v[26:29]
	v_mfma_f32_16x16x32_bf16 v[18:21], v[174:177], v[206:209], v[18:21]
	v_mfma_f32_16x16x32_bf16 v[10:13], v[182:185], v[206:209], v[10:13]
	v_mfma_f32_16x16x32_bf16 v[6:9], v[174:177], v[214:217], v[6:9]
	v_mfma_f32_16x16x32_bf16 v[2:5], v[182:185], v[214:217], v[2:5]
	v_mfma_f32_16x16x32_bf16 v[50:53], v[178:181], v[194:197], v[50:53]
	v_mfma_f32_16x16x32_bf16 v[42:45], v[186:189], v[194:197], v[42:45]
	v_mfma_f32_16x16x32_bf16 v[34:37], v[178:181], v[202:205], v[34:37]
	v_mfma_f32_16x16x32_bf16 v[26:29], v[186:189], v[202:205], v[26:29]
	v_mfma_f32_16x16x32_bf16 v[18:21], v[178:181], v[210:213], v[18:21]
	v_mfma_f32_16x16x32_bf16 v[10:13], v[186:189], v[210:213], v[10:13]
	v_mfma_f32_16x16x32_bf16 v[6:9], v[178:181], v[218:221], v[6:9]
	v_mfma_f32_16x16x32_bf16 v[2:5], v[186:189], v[218:221], v[2:5]
	s_barrier
	s_add_i32 s85, s85, 2
	s_add_u32 s52, s52, 0x100
	s_addc_u32 s53, s53, 0
	s_add_u32 s83, s83, 0x100
	s_addc_u32 s84, s84, 0
	s_cmp_gt_u32 s85, 29
	ds_read_b128 v[130:133], v165
	ds_read_b128 v[134:137], v165 offset:1024
	ds_read_b128 v[158:161], v165 offset:2048
	ds_read_b128 v[170:173], v165 offset:3072
	ds_read_b128 v[174:177], v166
	ds_read_b128 v[178:181], v166 offset:1024
	ds_read_b128 v[182:185], v166 offset:2048
	ds_read_b128 v[186:189], v166 offset:3072
	s_add_u32 s34, s52, 0xfff80080
	s_addc_u32 s35, s53, -1
	s_cmp_eq_u32 s85, 28
	s_cselect_b32 s55, s13, s35
	s_cselect_b32 s54, s27, s34
	s_cselect_b32 s35, s25, s84
	s_cselect_b32 s34, s82, s83
	s_add_i32 m0, s61, 0xc000
	ds_read_b128 v[190:193], v167
	ds_read_b128 v[194:197], v167 offset:1024
	ds_read_b128 v[198:201], v167 offset:2048
	ds_read_b128 v[202:205], v167 offset:3072
	ds_read_b128 v[206:209], v167 offset:4096
	ds_read_b128 v[210:213], v167 offset:5120
	ds_read_b128 v[214:217], v167 offset:6144
	ds_read_b128 v[218:221], v167 offset:7168
	global_load_lds_dwordx4 v150, s[52:53]
	s_add_i32 m0, s61, 0xe000
	s_nop 0
	global_load_lds_dwordx4 v152, s[52:53]
	s_waitcnt vmcnt(8)
	s_waitcnt lgkmcnt(0)
	s_barrier
; #define PG8_STAGE(bufoff, gbase, voff) do { _Pragma("unroll") for (int _i = 0; _i < 2; ++_i) \
;         __builtin_amdgcn_global_load_lds((const unsigned*)((const char*)(gbase) + (voff)[_i]), (PG8_LAS unsigned*)(lds + (bufoff) + ldsw + _i * 8192), 16, 0, 0); } while (0)
; #define PG8_LDA(dst, b, h) do { _Pragma("unroll") for (int m = 0; m < 4; ++m) _Pragma("unroll") for (int k = 0; k < 2; ++k) dst[m][k] = *(const PG8_LAS bf16x8*)(lds + PG8_SA(b, h) + aoff + m * 2048 + k * 1024); } while (0)
; #define PG8_LDB(dst, b, h) do { _Pragma("unroll") for (int n = 0; n < 2; ++n) _Pragma("unroll") for (int k = 0; k < 2; ++k) dst[n][k] = *(const PG8_LAS bf16x8*)(lds + PG8_SB(b, h) + boff + n * 2048 + k * 1024); } while (0)
; #define PG8_MMA(ai, bj, At, Bt) do { __builtin_amdgcn_s_setprio(1); _Pragma("unroll") for (int m = 0; m < 4; ++m) _Pragma("unroll") for (int n = 0; n < 2; ++n) _Pragma("unroll") for (int k = 0; k < 2; ++k) \
;         acc[ai][bj][m][n] = __builtin_amdgcn_mfma_f32_16x16x32_bf16(Bt[n][k], At[m][k], acc[ai][bj][m][n], 0, 0, 0); __builtin_amdgcn_s_setprio(0); } while (0)
; #define PG8_WAIT_V(n) asm volatile("s_waitcnt vmcnt(" #n ")" ::: "memory")
; #define PG8_WAIT_L(n) asm volatile("s_waitcnt lgkmcnt(" #n ")" ::: "memory")
; #define PG8_BAR __builtin_amdgcn_s_barrier()
; #define PG8_SCHED __builtin_amdgcn_sched_barrier(0)
; #define PG8_WAIT_V(n) asm volatile("s_waitcnt vmcnt(" #n ")" ::: "memory")
; #define PG8_WAIT_L(n) asm volatile("s_waitcnt lgkmcnt(" #n ")" ::: "memory")
; #define PG8_BAR __builtin_amdgcn_s_barrier()
; template <class Epi, class Sched, bool ALIGN_EPI = false>
; __device__ __forceinline__ void gemm_phase(PG8_LAS unsigned char* lds, const Gemm g, const Sched& S, const Epi& E) {
;     ...
;             PG8_WAIT_V(8); PG8_WAIT_L(0); PG8_BAR; PG8_MMA(0, 0, At, B0); PG8_MMA(0, 1, At, B1); PG8_BAR; PG8_SCHED;
;             PG8_LDA(At, 0, 1); PG8_STAGE(PG8_SB(0, 0), b2, voffB); PG8_STAGE(PG8_SB(0, 1), b2 + hstepB, voffB); PG8_STAGE(PG8_SA(0, 0), a2, voffA);
;             PG8_WAIT_V(8); PG8_WAIT_L(0); PG8_BAR; PG8_MMA(1, 0, At, B0); PG8_MMA(1, 1, At, B1); PG8_BAR; PG8_SCHED;
;             PG8_LDB(B0, 1, 0); PG8_LDB(B1, 1, 1); PG8_SCHED; PG8_LDA(At, 1, 0); PG8_STAGE(PG8_SA(0, 1), a2 + hstepA, voffA);
;             PG8_WAIT_V(8); PG8_WAIT_L(0); PG8_BAR; PG8_MMA(0, 0, At, B0); PG8_MMA(0, 1, At, B1); PG8_BAR; PG8_SCHED;
	s_waitcnt lgkmcnt(0)
	v_mfma_f32_16x16x32_bf16 v[126:129], v[130:133], v[190:193], v[126:129]
	v_mfma_f32_16x16x32_bf16 v[122:125], v[158:161], v[190:193], v[122:125]
	v_mfma_f32_16x16x32_bf16 v[114:117], v[130:133], v[198:201], v[114:117]
	v_mfma_f32_16x16x32_bf16 v[106:109], v[158:161], v[198:201], v[106:109]
	v_mfma_f32_16x16x32_bf16 v[98:101], v[130:133], v[206:209], v[98:101]
	v_mfma_f32_16x16x32_bf16 v[90:93], v[158:161], v[206:209], v[90:93]
	v_mfma_f32_16x16x32_bf16 v[82:85], v[130:133], v[214:217], v[82:85]
	v_mfma_f32_16x16x32_bf16 v[74:77], v[158:161], v[214:217], v[74:77]
	v_mfma_f32_16x16x32_bf16 v[126:129], v[134:137], v[194:197], v[126:129]
	v_mfma_f32_16x16x32_bf16 v[122:125], v[170:173], v[194:197], v[122:125]
	v_mfma_f32_16x16x32_bf16 v[114:117], v[134:137], v[202:205], v[114:117]
	v_mfma_f32_16x16x32_bf16 v[106:109], v[170:173], v[202:205], v[106:109]
	v_mfma_f32_16x16x32_bf16 v[98:101], v[134:137], v[210:213], v[98:101]
	v_mfma_f32_16x16x32_bf16 v[90:93], v[170:173], v[210:213], v[90:93]
	v_mfma_f32_16x16x32_bf16 v[82:85], v[134:137], v[218:221], v[82:85]
	v_mfma_f32_16x16x32_bf16 v[74:77], v[170:173], v[218:221], v[74:77]
	v_mfma_f32_16x16x32_bf16 v[118:121], v[174:177], v[190:193], v[118:121]
	v_mfma_f32_16x16x32_bf16 v[110:113], v[182:185], v[190:193], v[110:113]
	v_mfma_f32_16x16x32_bf16 v[102:105], v[174:177], v[198:201], v[102:105]
	v_mfma_f32_16x16x32_bf16 v[94:97], v[182:185], v[198:201], v[94:97]
	v_mfma_f32_16x16x32_bf16 v[86:89], v[174:177], v[206:209], v[86:89]
	v_mfma_f32_16x16x32_bf16 v[78:81], v[182:185], v[206:209], v[78:81]
	v_mfma_f32_16x16x32_bf16 v[70:73], v[174:177], v[214:217], v[70:73]
	v_mfma_f32_16x16x32_bf16 v[66:69], v[182:185], v[214:217], v[66:69]
	v_mfma_f32_16x16x32_bf16 v[118:121], v[178:181], v[194:197], v[118:121]
	v_mfma_f32_16x16x32_bf16 v[110:113], v[186:189], v[194:197], v[110:113]
	v_mfma_f32_16x16x32_bf16 v[102:105], v[178:181], v[202:205], v[102:105]
	v_mfma_f32_16x16x32_bf16 v[94:97], v[186:189], v[202:205], v[94:97]
	v_mfma_f32_16x16x32_bf16 v[86:89], v[178:181], v[210:213], v[86:89]
	v_mfma_f32_16x16x32_bf16 v[78:81], v[186:189], v[210:213], v[78:81]
	v_mfma_f32_16x16x32_bf16 v[70:73], v[178:181], v[218:221], v[70:73]
	v_mfma_f32_16x16x32_bf16 v[66:69], v[186:189], v[218:221], v[66:69]
	s_barrier
	s_add_i32 s88, s72, s58
	s_mov_b32 m0, s88
	ds_read_b128 v[190:193], v167 offset:16384
	ds_read_b128 v[194:197], v167 offset:17408
	ds_read_b128 v[198:201], v167 offset:18432
	ds_read_b128 v[202:205], v167 offset:19456
	ds_read_b128 v[206:209], v167 offset:20480
	ds_read_b128 v[210:213], v167 offset:21504
	ds_read_b128 v[214:217], v167 offset:22528
	ds_read_b128 v[218:221], v167 offset:23552
	global_load_lds_dwordx4 v140, s[34:35]
	s_add_i32 m0, s88, 0x2000
	s_add_u32 s88, s34, 0x80000
	s_addc_u32 s89, s35, 0
	s_add_i32 s90, s73, s58
	global_load_lds_dwordx4 v144, s[34:35]
	s_mov_b32 m0, s90
	s_nop 0
	global_load_lds_dwordx4 v140, s[88:89]
	s_add_i32 m0, s90, 0x2000
	s_nop 0
	global_load_lds_dwordx4 v144, s[88:89]
	s_mov_b32 m0, s61
	s_nop 0
	global_load_lds_dwordx4 v138, s[54:55]
	s_mov_b32 m0, s62
	s_nop 0
	global_load_lds_dwordx4 v142, s[54:55]
	s_waitcnt vmcnt(8)
	s_waitcnt lgkmcnt(0)
	s_barrier
	s_waitcnt lgkmcnt(0)
	v_mfma_f32_16x16x32_bf16 v[62:65], v[130:133], v[190:193], v[62:65]
	v_mfma_f32_16x16x32_bf16 v[58:61], v[158:161], v[190:193], v[58:61]
	v_mfma_f32_16x16x32_bf16 v[54:57], v[130:133], v[198:201], v[54:57]
	v_mfma_f32_16x16x32_bf16 v[46:49], v[158:161], v[198:201], v[46:49]
	v_mfma_f32_16x16x32_bf16 v[38:41], v[130:133], v[206:209], v[38:41]
	v_mfma_f32_16x16x32_bf16 v[30:33], v[158:161], v[206:209], v[30:33]
	v_mfma_f32_16x16x32_bf16 v[22:25], v[130:133], v[214:217], v[22:25]
	v_mfma_f32_16x16x32_bf16 v[14:17], v[158:161], v[214:217], v[14:17]
	v_mfma_f32_16x16x32_bf16 v[62:65], v[134:137], v[194:197], v[62:65]
	v_mfma_f32_16x16x32_bf16 v[58:61], v[170:173], v[194:197], v[58:61]
	v_mfma_f32_16x16x32_bf16 v[54:57], v[134:137], v[202:205], v[54:57]
	v_mfma_f32_16x16x32_bf16 v[46:49], v[170:173], v[202:205], v[46:49]
	v_mfma_f32_16x16x32_bf16 v[38:41], v[134:137], v[210:213], v[38:41]
	v_mfma_f32_16x16x32_bf16 v[30:33], v[170:173], v[210:213], v[30:33]
	v_mfma_f32_16x16x32_bf16 v[22:25], v[134:137], v[218:221], v[22:25]
	v_mfma_f32_16x16x32_bf16 v[14:17], v[170:173], v[218:221], v[14:17]
	v_mfma_f32_16x16x32_bf16 v[50:53], v[174:177], v[190:193], v[50:53]
	v_mfma_f32_16x16x32_bf16 v[42:45], v[182:185], v[190:193], v[42:45]
	v_mfma_f32_16x16x32_bf16 v[34:37], v[174:177], v[198:201], v[34:37]
	v_mfma_f32_16x16x32_bf16 v[26:29], v[182:185], v[198:201], v[26:29]
	v_mfma_f32_16x16x32_bf16 v[18:21], v[174:177], v[206:209], v[18:21]
	v_mfma_f32_16x16x32_bf16 v[10:13], v[182:185], v[206:209], v[10:13]
	v_mfma_f32_16x16x32_bf16 v[6:9], v[174:177], v[214:217], v[6:9]
	v_mfma_f32_16x16x32_bf16 v[2:5], v[182:185], v[214:217], v[2:5]
	v_mfma_f32_16x16x32_bf16 v[50:53], v[178:181], v[194:197], v[50:53]
	v_mfma_f32_16x16x32_bf16 v[42:45], v[186:189], v[194:197], v[42:45]
	v_mfma_f32_16x16x32_bf16 v[34:37], v[178:181], v[202:205], v[34:37]
	v_mfma_f32_16x16x32_bf16 v[26:29], v[186:189], v[202:205], v[26:29]
	v_mfma_f32_16x16x32_bf16 v[18:21], v[178:181], v[210:213], v[18:21]
	v_mfma_f32_16x16x32_bf16 v[10:13], v[186:189], v[210:213], v[10:13]
	v_mfma_f32_16x16x32_bf16 v[6:9], v[178:181], v[218:221], v[6:9]
	v_mfma_f32_16x16x32_bf16 v[2:5], v[186:189], v[218:221], v[2:5]
	s_barrier
; #define PG8_STAGE(bufoff, gbase, voff) do { _Pragma("unroll") for (int _i = 0; _i < 2; ++_i) \
;         __builtin_amdgcn_global_load_lds((const unsigned*)((const char*)(gbase) + (voff)[_i]), (PG8_LAS unsigned*)(lds + (bufoff) + ldsw + _i * 8192), 16, 0, 0); } while (0)
; #define PG8_LDA(dst, b, h) do { _Pragma("unroll") for (int m = 0; m < 4; ++m) _Pragma("unroll") for (int k = 0; k < 2; ++k) dst[m][k] = *(const PG8_LAS bf16x8*)(lds + PG8_SA(b, h) + aoff + m * 2048 + k * 1024); } while (0)
; #define PG8_LDB(dst, b, h) do { _Pragma("unroll") for (int n = 0; n < 2; ++n) _Pragma("unroll") for (int k = 0; k < 2; ++k) dst[n][k] = *(const PG8_LAS bf16x8*)(lds + PG8_SB(b, h) + boff + n * 2048 + k * 1024); } while (0)
; #define PG8_MMA(ai, bj, At, Bt) do { __builtin_amdgcn_s_setprio(1); _Pragma("unroll") for (int m = 0; m < 4; ++m) _Pragma("unroll") for (int n = 0; n < 2; ++n) _Pragma("unroll") for (int k = 0; k < 2; ++k) \
;         acc[ai][bj][m][n] = __builtin_amdgcn_mfma_f32_16x16x32_bf16(Bt[n][k], At[m][k], acc[ai][bj][m][n], 0, 0, 0); __builtin_amdgcn_s_setprio(0); } while (0)
; #define PG8_WAIT_V(n) asm volatile("s_waitcnt vmcnt(" #n ")" ::: "memory")
; #define PG8_WAIT_L(n) asm volatile("s_waitcnt lgkmcnt(" #n ")" ::: "memory")
; #define PG8_BAR __builtin_amdgcn_s_barrier()
; #define PG8_SCHED __builtin_amdgcn_sched_barrier(0)
; #define PG8_STAGE(bufoff, gbase, voff) do { _Pragma("unroll") for (int _i = 0; _i < 2; ++_i) \
;         __builtin_amdgcn_global_load_lds((const unsigned*)((const char*)(gbase) + (voff)[_i]), (PG8_LAS unsigned*)(lds + (bufoff) + ldsw + _i * 8192), 16, 0, 0); } while (0)
; #define PG8_BAR __builtin_amdgcn_s_barrier()
; template <class Epi, class Sched, bool ALIGN_EPI = false>
; __device__ __forceinline__ void gemm_phase(PG8_LAS unsigned char* lds, const Gemm g, const Sched& S, const Epi& E) {
;     ...
;             PG8_LDB(B0, 1, 0); PG8_LDB(B1, 1, 1); PG8_SCHED; PG8_LDA(At, 1, 0); PG8_STAGE(PG8_SA(0, 1), a2 + hstepA, voffA);
;             PG8_WAIT_V(8); PG8_WAIT_L(0); PG8_BAR; PG8_MMA(0, 0, At, B0); PG8_MMA(0, 1, At, B1); PG8_BAR; PG8_SCHED;
;             PG8_LDA(At, 1, 1); PG8_STAGE(PG8_SB(1, 0), b3, voffB); PG8_STAGE(PG8_SB(1, 1), b3 + hstepB, voffB); PG8_STAGE(PG8_SA(1, 0), a3, voffA);
;             PG8_WAIT_V(8); PG8_WAIT_L(0); PG8_BAR; PG8_MMA(1, 0, At, B0); PG8_MMA(1, 1, At, B1); PG8_BAR; PG8_SCHED;
;         }
	s_add_i32 s88, 0, 0x18000
	v_add_u32_e32 v146, s88, v164
	s_add_i32 s89, 0, 0x1c000
	ds_read_b128 v[130:133], v146
	ds_read_b128 v[134:137], v146 offset:1024
	ds_read_b128 v[158:161], v146 offset:2048
	ds_read_b128 v[170:173], v146 offset:3072
	v_add_u32_e32 v146, s89, v164
	ds_read_b128 v[174:177], v146
	ds_read_b128 v[178:181], v146 offset:1024
	ds_read_b128 v[182:185], v146 offset:2048
	ds_read_b128 v[186:189], v146 offset:3072
	s_add_u32 s54, s54, 0x80000
	s_addc_u32 s55, s55, 0
	s_mov_b32 m0, s63
	ds_read_b128 v[190:193], v167 offset:32768
	ds_read_b128 v[194:197], v167 offset:33792
	ds_read_b128 v[198:201], v167 offset:34816
	ds_read_b128 v[202:205], v167 offset:35840
	ds_read_b128 v[206:209], v167 offset:36864
	ds_read_b128 v[210:213], v167 offset:37888
	ds_read_b128 v[214:217], v167 offset:38912
	ds_read_b128 v[218:221], v167 offset:39936
	global_load_lds_dwordx4 v138, s[54:55]
	s_mov_b32 m0, s64
	s_nop 0
	global_load_lds_dwordx4 v142, s[54:55]
	s_waitcnt vmcnt(8)
	s_waitcnt lgkmcnt(0)
	s_barrier
	s_waitcnt lgkmcnt(0)
	v_mfma_f32_16x16x32_bf16 v[126:129], v[130:133], v[190:193], v[126:129]
	v_mfma_f32_16x16x32_bf16 v[122:125], v[158:161], v[190:193], v[122:125]
	v_mfma_f32_16x16x32_bf16 v[114:117], v[130:133], v[198:201], v[114:117]
	v_mfma_f32_16x16x32_bf16 v[106:109], v[158:161], v[198:201], v[106:109]
	v_mfma_f32_16x16x32_bf16 v[98:101], v[130:133], v[206:209], v[98:101]
	v_mfma_f32_16x16x32_bf16 v[90:93], v[158:161], v[206:209], v[90:93]
	v_mfma_f32_16x16x32_bf16 v[82:85], v[130:133], v[214:217], v[82:85]
	v_mfma_f32_16x16x32_bf16 v[74:77], v[158:161], v[214:217], v[74:77]
	v_mfma_f32_16x16x32_bf16 v[126:129], v[134:137], v[194:197], v[126:129]
	v_mfma_f32_16x16x32_bf16 v[122:125], v[170:173], v[194:197], v[122:125]
	v_mfma_f32_16x16x32_bf16 v[114:117], v[134:137], v[202:205], v[114:117]
	v_mfma_f32_16x16x32_bf16 v[106:109], v[170:173], v[202:205], v[106:109]
	v_mfma_f32_16x16x32_bf16 v[98:101], v[134:137], v[210:213], v[98:101]
	v_mfma_f32_16x16x32_bf16 v[90:93], v[170:173], v[210:213], v[90:93]
	v_mfma_f32_16x16x32_bf16 v[82:85], v[134:137], v[218:221], v[82:85]
	v_mfma_f32_16x16x32_bf16 v[74:77], v[170:173], v[218:221], v[74:77]
	v_mfma_f32_16x16x32_bf16 v[118:121], v[174:177], v[190:193], v[118:121]
	v_mfma_f32_16x16x32_bf16 v[110:113], v[182:185], v[190:193], v[110:113]
	v_mfma_f32_16x16x32_bf16 v[102:105], v[174:177], v[198:201], v[102:105]
	v_mfma_f32_16x16x32_bf16 v[94:97], v[182:185], v[198:201], v[94:97]
	v_mfma_f32_16x16x32_bf16 v[86:89], v[174:177], v[206:209], v[86:89]
	v_mfma_f32_16x16x32_bf16 v[78:81], v[182:185], v[206:209], v[78:81]
	v_mfma_f32_16x16x32_bf16 v[70:73], v[174:177], v[214:217], v[70:73]
	v_mfma_f32_16x16x32_bf16 v[66:69], v[182:185], v[214:217], v[66:69]
	v_mfma_f32_16x16x32_bf16 v[118:121], v[178:181], v[194:197], v[118:121]
	v_mfma_f32_16x16x32_bf16 v[110:113], v[186:189], v[194:197], v[110:113]
	v_mfma_f32_16x16x32_bf16 v[102:105], v[178:181], v[202:205], v[102:105]
	v_mfma_f32_16x16x32_bf16 v[94:97], v[186:189], v[202:205], v[94:97]
	v_mfma_f32_16x16x32_bf16 v[86:89], v[178:181], v[210:213], v[86:89]
	v_mfma_f32_16x16x32_bf16 v[78:81], v[186:189], v[210:213], v[78:81]
	v_mfma_f32_16x16x32_bf16 v[70:73], v[178:181], v[218:221], v[70:73]
	v_mfma_f32_16x16x32_bf16 v[66:69], v[186:189], v[218:221], v[66:69]
	s_barrier
	s_add_i32 s101, s88, s58
	s_add_u32 s98, s34, s10
	s_addc_u32 s99, s35, s11
	s_mov_b32 m0, s101
	ds_read_b128 v[190:193], v167 offset:49152
	ds_read_b128 v[194:197], v167 offset:50176
	ds_read_b128 v[198:201], v167 offset:51200
	ds_read_b128 v[202:205], v167 offset:52224
	ds_read_b128 v[206:209], v167 offset:53248
	ds_read_b128 v[210:213], v167 offset:54272
	ds_read_b128 v[214:217], v167 offset:55296
	ds_read_b128 v[218:221], v167 offset:56320
	global_load_lds_dwordx4 v140, s[98:99]
	s_add_i32 m0, s101, 0x2000
	s_add_u32 s34, s34, 0x80080
	s_addc_u32 s35, s35, 0
	s_add_i32 s101, s89, s58
	global_load_lds_dwordx4 v144, s[98:99]
	s_add_u32 s98, s54, s10
	s_addc_u32 s99, s55, s11
	s_sub_u32 s98, s98, 0x80000
	s_subb_u32 s99, s99, 0
	s_mov_b32 m0, s101
	s_nop 0
	global_load_lds_dwordx4 v140, s[34:35]
	s_add_i32 m0, s101, 0x2000
	s_nop 0
	global_load_lds_dwordx4 v144, s[34:35]
	s_mov_b32 m0, s70
	s_nop 0
	global_load_lds_dwordx4 v138, s[98:99]
	s_mov_b32 m0, s71
	s_nop 0
	global_load_lds_dwordx4 v142, s[98:99]
	s_waitcnt vmcnt(8)
	s_waitcnt lgkmcnt(0)
	s_barrier
	s_waitcnt lgkmcnt(0)
	v_mfma_f32_16x16x32_bf16 v[62:65], v[130:133], v[190:193], v[62:65]
	v_mfma_f32_16x16x32_bf16 v[58:61], v[158:161], v[190:193], v[58:61]
	v_mfma_f32_16x16x32_bf16 v[54:57], v[130:133], v[198:201], v[54:57]
	v_mfma_f32_16x16x32_bf16 v[46:49], v[158:161], v[198:201], v[46:49]
	v_mfma_f32_16x16x32_bf16 v[38:41], v[130:133], v[206:209], v[38:41]
	v_mfma_f32_16x16x32_bf16 v[30:33], v[158:161], v[206:209], v[30:33]
	v_mfma_f32_16x16x32_bf16 v[22:25], v[130:133], v[214:217], v[22:25]
	v_mfma_f32_16x16x32_bf16 v[14:17], v[158:161], v[214:217], v[14:17]
	v_mfma_f32_16x16x32_bf16 v[62:65], v[134:137], v[194:197], v[62:65]
	v_mfma_f32_16x16x32_bf16 v[58:61], v[170:173], v[194:197], v[58:61]
	v_mfma_f32_16x16x32_bf16 v[54:57], v[134:137], v[202:205], v[54:57]
	v_mfma_f32_16x16x32_bf16 v[46:49], v[170:173], v[202:205], v[46:49]
	v_mfma_f32_16x16x32_bf16 v[38:41], v[134:137], v[210:213], v[38:41]
	v_mfma_f32_16x16x32_bf16 v[30:33], v[170:173], v[210:213], v[30:33]
	v_mfma_f32_16x16x32_bf16 v[22:25], v[134:137], v[218:221], v[22:25]
	v_mfma_f32_16x16x32_bf16 v[14:17], v[170:173], v[218:221], v[14:17]
	v_mfma_f32_16x16x32_bf16 v[50:53], v[174:177], v[190:193], v[50:53]
	v_mfma_f32_16x16x32_bf16 v[42:45], v[182:185], v[190:193], v[42:45]
	v_mfma_f32_16x16x32_bf16 v[34:37], v[174:177], v[198:201], v[34:37]
	v_mfma_f32_16x16x32_bf16 v[26:29], v[182:185], v[198:201], v[26:29]
	v_mfma_f32_16x16x32_bf16 v[18:21], v[174:177], v[206:209], v[18:21]
	v_mfma_f32_16x16x32_bf16 v[10:13], v[182:185], v[206:209], v[10:13]
	v_mfma_f32_16x16x32_bf16 v[6:9], v[174:177], v[214:217], v[6:9]
	v_mfma_f32_16x16x32_bf16 v[2:5], v[182:185], v[214:217], v[2:5]
	v_mfma_f32_16x16x32_bf16 v[50:53], v[178:181], v[194:197], v[50:53]
	v_mfma_f32_16x16x32_bf16 v[42:45], v[186:189], v[194:197], v[42:45]
	v_mfma_f32_16x16x32_bf16 v[34:37], v[178:181], v[202:205], v[34:37]
	v_mfma_f32_16x16x32_bf16 v[26:29], v[186:189], v[202:205], v[26:29]
	v_mfma_f32_16x16x32_bf16 v[18:21], v[178:181], v[210:213], v[18:21]
	v_mfma_f32_16x16x32_bf16 v[10:13], v[186:189], v[210:213], v[10:13]
	v_mfma_f32_16x16x32_bf16 v[6:9], v[178:181], v[218:221], v[6:9]
	v_mfma_f32_16x16x32_bf16 v[2:5], v[186:189], v[218:221], v[2:5]
	s_barrier
	s_add_i32 s85, s85, 2
	s_add_u32 s52, s52, 0x100
	s_addc_u32 s53, s53, 0
	s_add_u32 s83, s83, 0x100
	s_addc_u32 s84, s84, 0
	s_cmp_gt_u32 s85, 29
	s_cbranch_scc1 .Lpx_2
; #define PG8_STAGE(bufoff, gbase, voff) do { _Pragma("unroll") for (int _i = 0; _i < 2; ++_i) \
;         __builtin_amdgcn_global_load_lds((const unsigned*)((const char*)(gbase) + (voff)[_i]), (PG8_LAS unsigned*)(lds + (bufoff) + ldsw + _i * 8192), 16, 0, 0); } while (0)
; #define PG8_LDA(dst, b, h) do { _Pragma("unroll") for (int m = 0; m < 4; ++m) _Pragma("unroll") for (int k = 0; k < 2; ++k) dst[m][k] = *(const PG8_LAS bf16x8*)(lds + PG8_SA(b, h) + aoff + m * 2048 + k * 1024); } while (0)
; #define PG8_LDB(dst, b, h) do { _Pragma("unroll") for (int n = 0; n < 2; ++n) _Pragma("unroll") for (int k = 0; k < 2; ++k) dst[n][k] = *(const PG8_LAS bf16x8*)(lds + PG8_SB(b, h) + boff + n * 2048 + k * 1024); } while (0)
; #define PG8_WAIT_V(n) asm volatile("s_waitcnt vmcnt(" #n ")" ::: "memory")
; #define PG8_WAIT_L(n) asm volatile("s_waitcnt lgkmcnt(" #n ")" ::: "memory")
; #define PG8_BAR __builtin_amdgcn_s_barrier()
; #define PG8_SCHED __builtin_amdgcn_sched_barrier(0)
; #define PG8_BAR __builtin_amdgcn_s_barrier()
; template <class Epi, class Sched, bool ALIGN_EPI = false>
; __device__ __forceinline__ void gemm_phase(PG8_LAS unsigned char* lds, const Gemm g, const Sched& S, const Epi& E) {
;     ...
;         for (int t = 0; t < nt; t += 2) {
;             const bool last = (t == nt - 2);
;             const char* a1 = cA + (size_t)(t + 1) * kstep;
;             const char* a2 = last ? nA : cA + (size_t)(t + 2) * kstep; const char* b2 = last ? nB : cB + (size_t)(t + 2) * kstep;
;             const char* a3 = a2 + kstep; const char* b3 = b2 + kstep;
;             if (last && has_next) S.a_ready(nxt);
;             PG8_LDB(B0, 0, 0); PG8_LDB(B1, 0, 1); PG8_SCHED; PG8_LDA(At, 0, 0); PG8_STAGE(PG8_SA(1, 1), a1 + hstepA, voffA);
;             PG8_WAIT_V(8); PG8_WAIT_L(0); PG8_BAR; PG8_MMA(0, 0, At, B0); PG8_MMA(0, 1, At, B1); PG8_BAR; PG8_SCHED;
;             PG8_LDA(At, 0, 1); PG8_STAGE(PG8_SB(0, 0), b2, voffB); PG8_STAGE(PG8_SB(0, 1), b2 + hstepB, voffB); PG8_STAGE(PG8_SA(0, 0), a2, voffA);
;             PG8_WAIT_V(8); PG8_WAIT_L(0); PG8_BAR; PG8_MMA(1, 0, At, B0); PG8_MMA(1, 1, At, B1); PG8_BAR; PG8_SCHED;
;             PG8_LDB(B0, 1, 0); PG8_LDB(B1, 1, 1); PG8_SCHED; PG8_LDA(At, 1, 0); PG8_STAGE(PG8_SA(0, 1), a2 + hstepA, voffA);
;             PG8_WAIT_V(8); PG8_WAIT_L(0); PG8_BAR; PG8_MMA(0, 0, At, B0); PG8_MMA(0, 1, At, B1); PG8_BAR; PG8_SCHED;
.LBB0_734:
	ds_read_b128 v[130:133], v165
	ds_read_b128 v[134:137], v165 offset:1024
	ds_read_b128 v[158:161], v165 offset:2048
	ds_read_b128 v[170:173], v165 offset:3072
	ds_read_b128 v[174:177], v166
	ds_read_b128 v[178:181], v166 offset:1024
	ds_read_b128 v[182:185], v166 offset:2048
	ds_read_b128 v[186:189], v166 offset:3072
	s_add_u32 s34, s52, 0xfff80080
	s_addc_u32 s35, s53, -1
	s_cmp_eq_u32 s85, 28
	s_cselect_b32 s55, s13, s35
	s_cselect_b32 s54, s27, s34
	s_cselect_b32 s35, s25, s84
	s_cselect_b32 s34, s82, s83
	s_add_i32 m0, s61, 0xc000
	ds_read_b128 v[190:193], v167
	ds_read_b128 v[194:197], v167 offset:1024
	ds_read_b128 v[198:201], v167 offset:2048
	ds_read_b128 v[202:205], v167 offset:3072
	ds_read_b128 v[206:209], v167 offset:4096
	ds_read_b128 v[210:213], v167 offset:5120
	ds_read_b128 v[214:217], v167 offset:6144
	ds_read_b128 v[218:221], v167 offset:7168
	global_load_lds_dwordx4 v150, s[52:53]
	s_add_i32 m0, s61, 0xe000
	s_nop 0
	global_load_lds_dwordx4 v152, s[52:53]
	s_waitcnt vmcnt(8)
	s_waitcnt lgkmcnt(0)
	s_barrier
	s_waitcnt lgkmcnt(0)
	v_mfma_f32_16x16x32_bf16 v[126:129], v[130:133], v[190:193], v[126:129]
	v_mfma_f32_16x16x32_bf16 v[122:125], v[158:161], v[190:193], v[122:125]
	v_mfma_f32_16x16x32_bf16 v[114:117], v[130:133], v[198:201], v[114:117]
	v_mfma_f32_16x16x32_bf16 v[106:109], v[158:161], v[198:201], v[106:109]
	v_mfma_f32_16x16x32_bf16 v[98:101], v[130:133], v[206:209], v[98:101]
	v_mfma_f32_16x16x32_bf16 v[90:93], v[158:161], v[206:209], v[90:93]
	v_mfma_f32_16x16x32_bf16 v[82:85], v[130:133], v[214:217], v[82:85]
	v_mfma_f32_16x16x32_bf16 v[74:77], v[158:161], v[214:217], v[74:77]
	v_mfma_f32_16x16x32_bf16 v[126:129], v[134:137], v[194:197], v[126:129]
	v_mfma_f32_16x16x32_bf16 v[122:125], v[170:173], v[194:197], v[122:125]
	v_mfma_f32_16x16x32_bf16 v[114:117], v[134:137], v[202:205], v[114:117]
	v_mfma_f32_16x16x32_bf16 v[106:109], v[170:173], v[202:205], v[106:109]
	v_mfma_f32_16x16x32_bf16 v[98:101], v[134:137], v[210:213], v[98:101]
	v_mfma_f32_16x16x32_bf16 v[90:93], v[170:173], v[210:213], v[90:93]
	v_mfma_f32_16x16x32_bf16 v[82:85], v[134:137], v[218:221], v[82:85]
	v_mfma_f32_16x16x32_bf16 v[74:77], v[170:173], v[218:221], v[74:77]
	v_mfma_f32_16x16x32_bf16 v[118:121], v[174:177], v[190:193], v[118:121]
	v_mfma_f32_16x16x32_bf16 v[110:113], v[182:185], v[190:193], v[110:113]
	v_mfma_f32_16x16x32_bf16 v[102:105], v[174:177], v[198:201], v[102:105]
	v_mfma_f32_16x16x32_bf16 v[94:97], v[182:185], v[198:201], v[94:97]
	v_mfma_f32_16x16x32_bf16 v[86:89], v[174:177], v[206:209], v[86:89]
	v_mfma_f32_16x16x32_bf16 v[78:81], v[182:185], v[206:209], v[78:81]
	v_mfma_f32_16x16x32_bf16 v[70:73], v[174:177], v[214:217], v[70:73]
	v_mfma_f32_16x16x32_bf16 v[66:69], v[182:185], v[214:217], v[66:69]
	v_mfma_f32_16x16x32_bf16 v[118:121], v[178:181], v[194:197], v[118:121]
	v_mfma_f32_16x16x32_bf16 v[110:113], v[186:189], v[194:197], v[110:113]
	v_mfma_f32_16x16x32_bf16 v[102:105], v[178:181], v[202:205], v[102:105]
	v_mfma_f32_16x16x32_bf16 v[94:97], v[186:189], v[202:205], v[94:97]
	v_mfma_f32_16x16x32_bf16 v[86:89], v[178:181], v[210:213], v[86:89]
	v_mfma_f32_16x16x32_bf16 v[78:81], v[186:189], v[210:213], v[78:81]
	v_mfma_f32_16x16x32_bf16 v[70:73], v[178:181], v[218:221], v[70:73]
	v_mfma_f32_16x16x32_bf16 v[66:69], v[186:189], v[218:221], v[66:69]
	s_barrier
	s_add_i32 s88, s72, s58
	s_mov_b32 m0, s88
	ds_read_b128 v[190:193], v167 offset:16384
	ds_read_b128 v[194:197], v167 offset:17408
	ds_read_b128 v[198:201], v167 offset:18432
	ds_read_b128 v[202:205], v167 offset:19456
	ds_read_b128 v[206:209], v167 offset:20480
	ds_read_b128 v[210:213], v167 offset:21504
	ds_read_b128 v[214:217], v167 offset:22528
	ds_read_b128 v[218:221], v167 offset:23552
	global_load_lds_dwordx4 v140, s[34:35]
	s_add_i32 m0, s88, 0x2000
	s_add_u32 s88, s34, 0x80000
	s_addc_u32 s89, s35, 0
	s_add_i32 s90, s73, s58
	global_load_lds_dwordx4 v144, s[34:35]
	s_mov_b32 m0, s90
	s_nop 0
	global_load_lds_dwordx4 v140, s[88:89]
	s_add_i32 m0, s90, 0x2000
	s_nop 0
	global_load_lds_dwordx4 v144, s[88:89]
	s_mov_b32 m0, s61
	s_nop 0
	global_load_lds_dwordx4 v138, s[54:55]
	s_mov_b32 m0, s62
	s_nop 0
	global_load_lds_dwordx4 v142, s[54:55]
	s_waitcnt vmcnt(8)
	s_waitcnt lgkmcnt(0)
	s_barrier
	s_waitcnt lgkmcnt(0)
	v_mfma_f32_16x16x32_bf16 v[62:65], v[130:133], v[190:193], v[62:65]
	v_mfma_f32_16x16x32_bf16 v[58:61], v[158:161], v[190:193], v[58:61]
	v_mfma_f32_16x16x32_bf16 v[54:57], v[130:133], v[198:201], v[54:57]
	v_mfma_f32_16x16x32_bf16 v[46:49], v[158:161], v[198:201], v[46:49]
	v_mfma_f32_16x16x32_bf16 v[38:41], v[130:133], v[206:209], v[38:41]
	v_mfma_f32_16x16x32_bf16 v[30:33], v[158:161], v[206:209], v[30:33]
	v_mfma_f32_16x16x32_bf16 v[22:25], v[130:133], v[214:217], v[22:25]
	v_mfma_f32_16x16x32_bf16 v[14:17], v[158:161], v[214:217], v[14:17]
	v_mfma_f32_16x16x32_bf16 v[62:65], v[134:137], v[194:197], v[62:65]
	v_mfma_f32_16x16x32_bf16 v[58:61], v[170:173], v[194:197], v[58:61]
	v_mfma_f32_16x16x32_bf16 v[54:57], v[134:137], v[202:205], v[54:57]
	v_mfma_f32_16x16x32_bf16 v[46:49], v[170:173], v[202:205], v[46:49]
	v_mfma_f32_16x16x32_bf16 v[38:41], v[134:137], v[210:213], v[38:41]
	v_mfma_f32_16x16x32_bf16 v[30:33], v[170:173], v[210:213], v[30:33]
	v_mfma_f32_16x16x32_bf16 v[22:25], v[134:137], v[218:221], v[22:25]
	v_mfma_f32_16x16x32_bf16 v[14:17], v[170:173], v[218:221], v[14:17]
	v_mfma_f32_16x16x32_bf16 v[50:53], v[174:177], v[190:193], v[50:53]
	v_mfma_f32_16x16x32_bf16 v[42:45], v[182:185], v[190:193], v[42:45]
	v_mfma_f32_16x16x32_bf16 v[34:37], v[174:177], v[198:201], v[34:37]
	v_mfma_f32_16x16x32_bf16 v[26:29], v[182:185], v[198:201], v[26:29]
	v_mfma_f32_16x16x32_bf16 v[18:21], v[174:177], v[206:209], v[18:21]
	v_mfma_f32_16x16x32_bf16 v[10:13], v[182:185], v[206:209], v[10:13]
	v_mfma_f32_16x16x32_bf16 v[6:9], v[174:177], v[214:217], v[6:9]
	v_mfma_f32_16x16x32_bf16 v[2:5], v[182:185], v[214:217], v[2:5]
	v_mfma_f32_16x16x32_bf16 v[50:53], v[178:181], v[194:197], v[50:53]
	v_mfma_f32_16x16x32_bf16 v[42:45], v[186:189], v[194:197], v[42:45]
	v_mfma_f32_16x16x32_bf16 v[34:37], v[178:181], v[202:205], v[34:37]
	v_mfma_f32_16x16x32_bf16 v[26:29], v[186:189], v[202:205], v[26:29]
	v_mfma_f32_16x16x32_bf16 v[18:21], v[178:181], v[210:213], v[18:21]
	v_mfma_f32_16x16x32_bf16 v[10:13], v[186:189], v[210:213], v[10:13]
	v_mfma_f32_16x16x32_bf16 v[6:9], v[178:181], v[218:221], v[6:9]
	v_mfma_f32_16x16x32_bf16 v[2:5], v[186:189], v[218:221], v[2:5]
	s_barrier
; #define PG8_STAGE(bufoff, gbase, voff) do { _Pragma("unroll") for (int _i = 0; _i < 2; ++_i) \
;         __builtin_amdgcn_global_load_lds((const unsigned*)((const char*)(gbase) + (voff)[_i]), (PG8_LAS unsigned*)(lds + (bufoff) + ldsw + _i * 8192), 16, 0, 0); } while (0)
; #define PG8_LDA(dst, b, h) do { _Pragma("unroll") for (int m = 0; m < 4; ++m) _Pragma("unroll") for (int k = 0; k < 2; ++k) dst[m][k] = *(const PG8_LAS bf16x8*)(lds + PG8_SA(b, h) + aoff + m * 2048 + k * 1024); } while (0)
; #define PG8_LDB(dst, b, h) do { _Pragma("unroll") for (int n = 0; n < 2; ++n) _Pragma("unroll") for (int k = 0; k < 2; ++k) dst[n][k] = *(const PG8_LAS bf16x8*)(lds + PG8_SB(b, h) + boff + n * 2048 + k * 1024); } while (0)
; #define PG8_MMA(ai, bj, At, Bt) do { __builtin_amdgcn_s_setprio(1); _Pragma("unroll") for (int m = 0; m < 4; ++m) _Pragma("unroll") for (int n = 0; n < 2; ++n) _Pragma("unroll") for (int k = 0; k < 2; ++k) \
;         acc[ai][bj][m][n] = __builtin_amdgcn_mfma_f32_16x16x32_bf16(Bt[n][k], At[m][k], acc[ai][bj][m][n], 0, 0, 0); __builtin_amdgcn_s_setprio(0); } while (0)
; #define PG8_WAIT_V(n) asm volatile("s_waitcnt vmcnt(" #n ")" ::: "memory")
; #define PG8_WAIT_L(n) asm volatile("s_waitcnt lgkmcnt(" #n ")" ::: "memory")
; #define PG8_BAR __builtin_amdgcn_s_barrier()
; #define PG8_SCHED __builtin_amdgcn_sched_barrier(0)
; #define PG8_STAGE(bufoff, gbase, voff) do { _Pragma("unroll") for (int _i = 0; _i < 2; ++_i) \
;         __builtin_amdgcn_global_load_lds((const unsigned*)((const char*)(gbase) + (voff)[_i]), (PG8_LAS unsigned*)(lds + (bufoff) + ldsw + _i * 8192), 16, 0, 0); } while (0)
; #define PG8_WAIT_V(n) asm volatile("s_waitcnt vmcnt(" #n ")" ::: "memory")
; template <class Epi, class Sched, bool ALIGN_EPI = false>
; __device__ __forceinline__ void gemm_phase(PG8_LAS unsigned char* lds, const Gemm g, const Sched& S, const Epi& E) {
;     ...
;             PG8_LDB(B0, 1, 0); PG8_LDB(B1, 1, 1); PG8_SCHED; PG8_LDA(At, 1, 0); PG8_STAGE(PG8_SA(0, 1), a2 + hstepA, voffA);
;             PG8_WAIT_V(8); PG8_WAIT_L(0); PG8_BAR; PG8_MMA(0, 0, At, B0); PG8_MMA(0, 1, At, B1); PG8_BAR; PG8_SCHED;
;             PG8_LDA(At, 1, 1); PG8_STAGE(PG8_SB(1, 0), b3, voffB); PG8_STAGE(PG8_SB(1, 1), b3 + hstepB, voffB); PG8_STAGE(PG8_SA(1, 0), a3, voffA);
;             PG8_WAIT_V(8); PG8_WAIT_L(0); PG8_BAR; PG8_MMA(1, 0, At, B0); PG8_MMA(1, 1, At, B1); PG8_BAR; PG8_SCHED;
	s_add_i32 s88, 0, 0x18000
	v_add_u32_e32 v146, s88, v164
	s_add_i32 s89, 0, 0x1c000
	ds_read_b128 v[130:133], v146
	ds_read_b128 v[134:137], v146 offset:1024
	ds_read_b128 v[158:161], v146 offset:2048
	ds_read_b128 v[170:173], v146 offset:3072
	v_add_u32_e32 v146, s89, v164
	ds_read_b128 v[174:177], v146
	ds_read_b128 v[178:181], v146 offset:1024
	ds_read_b128 v[182:185], v146 offset:2048
	ds_read_b128 v[186:189], v146 offset:3072
	s_add_u32 s54, s54, 0x80000
	s_addc_u32 s55, s55, 0
	s_mov_b32 m0, s63
	ds_read_b128 v[190:193], v167 offset:32768
	ds_read_b128 v[194:197], v167 offset:33792
	ds_read_b128 v[198:201], v167 offset:34816
	ds_read_b128 v[202:205], v167 offset:35840
	ds_read_b128 v[206:209], v167 offset:36864
	ds_read_b128 v[210:213], v167 offset:37888
	ds_read_b128 v[214:217], v167 offset:38912
	ds_read_b128 v[218:221], v167 offset:39936
	global_load_lds_dwordx4 v138, s[54:55]
	s_mov_b32 m0, s64
	s_nop 0
	global_load_lds_dwordx4 v142, s[54:55]
	s_waitcnt vmcnt(8)
	s_waitcnt lgkmcnt(0)
	s_barrier
	s_waitcnt lgkmcnt(0)
	v_mfma_f32_16x16x32_bf16 v[126:129], v[130:133], v[190:193], v[126:129]
	v_mfma_f32_16x16x32_bf16 v[122:125], v[158:161], v[190:193], v[122:125]
	v_mfma_f32_16x16x32_bf16 v[114:117], v[130:133], v[198:201], v[114:117]
	v_mfma_f32_16x16x32_bf16 v[106:109], v[158:161], v[198:201], v[106:109]
	v_mfma_f32_16x16x32_bf16 v[98:101], v[130:133], v[206:209], v[98:101]
	v_mfma_f32_16x16x32_bf16 v[90:93], v[158:161], v[206:209], v[90:93]
	v_mfma_f32_16x16x32_bf16 v[82:85], v[130:133], v[214:217], v[82:85]
	v_mfma_f32_16x16x32_bf16 v[74:77], v[158:161], v[214:217], v[74:77]
	v_mfma_f32_16x16x32_bf16 v[126:129], v[134:137], v[194:197], v[126:129]
	v_mfma_f32_16x16x32_bf16 v[122:125], v[170:173], v[194:197], v[122:125]
	v_mfma_f32_16x16x32_bf16 v[114:117], v[134:137], v[202:205], v[114:117]
	v_mfma_f32_16x16x32_bf16 v[106:109], v[170:173], v[202:205], v[106:109]
	v_mfma_f32_16x16x32_bf16 v[98:101], v[134:137], v[210:213], v[98:101]
	v_mfma_f32_16x16x32_bf16 v[90:93], v[170:173], v[210:213], v[90:93]
	v_mfma_f32_16x16x32_bf16 v[82:85], v[134:137], v[218:221], v[82:85]
	v_mfma_f32_16x16x32_bf16 v[74:77], v[170:173], v[218:221], v[74:77]
	v_mfma_f32_16x16x32_bf16 v[118:121], v[174:177], v[190:193], v[118:121]
	v_mfma_f32_16x16x32_bf16 v[110:113], v[182:185], v[190:193], v[110:113]
	v_mfma_f32_16x16x32_bf16 v[102:105], v[174:177], v[198:201], v[102:105]
	v_mfma_f32_16x16x32_bf16 v[94:97], v[182:185], v[198:201], v[94:97]
	v_mfma_f32_16x16x32_bf16 v[86:89], v[174:177], v[206:209], v[86:89]
	v_mfma_f32_16x16x32_bf16 v[78:81], v[182:185], v[206:209], v[78:81]
	v_mfma_f32_16x16x32_bf16 v[70:73], v[174:177], v[214:217], v[70:73]
	v_mfma_f32_16x16x32_bf16 v[66:69], v[182:185], v[214:217], v[66:69]
	v_mfma_f32_16x16x32_bf16 v[118:121], v[178:181], v[194:197], v[118:121]
	v_mfma_f32_16x16x32_bf16 v[110:113], v[186:189], v[194:197], v[110:113]
	v_mfma_f32_16x16x32_bf16 v[102:105], v[178:181], v[202:205], v[102:105]
	v_mfma_f32_16x16x32_bf16 v[94:97], v[186:189], v[202:205], v[94:97]
	v_mfma_f32_16x16x32_bf16 v[86:89], v[178:181], v[210:213], v[86:89]
	v_mfma_f32_16x16x32_bf16 v[78:81], v[186:189], v[210:213], v[78:81]
	v_mfma_f32_16x16x32_bf16 v[70:73], v[178:181], v[218:221], v[70:73]
	v_mfma_f32_16x16x32_bf16 v[66:69], v[186:189], v[218:221], v[66:69]
	s_barrier
	s_add_i32 s101, s88, s58
	s_add_u32 s98, s34, s10
	s_addc_u32 s99, s35, s11
	s_mov_b32 m0, s101
	ds_read_b128 v[190:193], v167 offset:49152
	ds_read_b128 v[194:197], v167 offset:50176
	ds_read_b128 v[198:201], v167 offset:51200
	ds_read_b128 v[202:205], v167 offset:52224
	ds_read_b128 v[206:209], v167 offset:53248
	ds_read_b128 v[210:213], v167 offset:54272
	ds_read_b128 v[214:217], v167 offset:55296
	ds_read_b128 v[218:221], v167 offset:56320
	global_load_lds_dwordx4 v140, s[98:99]
	s_add_i32 m0, s101, 0x2000
	s_add_u32 s34, s34, 0x80080
	s_addc_u32 s35, s35, 0
	s_add_i32 s101, s89, s58
	global_load_lds_dwordx4 v144, s[98:99]
	s_add_u32 s98, s54, s10
	s_addc_u32 s99, s55, s11
	s_sub_u32 s98, s98, 0x80000
	s_subb_u32 s99, s99, 0
	s_mov_b32 m0, s101
	s_nop 0
	global_load_lds_dwordx4 v140, s[34:35]
	s_add_i32 m0, s101, 0x2000
	s_nop 0
	global_load_lds_dwordx4 v144, s[34:35]
	s_mov_b32 m0, s70
	s_nop 0
	global_load_lds_dwordx4 v138, s[98:99]
	s_mov_b32 m0, s71
	s_nop 0
	global_load_lds_dwordx4 v142, s[98:99]
	s_waitcnt vmcnt(8)
	s_waitcnt lgkmcnt(0)
	s_barrier
	s_waitcnt lgkmcnt(0)
	v_mfma_f32_16x16x32_bf16 v[62:65], v[130:133], v[190:193], v[62:65]
	v_mfma_f32_16x16x32_bf16 v[58:61], v[158:161], v[190:193], v[58:61]
	v_mfma_f32_16x16x32_bf16 v[54:57], v[130:133], v[198:201], v[54:57]
	v_mfma_f32_16x16x32_bf16 v[46:49], v[158:161], v[198:201], v[46:49]
	v_mfma_f32_16x16x32_bf16 v[38:41], v[130:133], v[206:209], v[38:41]
	v_mfma_f32_16x16x32_bf16 v[30:33], v[158:161], v[206:209], v[30:33]
	v_mfma_f32_16x16x32_bf16 v[22:25], v[130:133], v[214:217], v[22:25]
	v_mfma_f32_16x16x32_bf16 v[14:17], v[158:161], v[214:217], v[14:17]
	v_mfma_f32_16x16x32_bf16 v[62:65], v[134:137], v[194:197], v[62:65]
	v_mfma_f32_16x16x32_bf16 v[58:61], v[170:173], v[194:197], v[58:61]
	v_mfma_f32_16x16x32_bf16 v[54:57], v[134:137], v[202:205], v[54:57]
	v_mfma_f32_16x16x32_bf16 v[46:49], v[170:173], v[202:205], v[46:49]
	v_mfma_f32_16x16x32_bf16 v[38:41], v[134:137], v[210:213], v[38:41]
	v_mfma_f32_16x16x32_bf16 v[30:33], v[170:173], v[210:213], v[30:33]
	v_mfma_f32_16x16x32_bf16 v[22:25], v[134:137], v[218:221], v[22:25]
	v_mfma_f32_16x16x32_bf16 v[14:17], v[170:173], v[218:221], v[14:17]
	v_mfma_f32_16x16x32_bf16 v[50:53], v[174:177], v[190:193], v[50:53]
	v_mfma_f32_16x16x32_bf16 v[42:45], v[182:185], v[190:193], v[42:45]
	v_mfma_f32_16x16x32_bf16 v[34:37], v[174:177], v[198:201], v[34:37]
	v_mfma_f32_16x16x32_bf16 v[26:29], v[182:185], v[198:201], v[26:29]
	v_mfma_f32_16x16x32_bf16 v[18:21], v[174:177], v[206:209], v[18:21]
	v_mfma_f32_16x16x32_bf16 v[10:13], v[182:185], v[206:209], v[10:13]
	v_mfma_f32_16x16x32_bf16 v[6:9], v[174:177], v[214:217], v[6:9]
	v_mfma_f32_16x16x32_bf16 v[2:5], v[182:185], v[214:217], v[2:5]
	v_mfma_f32_16x16x32_bf16 v[50:53], v[178:181], v[194:197], v[50:53]
	v_mfma_f32_16x16x32_bf16 v[42:45], v[186:189], v[194:197], v[42:45]
	v_mfma_f32_16x16x32_bf16 v[34:37], v[178:181], v[202:205], v[34:37]
	v_mfma_f32_16x16x32_bf16 v[26:29], v[186:189], v[202:205], v[26:29]
	v_mfma_f32_16x16x32_bf16 v[18:21], v[178:181], v[210:213], v[18:21]
	v_mfma_f32_16x16x32_bf16 v[10:13], v[186:189], v[210:213], v[10:13]
	v_mfma_f32_16x16x32_bf16 v[6:9], v[178:181], v[218:221], v[6:9]
	v_mfma_f32_16x16x32_bf16 v[2:5], v[186:189], v[218:221], v[2:5]
	s_barrier
; #define PG8_STAGE(bufoff, gbase, voff) do { _Pragma("unroll") for (int _i = 0; _i < 2; ++_i) \
;         __builtin_amdgcn_global_load_lds((const unsigned*)((const char*)(gbase) + (voff)[_i]), (PG8_LAS unsigned*)(lds + (bufoff) + ldsw + _i * 8192), 16, 0, 0); } while (0)
; #define PG8_LDA(dst, b, h) do { _Pragma("unroll") for (int m = 0; m < 4; ++m) _Pragma("unroll") for (int k = 0; k < 2; ++k) dst[m][k] = *(const PG8_LAS bf16x8*)(lds + PG8_SA(b, h) + aoff + m * 2048 + k * 1024); } while (0)
; #define PG8_LDB(dst, b, h) do { _Pragma("unroll") for (int n = 0; n < 2; ++n) _Pragma("unroll") for (int k = 0; k < 2; ++k) dst[n][k] = *(const PG8_LAS bf16x8*)(lds + PG8_SB(b, h) + boff + n * 2048 + k * 1024); } while (0)
; #define PG8_MMA(ai, bj, At, Bt) do { __builtin_amdgcn_s_setprio(1); _Pragma("unroll") for (int m = 0; m < 4; ++m) _Pragma("unroll") for (int n = 0; n < 2; ++n) _Pragma("unroll") for (int k = 0; k < 2; ++k) \
;         acc[ai][bj][m][n] = __builtin_amdgcn_mfma_f32_16x16x32_bf16(Bt[n][k], At[m][k], acc[ai][bj][m][n], 0, 0, 0); __builtin_amdgcn_s_setprio(0); } while (0)
; #define PG8_WAIT_V(n) asm volatile("s_waitcnt vmcnt(" #n ")" ::: "memory")
; #define PG8_WAIT_L(n) asm volatile("s_waitcnt lgkmcnt(" #n ")" ::: "memory")
; #define PG8_BAR __builtin_amdgcn_s_barrier()
; template <class Epi, class Sched, bool ALIGN_EPI = false>
; __device__ __forceinline__ void gemm_phase(PG8_LAS unsigned char* lds, const Gemm g, const Sched& S, const Epi& E) {
;     ...
;         for (int t = 0; t < nt; t += 2) {
;             const bool last = (t == nt - 2);
;             const char* a1 = cA + (size_t)(t + 1) * kstep;
;             const char* a2 = last ? nA : cA + (size_t)(t + 2) * kstep; const char* b2 = last ? nB : cB + (size_t)(t + 2) * kstep;
;             const char* a3 = a2 + kstep; const char* b3 = b2 + kstep;
;             if (last && has_next) S.a_ready(nxt);
;             PG8_LDB(B0, 0, 0); PG8_LDB(B1, 0, 1); PG8_SCHED; PG8_LDA(At, 0, 0); PG8_STAGE(PG8_SA(1, 1), a1 + hstepA, voffA);
;             PG8_WAIT_V(8); PG8_WAIT_L(0); PG8_BAR; PG8_MMA(0, 0, At, B0); PG8_MMA(0, 1, At, B1); PG8_BAR; PG8_SCHED;
;             PG8_LDA(At, 0, 1); PG8_STAGE(PG8_SB(0, 0), b2, voffB); PG8_STAGE(PG8_SB(0, 1), b2 + hstepB, voffB); PG8_STAGE(PG8_SA(0, 0), a2, voffA);
;             PG8_WAIT_V(8); PG8_WAIT_L(0); PG8_BAR; PG8_MMA(1, 0, At, B0); PG8_MMA(1, 1, At, B1); PG8_BAR; PG8_SCHED;
	s_add_i32 s85, s85, 2
	s_add_u32 s52, s52, 0x100
	s_addc_u32 s53, s53, 0
	s_add_u32 s83, s83, 0x100
	s_addc_u32 s84, s84, 0
	s_cmp_gt_u32 s85, 29
	ds_read_b128 v[130:133], v165
	ds_read_b128 v[134:137], v165 offset:1024
	ds_read_b128 v[158:161], v165 offset:2048
	ds_read_b128 v[170:173], v165 offset:3072
	ds_read_b128 v[174:177], v166
	ds_read_b128 v[178:181], v166 offset:1024
	ds_read_b128 v[182:185], v166 offset:2048
	ds_read_b128 v[186:189], v166 offset:3072
	s_add_u32 s34, s52, 0xfff80080
	s_addc_u32 s35, s53, -1
	s_cmp_eq_u32 s85, 28
	s_cselect_b32 s55, s13, s35
	s_cselect_b32 s54, s27, s34
	s_cselect_b32 s35, s25, s84
	s_cselect_b32 s34, s82, s83
	s_add_i32 m0, s61, 0xc000
	ds_read_b128 v[190:193], v167
	ds_read_b128 v[194:197], v167 offset:1024
	ds_read_b128 v[198:201], v167 offset:2048
	ds_read_b128 v[202:205], v167 offset:3072
	ds_read_b128 v[206:209], v167 offset:4096
	ds_read_b128 v[210:213], v167 offset:5120
	ds_read_b128 v[214:217], v167 offset:6144
	ds_read_b128 v[218:221], v167 offset:7168
	global_load_lds_dwordx4 v150, s[52:53]
	s_add_i32 m0, s61, 0xe000
	s_nop 0
	global_load_lds_dwordx4 v152, s[52:53]
	s_waitcnt vmcnt(8)
	s_waitcnt lgkmcnt(0)
	s_barrier
	s_waitcnt lgkmcnt(0)
	v_mfma_f32_16x16x32_bf16 v[126:129], v[130:133], v[190:193], v[126:129]
	v_mfma_f32_16x16x32_bf16 v[122:125], v[158:161], v[190:193], v[122:125]
	v_mfma_f32_16x16x32_bf16 v[114:117], v[130:133], v[198:201], v[114:117]
	v_mfma_f32_16x16x32_bf16 v[106:109], v[158:161], v[198:201], v[106:109]
	v_mfma_f32_16x16x32_bf16 v[98:101], v[130:133], v[206:209], v[98:101]
	v_mfma_f32_16x16x32_bf16 v[90:93], v[158:161], v[206:209], v[90:93]
	v_mfma_f32_16x16x32_bf16 v[82:85], v[130:133], v[214:217], v[82:85]
	v_mfma_f32_16x16x32_bf16 v[74:77], v[158:161], v[214:217], v[74:77]
	v_mfma_f32_16x16x32_bf16 v[126:129], v[134:137], v[194:197], v[126:129]
	v_mfma_f32_16x16x32_bf16 v[122:125], v[170:173], v[194:197], v[122:125]
	v_mfma_f32_16x16x32_bf16 v[114:117], v[134:137], v[202:205], v[114:117]
	v_mfma_f32_16x16x32_bf16 v[106:109], v[170:173], v[202:205], v[106:109]
	v_mfma_f32_16x16x32_bf16 v[98:101], v[134:137], v[210:213], v[98:101]
	v_mfma_f32_16x16x32_bf16 v[90:93], v[170:173], v[210:213], v[90:93]
	v_mfma_f32_16x16x32_bf16 v[82:85], v[134:137], v[218:221], v[82:85]
	v_mfma_f32_16x16x32_bf16 v[74:77], v[170:173], v[218:221], v[74:77]
	v_mfma_f32_16x16x32_bf16 v[118:121], v[174:177], v[190:193], v[118:121]
	v_mfma_f32_16x16x32_bf16 v[110:113], v[182:185], v[190:193], v[110:113]
	v_mfma_f32_16x16x32_bf16 v[102:105], v[174:177], v[198:201], v[102:105]
	v_mfma_f32_16x16x32_bf16 v[94:97], v[182:185], v[198:201], v[94:97]
	v_mfma_f32_16x16x32_bf16 v[86:89], v[174:177], v[206:209], v[86:89]
	v_mfma_f32_16x16x32_bf16 v[78:81], v[182:185], v[206:209], v[78:81]
	v_mfma_f32_16x16x32_bf16 v[70:73], v[174:177], v[214:217], v[70:73]
	v_mfma_f32_16x16x32_bf16 v[66:69], v[182:185], v[214:217], v[66:69]
	v_mfma_f32_16x16x32_bf16 v[118:121], v[178:181], v[194:197], v[118:121]
	v_mfma_f32_16x16x32_bf16 v[110:113], v[186:189], v[194:197], v[110:113]
	v_mfma_f32_16x16x32_bf16 v[102:105], v[178:181], v[202:205], v[102:105]
	v_mfma_f32_16x16x32_bf16 v[94:97], v[186:189], v[202:205], v[94:97]
	v_mfma_f32_16x16x32_bf16 v[86:89], v[178:181], v[210:213], v[86:89]
	v_mfma_f32_16x16x32_bf16 v[78:81], v[186:189], v[210:213], v[78:81]
	v_mfma_f32_16x16x32_bf16 v[70:73], v[178:181], v[218:221], v[70:73]
	v_mfma_f32_16x16x32_bf16 v[66:69], v[186:189], v[218:221], v[66:69]
	s_barrier
	s_add_i32 s88, s72, s58
	s_mov_b32 m0, s88
	ds_read_b128 v[190:193], v167 offset:16384
	ds_read_b128 v[194:197], v167 offset:17408
	ds_read_b128 v[198:201], v167 offset:18432
	ds_read_b128 v[202:205], v167 offset:19456
	ds_read_b128 v[206:209], v167 offset:20480
	ds_read_b128 v[210:213], v167 offset:21504
	ds_read_b128 v[214:217], v167 offset:22528
	ds_read_b128 v[218:221], v167 offset:23552
	global_load_lds_dwordx4 v140, s[34:35]
	s_add_i32 m0, s88, 0x2000
	s_add_u32 s88, s34, 0x80000
	s_addc_u32 s89, s35, 0
	s_add_i32 s90, s73, s58
	global_load_lds_dwordx4 v144, s[34:35]
	s_mov_b32 m0, s90
	s_nop 0
	global_load_lds_dwordx4 v140, s[88:89]
	s_add_i32 m0, s90, 0x2000
	s_nop 0
	global_load_lds_dwordx4 v144, s[88:89]
	s_mov_b32 m0, s61
	s_nop 0
	global_load_lds_dwordx4 v138, s[54:55]
	s_mov_b32 m0, s62
	s_nop 0
	global_load_lds_dwordx4 v142, s[54:55]
	s_waitcnt vmcnt(8)
	s_waitcnt lgkmcnt(0)
	s_barrier
	s_waitcnt lgkmcnt(0)
	v_mfma_f32_16x16x32_bf16 v[62:65], v[130:133], v[190:193], v[62:65]
	v_mfma_f32_16x16x32_bf16 v[58:61], v[158:161], v[190:193], v[58:61]
	v_mfma_f32_16x16x32_bf16 v[54:57], v[130:133], v[198:201], v[54:57]
	v_mfma_f32_16x16x32_bf16 v[46:49], v[158:161], v[198:201], v[46:49]
	v_mfma_f32_16x16x32_bf16 v[38:41], v[130:133], v[206:209], v[38:41]
	v_mfma_f32_16x16x32_bf16 v[30:33], v[158:161], v[206:209], v[30:33]
	v_mfma_f32_16x16x32_bf16 v[22:25], v[130:133], v[214:217], v[22:25]
	v_mfma_f32_16x16x32_bf16 v[14:17], v[158:161], v[214:217], v[14:17]
	v_mfma_f32_16x16x32_bf16 v[62:65], v[134:137], v[194:197], v[62:65]
	v_mfma_f32_16x16x32_bf16 v[58:61], v[170:173], v[194:197], v[58:61]
	v_mfma_f32_16x16x32_bf16 v[54:57], v[134:137], v[202:205], v[54:57]
	v_mfma_f32_16x16x32_bf16 v[46:49], v[170:173], v[202:205], v[46:49]
	v_mfma_f32_16x16x32_bf16 v[38:41], v[134:137], v[210:213], v[38:41]
	v_mfma_f32_16x16x32_bf16 v[30:33], v[170:173], v[210:213], v[30:33]
	v_mfma_f32_16x16x32_bf16 v[22:25], v[134:137], v[218:221], v[22:25]
	v_mfma_f32_16x16x32_bf16 v[14:17], v[170:173], v[218:221], v[14:17]
	v_mfma_f32_16x16x32_bf16 v[50:53], v[174:177], v[190:193], v[50:53]
	v_mfma_f32_16x16x32_bf16 v[42:45], v[182:185], v[190:193], v[42:45]
	v_mfma_f32_16x16x32_bf16 v[34:37], v[174:177], v[198:201], v[34:37]
	v_mfma_f32_16x16x32_bf16 v[26:29], v[182:185], v[198:201], v[26:29]
	v_mfma_f32_16x16x32_bf16 v[18:21], v[174:177], v[206:209], v[18:21]
	v_mfma_f32_16x16x32_bf16 v[10:13], v[182:185], v[206:209], v[10:13]
	v_mfma_f32_16x16x32_bf16 v[6:9], v[174:177], v[214:217], v[6:9]
	v_mfma_f32_16x16x32_bf16 v[2:5], v[182:185], v[214:217], v[2:5]
	v_mfma_f32_16x16x32_bf16 v[50:53], v[178:181], v[194:197], v[50:53]
	v_mfma_f32_16x16x32_bf16 v[42:45], v[186:189], v[194:197], v[42:45]
	v_mfma_f32_16x16x32_bf16 v[34:37], v[178:181], v[202:205], v[34:37]
	v_mfma_f32_16x16x32_bf16 v[26:29], v[186:189], v[202:205], v[26:29]
	v_mfma_f32_16x16x32_bf16 v[18:21], v[178:181], v[210:213], v[18:21]
	v_mfma_f32_16x16x32_bf16 v[10:13], v[186:189], v[210:213], v[10:13]
	v_mfma_f32_16x16x32_bf16 v[6:9], v[178:181], v[218:221], v[6:9]
	v_mfma_f32_16x16x32_bf16 v[2:5], v[186:189], v[218:221], v[2:5]
	s_barrier
; #define PG8_STAGE(bufoff, gbase, voff) do { _Pragma("unroll") for (int _i = 0; _i < 2; ++_i) \
;         __builtin_amdgcn_global_load_lds((const unsigned*)((const char*)(gbase) + (voff)[_i]), (PG8_LAS unsigned*)(lds + (bufoff) + ldsw + _i * 8192), 16, 0, 0); } while (0)
; #define PG8_LDA(dst, b, h) do { _Pragma("unroll") for (int m = 0; m < 4; ++m) _Pragma("unroll") for (int k = 0; k < 2; ++k) dst[m][k] = *(const PG8_LAS bf16x8*)(lds + PG8_SA(b, h) + aoff + m * 2048 + k * 1024); } while (0)
; #define PG8_LDB(dst, b, h) do { _Pragma("unroll") for (int n = 0; n < 2; ++n) _Pragma("unroll") for (int k = 0; k < 2; ++k) dst[n][k] = *(const PG8_LAS bf16x8*)(lds + PG8_SB(b, h) + boff + n * 2048 + k * 1024); } while (0)
; #define PG8_MMA(ai, bj, At, Bt) do { __builtin_amdgcn_s_setprio(1); _Pragma("unroll") for (int m = 0; m < 4; ++m) _Pragma("unroll") for (int n = 0; n < 2; ++n) _Pragma("unroll") for (int k = 0; k < 2; ++k) \
;         acc[ai][bj][m][n] = __builtin_amdgcn_mfma_f32_16x16x32_bf16(Bt[n][k], At[m][k], acc[ai][bj][m][n], 0, 0, 0); __builtin_amdgcn_s_setprio(0); } while (0)
; #define PG8_WAIT_V(n) asm volatile("s_waitcnt vmcnt(" #n ")" ::: "memory")
; #define PG8_WAIT_L(n) asm volatile("s_waitcnt lgkmcnt(" #n ")" ::: "memory")
; #define PG8_BAR __builtin_amdgcn_s_barrier()
; #define PG8_SCHED __builtin_amdgcn_sched_barrier(0)
; #define PG8_STAGE(bufoff, gbase, voff) do { _Pragma("unroll") for (int _i = 0; _i < 2; ++_i) \
;         __builtin_amdgcn_global_load_lds((const unsigned*)((const char*)(gbase) + (voff)[_i]), (PG8_LAS unsigned*)(lds + (bufoff) + ldsw + _i * 8192), 16, 0, 0); } while (0)
; #define PG8_BAR __builtin_amdgcn_s_barrier()
; template <class Epi, class Sched, bool ALIGN_EPI = false>
; __device__ __forceinline__ void gemm_phase(PG8_LAS unsigned char* lds, const Gemm g, const Sched& S, const Epi& E) {
;     ...
;             PG8_LDB(B0, 1, 0); PG8_LDB(B1, 1, 1); PG8_SCHED; PG8_LDA(At, 1, 0); PG8_STAGE(PG8_SA(0, 1), a2 + hstepA, voffA);
;             PG8_WAIT_V(8); PG8_WAIT_L(0); PG8_BAR; PG8_MMA(0, 0, At, B0); PG8_MMA(0, 1, At, B1); PG8_BAR; PG8_SCHED;
;             PG8_LDA(At, 1, 1); PG8_STAGE(PG8_SB(1, 0), b3, voffB); PG8_STAGE(PG8_SB(1, 1), b3 + hstepB, voffB); PG8_STAGE(PG8_SA(1, 0), a3, voffA);
;             PG8_WAIT_V(8); PG8_WAIT_L(0); PG8_BAR; PG8_MMA(1, 0, At, B0); PG8_MMA(1, 1, At, B1); PG8_BAR; PG8_SCHED;
;         }
	s_add_i32 s88, 0, 0x18000
	v_add_u32_e32 v146, s88, v164
	s_add_i32 s89, 0, 0x1c000
	ds_read_b128 v[130:133], v146
	ds_read_b128 v[134:137], v146 offset:1024
	ds_read_b128 v[158:161], v146 offset:2048
	ds_read_b128 v[170:173], v146 offset:3072
	v_add_u32_e32 v146, s89, v164
	ds_read_b128 v[174:177], v146
	ds_read_b128 v[178:181], v146 offset:1024
	ds_read_b128 v[182:185], v146 offset:2048
	ds_read_b128 v[186:189], v146 offset:3072
	s_add_u32 s54, s54, 0x80000
	s_addc_u32 s55, s55, 0
	s_mov_b32 m0, s63
	ds_read_b128 v[190:193], v167 offset:32768
	ds_read_b128 v[194:197], v167 offset:33792
	ds_read_b128 v[198:201], v167 offset:34816
	ds_read_b128 v[202:205], v167 offset:35840
	ds_read_b128 v[206:209], v167 offset:36864
	ds_read_b128 v[210:213], v167 offset:37888
	ds_read_b128 v[214:217], v167 offset:38912
	ds_read_b128 v[218:221], v167 offset:39936
	global_load_lds_dwordx4 v138, s[54:55]
	s_mov_b32 m0, s64
	s_nop 0
	global_load_lds_dwordx4 v142, s[54:55]
	s_waitcnt vmcnt(8)
	s_waitcnt lgkmcnt(0)
	s_barrier
	s_waitcnt lgkmcnt(0)
	v_mfma_f32_16x16x32_bf16 v[126:129], v[130:133], v[190:193], v[126:129]
	v_mfma_f32_16x16x32_bf16 v[122:125], v[158:161], v[190:193], v[122:125]
	v_mfma_f32_16x16x32_bf16 v[114:117], v[130:133], v[198:201], v[114:117]
	v_mfma_f32_16x16x32_bf16 v[106:109], v[158:161], v[198:201], v[106:109]
	v_mfma_f32_16x16x32_bf16 v[98:101], v[130:133], v[206:209], v[98:101]
	v_mfma_f32_16x16x32_bf16 v[90:93], v[158:161], v[206:209], v[90:93]
	v_mfma_f32_16x16x32_bf16 v[82:85], v[130:133], v[214:217], v[82:85]
	v_mfma_f32_16x16x32_bf16 v[74:77], v[158:161], v[214:217], v[74:77]
	v_mfma_f32_16x16x32_bf16 v[126:129], v[134:137], v[194:197], v[126:129]
	v_mfma_f32_16x16x32_bf16 v[122:125], v[170:173], v[194:197], v[122:125]
	v_mfma_f32_16x16x32_bf16 v[114:117], v[134:137], v[202:205], v[114:117]
	v_mfma_f32_16x16x32_bf16 v[106:109], v[170:173], v[202:205], v[106:109]
	v_mfma_f32_16x16x32_bf16 v[98:101], v[134:137], v[210:213], v[98:101]
	v_mfma_f32_16x16x32_bf16 v[90:93], v[170:173], v[210:213], v[90:93]
	v_mfma_f32_16x16x32_bf16 v[82:85], v[134:137], v[218:221], v[82:85]
	v_mfma_f32_16x16x32_bf16 v[74:77], v[170:173], v[218:221], v[74:77]
	v_mfma_f32_16x16x32_bf16 v[118:121], v[174:177], v[190:193], v[118:121]
	v_mfma_f32_16x16x32_bf16 v[110:113], v[182:185], v[190:193], v[110:113]
	v_mfma_f32_16x16x32_bf16 v[102:105], v[174:177], v[198:201], v[102:105]
	v_mfma_f32_16x16x32_bf16 v[94:97], v[182:185], v[198:201], v[94:97]
	v_mfma_f32_16x16x32_bf16 v[86:89], v[174:177], v[206:209], v[86:89]
	v_mfma_f32_16x16x32_bf16 v[78:81], v[182:185], v[206:209], v[78:81]
	v_mfma_f32_16x16x32_bf16 v[70:73], v[174:177], v[214:217], v[70:73]
	v_mfma_f32_16x16x32_bf16 v[66:69], v[182:185], v[214:217], v[66:69]
	v_mfma_f32_16x16x32_bf16 v[118:121], v[178:181], v[194:197], v[118:121]
	v_mfma_f32_16x16x32_bf16 v[110:113], v[186:189], v[194:197], v[110:113]
	v_mfma_f32_16x16x32_bf16 v[102:105], v[178:181], v[202:205], v[102:105]
	v_mfma_f32_16x16x32_bf16 v[94:97], v[186:189], v[202:205], v[94:97]
	v_mfma_f32_16x16x32_bf16 v[86:89], v[178:181], v[210:213], v[86:89]
	v_mfma_f32_16x16x32_bf16 v[78:81], v[186:189], v[210:213], v[78:81]
	v_mfma_f32_16x16x32_bf16 v[70:73], v[178:181], v[218:221], v[70:73]
	v_mfma_f32_16x16x32_bf16 v[66:69], v[186:189], v[218:221], v[66:69]
	s_barrier
	s_add_i32 s101, s88, s58
	s_add_u32 s98, s34, s10
	s_addc_u32 s99, s35, s11
	s_mov_b32 m0, s101
	ds_read_b128 v[190:193], v167 offset:49152
	ds_read_b128 v[194:197], v167 offset:50176
	ds_read_b128 v[198:201], v167 offset:51200
	ds_read_b128 v[202:205], v167 offset:52224
	ds_read_b128 v[206:209], v167 offset:53248
	ds_read_b128 v[210:213], v167 offset:54272
	ds_read_b128 v[214:217], v167 offset:55296
	ds_read_b128 v[218:221], v167 offset:56320
	global_load_lds_dwordx4 v140, s[98:99]
	s_add_i32 m0, s101, 0x2000
	s_add_u32 s34, s34, 0x80080
	s_addc_u32 s35, s35, 0
	s_add_i32 s101, s89, s58
	global_load_lds_dwordx4 v144, s[98:99]
	s_add_u32 s98, s54, s10
	s_addc_u32 s99, s55, s11
	s_sub_u32 s98, s98, 0x80000
	s_subb_u32 s99, s99, 0
	s_mov_b32 m0, s101
	s_nop 0
	global_load_lds_dwordx4 v140, s[34:35]
	s_add_i32 m0, s101, 0x2000
	s_nop 0
	global_load_lds_dwordx4 v144, s[34:35]
	s_mov_b32 m0, s70
	s_nop 0
	global_load_lds_dwordx4 v138, s[98:99]
	s_mov_b32 m0, s71
	s_nop 0
	global_load_lds_dwordx4 v142, s[98:99]
	s_waitcnt vmcnt(8)
	s_waitcnt lgkmcnt(0)
	s_barrier
	s_waitcnt lgkmcnt(0)
	v_mfma_f32_16x16x32_bf16 v[62:65], v[130:133], v[190:193], v[62:65]
	v_mfma_f32_16x16x32_bf16 v[58:61], v[158:161], v[190:193], v[58:61]
	v_mfma_f32_16x16x32_bf16 v[54:57], v[130:133], v[198:201], v[54:57]
	v_mfma_f32_16x16x32_bf16 v[46:49], v[158:161], v[198:201], v[46:49]
	v_mfma_f32_16x16x32_bf16 v[38:41], v[130:133], v[206:209], v[38:41]
	v_mfma_f32_16x16x32_bf16 v[30:33], v[158:161], v[206:209], v[30:33]
	v_mfma_f32_16x16x32_bf16 v[22:25], v[130:133], v[214:217], v[22:25]
	v_mfma_f32_16x16x32_bf16 v[14:17], v[158:161], v[214:217], v[14:17]
	v_mfma_f32_16x16x32_bf16 v[62:65], v[134:137], v[194:197], v[62:65]
	v_mfma_f32_16x16x32_bf16 v[58:61], v[170:173], v[194:197], v[58:61]
	v_mfma_f32_16x16x32_bf16 v[54:57], v[134:137], v[202:205], v[54:57]
	v_mfma_f32_16x16x32_bf16 v[46:49], v[170:173], v[202:205], v[46:49]
	v_mfma_f32_16x16x32_bf16 v[38:41], v[134:137], v[210:213], v[38:41]
	v_mfma_f32_16x16x32_bf16 v[30:33], v[170:173], v[210:213], v[30:33]
	v_mfma_f32_16x16x32_bf16 v[22:25], v[134:137], v[218:221], v[22:25]
	v_mfma_f32_16x16x32_bf16 v[14:17], v[170:173], v[218:221], v[14:17]
	v_mfma_f32_16x16x32_bf16 v[50:53], v[174:177], v[190:193], v[50:53]
	v_mfma_f32_16x16x32_bf16 v[42:45], v[182:185], v[190:193], v[42:45]
	v_mfma_f32_16x16x32_bf16 v[34:37], v[174:177], v[198:201], v[34:37]
	v_mfma_f32_16x16x32_bf16 v[26:29], v[182:185], v[198:201], v[26:29]
	v_mfma_f32_16x16x32_bf16 v[18:21], v[174:177], v[206:209], v[18:21]
	v_mfma_f32_16x16x32_bf16 v[10:13], v[182:185], v[206:209], v[10:13]
	v_mfma_f32_16x16x32_bf16 v[6:9], v[174:177], v[214:217], v[6:9]
	v_mfma_f32_16x16x32_bf16 v[2:5], v[182:185], v[214:217], v[2:5]
	v_mfma_f32_16x16x32_bf16 v[50:53], v[178:181], v[194:197], v[50:53]
	v_mfma_f32_16x16x32_bf16 v[42:45], v[186:189], v[194:197], v[42:45]
	v_mfma_f32_16x16x32_bf16 v[34:37], v[178:181], v[202:205], v[34:37]
	v_mfma_f32_16x16x32_bf16 v[26:29], v[186:189], v[202:205], v[26:29]
	v_mfma_f32_16x16x32_bf16 v[18:21], v[178:181], v[210:213], v[18:21]
	v_mfma_f32_16x16x32_bf16 v[10:13], v[186:189], v[210:213], v[10:13]
	v_mfma_f32_16x16x32_bf16 v[6:9], v[178:181], v[218:221], v[6:9]
	v_mfma_f32_16x16x32_bf16 v[2:5], v[186:189], v[218:221], v[2:5]
	s_barrier
	s_add_i32 s85, s85, 2
	s_add_u32 s52, s52, 0x100
	s_addc_u32 s53, s53, 0
	s_add_u32 s83, s83, 0x100
	s_addc_u32 s84, s84, 0
	s_cmp_gt_u32 s85, 29
	s_cbranch_scc0 .LBB0_734

; #define PG8_STAGE(bufoff, gbase, voff) do { _Pragma("unroll") for (int _i = 0; _i < 2; ++_i) \
;         __builtin_amdgcn_global_load_lds((const unsigned*)((const char*)(gbase) + (voff)[_i]), (PG8_LAS unsigned*)(lds + (bufoff) + ldsw + _i * 8192), 16, 0, 0); } while (0)
; #define PG8_LDA(dst, b, h) do { _Pragma("unroll") for (int m = 0; m < 4; ++m) _Pragma("unroll") for (int k = 0; k < 2; ++k) dst[m][k] = *(const PG8_LAS bf16x8*)(lds + PG8_SA(b, h) + aoff + m * 2048 + k * 1024); } while (0)
; #define PG8_LDB(dst, b, h) do { _Pragma("unroll") for (int n = 0; n < 2; ++n) _Pragma("unroll") for (int k = 0; k < 2; ++k) dst[n][k] = *(const PG8_LAS bf16x8*)(lds + PG8_SB(b, h) + boff + n * 2048 + k * 1024); } while (0)
; #define PG8_WAIT_V(n) asm volatile("s_waitcnt vmcnt(" #n ")" ::: "memory")
; #define PG8_WAIT_L(n) asm volatile("s_waitcnt lgkmcnt(" #n ")" ::: "memory")
; template <class Epi, class Sched, bool ALIGN_EPI = false>
; __device__ __forceinline__ void gemm_phase8(PG8_LAS unsigned char* lds, const Gemm g, const Sched& S, const Epi& E) {
;     ...
;         const bool has_next = S.next(ui + 1, nxt);
;         const size_t nko = (has_next && nxt.kp > 0) ? (size_t)nxt.kp * g.kpiece : 0;
;         const char* nA = has_next ? (const char*)g.A + (size_t)nxt.pm * tstepA + (size_t)nxt.pn * astep + nko : cA; const char* nB = has_next ? (const char*)g.Bt + (size_t)nxt.pn * tstepB + nko : cB;
;         const int nt = (cur.kp < 0 ? g.K : g.kpiece) / 128;
;         for (int t = 0; t < nt; t += 2) {
;             const bool last = (t == nt - 2);
;             const char* a1 = cA + (size_t)(t + 1) * kstep;
;             const char* a2 = last ? nA : cA + (size_t)(t + 2) * kstep; const char* b2 = last ? nB : cB + (size_t)(t + 2) * kstep;
;             const char* a3 = a2 + kstep; const char* b3 = b2 + kstep;
;             if (last && has_next) S.a_ready(nxt);
;             PG8_LDB(B0, 0, 0); PG8_LDB(B1, 0, 1); PG8_SCHED; PG8_LDA(At, 0, 0); PG8_STAGE(PG8_SA(1, 1), a1 + hstepA, voffA);
;             PG8_WAIT_V(8); PG8_WAIT_L(0); PG8_BAR; PG8_MMA(0, 0, At, B0); PG8_MMA(0, 1, At, B1); PG8_BAR; PG8_SCHED;
;             PG8_LDA(At, 0, 1); PG8_STAGE(PG8_SB(0, 0), b2, voffB); PG8_STAGE(PG8_SB(0, 1), b2 + hstepB, voffB); PG8_STAGE(PG8_SA(0, 0), a2, voffA);
;             PG8_WAIT_V(8); PG8_WAIT_L(0); PG8_BAR; PG8_MMA(1, 0, At, B0); PG8_MMA(1, 1, At, B1); PG8_BAR; PG8_SCHED;
.LBB0_1186:
	s_cmp_gt_i32 s0, 0
	s_cselect_b64 s[24:25], -1, 0
	s_and_b64 s[24:25], s[22:23], s[24:25]
	s_lshl_b64 s[26:27], s[0:1], 9
	s_and_b64 s[24:25], s[24:25], exec
	s_cselect_b32 s54, s27, 0
	s_cselect_b32 s55, s26, 0
	s_ashr_i32 s19, s18, 31
	s_lshl_b64 s[24:25], s[18:19], 19
	s_add_u32 s19, s33, s24
	s_addc_u32 s21, s60, s25
	s_add_u32 s24, s19, s55
	s_addc_u32 s25, s21, s54
	s_and_b64 s[26:27], s[22:23], exec
	s_cselect_b32 s19, s25, s57
	s_cselect_b32 s31, s24, s56
	s_ashr_i32 s21, s20, 31
	s_lshl_b64 s[26:27], s[20:21], 19
	s_add_u32 s21, s2, s26
	s_addc_u32 s27, s3, s27
	s_add_u32 s26, s21, s55
	s_addc_u32 s27, s27, s54
	s_and_b64 s[54:55], s[22:23], exec
	s_cselect_b32 s21, s27, s35
	s_cselect_b32 s75, s26, s34
	s_cmp_gt_i32 s30, -1
	s_cselect_b64 s[54:55], -1, 0
	s_cmp_lt_i32 s30, 0
	s_cselect_b32 s76, 16, 4
	s_add_i32 s77, s76, -2
	s_add_u32 s56, s56, 0x40080
	s_addc_u32 s57, s57, 0
	s_add_u32 s78, s34, 0x100
	s_mov_b32 s58, 0
	s_addc_u32 s79, s35, 0
	ds_read_b128 v[18:21], v187
	ds_read_b128 v[26:29], v187 offset:2048
	ds_read_b128 v[22:25], v188
	ds_read_b128 v[30:33], v188 offset:2048
	ds_read_b128 v[2:5], v189
	ds_read_b128 v[10:13], v189 offset:2048
	ds_read_b128 v[6:9], v190
	ds_read_b128 v[14:17], v190 offset:2048
	s_add_i32 s80, s58, 2
	s_add_u32 s34, s56, 0xfffc0080
	s_addc_u32 s35, s57, -1
	s_cmp_eq_u32 s77, s58
	s_cselect_b32 s58, s31, s34
	s_cselect_b32 s59, s19, s35
	s_cselect_b32 s35, s21, s79
	s_cselect_b32 s34, s75, s78
	s_add_i32 m0, s29, 0xc000
	ds_read_b128 v[174:177], v191
	ds_read_b128 v[194:197], v191 offset:2048
	ds_read_b128 v[178:181], v192
	ds_read_b128 v[198:201], v192 offset:2048
	ds_read_b128 v[202:205], v191 offset:4096
	ds_read_b128 v[210:213], v191 offset:6144
	ds_read_b128 v[206:209], v192 offset:4096
	ds_read_b128 v[214:217], v192 offset:6144
	global_load_lds_dwordx4 v170, s[56:57]
	s_add_i32 m0, s29, 0xe000
	s_nop 0
	global_load_lds_dwordx4 v172, s[56:57]
	s_waitcnt vmcnt(8)
	s_waitcnt lgkmcnt(0)
	s_barrier
	s_setprio 1
	s_waitcnt lgkmcnt(0)
	v_mfma_scale_f32_16x16x128_f8f6f4 v[158:161], v[18:25], v[174:181], 0, v1, v182 op_sel_hi:[0,0,0]
	v_mfma_scale_f32_16x16x128_f8f6f4 v[154:157], v[26:33], v[174:181], 0, v1, v182 op_sel_hi:[0,0,0]
	v_mfma_scale_f32_16x16x128_f8f6f4 v[150:153], v[18:25], v[194:201], 0, v1, v182 op_sel_hi:[0,0,0]
	v_mfma_scale_f32_16x16x128_f8f6f4 v[138:141], v[26:33], v[194:201], 0, v1, v182 op_sel_hi:[0,0,0]
	v_mfma_scale_f32_16x16x128_f8f6f4 v[130:133], v[18:25], v[202:209], 0, v1, v182 op_sel_hi:[0,0,0]
	v_mfma_scale_f32_16x16x128_f8f6f4 v[122:125], v[26:33], v[202:209], 0, v1, v182 op_sel_hi:[0,0,0]
	v_mfma_scale_f32_16x16x128_f8f6f4 v[118:121], v[18:25], v[210:217], 0, v1, v182 op_sel_hi:[0,0,0]
	v_mfma_scale_f32_16x16x128_f8f6f4 v[106:109], v[26:33], v[210:217], 0, v1, v182 op_sel_hi:[0,0,0]
	s_setprio 0
	s_setprio 1
	v_mfma_scale_f32_16x16x128_f8f6f4 v[146:149], v[2:9], v[174:181], 0, v1, v182 op_sel_hi:[0,0,0]
	v_mfma_scale_f32_16x16x128_f8f6f4 v[142:145], v[10:17], v[174:181], 0, v1, v182 op_sel_hi:[0,0,0]
	v_mfma_scale_f32_16x16x128_f8f6f4 v[134:137], v[2:9], v[194:201], 0, v1, v182 op_sel_hi:[0,0,0]
	v_mfma_scale_f32_16x16x128_f8f6f4 v[126:129], v[10:17], v[194:201], 0, v1, v182 op_sel_hi:[0,0,0]
	v_mfma_scale_f32_16x16x128_f8f6f4 v[114:117], v[2:9], v[202:209], 0, v1, v182 op_sel_hi:[0,0,0]
	v_mfma_scale_f32_16x16x128_f8f6f4 v[110:113], v[10:17], v[202:209], 0, v1, v182 op_sel_hi:[0,0,0]
	v_mfma_scale_f32_16x16x128_f8f6f4 v[102:105], v[2:9], v[210:217], 0, v1, v182 op_sel_hi:[0,0,0]
	v_mfma_scale_f32_16x16x128_f8f6f4 v[98:101], v[10:17], v[210:217], 0, v1, v182 op_sel_hi:[0,0,0]
	s_setprio 0
	s_barrier
	s_add_i32 s81, s71, s61
	s_mov_b32 m0, s81
	ds_read_b128 v[194:197], v191 offset:16384
	ds_read_b128 v[202:205], v191 offset:18432
	ds_read_b128 v[198:201], v192 offset:16384
	ds_read_b128 v[206:209], v192 offset:18432
	ds_read_b128 v[210:213], v191 offset:20480
	ds_read_b128 v[218:221], v191 offset:22528
	ds_read_b128 v[214:217], v192 offset:20480
	ds_read_b128 v[222:225], v192 offset:22528
	global_load_lds_dwordx4 v164, s[34:35]
	s_add_i32 m0, s81, 0x2000
	s_add_u32 s82, s34, 0x40000
	s_addc_u32 s83, s35, 0
	s_add_i32 s81, s72, s61
	global_load_lds_dwordx4 v168, s[34:35]
	s_mov_b32 m0, s81
	s_nop 0
	global_load_lds_dwordx4 v164, s[82:83]
	s_add_i32 m0, s81, 0x2000
	s_nop 0
	global_load_lds_dwordx4 v168, s[82:83]
	s_mov_b32 m0, s29
	s_nop 0
	global_load_lds_dwordx4 v162, s[58:59]
	s_mov_b32 m0, s53
	s_nop 0
	global_load_lds_dwordx4 v166, s[58:59]
	s_waitcnt vmcnt(8)
	s_waitcnt lgkmcnt(0)
	s_barrier
	s_setprio 1
	s_waitcnt lgkmcnt(0)
	v_mfma_scale_f32_16x16x128_f8f6f4 v[94:97], v[18:25], v[194:201], 0, v1, v182 op_sel_hi:[0,0,0]
	v_mfma_scale_f32_16x16x128_f8f6f4 v[90:93], v[26:33], v[194:201], 0, v1, v182 op_sel_hi:[0,0,0]
	v_mfma_scale_f32_16x16x128_f8f6f4 v[82:85], v[18:25], v[202:209], 0, v1, v182 op_sel_hi:[0,0,0]
	v_mfma_scale_f32_16x16x128_f8f6f4 v[74:77], v[26:33], v[202:209], 0, v1, v182 op_sel_hi:[0,0,0]
	v_mfma_scale_f32_16x16x128_f8f6f4 v[66:69], v[18:25], v[210:217], 0, v1, v182 op_sel_hi:[0,0,0]
	v_mfma_scale_f32_16x16x128_f8f6f4 v[58:61], v[26:33], v[210:217], 0, v1, v182 op_sel_hi:[0,0,0]
	v_mfma_scale_f32_16x16x128_f8f6f4 v[50:53], v[18:25], v[218:225], 0, v1, v182 op_sel_hi:[0,0,0]
	v_mfma_scale_f32_16x16x128_f8f6f4 v[42:45], v[26:33], v[218:225], 0, v1, v182 op_sel_hi:[0,0,0]
	s_setprio 0
	s_setprio 1
	v_mfma_scale_f32_16x16x128_f8f6f4 v[86:89], v[2:9], v[194:201], 0, v1, v182 op_sel_hi:[0,0,0]
	v_mfma_scale_f32_16x16x128_f8f6f4 v[78:81], v[10:17], v[194:201], 0, v1, v182 op_sel_hi:[0,0,0]
	v_mfma_scale_f32_16x16x128_f8f6f4 v[70:73], v[2:9], v[202:209], 0, v1, v182 op_sel_hi:[0,0,0]
	v_mfma_scale_f32_16x16x128_f8f6f4 v[62:65], v[10:17], v[202:209], 0, v1, v182 op_sel_hi:[0,0,0]
	v_mfma_scale_f32_16x16x128_f8f6f4 v[54:57], v[2:9], v[210:217], 0, v1, v182 op_sel_hi:[0,0,0]
	v_mfma_scale_f32_16x16x128_f8f6f4 v[46:49], v[10:17], v[210:217], 0, v1, v182 op_sel_hi:[0,0,0]
	v_mfma_scale_f32_16x16x128_f8f6f4 v[38:41], v[2:9], v[218:225], 0, v1, v182 op_sel_hi:[0,0,0]
	v_mfma_scale_f32_16x16x128_f8f6f4 v[34:37], v[10:17], v[218:225], 0, v1, v182 op_sel_hi:[0,0,0]
	s_setprio 0
	s_barrier
; #define PG8_STAGE(bufoff, gbase, voff) do { _Pragma("unroll") for (int _i = 0; _i < 2; ++_i) \
;         __builtin_amdgcn_global_load_lds((const unsigned*)((const char*)(gbase) + (voff)[_i]), (PG8_LAS unsigned*)(lds + (bufoff) + ldsw + _i * 8192), 16, 0, 0); } while (0)
; #define PG8_LDA(dst, b, h) do { _Pragma("unroll") for (int m = 0; m < 4; ++m) _Pragma("unroll") for (int k = 0; k < 2; ++k) dst[m][k] = *(const PG8_LAS bf16x8*)(lds + PG8_SA(b, h) + aoff + m * 2048 + k * 1024); } while (0)
; #define PG8_LDB(dst, b, h) do { _Pragma("unroll") for (int n = 0; n < 2; ++n) _Pragma("unroll") for (int k = 0; k < 2; ++k) dst[n][k] = *(const PG8_LAS bf16x8*)(lds + PG8_SB(b, h) + boff + n * 2048 + k * 1024); } while (0)
; #define PG8_MMA(ai, bj, At, Bt) do { __builtin_amdgcn_s_setprio(1); _Pragma("unroll") for (int m = 0; m < 4; ++m) _Pragma("unroll") for (int n = 0; n < 2; ++n) _Pragma("unroll") for (int k = 0; k < 2; ++k) \
;         acc[ai][bj][m][n] = __builtin_amdgcn_mfma_f32_16x16x32_bf16(Bt[n][k], At[m][k], acc[ai][bj][m][n], 0, 0, 0); __builtin_amdgcn_s_setprio(0); } while (0)
; #define PG8_WAIT_V(n) asm volatile("s_waitcnt vmcnt(" #n ")" ::: "memory")
; #define PG8_WAIT_L(n) asm volatile("s_waitcnt lgkmcnt(" #n ")" ::: "memory")
; #define PG8_BAR __builtin_amdgcn_s_barrier()
; #define PG8_SCHED __builtin_amdgcn_sched_barrier(0)
; #define PG8_STAGE(bufoff, gbase, voff) do { _Pragma("unroll") for (int _i = 0; _i < 2; ++_i) \
;         __builtin_amdgcn_global_load_lds((const unsigned*)((const char*)(gbase) + (voff)[_i]), (PG8_LAS unsigned*)(lds + (bufoff) + ldsw + _i * 8192), 16, 0, 0); } while (0)
; #define PG8_WAIT_V(n) asm volatile("s_waitcnt vmcnt(" #n ")" ::: "memory")
; template <class Epi, class Sched, bool ALIGN_EPI = false>
; __device__ __forceinline__ void gemm_phase8(PG8_LAS unsigned char* lds, const Gemm g, const Sched& S, const Epi& E) {
;     ...
;             PG8_LDB(B0, 1, 0); PG8_LDB(B1, 1, 1); PG8_SCHED; PG8_LDA(At, 1, 0); PG8_STAGE(PG8_SA(0, 1), a2 + hstepA, voffA);
;             PG8_WAIT_V(8); PG8_WAIT_L(0); PG8_BAR; PG8_MMA(0, 0, At, B0); PG8_MMA(0, 1, At, B1); PG8_BAR; PG8_SCHED;
;             PG8_LDA(At, 1, 1); PG8_STAGE(PG8_SB(1, 0), b3, voffB); PG8_STAGE(PG8_SB(1, 1), b3 + hstepB, voffB); PG8_STAGE(PG8_SA(1, 0), a3, voffA);
;             PG8_WAIT_V(8); PG8_WAIT_L(0); PG8_BAR; PG8_MMA(1, 0, At, B0); PG8_MMA(1, 1, At, B1); PG8_BAR; PG8_SCHED;
	s_add_i32 s81, 0, 0x18000
	s_add_i32 s82, 0, 0x1c000
	v_add_u32_e32 v6, s81, v184
	v_add_u32_e32 v14, s81, v185
	v_add_u32_e32 v22, s82, v184
	v_add_u32_e32 v30, s82, v185
	ds_read_b128 v[2:5], v6
	ds_read_b128 v[10:13], v6 offset:2048
	ds_read_b128 v[6:9], v14
	ds_read_b128 v[14:17], v14 offset:2048
	ds_read_b128 v[18:21], v22
	ds_read_b128 v[26:29], v22 offset:2048
	ds_read_b128 v[22:25], v30
	ds_read_b128 v[30:33], v30 offset:2048
	s_add_u32 s58, s58, 0x40000
	s_addc_u32 s59, s59, 0
	s_mov_b32 m0, s62
	ds_read_b128 v[194:197], v191 offset:32768
	ds_read_b128 v[202:205], v191 offset:34816
	ds_read_b128 v[198:201], v192 offset:32768
	ds_read_b128 v[206:209], v192 offset:34816
	ds_read_b128 v[210:213], v191 offset:36864
	ds_read_b128 v[218:221], v191 offset:38912
	ds_read_b128 v[214:217], v192 offset:36864
	ds_read_b128 v[222:225], v192 offset:38912
	global_load_lds_dwordx4 v162, s[58:59]
	s_mov_b32 m0, s63
	s_nop 0
	global_load_lds_dwordx4 v166, s[58:59]
	s_waitcnt vmcnt(8)
	s_waitcnt lgkmcnt(0)
	s_barrier
	s_setprio 1
	s_waitcnt lgkmcnt(0)
	v_mfma_scale_f32_16x16x128_f8f6f4 v[158:161], v[2:9], v[194:201], v[158:161], v1, v182 op_sel_hi:[0,0,0]
	v_mfma_scale_f32_16x16x128_f8f6f4 v[154:157], v[10:17], v[194:201], v[154:157], v1, v182 op_sel_hi:[0,0,0]
	v_mfma_scale_f32_16x16x128_f8f6f4 v[150:153], v[2:9], v[202:209], v[150:153], v1, v182 op_sel_hi:[0,0,0]
	v_mfma_scale_f32_16x16x128_f8f6f4 v[138:141], v[10:17], v[202:209], v[138:141], v1, v182 op_sel_hi:[0,0,0]
	v_mfma_scale_f32_16x16x128_f8f6f4 v[130:133], v[2:9], v[210:217], v[130:133], v1, v182 op_sel_hi:[0,0,0]
	v_mfma_scale_f32_16x16x128_f8f6f4 v[122:125], v[10:17], v[210:217], v[122:125], v1, v182 op_sel_hi:[0,0,0]
	v_mfma_scale_f32_16x16x128_f8f6f4 v[118:121], v[2:9], v[218:225], v[118:121], v1, v182 op_sel_hi:[0,0,0]
	v_mfma_scale_f32_16x16x128_f8f6f4 v[106:109], v[10:17], v[218:225], v[106:109], v1, v182 op_sel_hi:[0,0,0]
	s_setprio 0
	s_setprio 1
	v_mfma_scale_f32_16x16x128_f8f6f4 v[146:149], v[18:25], v[194:201], v[146:149], v1, v182 op_sel_hi:[0,0,0]
	v_mfma_scale_f32_16x16x128_f8f6f4 v[142:145], v[26:33], v[194:201], v[142:145], v1, v182 op_sel_hi:[0,0,0]
	v_mfma_scale_f32_16x16x128_f8f6f4 v[134:137], v[18:25], v[202:209], v[134:137], v1, v182 op_sel_hi:[0,0,0]
	v_mfma_scale_f32_16x16x128_f8f6f4 v[126:129], v[26:33], v[202:209], v[126:129], v1, v182 op_sel_hi:[0,0,0]
	v_mfma_scale_f32_16x16x128_f8f6f4 v[114:117], v[18:25], v[210:217], v[114:117], v1, v182 op_sel_hi:[0,0,0]
	v_mfma_scale_f32_16x16x128_f8f6f4 v[110:113], v[26:33], v[210:217], v[110:113], v1, v182 op_sel_hi:[0,0,0]
	v_mfma_scale_f32_16x16x128_f8f6f4 v[102:105], v[18:25], v[218:225], v[102:105], v1, v182 op_sel_hi:[0,0,0]
	v_mfma_scale_f32_16x16x128_f8f6f4 v[98:101], v[26:33], v[218:225], v[98:101], v1, v182 op_sel_hi:[0,0,0]
	s_setprio 0
	s_barrier
	s_add_i32 s101, s81, s61
	s_add_u32 s98, s34, s10
	s_addc_u32 s99, s35, s11
	s_mov_b32 m0, s101
	ds_read_b128 v[194:197], v191 offset:49152
	ds_read_b128 v[202:205], v191 offset:51200
	ds_read_b128 v[198:201], v192 offset:49152
	ds_read_b128 v[206:209], v192 offset:51200
	ds_read_b128 v[210:213], v191 offset:53248
	ds_read_b128 v[218:221], v191 offset:55296
	ds_read_b128 v[214:217], v192 offset:53248
	ds_read_b128 v[222:225], v192 offset:55296
	global_load_lds_dwordx4 v164, s[98:99]
	s_add_i32 m0, s101, 0x2000
	s_add_u32 s34, s34, 0x40080
	s_addc_u32 s35, s35, 0
	s_add_i32 s101, s82, s61
	global_load_lds_dwordx4 v168, s[98:99]
	s_add_u32 s98, s58, s10
	s_addc_u32 s99, s59, s11
	s_sub_u32 s98, s98, 0x40000
	s_subb_u32 s99, s99, 0
	s_mov_b32 m0, s101
	s_nop 0
	global_load_lds_dwordx4 v164, s[34:35]
	s_add_i32 m0, s101, 0x2000
	s_nop 0
	global_load_lds_dwordx4 v168, s[34:35]
	s_mov_b32 m0, s69
	s_nop 0
	global_load_lds_dwordx4 v162, s[98:99]
	s_mov_b32 m0, s70
	s_nop 0
	global_load_lds_dwordx4 v166, s[98:99]
	s_waitcnt vmcnt(8)
	s_waitcnt lgkmcnt(0)
	s_barrier
	s_setprio 1
	s_waitcnt lgkmcnt(0)
	v_mfma_scale_f32_16x16x128_f8f6f4 v[94:97], v[2:9], v[194:201], v[94:97], v1, v182 op_sel_hi:[0,0,0]
	v_mfma_scale_f32_16x16x128_f8f6f4 v[90:93], v[10:17], v[194:201], v[90:93], v1, v182 op_sel_hi:[0,0,0]
	v_mfma_scale_f32_16x16x128_f8f6f4 v[82:85], v[2:9], v[202:209], v[82:85], v1, v182 op_sel_hi:[0,0,0]
	v_mfma_scale_f32_16x16x128_f8f6f4 v[74:77], v[10:17], v[202:209], v[74:77], v1, v182 op_sel_hi:[0,0,0]
	v_mfma_scale_f32_16x16x128_f8f6f4 v[66:69], v[2:9], v[210:217], v[66:69], v1, v182 op_sel_hi:[0,0,0]
	v_mfma_scale_f32_16x16x128_f8f6f4 v[58:61], v[10:17], v[210:217], v[58:61], v1, v182 op_sel_hi:[0,0,0]
	v_mfma_scale_f32_16x16x128_f8f6f4 v[50:53], v[2:9], v[218:225], v[50:53], v1, v182 op_sel_hi:[0,0,0]
	v_mfma_scale_f32_16x16x128_f8f6f4 v[42:45], v[10:17], v[218:225], v[42:45], v1, v182 op_sel_hi:[0,0,0]
	s_setprio 0
	s_setprio 1
	v_mfma_scale_f32_16x16x128_f8f6f4 v[86:89], v[18:25], v[194:201], v[86:89], v1, v182 op_sel_hi:[0,0,0]
	v_mfma_scale_f32_16x16x128_f8f6f4 v[78:81], v[26:33], v[194:201], v[78:81], v1, v182 op_sel_hi:[0,0,0]
	v_mfma_scale_f32_16x16x128_f8f6f4 v[70:73], v[18:25], v[202:209], v[70:73], v1, v182 op_sel_hi:[0,0,0]
	v_mfma_scale_f32_16x16x128_f8f6f4 v[62:65], v[26:33], v[202:209], v[62:65], v1, v182 op_sel_hi:[0,0,0]
	v_mfma_scale_f32_16x16x128_f8f6f4 v[54:57], v[18:25], v[210:217], v[54:57], v1, v182 op_sel_hi:[0,0,0]
	v_mfma_scale_f32_16x16x128_f8f6f4 v[46:49], v[26:33], v[210:217], v[46:49], v1, v182 op_sel_hi:[0,0,0]
	v_mfma_scale_f32_16x16x128_f8f6f4 v[38:41], v[18:25], v[218:225], v[38:41], v1, v182 op_sel_hi:[0,0,0]
	v_mfma_scale_f32_16x16x128_f8f6f4 v[34:37], v[26:33], v[218:225], v[34:37], v1, v182 op_sel_hi:[0,0,0]
	s_setprio 0
	s_barrier
; #define PG8_STAGE(bufoff, gbase, voff) do { _Pragma("unroll") for (int _i = 0; _i < 2; ++_i) \
;         __builtin_amdgcn_global_load_lds((const unsigned*)((const char*)(gbase) + (voff)[_i]), (PG8_LAS unsigned*)(lds + (bufoff) + ldsw + _i * 8192), 16, 0, 0); } while (0)
; #define PG8_LDA(dst, b, h) do { _Pragma("unroll") for (int m = 0; m < 4; ++m) _Pragma("unroll") for (int k = 0; k < 2; ++k) dst[m][k] = *(const PG8_LAS bf16x8*)(lds + PG8_SA(b, h) + aoff + m * 2048 + k * 1024); } while (0)
; #define PG8_LDB(dst, b, h) do { _Pragma("unroll") for (int n = 0; n < 2; ++n) _Pragma("unroll") for (int k = 0; k < 2; ++k) dst[n][k] = *(const PG8_LAS bf16x8*)(lds + PG8_SB(b, h) + boff + n * 2048 + k * 1024); } while (0)
; #define PG8_MMA(ai, bj, At, Bt) do { __builtin_amdgcn_s_setprio(1); _Pragma("unroll") for (int m = 0; m < 4; ++m) _Pragma("unroll") for (int n = 0; n < 2; ++n) _Pragma("unroll") for (int k = 0; k < 2; ++k) \
;         acc[ai][bj][m][n] = __builtin_amdgcn_mfma_f32_16x16x32_bf16(Bt[n][k], At[m][k], acc[ai][bj][m][n], 0, 0, 0); __builtin_amdgcn_s_setprio(0); } while (0)
; #define PG8_WAIT_V(n) asm volatile("s_waitcnt vmcnt(" #n ")" ::: "memory")
; #define PG8_WAIT_L(n) asm volatile("s_waitcnt lgkmcnt(" #n ")" ::: "memory")
; template <class Epi, class Sched, bool ALIGN_EPI = false>
; __device__ __forceinline__ void gemm_phase8(PG8_LAS unsigned char* lds, const Gemm g, const Sched& S, const Epi& E) {
;     ...
;         for (int t = 0; t < nt; t += 2) {
;             const bool last = (t == nt - 2);
;             const char* a1 = cA + (size_t)(t + 1) * kstep;
;             const char* a2 = last ? nA : cA + (size_t)(t + 2) * kstep; const char* b2 = last ? nB : cB + (size_t)(t + 2) * kstep;
;             const char* a3 = a2 + kstep; const char* b3 = b2 + kstep;
;             if (last && has_next) S.a_ready(nxt);
;             PG8_LDB(B0, 0, 0); PG8_LDB(B1, 0, 1); PG8_SCHED; PG8_LDA(At, 0, 0); PG8_STAGE(PG8_SA(1, 1), a1 + hstepA, voffA);
;             PG8_WAIT_V(8); PG8_WAIT_L(0); PG8_BAR; PG8_MMA(0, 0, At, B0); PG8_MMA(0, 1, At, B1); PG8_BAR; PG8_SCHED;
;             PG8_LDA(At, 0, 1); PG8_STAGE(PG8_SB(0, 0), b2, voffB); PG8_STAGE(PG8_SB(0, 1), b2 + hstepB, voffB); PG8_STAGE(PG8_SA(0, 0), a2, voffA);
;             PG8_WAIT_V(8); PG8_WAIT_L(0); PG8_BAR; PG8_MMA(1, 0, At, B0); PG8_MMA(1, 1, At, B1); PG8_BAR; PG8_SCHED;
	s_add_u32 s56, s56, 0x100
	s_addc_u32 s57, s57, 0
	s_add_u32 s78, s78, 0x100
	s_addc_u32 s79, s79, 0
	s_cmp_ge_u32 s80, s76
	s_mov_b32 s58, s80
	ds_read_b128 v[18:21], v187
	ds_read_b128 v[26:29], v187 offset:2048
	ds_read_b128 v[22:25], v188
	ds_read_b128 v[30:33], v188 offset:2048
	ds_read_b128 v[2:5], v189
	ds_read_b128 v[10:13], v189 offset:2048
	ds_read_b128 v[6:9], v190
	ds_read_b128 v[14:17], v190 offset:2048
	s_add_i32 s80, s58, 2
	s_add_u32 s34, s56, 0xfffc0080
	s_addc_u32 s35, s57, -1
	s_cmp_eq_u32 s77, s58
	s_cselect_b32 s58, s31, s34
	s_cselect_b32 s59, s19, s35
	s_cselect_b32 s35, s21, s79
	s_cselect_b32 s34, s75, s78
	s_add_i32 m0, s29, 0xc000
	ds_read_b128 v[174:177], v191
	ds_read_b128 v[194:197], v191 offset:2048
	ds_read_b128 v[178:181], v192
	ds_read_b128 v[198:201], v192 offset:2048
	ds_read_b128 v[202:205], v191 offset:4096
	ds_read_b128 v[210:213], v191 offset:6144
	ds_read_b128 v[206:209], v192 offset:4096
	ds_read_b128 v[214:217], v192 offset:6144
	global_load_lds_dwordx4 v170, s[56:57]
	s_add_i32 m0, s29, 0xe000
	s_nop 0
	global_load_lds_dwordx4 v172, s[56:57]
	s_waitcnt vmcnt(8)
	s_waitcnt lgkmcnt(0)
	s_barrier
	s_setprio 1
	s_waitcnt lgkmcnt(0)
	v_mfma_scale_f32_16x16x128_f8f6f4 v[158:161], v[18:25], v[174:181], v[158:161], v1, v182 op_sel_hi:[0,0,0]
	v_mfma_scale_f32_16x16x128_f8f6f4 v[154:157], v[26:33], v[174:181], v[154:157], v1, v182 op_sel_hi:[0,0,0]
	v_mfma_scale_f32_16x16x128_f8f6f4 v[150:153], v[18:25], v[194:201], v[150:153], v1, v182 op_sel_hi:[0,0,0]
	v_mfma_scale_f32_16x16x128_f8f6f4 v[138:141], v[26:33], v[194:201], v[138:141], v1, v182 op_sel_hi:[0,0,0]
	v_mfma_scale_f32_16x16x128_f8f6f4 v[130:133], v[18:25], v[202:209], v[130:133], v1, v182 op_sel_hi:[0,0,0]
	v_mfma_scale_f32_16x16x128_f8f6f4 v[122:125], v[26:33], v[202:209], v[122:125], v1, v182 op_sel_hi:[0,0,0]
	v_mfma_scale_f32_16x16x128_f8f6f4 v[118:121], v[18:25], v[210:217], v[118:121], v1, v182 op_sel_hi:[0,0,0]
	v_mfma_scale_f32_16x16x128_f8f6f4 v[106:109], v[26:33], v[210:217], v[106:109], v1, v182 op_sel_hi:[0,0,0]
	s_setprio 0
	s_setprio 1
	v_mfma_scale_f32_16x16x128_f8f6f4 v[146:149], v[2:9], v[174:181], v[146:149], v1, v182 op_sel_hi:[0,0,0]
	v_mfma_scale_f32_16x16x128_f8f6f4 v[142:145], v[10:17], v[174:181], v[142:145], v1, v182 op_sel_hi:[0,0,0]
	v_mfma_scale_f32_16x16x128_f8f6f4 v[134:137], v[2:9], v[194:201], v[134:137], v1, v182 op_sel_hi:[0,0,0]
	v_mfma_scale_f32_16x16x128_f8f6f4 v[126:129], v[10:17], v[194:201], v[126:129], v1, v182 op_sel_hi:[0,0,0]
	v_mfma_scale_f32_16x16x128_f8f6f4 v[114:117], v[2:9], v[202:209], v[114:117], v1, v182 op_sel_hi:[0,0,0]
	v_mfma_scale_f32_16x16x128_f8f6f4 v[110:113], v[10:17], v[202:209], v[110:113], v1, v182 op_sel_hi:[0,0,0]
	v_mfma_scale_f32_16x16x128_f8f6f4 v[102:105], v[2:9], v[210:217], v[102:105], v1, v182 op_sel_hi:[0,0,0]
	v_mfma_scale_f32_16x16x128_f8f6f4 v[98:101], v[10:17], v[210:217], v[98:101], v1, v182 op_sel_hi:[0,0,0]
	s_setprio 0
	s_barrier
	s_add_i32 s81, s71, s61
	s_mov_b32 m0, s81
	ds_read_b128 v[194:197], v191 offset:16384
	ds_read_b128 v[202:205], v191 offset:18432
	ds_read_b128 v[198:201], v192 offset:16384
	ds_read_b128 v[206:209], v192 offset:18432
	ds_read_b128 v[210:213], v191 offset:20480
	ds_read_b128 v[218:221], v191 offset:22528
	ds_read_b128 v[214:217], v192 offset:20480
	ds_read_b128 v[222:225], v192 offset:22528
	global_load_lds_dwordx4 v164, s[34:35]
	s_add_i32 m0, s81, 0x2000
	s_add_u32 s82, s34, 0x40000
	s_addc_u32 s83, s35, 0
	s_add_i32 s81, s72, s61
	global_load_lds_dwordx4 v168, s[34:35]
	s_mov_b32 m0, s81
	s_nop 0
	global_load_lds_dwordx4 v164, s[82:83]
	s_add_i32 m0, s81, 0x2000
	s_nop 0
	global_load_lds_dwordx4 v168, s[82:83]
	s_mov_b32 m0, s29
	s_nop 0
	global_load_lds_dwordx4 v162, s[58:59]
	s_mov_b32 m0, s53
	s_nop 0
	global_load_lds_dwordx4 v166, s[58:59]
	s_waitcnt vmcnt(8)
	s_waitcnt lgkmcnt(0)
	s_barrier
	s_setprio 1
	s_waitcnt lgkmcnt(0)
	v_mfma_scale_f32_16x16x128_f8f6f4 v[94:97], v[18:25], v[194:201], v[94:97], v1, v182 op_sel_hi:[0,0,0]
	v_mfma_scale_f32_16x16x128_f8f6f4 v[90:93], v[26:33], v[194:201], v[90:93], v1, v182 op_sel_hi:[0,0,0]
	v_mfma_scale_f32_16x16x128_f8f6f4 v[82:85], v[18:25], v[202:209], v[82:85], v1, v182 op_sel_hi:[0,0,0]
	v_mfma_scale_f32_16x16x128_f8f6f4 v[74:77], v[26:33], v[202:209], v[74:77], v1, v182 op_sel_hi:[0,0,0]
	v_mfma_scale_f32_16x16x128_f8f6f4 v[66:69], v[18:25], v[210:217], v[66:69], v1, v182 op_sel_hi:[0,0,0]
	v_mfma_scale_f32_16x16x128_f8f6f4 v[58:61], v[26:33], v[210:217], v[58:61], v1, v182 op_sel_hi:[0,0,0]
	v_mfma_scale_f32_16x16x128_f8f6f4 v[50:53], v[18:25], v[218:225], v[50:53], v1, v182 op_sel_hi:[0,0,0]
	v_mfma_scale_f32_16x16x128_f8f6f4 v[42:45], v[26:33], v[218:225], v[42:45], v1, v182 op_sel_hi:[0,0,0]
	s_setprio 0
	s_setprio 1
	v_mfma_scale_f32_16x16x128_f8f6f4 v[86:89], v[2:9], v[194:201], v[86:89], v1, v182 op_sel_hi:[0,0,0]
	v_mfma_scale_f32_16x16x128_f8f6f4 v[78:81], v[10:17], v[194:201], v[78:81], v1, v182 op_sel_hi:[0,0,0]
	v_mfma_scale_f32_16x16x128_f8f6f4 v[70:73], v[2:9], v[202:209], v[70:73], v1, v182 op_sel_hi:[0,0,0]
	v_mfma_scale_f32_16x16x128_f8f6f4 v[62:65], v[10:17], v[202:209], v[62:65], v1, v182 op_sel_hi:[0,0,0]
	v_mfma_scale_f32_16x16x128_f8f6f4 v[54:57], v[2:9], v[210:217], v[54:57], v1, v182 op_sel_hi:[0,0,0]
	v_mfma_scale_f32_16x16x128_f8f6f4 v[46:49], v[10:17], v[210:217], v[46:49], v1, v182 op_sel_hi:[0,0,0]
	v_mfma_scale_f32_16x16x128_f8f6f4 v[38:41], v[2:9], v[218:225], v[38:41], v1, v182 op_sel_hi:[0,0,0]
	v_mfma_scale_f32_16x16x128_f8f6f4 v[34:37], v[10:17], v[218:225], v[34:37], v1, v182 op_sel_hi:[0,0,0]
	s_setprio 0
	s_barrier
; #define PG8_STAGE(bufoff, gbase, voff) do { _Pragma("unroll") for (int _i = 0; _i < 2; ++_i) \
;         __builtin_amdgcn_global_load_lds((const unsigned*)((const char*)(gbase) + (voff)[_i]), (PG8_LAS unsigned*)(lds + (bufoff) + ldsw + _i * 8192), 16, 0, 0); } while (0)
; #define PG8_LDA(dst, b, h) do { _Pragma("unroll") for (int m = 0; m < 4; ++m) _Pragma("unroll") for (int k = 0; k < 2; ++k) dst[m][k] = *(const PG8_LAS bf16x8*)(lds + PG8_SA(b, h) + aoff + m * 2048 + k * 1024); } while (0)
; #define PG8_LDB(dst, b, h) do { _Pragma("unroll") for (int n = 0; n < 2; ++n) _Pragma("unroll") for (int k = 0; k < 2; ++k) dst[n][k] = *(const PG8_LAS bf16x8*)(lds + PG8_SB(b, h) + boff + n * 2048 + k * 1024); } while (0)
; #define PG8_MMA(ai, bj, At, Bt) do { __builtin_amdgcn_s_setprio(1); _Pragma("unroll") for (int m = 0; m < 4; ++m) _Pragma("unroll") for (int n = 0; n < 2; ++n) _Pragma("unroll") for (int k = 0; k < 2; ++k) \
;         acc[ai][bj][m][n] = __builtin_amdgcn_mfma_f32_16x16x32_bf16(Bt[n][k], At[m][k], acc[ai][bj][m][n], 0, 0, 0); __builtin_amdgcn_s_setprio(0); } while (0)
; #define PG8_WAIT_V(n) asm volatile("s_waitcnt vmcnt(" #n ")" ::: "memory")
; #define PG8_WAIT_L(n) asm volatile("s_waitcnt lgkmcnt(" #n ")" ::: "memory")
; #define PG8_BAR __builtin_amdgcn_s_barrier()
; #define PG8_SCHED __builtin_amdgcn_sched_barrier(0)
; #define PG8_STAGE(bufoff, gbase, voff) do { _Pragma("unroll") for (int _i = 0; _i < 2; ++_i) \
;         __builtin_amdgcn_global_load_lds((const unsigned*)((const char*)(gbase) + (voff)[_i]), (PG8_LAS unsigned*)(lds + (bufoff) + ldsw + _i * 8192), 16, 0, 0); } while (0)
; #define PG8_BAR __builtin_amdgcn_s_barrier()
; template <class Epi, class Sched, bool ALIGN_EPI = false>
; __device__ __forceinline__ void gemm_phase8(PG8_LAS unsigned char* lds, const Gemm g, const Sched& S, const Epi& E) {
;     ...
;             PG8_LDB(B0, 1, 0); PG8_LDB(B1, 1, 1); PG8_SCHED; PG8_LDA(At, 1, 0); PG8_STAGE(PG8_SA(0, 1), a2 + hstepA, voffA);
;             PG8_WAIT_V(8); PG8_WAIT_L(0); PG8_BAR; PG8_MMA(0, 0, At, B0); PG8_MMA(0, 1, At, B1); PG8_BAR; PG8_SCHED;
;             PG8_LDA(At, 1, 1); PG8_STAGE(PG8_SB(1, 0), b3, voffB); PG8_STAGE(PG8_SB(1, 1), b3 + hstepB, voffB); PG8_STAGE(PG8_SA(1, 0), a3, voffA);
;             PG8_WAIT_V(8); PG8_WAIT_L(0); PG8_BAR; PG8_MMA(1, 0, At, B0); PG8_MMA(1, 1, At, B1); PG8_BAR; PG8_SCHED;
;         }
	s_add_i32 s81, 0, 0x18000
	s_add_i32 s82, 0, 0x1c000
	v_add_u32_e32 v6, s81, v184
	v_add_u32_e32 v14, s81, v185
	v_add_u32_e32 v22, s82, v184
	v_add_u32_e32 v30, s82, v185
	ds_read_b128 v[2:5], v6
	ds_read_b128 v[10:13], v6 offset:2048
	ds_read_b128 v[6:9], v14
	ds_read_b128 v[14:17], v14 offset:2048
	ds_read_b128 v[18:21], v22
	ds_read_b128 v[26:29], v22 offset:2048
	ds_read_b128 v[22:25], v30
	ds_read_b128 v[30:33], v30 offset:2048
	s_add_u32 s58, s58, 0x40000
	s_addc_u32 s59, s59, 0
	s_mov_b32 m0, s62
	ds_read_b128 v[194:197], v191 offset:32768
	ds_read_b128 v[202:205], v191 offset:34816
	ds_read_b128 v[198:201], v192 offset:32768
	ds_read_b128 v[206:209], v192 offset:34816
	ds_read_b128 v[210:213], v191 offset:36864
	ds_read_b128 v[218:221], v191 offset:38912
	ds_read_b128 v[214:217], v192 offset:36864
	ds_read_b128 v[222:225], v192 offset:38912
	global_load_lds_dwordx4 v162, s[58:59]
	s_mov_b32 m0, s63
	s_nop 0
	global_load_lds_dwordx4 v166, s[58:59]
	s_waitcnt vmcnt(8)
	s_waitcnt lgkmcnt(0)
	s_barrier
	s_setprio 1
	s_waitcnt lgkmcnt(0)
	v_mfma_scale_f32_16x16x128_f8f6f4 v[158:161], v[2:9], v[194:201], v[158:161], v1, v182 op_sel_hi:[0,0,0]
	v_mfma_scale_f32_16x16x128_f8f6f4 v[154:157], v[10:17], v[194:201], v[154:157], v1, v182 op_sel_hi:[0,0,0]
	v_mfma_scale_f32_16x16x128_f8f6f4 v[150:153], v[2:9], v[202:209], v[150:153], v1, v182 op_sel_hi:[0,0,0]
	v_mfma_scale_f32_16x16x128_f8f6f4 v[138:141], v[10:17], v[202:209], v[138:141], v1, v182 op_sel_hi:[0,0,0]
	v_mfma_scale_f32_16x16x128_f8f6f4 v[130:133], v[2:9], v[210:217], v[130:133], v1, v182 op_sel_hi:[0,0,0]
	v_mfma_scale_f32_16x16x128_f8f6f4 v[122:125], v[10:17], v[210:217], v[122:125], v1, v182 op_sel_hi:[0,0,0]
	v_mfma_scale_f32_16x16x128_f8f6f4 v[118:121], v[2:9], v[218:225], v[118:121], v1, v182 op_sel_hi:[0,0,0]
	v_mfma_scale_f32_16x16x128_f8f6f4 v[106:109], v[10:17], v[218:225], v[106:109], v1, v182 op_sel_hi:[0,0,0]
	s_setprio 0
	s_setprio 1
	v_mfma_scale_f32_16x16x128_f8f6f4 v[146:149], v[18:25], v[194:201], v[146:149], v1, v182 op_sel_hi:[0,0,0]
	v_mfma_scale_f32_16x16x128_f8f6f4 v[142:145], v[26:33], v[194:201], v[142:145], v1, v182 op_sel_hi:[0,0,0]
	v_mfma_scale_f32_16x16x128_f8f6f4 v[134:137], v[18:25], v[202:209], v[134:137], v1, v182 op_sel_hi:[0,0,0]
	v_mfma_scale_f32_16x16x128_f8f6f4 v[126:129], v[26:33], v[202:209], v[126:129], v1, v182 op_sel_hi:[0,0,0]
	v_mfma_scale_f32_16x16x128_f8f6f4 v[114:117], v[18:25], v[210:217], v[114:117], v1, v182 op_sel_hi:[0,0,0]
	v_mfma_scale_f32_16x16x128_f8f6f4 v[110:113], v[26:33], v[210:217], v[110:113], v1, v182 op_sel_hi:[0,0,0]
	v_mfma_scale_f32_16x16x128_f8f6f4 v[102:105], v[18:25], v[218:225], v[102:105], v1, v182 op_sel_hi:[0,0,0]
	v_mfma_scale_f32_16x16x128_f8f6f4 v[98:101], v[26:33], v[218:225], v[98:101], v1, v182 op_sel_hi:[0,0,0]
	s_setprio 0
	s_barrier
	s_add_i32 s101, s81, s61
	s_add_u32 s98, s34, s10
	s_addc_u32 s99, s35, s11
	s_mov_b32 m0, s101
	ds_read_b128 v[194:197], v191 offset:49152
	ds_read_b128 v[202:205], v191 offset:51200
	ds_read_b128 v[198:201], v192 offset:49152
	ds_read_b128 v[206:209], v192 offset:51200
	ds_read_b128 v[210:213], v191 offset:53248
	ds_read_b128 v[218:221], v191 offset:55296
	ds_read_b128 v[214:217], v192 offset:53248
	ds_read_b128 v[222:225], v192 offset:55296
	global_load_lds_dwordx4 v164, s[98:99]
	s_add_i32 m0, s101, 0x2000
	s_add_u32 s34, s34, 0x40080
	s_addc_u32 s35, s35, 0
	s_add_i32 s101, s82, s61
	global_load_lds_dwordx4 v168, s[98:99]
	s_add_u32 s98, s58, s10
	s_addc_u32 s99, s59, s11
	s_sub_u32 s98, s98, 0x40000
	s_subb_u32 s99, s99, 0
	s_mov_b32 m0, s101
	s_nop 0
	global_load_lds_dwordx4 v164, s[34:35]
	s_add_i32 m0, s101, 0x2000
	s_nop 0
	global_load_lds_dwordx4 v168, s[34:35]
	s_mov_b32 m0, s69
	s_nop 0
	global_load_lds_dwordx4 v162, s[98:99]
	s_mov_b32 m0, s70
	s_nop 0
	global_load_lds_dwordx4 v166, s[98:99]
	s_waitcnt vmcnt(8)
	s_waitcnt lgkmcnt(0)
	s_barrier
	s_setprio 1
	s_waitcnt lgkmcnt(0)
	v_mfma_scale_f32_16x16x128_f8f6f4 v[94:97], v[2:9], v[194:201], v[94:97], v1, v182 op_sel_hi:[0,0,0]
	v_mfma_scale_f32_16x16x128_f8f6f4 v[90:93], v[10:17], v[194:201], v[90:93], v1, v182 op_sel_hi:[0,0,0]
	v_mfma_scale_f32_16x16x128_f8f6f4 v[82:85], v[2:9], v[202:209], v[82:85], v1, v182 op_sel_hi:[0,0,0]
	v_mfma_scale_f32_16x16x128_f8f6f4 v[74:77], v[10:17], v[202:209], v[74:77], v1, v182 op_sel_hi:[0,0,0]
	v_mfma_scale_f32_16x16x128_f8f6f4 v[66:69], v[2:9], v[210:217], v[66:69], v1, v182 op_sel_hi:[0,0,0]
	v_mfma_scale_f32_16x16x128_f8f6f4 v[58:61], v[10:17], v[210:217], v[58:61], v1, v182 op_sel_hi:[0,0,0]
	v_mfma_scale_f32_16x16x128_f8f6f4 v[50:53], v[2:9], v[218:225], v[50:53], v1, v182 op_sel_hi:[0,0,0]
	v_mfma_scale_f32_16x16x128_f8f6f4 v[42:45], v[10:17], v[218:225], v[42:45], v1, v182 op_sel_hi:[0,0,0]
	s_setprio 0
	s_setprio 1
	v_mfma_scale_f32_16x16x128_f8f6f4 v[86:89], v[18:25], v[194:201], v[86:89], v1, v182 op_sel_hi:[0,0,0]
	v_mfma_scale_f32_16x16x128_f8f6f4 v[78:81], v[26:33], v[194:201], v[78:81], v1, v182 op_sel_hi:[0,0,0]
	v_mfma_scale_f32_16x16x128_f8f6f4 v[70:73], v[18:25], v[202:209], v[70:73], v1, v182 op_sel_hi:[0,0,0]
	v_mfma_scale_f32_16x16x128_f8f6f4 v[62:65], v[26:33], v[202:209], v[62:65], v1, v182 op_sel_hi:[0,0,0]
	v_mfma_scale_f32_16x16x128_f8f6f4 v[54:57], v[18:25], v[210:217], v[54:57], v1, v182 op_sel_hi:[0,0,0]
	v_mfma_scale_f32_16x16x128_f8f6f4 v[46:49], v[26:33], v[210:217], v[46:49], v1, v182 op_sel_hi:[0,0,0]
	v_mfma_scale_f32_16x16x128_f8f6f4 v[38:41], v[18:25], v[218:225], v[38:41], v1, v182 op_sel_hi:[0,0,0]
	v_mfma_scale_f32_16x16x128_f8f6f4 v[34:37], v[26:33], v[218:225], v[34:37], v1, v182 op_sel_hi:[0,0,0]
	s_setprio 0
	s_barrier
	s_add_u32 s56, s56, 0x100
	s_addc_u32 s57, s57, 0
	s_add_u32 s78, s78, 0x100
	s_addc_u32 s79, s79, 0
	s_cmp_ge_u32 s80, s76
	s_mov_b32 s58, s80
	s_cbranch_scc1 .Lpx_3
; #define PG8_STAGE(bufoff, gbase, voff) do { _Pragma("unroll") for (int _i = 0; _i < 2; ++_i) \
;         __builtin_amdgcn_global_load_lds((const unsigned*)((const char*)(gbase) + (voff)[_i]), (PG8_LAS unsigned*)(lds + (bufoff) + ldsw + _i * 8192), 16, 0, 0); } while (0)
; #define PG8_LDA(dst, b, h) do { _Pragma("unroll") for (int m = 0; m < 4; ++m) _Pragma("unroll") for (int k = 0; k < 2; ++k) dst[m][k] = *(const PG8_LAS bf16x8*)(lds + PG8_SA(b, h) + aoff + m * 2048 + k * 1024); } while (0)
; #define PG8_LDB(dst, b, h) do { _Pragma("unroll") for (int n = 0; n < 2; ++n) _Pragma("unroll") for (int k = 0; k < 2; ++k) dst[n][k] = *(const PG8_LAS bf16x8*)(lds + PG8_SB(b, h) + boff + n * 2048 + k * 1024); } while (0)
; #define PG8_MMA(ai, bj, At, Bt) do { __builtin_amdgcn_s_setprio(1); _Pragma("unroll") for (int m = 0; m < 4; ++m) _Pragma("unroll") for (int n = 0; n < 2; ++n) _Pragma("unroll") for (int k = 0; k < 2; ++k) \
;         acc[ai][bj][m][n] = __builtin_amdgcn_mfma_f32_16x16x32_bf16(Bt[n][k], At[m][k], acc[ai][bj][m][n], 0, 0, 0); __builtin_amdgcn_s_setprio(0); } while (0)
; #define PG8_WAIT_V(n) asm volatile("s_waitcnt vmcnt(" #n ")" ::: "memory")
; #define PG8_WAIT_L(n) asm volatile("s_waitcnt lgkmcnt(" #n ")" ::: "memory")
; template <class Epi, class Sched, bool ALIGN_EPI = false>
; __device__ __forceinline__ void gemm_phase8(PG8_LAS unsigned char* lds, const Gemm g, const Sched& S, const Epi& E) {
;     ...
;         for (int t = 0; t < nt; t += 2) {
;             const bool last = (t == nt - 2);
;             const char* a1 = cA + (size_t)(t + 1) * kstep;
;             const char* a2 = last ? nA : cA + (size_t)(t + 2) * kstep; const char* b2 = last ? nB : cB + (size_t)(t + 2) * kstep;
;             const char* a3 = a2 + kstep; const char* b3 = b2 + kstep;
;             if (last && has_next) S.a_ready(nxt);
;             PG8_LDB(B0, 0, 0); PG8_LDB(B1, 0, 1); PG8_SCHED; PG8_LDA(At, 0, 0); PG8_STAGE(PG8_SA(1, 1), a1 + hstepA, voffA);
;             PG8_WAIT_V(8); PG8_WAIT_L(0); PG8_BAR; PG8_MMA(0, 0, At, B0); PG8_MMA(0, 1, At, B1); PG8_BAR; PG8_SCHED;
;             PG8_LDA(At, 0, 1); PG8_STAGE(PG8_SB(0, 0), b2, voffB); PG8_STAGE(PG8_SB(0, 1), b2 + hstepB, voffB); PG8_STAGE(PG8_SA(0, 0), a2, voffA);
;             PG8_WAIT_V(8); PG8_WAIT_L(0); PG8_BAR; PG8_MMA(1, 0, At, B0); PG8_MMA(1, 1, At, B1); PG8_BAR; PG8_SCHED;
.LBB0_1187:
	ds_read_b128 v[18:21], v187
	ds_read_b128 v[26:29], v187 offset:2048
	ds_read_b128 v[22:25], v188
	ds_read_b128 v[30:33], v188 offset:2048
	ds_read_b128 v[2:5], v189
	ds_read_b128 v[10:13], v189 offset:2048
	ds_read_b128 v[6:9], v190
	ds_read_b128 v[14:17], v190 offset:2048
	s_add_i32 s80, s58, 2
	s_add_u32 s34, s56, 0xfffc0080
	s_addc_u32 s35, s57, -1
	s_cmp_eq_u32 s77, s58
	s_cselect_b32 s58, s31, s34
	s_cselect_b32 s59, s19, s35
	s_cselect_b32 s35, s21, s79
	s_cselect_b32 s34, s75, s78
	s_add_i32 m0, s29, 0xc000
	ds_read_b128 v[174:177], v191
	ds_read_b128 v[194:197], v191 offset:2048
	ds_read_b128 v[178:181], v192
	ds_read_b128 v[198:201], v192 offset:2048
	ds_read_b128 v[202:205], v191 offset:4096
	ds_read_b128 v[210:213], v191 offset:6144
	ds_read_b128 v[206:209], v192 offset:4096
	ds_read_b128 v[214:217], v192 offset:6144
	global_load_lds_dwordx4 v170, s[56:57]
	s_add_i32 m0, s29, 0xe000
	s_nop 0
	global_load_lds_dwordx4 v172, s[56:57]
	s_waitcnt vmcnt(8)
	s_waitcnt lgkmcnt(0)
	s_barrier
	s_setprio 1
	s_waitcnt lgkmcnt(0)
	v_mfma_scale_f32_16x16x128_f8f6f4 v[158:161], v[18:25], v[174:181], v[158:161], v1, v182 op_sel_hi:[0,0,0]
	v_mfma_scale_f32_16x16x128_f8f6f4 v[154:157], v[26:33], v[174:181], v[154:157], v1, v182 op_sel_hi:[0,0,0]
	v_mfma_scale_f32_16x16x128_f8f6f4 v[150:153], v[18:25], v[194:201], v[150:153], v1, v182 op_sel_hi:[0,0,0]
	v_mfma_scale_f32_16x16x128_f8f6f4 v[138:141], v[26:33], v[194:201], v[138:141], v1, v182 op_sel_hi:[0,0,0]
	v_mfma_scale_f32_16x16x128_f8f6f4 v[130:133], v[18:25], v[202:209], v[130:133], v1, v182 op_sel_hi:[0,0,0]
	v_mfma_scale_f32_16x16x128_f8f6f4 v[122:125], v[26:33], v[202:209], v[122:125], v1, v182 op_sel_hi:[0,0,0]
	v_mfma_scale_f32_16x16x128_f8f6f4 v[118:121], v[18:25], v[210:217], v[118:121], v1, v182 op_sel_hi:[0,0,0]
	v_mfma_scale_f32_16x16x128_f8f6f4 v[106:109], v[26:33], v[210:217], v[106:109], v1, v182 op_sel_hi:[0,0,0]
	s_setprio 0
	s_setprio 1
	v_mfma_scale_f32_16x16x128_f8f6f4 v[146:149], v[2:9], v[174:181], v[146:149], v1, v182 op_sel_hi:[0,0,0]
	v_mfma_scale_f32_16x16x128_f8f6f4 v[142:145], v[10:17], v[174:181], v[142:145], v1, v182 op_sel_hi:[0,0,0]
	v_mfma_scale_f32_16x16x128_f8f6f4 v[134:137], v[2:9], v[194:201], v[134:137], v1, v182 op_sel_hi:[0,0,0]
	v_mfma_scale_f32_16x16x128_f8f6f4 v[126:129], v[10:17], v[194:201], v[126:129], v1, v182 op_sel_hi:[0,0,0]
	v_mfma_scale_f32_16x16x128_f8f6f4 v[114:117], v[2:9], v[202:209], v[114:117], v1, v182 op_sel_hi:[0,0,0]
	v_mfma_scale_f32_16x16x128_f8f6f4 v[110:113], v[10:17], v[202:209], v[110:113], v1, v182 op_sel_hi:[0,0,0]
	v_mfma_scale_f32_16x16x128_f8f6f4 v[102:105], v[2:9], v[210:217], v[102:105], v1, v182 op_sel_hi:[0,0,0]
	v_mfma_scale_f32_16x16x128_f8f6f4 v[98:101], v[10:17], v[210:217], v[98:101], v1, v182 op_sel_hi:[0,0,0]
	s_setprio 0
	s_barrier
	s_add_i32 s81, s71, s61
	s_mov_b32 m0, s81
	ds_read_b128 v[194:197], v191 offset:16384
	ds_read_b128 v[202:205], v191 offset:18432
	ds_read_b128 v[198:201], v192 offset:16384
	ds_read_b128 v[206:209], v192 offset:18432
	ds_read_b128 v[210:213], v191 offset:20480
	ds_read_b128 v[218:221], v191 offset:22528
	ds_read_b128 v[214:217], v192 offset:20480
	ds_read_b128 v[222:225], v192 offset:22528
	global_load_lds_dwordx4 v164, s[34:35]
	s_add_i32 m0, s81, 0x2000
	s_add_u32 s82, s34, 0x40000
	s_addc_u32 s83, s35, 0
	s_add_i32 s81, s72, s61
	global_load_lds_dwordx4 v168, s[34:35]
	s_mov_b32 m0, s81
	s_nop 0
	global_load_lds_dwordx4 v164, s[82:83]
	s_add_i32 m0, s81, 0x2000
	s_nop 0
	global_load_lds_dwordx4 v168, s[82:83]
	s_mov_b32 m0, s29
	s_nop 0
	global_load_lds_dwordx4 v162, s[58:59]
	s_mov_b32 m0, s53
	s_nop 0
	global_load_lds_dwordx4 v166, s[58:59]
	s_waitcnt vmcnt(8)
	s_waitcnt lgkmcnt(0)
	s_barrier
	s_setprio 1
	s_waitcnt lgkmcnt(0)
	v_mfma_scale_f32_16x16x128_f8f6f4 v[94:97], v[18:25], v[194:201], v[94:97], v1, v182 op_sel_hi:[0,0,0]
	v_mfma_scale_f32_16x16x128_f8f6f4 v[90:93], v[26:33], v[194:201], v[90:93], v1, v182 op_sel_hi:[0,0,0]
	v_mfma_scale_f32_16x16x128_f8f6f4 v[82:85], v[18:25], v[202:209], v[82:85], v1, v182 op_sel_hi:[0,0,0]
	v_mfma_scale_f32_16x16x128_f8f6f4 v[74:77], v[26:33], v[202:209], v[74:77], v1, v182 op_sel_hi:[0,0,0]
	v_mfma_scale_f32_16x16x128_f8f6f4 v[66:69], v[18:25], v[210:217], v[66:69], v1, v182 op_sel_hi:[0,0,0]
	v_mfma_scale_f32_16x16x128_f8f6f4 v[58:61], v[26:33], v[210:217], v[58:61], v1, v182 op_sel_hi:[0,0,0]
	v_mfma_scale_f32_16x16x128_f8f6f4 v[50:53], v[18:25], v[218:225], v[50:53], v1, v182 op_sel_hi:[0,0,0]
	v_mfma_scale_f32_16x16x128_f8f6f4 v[42:45], v[26:33], v[218:225], v[42:45], v1, v182 op_sel_hi:[0,0,0]
	s_setprio 0
	s_setprio 1
	v_mfma_scale_f32_16x16x128_f8f6f4 v[86:89], v[2:9], v[194:201], v[86:89], v1, v182 op_sel_hi:[0,0,0]
	v_mfma_scale_f32_16x16x128_f8f6f4 v[78:81], v[10:17], v[194:201], v[78:81], v1, v182 op_sel_hi:[0,0,0]
	v_mfma_scale_f32_16x16x128_f8f6f4 v[70:73], v[2:9], v[202:209], v[70:73], v1, v182 op_sel_hi:[0,0,0]
	v_mfma_scale_f32_16x16x128_f8f6f4 v[62:65], v[10:17], v[202:209], v[62:65], v1, v182 op_sel_hi:[0,0,0]
	v_mfma_scale_f32_16x16x128_f8f6f4 v[54:57], v[2:9], v[210:217], v[54:57], v1, v182 op_sel_hi:[0,0,0]
	v_mfma_scale_f32_16x16x128_f8f6f4 v[46:49], v[10:17], v[210:217], v[46:49], v1, v182 op_sel_hi:[0,0,0]
	v_mfma_scale_f32_16x16x128_f8f6f4 v[38:41], v[2:9], v[218:225], v[38:41], v1, v182 op_sel_hi:[0,0,0]
	v_mfma_scale_f32_16x16x128_f8f6f4 v[34:37], v[10:17], v[218:225], v[34:37], v1, v182 op_sel_hi:[0,0,0]
	s_setprio 0
	s_barrier
; #define PG8_STAGE(bufoff, gbase, voff) do { _Pragma("unroll") for (int _i = 0; _i < 2; ++_i) \
;         __builtin_amdgcn_global_load_lds((const unsigned*)((const char*)(gbase) + (voff)[_i]), (PG8_LAS unsigned*)(lds + (bufoff) + ldsw + _i * 8192), 16, 0, 0); } while (0)
; #define PG8_LDA(dst, b, h) do { _Pragma("unroll") for (int m = 0; m < 4; ++m) _Pragma("unroll") for (int k = 0; k < 2; ++k) dst[m][k] = *(const PG8_LAS bf16x8*)(lds + PG8_SA(b, h) + aoff + m * 2048 + k * 1024); } while (0)
; #define PG8_LDB(dst, b, h) do { _Pragma("unroll") for (int n = 0; n < 2; ++n) _Pragma("unroll") for (int k = 0; k < 2; ++k) dst[n][k] = *(const PG8_LAS bf16x8*)(lds + PG8_SB(b, h) + boff + n * 2048 + k * 1024); } while (0)
; #define PG8_MMA(ai, bj, At, Bt) do { __builtin_amdgcn_s_setprio(1); _Pragma("unroll") for (int m = 0; m < 4; ++m) _Pragma("unroll") for (int n = 0; n < 2; ++n) _Pragma("unroll") for (int k = 0; k < 2; ++k) \
;         acc[ai][bj][m][n] = __builtin_amdgcn_mfma_f32_16x16x32_bf16(Bt[n][k], At[m][k], acc[ai][bj][m][n], 0, 0, 0); __builtin_amdgcn_s_setprio(0); } while (0)
; #define PG8_WAIT_V(n) asm volatile("s_waitcnt vmcnt(" #n ")" ::: "memory")
; #define PG8_WAIT_L(n) asm volatile("s_waitcnt lgkmcnt(" #n ")" ::: "memory")
; #define PG8_BAR __builtin_amdgcn_s_barrier()
; #define PG8_SCHED __builtin_amdgcn_sched_barrier(0)
; #define PG8_STAGE(bufoff, gbase, voff) do { _Pragma("unroll") for (int _i = 0; _i < 2; ++_i) \
;         __builtin_amdgcn_global_load_lds((const unsigned*)((const char*)(gbase) + (voff)[_i]), (PG8_LAS unsigned*)(lds + (bufoff) + ldsw + _i * 8192), 16, 0, 0); } while (0)
; #define PG8_WAIT_V(n) asm volatile("s_waitcnt vmcnt(" #n ")" ::: "memory")
; template <class Epi, class Sched, bool ALIGN_EPI = false>
; __device__ __forceinline__ void gemm_phase8(PG8_LAS unsigned char* lds, const Gemm g, const Sched& S, const Epi& E) {
;     ...
;             PG8_LDB(B0, 1, 0); PG8_LDB(B1, 1, 1); PG8_SCHED; PG8_LDA(At, 1, 0); PG8_STAGE(PG8_SA(0, 1), a2 + hstepA, voffA);
;             PG8_WAIT_V(8); PG8_WAIT_L(0); PG8_BAR; PG8_MMA(0, 0, At, B0); PG8_MMA(0, 1, At, B1); PG8_BAR; PG8_SCHED;
;             PG8_LDA(At, 1, 1); PG8_STAGE(PG8_SB(1, 0), b3, voffB); PG8_STAGE(PG8_SB(1, 1), b3 + hstepB, voffB); PG8_STAGE(PG8_SA(1, 0), a3, voffA);
;             PG8_WAIT_V(8); PG8_WAIT_L(0); PG8_BAR; PG8_MMA(1, 0, At, B0); PG8_MMA(1, 1, At, B1); PG8_BAR; PG8_SCHED;
	s_add_i32 s81, 0, 0x18000
	s_add_i32 s82, 0, 0x1c000
	v_add_u32_e32 v6, s81, v184
	v_add_u32_e32 v14, s81, v185
	v_add_u32_e32 v22, s82, v184
	v_add_u32_e32 v30, s82, v185
	ds_read_b128 v[2:5], v6
	ds_read_b128 v[10:13], v6 offset:2048
	ds_read_b128 v[6:9], v14
	ds_read_b128 v[14:17], v14 offset:2048
	ds_read_b128 v[18:21], v22
	ds_read_b128 v[26:29], v22 offset:2048
	ds_read_b128 v[22:25], v30
	ds_read_b128 v[30:33], v30 offset:2048
	s_add_u32 s58, s58, 0x40000
	s_addc_u32 s59, s59, 0
	s_mov_b32 m0, s62
	ds_read_b128 v[194:197], v191 offset:32768
	ds_read_b128 v[202:205], v191 offset:34816
	ds_read_b128 v[198:201], v192 offset:32768
	ds_read_b128 v[206:209], v192 offset:34816
	ds_read_b128 v[210:213], v191 offset:36864
	ds_read_b128 v[218:221], v191 offset:38912
	ds_read_b128 v[214:217], v192 offset:36864
	ds_read_b128 v[222:225], v192 offset:38912
	global_load_lds_dwordx4 v162, s[58:59]
	s_mov_b32 m0, s63
	s_nop 0
	global_load_lds_dwordx4 v166, s[58:59]
	s_waitcnt vmcnt(8)
	s_waitcnt lgkmcnt(0)
	s_barrier
	s_setprio 1
	s_waitcnt lgkmcnt(0)
	v_mfma_scale_f32_16x16x128_f8f6f4 v[158:161], v[2:9], v[194:201], v[158:161], v1, v182 op_sel_hi:[0,0,0]
	v_mfma_scale_f32_16x16x128_f8f6f4 v[154:157], v[10:17], v[194:201], v[154:157], v1, v182 op_sel_hi:[0,0,0]
	v_mfma_scale_f32_16x16x128_f8f6f4 v[150:153], v[2:9], v[202:209], v[150:153], v1, v182 op_sel_hi:[0,0,0]
	v_mfma_scale_f32_16x16x128_f8f6f4 v[138:141], v[10:17], v[202:209], v[138:141], v1, v182 op_sel_hi:[0,0,0]
	v_mfma_scale_f32_16x16x128_f8f6f4 v[130:133], v[2:9], v[210:217], v[130:133], v1, v182 op_sel_hi:[0,0,0]
	v_mfma_scale_f32_16x16x128_f8f6f4 v[122:125], v[10:17], v[210:217], v[122:125], v1, v182 op_sel_hi:[0,0,0]
	v_mfma_scale_f32_16x16x128_f8f6f4 v[118:121], v[2:9], v[218:225], v[118:121], v1, v182 op_sel_hi:[0,0,0]
	v_mfma_scale_f32_16x16x128_f8f6f4 v[106:109], v[10:17], v[218:225], v[106:109], v1, v182 op_sel_hi:[0,0,0]
	s_setprio 0
	s_setprio 1
	v_mfma_scale_f32_16x16x128_f8f6f4 v[146:149], v[18:25], v[194:201], v[146:149], v1, v182 op_sel_hi:[0,0,0]
	v_mfma_scale_f32_16x16x128_f8f6f4 v[142:145], v[26:33], v[194:201], v[142:145], v1, v182 op_sel_hi:[0,0,0]
	v_mfma_scale_f32_16x16x128_f8f6f4 v[134:137], v[18:25], v[202:209], v[134:137], v1, v182 op_sel_hi:[0,0,0]
	v_mfma_scale_f32_16x16x128_f8f6f4 v[126:129], v[26:33], v[202:209], v[126:129], v1, v182 op_sel_hi:[0,0,0]
	v_mfma_scale_f32_16x16x128_f8f6f4 v[114:117], v[18:25], v[210:217], v[114:117], v1, v182 op_sel_hi:[0,0,0]
	v_mfma_scale_f32_16x16x128_f8f6f4 v[110:113], v[26:33], v[210:217], v[110:113], v1, v182 op_sel_hi:[0,0,0]
	v_mfma_scale_f32_16x16x128_f8f6f4 v[102:105], v[18:25], v[218:225], v[102:105], v1, v182 op_sel_hi:[0,0,0]
	v_mfma_scale_f32_16x16x128_f8f6f4 v[98:101], v[26:33], v[218:225], v[98:101], v1, v182 op_sel_hi:[0,0,0]
	s_setprio 0
	s_barrier
	s_add_i32 s101, s81, s61
	s_add_u32 s98, s34, s10
	s_addc_u32 s99, s35, s11
	s_mov_b32 m0, s101
	ds_read_b128 v[194:197], v191 offset:49152
	ds_read_b128 v[202:205], v191 offset:51200
	ds_read_b128 v[198:201], v192 offset:49152
	ds_read_b128 v[206:209], v192 offset:51200
	ds_read_b128 v[210:213], v191 offset:53248
	ds_read_b128 v[218:221], v191 offset:55296
	ds_read_b128 v[214:217], v192 offset:53248
	ds_read_b128 v[222:225], v192 offset:55296
	global_load_lds_dwordx4 v164, s[98:99]
	s_add_i32 m0, s101, 0x2000
	s_add_u32 s34, s34, 0x40080
	s_addc_u32 s35, s35, 0
	s_add_i32 s101, s82, s61
	global_load_lds_dwordx4 v168, s[98:99]
	s_add_u32 s98, s58, s10
	s_addc_u32 s99, s59, s11
	s_sub_u32 s98, s98, 0x40000
	s_subb_u32 s99, s99, 0
	s_mov_b32 m0, s101
	s_nop 0
	global_load_lds_dwordx4 v164, s[34:35]
	s_add_i32 m0, s101, 0x2000
	s_nop 0
	global_load_lds_dwordx4 v168, s[34:35]
	s_mov_b32 m0, s69
	s_nop 0
	global_load_lds_dwordx4 v162, s[98:99]
	s_mov_b32 m0, s70
	s_nop 0
	global_load_lds_dwordx4 v166, s[98:99]
	s_waitcnt vmcnt(8)
	s_waitcnt lgkmcnt(0)
	s_barrier
	s_setprio 1
	s_waitcnt lgkmcnt(0)
	v_mfma_scale_f32_16x16x128_f8f6f4 v[94:97], v[2:9], v[194:201], v[94:97], v1, v182 op_sel_hi:[0,0,0]
	v_mfma_scale_f32_16x16x128_f8f6f4 v[90:93], v[10:17], v[194:201], v[90:93], v1, v182 op_sel_hi:[0,0,0]
	v_mfma_scale_f32_16x16x128_f8f6f4 v[82:85], v[2:9], v[202:209], v[82:85], v1, v182 op_sel_hi:[0,0,0]
	v_mfma_scale_f32_16x16x128_f8f6f4 v[74:77], v[10:17], v[202:209], v[74:77], v1, v182 op_sel_hi:[0,0,0]
	v_mfma_scale_f32_16x16x128_f8f6f4 v[66:69], v[2:9], v[210:217], v[66:69], v1, v182 op_sel_hi:[0,0,0]
	v_mfma_scale_f32_16x16x128_f8f6f4 v[58:61], v[10:17], v[210:217], v[58:61], v1, v182 op_sel_hi:[0,0,0]
	v_mfma_scale_f32_16x16x128_f8f6f4 v[50:53], v[2:9], v[218:225], v[50:53], v1, v182 op_sel_hi:[0,0,0]
	v_mfma_scale_f32_16x16x128_f8f6f4 v[42:45], v[10:17], v[218:225], v[42:45], v1, v182 op_sel_hi:[0,0,0]
	s_setprio 0
	s_setprio 1
	v_mfma_scale_f32_16x16x128_f8f6f4 v[86:89], v[18:25], v[194:201], v[86:89], v1, v182 op_sel_hi:[0,0,0]
	v_mfma_scale_f32_16x16x128_f8f6f4 v[78:81], v[26:33], v[194:201], v[78:81], v1, v182 op_sel_hi:[0,0,0]
	v_mfma_scale_f32_16x16x128_f8f6f4 v[70:73], v[18:25], v[202:209], v[70:73], v1, v182 op_sel_hi:[0,0,0]
	v_mfma_scale_f32_16x16x128_f8f6f4 v[62:65], v[26:33], v[202:209], v[62:65], v1, v182 op_sel_hi:[0,0,0]
	v_mfma_scale_f32_16x16x128_f8f6f4 v[54:57], v[18:25], v[210:217], v[54:57], v1, v182 op_sel_hi:[0,0,0]
	v_mfma_scale_f32_16x16x128_f8f6f4 v[46:49], v[26:33], v[210:217], v[46:49], v1, v182 op_sel_hi:[0,0,0]
	v_mfma_scale_f32_16x16x128_f8f6f4 v[38:41], v[18:25], v[218:225], v[38:41], v1, v182 op_sel_hi:[0,0,0]
	v_mfma_scale_f32_16x16x128_f8f6f4 v[34:37], v[26:33], v[218:225], v[34:37], v1, v182 op_sel_hi:[0,0,0]
	s_setprio 0
	s_barrier
; #define PG8_STAGE(bufoff, gbase, voff) do { _Pragma("unroll") for (int _i = 0; _i < 2; ++_i) \
;         __builtin_amdgcn_global_load_lds((const unsigned*)((const char*)(gbase) + (voff)[_i]), (PG8_LAS unsigned*)(lds + (bufoff) + ldsw + _i * 8192), 16, 0, 0); } while (0)
; #define PG8_LDA(dst, b, h) do { _Pragma("unroll") for (int m = 0; m < 4; ++m) _Pragma("unroll") for (int k = 0; k < 2; ++k) dst[m][k] = *(const PG8_LAS bf16x8*)(lds + PG8_SA(b, h) + aoff + m * 2048 + k * 1024); } while (0)
; #define PG8_LDB(dst, b, h) do { _Pragma("unroll") for (int n = 0; n < 2; ++n) _Pragma("unroll") for (int k = 0; k < 2; ++k) dst[n][k] = *(const PG8_LAS bf16x8*)(lds + PG8_SB(b, h) + boff + n * 2048 + k * 1024); } while (0)
; #define PG8_MMA(ai, bj, At, Bt) do { __builtin_amdgcn_s_setprio(1); _Pragma("unroll") for (int m = 0; m < 4; ++m) _Pragma("unroll") for (int n = 0; n < 2; ++n) _Pragma("unroll") for (int k = 0; k < 2; ++k) \
;         acc[ai][bj][m][n] = __builtin_amdgcn_mfma_f32_16x16x32_bf16(Bt[n][k], At[m][k], acc[ai][bj][m][n], 0, 0, 0); __builtin_amdgcn_s_setprio(0); } while (0)
; #define PG8_WAIT_V(n) asm volatile("s_waitcnt vmcnt(" #n ")" ::: "memory")
; #define PG8_WAIT_L(n) asm volatile("s_waitcnt lgkmcnt(" #n ")" ::: "memory")
; template <class Epi, class Sched, bool ALIGN_EPI = false>
; __device__ __forceinline__ void gemm_phase8(PG8_LAS unsigned char* lds, const Gemm g, const Sched& S, const Epi& E) {
;     ...
;         for (int t = 0; t < nt; t += 2) {
;             const bool last = (t == nt - 2);
;             const char* a1 = cA + (size_t)(t + 1) * kstep;
;             const char* a2 = last ? nA : cA + (size_t)(t + 2) * kstep; const char* b2 = last ? nB : cB + (size_t)(t + 2) * kstep;
;             const char* a3 = a2 + kstep; const char* b3 = b2 + kstep;
;             if (last && has_next) S.a_ready(nxt);
;             PG8_LDB(B0, 0, 0); PG8_LDB(B1, 0, 1); PG8_SCHED; PG8_LDA(At, 0, 0); PG8_STAGE(PG8_SA(1, 1), a1 + hstepA, voffA);
;             PG8_WAIT_V(8); PG8_WAIT_L(0); PG8_BAR; PG8_MMA(0, 0, At, B0); PG8_MMA(0, 1, At, B1); PG8_BAR; PG8_SCHED;
;             PG8_LDA(At, 0, 1); PG8_STAGE(PG8_SB(0, 0), b2, voffB); PG8_STAGE(PG8_SB(0, 1), b2 + hstepB, voffB); PG8_STAGE(PG8_SA(0, 0), a2, voffA);
;             PG8_WAIT_V(8); PG8_WAIT_L(0); PG8_BAR; PG8_MMA(1, 0, At, B0); PG8_MMA(1, 1, At, B1); PG8_BAR; PG8_SCHED;
	s_add_u32 s56, s56, 0x100
	s_addc_u32 s57, s57, 0
	s_add_u32 s78, s78, 0x100
	s_addc_u32 s79, s79, 0
	s_cmp_ge_u32 s80, s76
	s_mov_b32 s58, s80
	ds_read_b128 v[18:21], v187
	ds_read_b128 v[26:29], v187 offset:2048
	ds_read_b128 v[22:25], v188
	ds_read_b128 v[30:33], v188 offset:2048
	ds_read_b128 v[2:5], v189
	ds_read_b128 v[10:13], v189 offset:2048
	ds_read_b128 v[6:9], v190
	ds_read_b128 v[14:17], v190 offset:2048
	s_add_i32 s80, s58, 2
	s_add_u32 s34, s56, 0xfffc0080
	s_addc_u32 s35, s57, -1
	s_cmp_eq_u32 s77, s58
	s_cselect_b32 s58, s31, s34
	s_cselect_b32 s59, s19, s35
	s_cselect_b32 s35, s21, s79
	s_cselect_b32 s34, s75, s78
	s_add_i32 m0, s29, 0xc000
	ds_read_b128 v[174:177], v191
	ds_read_b128 v[194:197], v191 offset:2048
	ds_read_b128 v[178:181], v192
	ds_read_b128 v[198:201], v192 offset:2048
	ds_read_b128 v[202:205], v191 offset:4096
	ds_read_b128 v[210:213], v191 offset:6144
	ds_read_b128 v[206:209], v192 offset:4096
	ds_read_b128 v[214:217], v192 offset:6144
	global_load_lds_dwordx4 v170, s[56:57]
	s_add_i32 m0, s29, 0xe000
	s_nop 0
	global_load_lds_dwordx4 v172, s[56:57]
	s_waitcnt vmcnt(8)
	s_waitcnt lgkmcnt(0)
	s_barrier
	s_setprio 1
	s_waitcnt lgkmcnt(0)
	v_mfma_scale_f32_16x16x128_f8f6f4 v[158:161], v[18:25], v[174:181], v[158:161], v1, v182 op_sel_hi:[0,0,0]
	v_mfma_scale_f32_16x16x128_f8f6f4 v[154:157], v[26:33], v[174:181], v[154:157], v1, v182 op_sel_hi:[0,0,0]
	v_mfma_scale_f32_16x16x128_f8f6f4 v[150:153], v[18:25], v[194:201], v[150:153], v1, v182 op_sel_hi:[0,0,0]
	v_mfma_scale_f32_16x16x128_f8f6f4 v[138:141], v[26:33], v[194:201], v[138:141], v1, v182 op_sel_hi:[0,0,0]
	v_mfma_scale_f32_16x16x128_f8f6f4 v[130:133], v[18:25], v[202:209], v[130:133], v1, v182 op_sel_hi:[0,0,0]
	v_mfma_scale_f32_16x16x128_f8f6f4 v[122:125], v[26:33], v[202:209], v[122:125], v1, v182 op_sel_hi:[0,0,0]
	v_mfma_scale_f32_16x16x128_f8f6f4 v[118:121], v[18:25], v[210:217], v[118:121], v1, v182 op_sel_hi:[0,0,0]
	v_mfma_scale_f32_16x16x128_f8f6f4 v[106:109], v[26:33], v[210:217], v[106:109], v1, v182 op_sel_hi:[0,0,0]
	s_setprio 0
	s_setprio 1
	v_mfma_scale_f32_16x16x128_f8f6f4 v[146:149], v[2:9], v[174:181], v[146:149], v1, v182 op_sel_hi:[0,0,0]
	v_mfma_scale_f32_16x16x128_f8f6f4 v[142:145], v[10:17], v[174:181], v[142:145], v1, v182 op_sel_hi:[0,0,0]
	v_mfma_scale_f32_16x16x128_f8f6f4 v[134:137], v[2:9], v[194:201], v[134:137], v1, v182 op_sel_hi:[0,0,0]
	v_mfma_scale_f32_16x16x128_f8f6f4 v[126:129], v[10:17], v[194:201], v[126:129], v1, v182 op_sel_hi:[0,0,0]
	v_mfma_scale_f32_16x16x128_f8f6f4 v[114:117], v[2:9], v[202:209], v[114:117], v1, v182 op_sel_hi:[0,0,0]
	v_mfma_scale_f32_16x16x128_f8f6f4 v[110:113], v[10:17], v[202:209], v[110:113], v1, v182 op_sel_hi:[0,0,0]
	v_mfma_scale_f32_16x16x128_f8f6f4 v[102:105], v[2:9], v[210:217], v[102:105], v1, v182 op_sel_hi:[0,0,0]
	v_mfma_scale_f32_16x16x128_f8f6f4 v[98:101], v[10:17], v[210:217], v[98:101], v1, v182 op_sel_hi:[0,0,0]
	s_setprio 0
	s_barrier
	s_add_i32 s81, s71, s61
	s_mov_b32 m0, s81
	ds_read_b128 v[194:197], v191 offset:16384
	ds_read_b128 v[202:205], v191 offset:18432
	ds_read_b128 v[198:201], v192 offset:16384
	ds_read_b128 v[206:209], v192 offset:18432
	ds_read_b128 v[210:213], v191 offset:20480
	ds_read_b128 v[218:221], v191 offset:22528
	ds_read_b128 v[214:217], v192 offset:20480
	ds_read_b128 v[222:225], v192 offset:22528
	global_load_lds_dwordx4 v164, s[34:35]
	s_add_i32 m0, s81, 0x2000
	s_add_u32 s82, s34, 0x40000
	s_addc_u32 s83, s35, 0
	s_add_i32 s81, s72, s61
	global_load_lds_dwordx4 v168, s[34:35]
	s_mov_b32 m0, s81
	s_nop 0
	global_load_lds_dwordx4 v164, s[82:83]
	s_add_i32 m0, s81, 0x2000
	s_nop 0
	global_load_lds_dwordx4 v168, s[82:83]
	s_mov_b32 m0, s29
	s_nop 0
	global_load_lds_dwordx4 v162, s[58:59]
	s_mov_b32 m0, s53
	s_nop 0
	global_load_lds_dwordx4 v166, s[58:59]
	s_waitcnt vmcnt(8)
	s_waitcnt lgkmcnt(0)
	s_barrier
	s_setprio 1
	s_waitcnt lgkmcnt(0)
	v_mfma_scale_f32_16x16x128_f8f6f4 v[94:97], v[18:25], v[194:201], v[94:97], v1, v182 op_sel_hi:[0,0,0]
	v_mfma_scale_f32_16x16x128_f8f6f4 v[90:93], v[26:33], v[194:201], v[90:93], v1, v182 op_sel_hi:[0,0,0]
	v_mfma_scale_f32_16x16x128_f8f6f4 v[82:85], v[18:25], v[202:209], v[82:85], v1, v182 op_sel_hi:[0,0,0]
	v_mfma_scale_f32_16x16x128_f8f6f4 v[74:77], v[26:33], v[202:209], v[74:77], v1, v182 op_sel_hi:[0,0,0]
	v_mfma_scale_f32_16x16x128_f8f6f4 v[66:69], v[18:25], v[210:217], v[66:69], v1, v182 op_sel_hi:[0,0,0]
	v_mfma_scale_f32_16x16x128_f8f6f4 v[58:61], v[26:33], v[210:217], v[58:61], v1, v182 op_sel_hi:[0,0,0]
	v_mfma_scale_f32_16x16x128_f8f6f4 v[50:53], v[18:25], v[218:225], v[50:53], v1, v182 op_sel_hi:[0,0,0]
	v_mfma_scale_f32_16x16x128_f8f6f4 v[42:45], v[26:33], v[218:225], v[42:45], v1, v182 op_sel_hi:[0,0,0]
	s_setprio 0
	s_setprio 1
	v_mfma_scale_f32_16x16x128_f8f6f4 v[86:89], v[2:9], v[194:201], v[86:89], v1, v182 op_sel_hi:[0,0,0]
	v_mfma_scale_f32_16x16x128_f8f6f4 v[78:81], v[10:17], v[194:201], v[78:81], v1, v182 op_sel_hi:[0,0,0]
	v_mfma_scale_f32_16x16x128_f8f6f4 v[70:73], v[2:9], v[202:209], v[70:73], v1, v182 op_sel_hi:[0,0,0]
	v_mfma_scale_f32_16x16x128_f8f6f4 v[62:65], v[10:17], v[202:209], v[62:65], v1, v182 op_sel_hi:[0,0,0]
	v_mfma_scale_f32_16x16x128_f8f6f4 v[54:57], v[2:9], v[210:217], v[54:57], v1, v182 op_sel_hi:[0,0,0]
	v_mfma_scale_f32_16x16x128_f8f6f4 v[46:49], v[10:17], v[210:217], v[46:49], v1, v182 op_sel_hi:[0,0,0]
	v_mfma_scale_f32_16x16x128_f8f6f4 v[38:41], v[2:9], v[218:225], v[38:41], v1, v182 op_sel_hi:[0,0,0]
	v_mfma_scale_f32_16x16x128_f8f6f4 v[34:37], v[10:17], v[218:225], v[34:37], v1, v182 op_sel_hi:[0,0,0]
	s_setprio 0
	s_barrier
; #define PG8_STAGE(bufoff, gbase, voff) do { _Pragma("unroll") for (int _i = 0; _i < 2; ++_i) \
;         __builtin_amdgcn_global_load_lds((const unsigned*)((const char*)(gbase) + (voff)[_i]), (PG8_LAS unsigned*)(lds + (bufoff) + ldsw + _i * 8192), 16, 0, 0); } while (0)
; #define PG8_LDA(dst, b, h) do { _Pragma("unroll") for (int m = 0; m < 4; ++m) _Pragma("unroll") for (int k = 0; k < 2; ++k) dst[m][k] = *(const PG8_LAS bf16x8*)(lds + PG8_SA(b, h) + aoff + m * 2048 + k * 1024); } while (0)
; #define PG8_LDB(dst, b, h) do { _Pragma("unroll") for (int n = 0; n < 2; ++n) _Pragma("unroll") for (int k = 0; k < 2; ++k) dst[n][k] = *(const PG8_LAS bf16x8*)(lds + PG8_SB(b, h) + boff + n * 2048 + k * 1024); } while (0)
; #define PG8_MMA(ai, bj, At, Bt) do { __builtin_amdgcn_s_setprio(1); _Pragma("unroll") for (int m = 0; m < 4; ++m) _Pragma("unroll") for (int n = 0; n < 2; ++n) _Pragma("unroll") for (int k = 0; k < 2; ++k) \
;         acc[ai][bj][m][n] = __builtin_amdgcn_mfma_f32_16x16x32_bf16(Bt[n][k], At[m][k], acc[ai][bj][m][n], 0, 0, 0); __builtin_amdgcn_s_setprio(0); } while (0)
; #define PG8_WAIT_V(n) asm volatile("s_waitcnt vmcnt(" #n ")" ::: "memory")
; #define PG8_WAIT_L(n) asm volatile("s_waitcnt lgkmcnt(" #n ")" ::: "memory")
; #define PG8_BAR __builtin_amdgcn_s_barrier()
; #define PG8_SCHED __builtin_amdgcn_sched_barrier(0)
; #define PG8_STAGE(bufoff, gbase, voff) do { _Pragma("unroll") for (int _i = 0; _i < 2; ++_i) \
;         __builtin_amdgcn_global_load_lds((const unsigned*)((const char*)(gbase) + (voff)[_i]), (PG8_LAS unsigned*)(lds + (bufoff) + ldsw + _i * 8192), 16, 0, 0); } while (0)
; #define PG8_BAR __builtin_amdgcn_s_barrier()
; template <class Epi, class Sched, bool ALIGN_EPI = false>
; __device__ __forceinline__ void gemm_phase8(PG8_LAS unsigned char* lds, const Gemm g, const Sched& S, const Epi& E) {
;     ...
;             PG8_LDB(B0, 1, 0); PG8_LDB(B1, 1, 1); PG8_SCHED; PG8_LDA(At, 1, 0); PG8_STAGE(PG8_SA(0, 1), a2 + hstepA, voffA);
;             PG8_WAIT_V(8); PG8_WAIT_L(0); PG8_BAR; PG8_MMA(0, 0, At, B0); PG8_MMA(0, 1, At, B1); PG8_BAR; PG8_SCHED;
;             PG8_LDA(At, 1, 1); PG8_STAGE(PG8_SB(1, 0), b3, voffB); PG8_STAGE(PG8_SB(1, 1), b3 + hstepB, voffB); PG8_STAGE(PG8_SA(1, 0), a3, voffA);
;             PG8_WAIT_V(8); PG8_WAIT_L(0); PG8_BAR; PG8_MMA(1, 0, At, B0); PG8_MMA(1, 1, At, B1); PG8_BAR; PG8_SCHED;
;         }
	s_add_i32 s81, 0, 0x18000
	s_add_i32 s82, 0, 0x1c000
	v_add_u32_e32 v6, s81, v184
	v_add_u32_e32 v14, s81, v185
	v_add_u32_e32 v22, s82, v184
	v_add_u32_e32 v30, s82, v185
	ds_read_b128 v[2:5], v6
	ds_read_b128 v[10:13], v6 offset:2048
	ds_read_b128 v[6:9], v14
	ds_read_b128 v[14:17], v14 offset:2048
	ds_read_b128 v[18:21], v22
	ds_read_b128 v[26:29], v22 offset:2048
	ds_read_b128 v[22:25], v30
	ds_read_b128 v[30:33], v30 offset:2048
	s_add_u32 s58, s58, 0x40000
	s_addc_u32 s59, s59, 0
	s_mov_b32 m0, s62
	ds_read_b128 v[194:197], v191 offset:32768
	ds_read_b128 v[202:205], v191 offset:34816
	ds_read_b128 v[198:201], v192 offset:32768
	ds_read_b128 v[206:209], v192 offset:34816
	ds_read_b128 v[210:213], v191 offset:36864
	ds_read_b128 v[218:221], v191 offset:38912
	ds_read_b128 v[214:217], v192 offset:36864
	ds_read_b128 v[222:225], v192 offset:38912
	global_load_lds_dwordx4 v162, s[58:59]
	s_mov_b32 m0, s63
	s_nop 0
	global_load_lds_dwordx4 v166, s[58:59]
	s_waitcnt vmcnt(8)
	s_waitcnt lgkmcnt(0)
	s_barrier
	s_setprio 1
	s_waitcnt lgkmcnt(0)
	v_mfma_scale_f32_16x16x128_f8f6f4 v[158:161], v[2:9], v[194:201], v[158:161], v1, v182 op_sel_hi:[0,0,0]
	v_mfma_scale_f32_16x16x128_f8f6f4 v[154:157], v[10:17], v[194:201], v[154:157], v1, v182 op_sel_hi:[0,0,0]
	v_mfma_scale_f32_16x16x128_f8f6f4 v[150:153], v[2:9], v[202:209], v[150:153], v1, v182 op_sel_hi:[0,0,0]
	v_mfma_scale_f32_16x16x128_f8f6f4 v[138:141], v[10:17], v[202:209], v[138:141], v1, v182 op_sel_hi:[0,0,0]
	v_mfma_scale_f32_16x16x128_f8f6f4 v[130:133], v[2:9], v[210:217], v[130:133], v1, v182 op_sel_hi:[0,0,0]
	v_mfma_scale_f32_16x16x128_f8f6f4 v[122:125], v[10:17], v[210:217], v[122:125], v1, v182 op_sel_hi:[0,0,0]
	v_mfma_scale_f32_16x16x128_f8f6f4 v[118:121], v[2:9], v[218:225], v[118:121], v1, v182 op_sel_hi:[0,0,0]
	v_mfma_scale_f32_16x16x128_f8f6f4 v[106:109], v[10:17], v[218:225], v[106:109], v1, v182 op_sel_hi:[0,0,0]
	s_setprio 0
	s_setprio 1
	v_mfma_scale_f32_16x16x128_f8f6f4 v[146:149], v[18:25], v[194:201], v[146:149], v1, v182 op_sel_hi:[0,0,0]
	v_mfma_scale_f32_16x16x128_f8f6f4 v[142:145], v[26:33], v[194:201], v[142:145], v1, v182 op_sel_hi:[0,0,0]
	v_mfma_scale_f32_16x16x128_f8f6f4 v[134:137], v[18:25], v[202:209], v[134:137], v1, v182 op_sel_hi:[0,0,0]
	v_mfma_scale_f32_16x16x128_f8f6f4 v[126:129], v[26:33], v[202:209], v[126:129], v1, v182 op_sel_hi:[0,0,0]
	v_mfma_scale_f32_16x16x128_f8f6f4 v[114:117], v[18:25], v[210:217], v[114:117], v1, v182 op_sel_hi:[0,0,0]
	v_mfma_scale_f32_16x16x128_f8f6f4 v[110:113], v[26:33], v[210:217], v[110:113], v1, v182 op_sel_hi:[0,0,0]
	v_mfma_scale_f32_16x16x128_f8f6f4 v[102:105], v[18:25], v[218:225], v[102:105], v1, v182 op_sel_hi:[0,0,0]
	v_mfma_scale_f32_16x16x128_f8f6f4 v[98:101], v[26:33], v[218:225], v[98:101], v1, v182 op_sel_hi:[0,0,0]
	s_setprio 0
	s_barrier
	s_add_i32 s101, s81, s61
	s_add_u32 s98, s34, s10
	s_addc_u32 s99, s35, s11
	s_mov_b32 m0, s101
	ds_read_b128 v[194:197], v191 offset:49152
	ds_read_b128 v[202:205], v191 offset:51200
	ds_read_b128 v[198:201], v192 offset:49152
	ds_read_b128 v[206:209], v192 offset:51200
	ds_read_b128 v[210:213], v191 offset:53248
	ds_read_b128 v[218:221], v191 offset:55296
	ds_read_b128 v[214:217], v192 offset:53248
	ds_read_b128 v[222:225], v192 offset:55296
	global_load_lds_dwordx4 v164, s[98:99]
	s_add_i32 m0, s101, 0x2000
	s_add_u32 s34, s34, 0x40080
	s_addc_u32 s35, s35, 0
	s_add_i32 s101, s82, s61
	global_load_lds_dwordx4 v168, s[98:99]
	s_add_u32 s98, s58, s10
	s_addc_u32 s99, s59, s11
	s_sub_u32 s98, s98, 0x40000
	s_subb_u32 s99, s99, 0
	s_mov_b32 m0, s101
	s_nop 0
	global_load_lds_dwordx4 v164, s[34:35]
	s_add_i32 m0, s101, 0x2000
	s_nop 0
	global_load_lds_dwordx4 v168, s[34:35]
	s_mov_b32 m0, s69
	s_nop 0
	global_load_lds_dwordx4 v162, s[98:99]
	s_mov_b32 m0, s70
	s_nop 0
	global_load_lds_dwordx4 v166, s[98:99]
	s_waitcnt vmcnt(8)
	s_waitcnt lgkmcnt(0)
	s_barrier
	s_setprio 1
	s_waitcnt lgkmcnt(0)
	v_mfma_scale_f32_16x16x128_f8f6f4 v[94:97], v[2:9], v[194:201], v[94:97], v1, v182 op_sel_hi:[0,0,0]
	v_mfma_scale_f32_16x16x128_f8f6f4 v[90:93], v[10:17], v[194:201], v[90:93], v1, v182 op_sel_hi:[0,0,0]
	v_mfma_scale_f32_16x16x128_f8f6f4 v[82:85], v[2:9], v[202:209], v[82:85], v1, v182 op_sel_hi:[0,0,0]
	v_mfma_scale_f32_16x16x128_f8f6f4 v[74:77], v[10:17], v[202:209], v[74:77], v1, v182 op_sel_hi:[0,0,0]
	v_mfma_scale_f32_16x16x128_f8f6f4 v[66:69], v[2:9], v[210:217], v[66:69], v1, v182 op_sel_hi:[0,0,0]
	v_mfma_scale_f32_16x16x128_f8f6f4 v[58:61], v[10:17], v[210:217], v[58:61], v1, v182 op_sel_hi:[0,0,0]
	v_mfma_scale_f32_16x16x128_f8f6f4 v[50:53], v[2:9], v[218:225], v[50:53], v1, v182 op_sel_hi:[0,0,0]
	v_mfma_scale_f32_16x16x128_f8f6f4 v[42:45], v[10:17], v[218:225], v[42:45], v1, v182 op_sel_hi:[0,0,0]
	s_setprio 0
	s_setprio 1
	v_mfma_scale_f32_16x16x128_f8f6f4 v[86:89], v[18:25], v[194:201], v[86:89], v1, v182 op_sel_hi:[0,0,0]
	v_mfma_scale_f32_16x16x128_f8f6f4 v[78:81], v[26:33], v[194:201], v[78:81], v1, v182 op_sel_hi:[0,0,0]
	v_mfma_scale_f32_16x16x128_f8f6f4 v[70:73], v[18:25], v[202:209], v[70:73], v1, v182 op_sel_hi:[0,0,0]
	v_mfma_scale_f32_16x16x128_f8f6f4 v[62:65], v[26:33], v[202:209], v[62:65], v1, v182 op_sel_hi:[0,0,0]
	v_mfma_scale_f32_16x16x128_f8f6f4 v[54:57], v[18:25], v[210:217], v[54:57], v1, v182 op_sel_hi:[0,0,0]
	v_mfma_scale_f32_16x16x128_f8f6f4 v[46:49], v[26:33], v[210:217], v[46:49], v1, v182 op_sel_hi:[0,0,0]
	v_mfma_scale_f32_16x16x128_f8f6f4 v[38:41], v[18:25], v[218:225], v[38:41], v1, v182 op_sel_hi:[0,0,0]
	v_mfma_scale_f32_16x16x128_f8f6f4 v[34:37], v[26:33], v[218:225], v[34:37], v1, v182 op_sel_hi:[0,0,0]
	s_setprio 0
	s_barrier
	s_add_u32 s56, s56, 0x100
	s_addc_u32 s57, s57, 0
	s_add_u32 s78, s78, 0x100
	s_addc_u32 s79, s79, 0
	s_cmp_ge_u32 s80, s76
	s_mov_b32 s58, s80
	s_cbranch_scc0 .LBB0_1187
.Lpx_3:
	s_and_b64 vcc, exec, s[12:13]
	s_cbranch_vccz .LBB0_1190
	s_barrier

; #define PG8_STAGE(bufoff, gbase, voff) do { _Pragma("unroll") for (int _i = 0; _i < 2; ++_i) \
;         __builtin_amdgcn_global_load_lds((const unsigned*)((const char*)(gbase) + (voff)[_i]), (PG8_LAS unsigned*)(lds + (bufoff) + ldsw + _i * 8192), 16, 0, 0); } while (0)
; #define PG8_LDA(dst, b, h) do { _Pragma("unroll") for (int m = 0; m < 4; ++m) _Pragma("unroll") for (int k = 0; k < 2; ++k) dst[m][k] = *(const PG8_LAS bf16x8*)(lds + PG8_SA(b, h) + aoff + m * 2048 + k * 1024); } while (0)
; #define PG8_LDB(dst, b, h) do { _Pragma("unroll") for (int n = 0; n < 2; ++n) _Pragma("unroll") for (int k = 0; k < 2; ++k) dst[n][k] = *(const PG8_LAS bf16x8*)(lds + PG8_SB(b, h) + boff + n * 2048 + k * 1024); } while (0)
; #define PG8_WAIT_V(n) asm volatile("s_waitcnt vmcnt(" #n ")" ::: "memory")
; #define PG8_WAIT_L(n) asm volatile("s_waitcnt lgkmcnt(" #n ")" ::: "memory")
; template <class Epi, class Sched, bool ALIGN_EPI = false>
; __device__ __forceinline__ void gemm_phase8(PG8_LAS unsigned char* lds, const Gemm g, const Sched& S, const Epi& E) {
;     ...
;         const bool has_next = S.next(ui + 1, nxt);
;         const size_t nko = (has_next && nxt.kp > 0) ? (size_t)nxt.kp * g.kpiece : 0;
;         const char* nA = has_next ? (const char*)g.A + (size_t)nxt.pm * tstepA + (size_t)nxt.pn * astep + nko : cA; const char* nB = has_next ? (const char*)g.Bt + (size_t)nxt.pn * tstepB + nko : cB;
;         const int nt = (cur.kp < 0 ? g.K : g.kpiece) / 128;
;         for (int t = 0; t < nt; t += 2) {
;             const bool last = (t == nt - 2);
;             const char* a1 = cA + (size_t)(t + 1) * kstep;
;             const char* a2 = last ? nA : cA + (size_t)(t + 2) * kstep; const char* b2 = last ? nB : cB + (size_t)(t + 2) * kstep;
;             const char* a3 = a2 + kstep; const char* b3 = b2 + kstep;
;             if (last && has_next) S.a_ready(nxt);
;             PG8_LDB(B0, 0, 0); PG8_LDB(B1, 0, 1); PG8_SCHED; PG8_LDA(At, 0, 0); PG8_STAGE(PG8_SA(1, 1), a1 + hstepA, voffA);
;             PG8_WAIT_V(8); PG8_WAIT_L(0); PG8_BAR; PG8_MMA(0, 0, At, B0); PG8_MMA(0, 1, At, B1); PG8_BAR; PG8_SCHED;
;             PG8_LDA(At, 0, 1); PG8_STAGE(PG8_SB(0, 0), b2, voffB); PG8_STAGE(PG8_SB(0, 1), b2 + hstepB, voffB); PG8_STAGE(PG8_SA(0, 0), a2, voffA);
;             PG8_WAIT_V(8); PG8_WAIT_L(0); PG8_BAR; PG8_MMA(1, 0, At, B0); PG8_MMA(1, 1, At, B1); PG8_BAR; PG8_SCHED;
.LBB0_1421:
	s_ashr_i32 s13, s12, 31
	s_lshl_b64 s[14:15], s[12:13], 19
	s_add_u32 s14, s26, s14
	s_addc_u32 s15, s27, s15
	s_and_b64 s[16:17], s[2:3], exec
	s_cselect_b32 s13, s15, s21
	s_cselect_b32 s45, s14, s20
	s_ashr_i32 s11, s10, 31
	s_lshl_b64 s[16:17], s[10:11], 19
	s_add_u32 s16, s28, s16
	s_addc_u32 s17, s29, s17
	s_and_b64 s[24:25], s[2:3], exec
	s_cselect_b32 s11, s17, s23
	s_cselect_b32 s52, s16, s22
	s_add_u32 s20, s20, 0x40080
	s_addc_u32 s21, s21, 0
	s_add_u32 s53, s22, 0x100
	s_addc_u32 s54, s23, 0
	s_mov_b32 s55, -2
	ds_read_b128 v[18:21], v191
	ds_read_b128 v[26:29], v191 offset:2048
	ds_read_b128 v[22:25], v192
	ds_read_b128 v[30:33], v192 offset:2048
	ds_read_b128 v[2:5], v193
	ds_read_b128 v[10:13], v193 offset:2048
	ds_read_b128 v[6:9], v194
	ds_read_b128 v[14:17], v194 offset:2048
	s_add_u32 s22, s20, 0xfffc0080
	s_addc_u32 s23, s21, -1
	s_cmp_eq_u32 s55, 12
	s_cselect_b32 s25, s13, s23
	s_cselect_b32 s24, s45, s22
	s_cselect_b32 s23, s11, s54
	s_cselect_b32 s22, s52, s53
	s_add_i32 m0, s19, 0xc000
	ds_read_b128 v[178:181], v195
	ds_read_b128 v[198:201], v195 offset:2048
	ds_read_b128 v[182:185], v196
	ds_read_b128 v[202:205], v196 offset:2048
	ds_read_b128 v[206:209], v195 offset:4096
	ds_read_b128 v[214:217], v195 offset:6144
	ds_read_b128 v[210:213], v196 offset:4096
	ds_read_b128 v[218:221], v196 offset:6144
	global_load_lds_dwordx4 v170, s[20:21]
	s_add_i32 m0, s19, 0xe000
	s_nop 0
	global_load_lds_dwordx4 v172, s[20:21]
	s_waitcnt vmcnt(8)
	s_waitcnt lgkmcnt(0)
	s_barrier
	s_setprio 1
	s_waitcnt lgkmcnt(0)
	v_mfma_scale_f32_16x16x128_f8f6f4 v[158:161], v[18:25], v[178:185], 0, v1, v186 op_sel_hi:[0,0,0]
	v_mfma_scale_f32_16x16x128_f8f6f4 v[150:153], v[26:33], v[178:185], 0, v1, v186 op_sel_hi:[0,0,0]
	v_mfma_scale_f32_16x16x128_f8f6f4 v[142:145], v[18:25], v[198:205], 0, v1, v186 op_sel_hi:[0,0,0]
	v_mfma_scale_f32_16x16x128_f8f6f4 v[134:137], v[26:33], v[198:205], 0, v1, v186 op_sel_hi:[0,0,0]
	v_mfma_scale_f32_16x16x128_f8f6f4 v[126:129], v[18:25], v[206:213], 0, v1, v186 op_sel_hi:[0,0,0]
	v_mfma_scale_f32_16x16x128_f8f6f4 v[118:121], v[26:33], v[206:213], 0, v1, v186 op_sel_hi:[0,0,0]
	v_mfma_scale_f32_16x16x128_f8f6f4 v[110:113], v[18:25], v[214:221], 0, v1, v186 op_sel_hi:[0,0,0]
	v_mfma_scale_f32_16x16x128_f8f6f4 v[102:105], v[26:33], v[214:221], 0, v1, v186 op_sel_hi:[0,0,0]
	s_setprio 0
	s_setprio 1
	v_mfma_scale_f32_16x16x128_f8f6f4 v[154:157], v[2:9], v[178:185], 0, v1, v186 op_sel_hi:[0,0,0]
	v_mfma_scale_f32_16x16x128_f8f6f4 v[146:149], v[10:17], v[178:185], 0, v1, v186 op_sel_hi:[0,0,0]
	v_mfma_scale_f32_16x16x128_f8f6f4 v[138:141], v[2:9], v[198:205], 0, v1, v186 op_sel_hi:[0,0,0]
	v_mfma_scale_f32_16x16x128_f8f6f4 v[130:133], v[10:17], v[198:205], 0, v1, v186 op_sel_hi:[0,0,0]
	v_mfma_scale_f32_16x16x128_f8f6f4 v[122:125], v[2:9], v[206:213], 0, v1, v186 op_sel_hi:[0,0,0]
	v_mfma_scale_f32_16x16x128_f8f6f4 v[114:117], v[10:17], v[206:213], 0, v1, v186 op_sel_hi:[0,0,0]
	v_mfma_scale_f32_16x16x128_f8f6f4 v[106:109], v[2:9], v[214:221], 0, v1, v186 op_sel_hi:[0,0,0]
	v_mfma_scale_f32_16x16x128_f8f6f4 v[98:101], v[10:17], v[214:221], 0, v1, v186 op_sel_hi:[0,0,0]
	s_setprio 0
	s_barrier
	s_add_i32 s56, s41, s30
	s_mov_b32 m0, s56
	ds_read_b128 v[198:201], v195 offset:16384
	ds_read_b128 v[206:209], v195 offset:18432
	ds_read_b128 v[202:205], v196 offset:16384
	ds_read_b128 v[210:213], v196 offset:18432
	ds_read_b128 v[214:217], v195 offset:20480
	ds_read_b128 v[222:225], v195 offset:22528
	ds_read_b128 v[218:221], v196 offset:20480
	ds_read_b128 v[226:229], v196 offset:22528
	global_load_lds_dwordx4 v164, s[22:23]
	s_add_i32 m0, s56, 0x2000
	s_add_u32 s56, s22, 0x40000
	s_addc_u32 s57, s23, 0
	s_add_i32 s58, s42, s30
	global_load_lds_dwordx4 v168, s[22:23]
	s_mov_b32 m0, s58
	s_nop 0
	global_load_lds_dwordx4 v164, s[56:57]
	s_add_i32 m0, s58, 0x2000
	s_nop 0
	global_load_lds_dwordx4 v168, s[56:57]
	s_mov_b32 m0, s19
	s_nop 0
	global_load_lds_dwordx4 v162, s[24:25]
	s_mov_b32 m0, s34
	s_nop 0
	global_load_lds_dwordx4 v166, s[24:25]
	s_waitcnt vmcnt(8)
	s_waitcnt lgkmcnt(0)
	s_barrier
	s_setprio 1
	s_waitcnt lgkmcnt(0)
	v_mfma_scale_f32_16x16x128_f8f6f4 v[94:97], v[18:25], v[198:205], 0, v1, v186 op_sel_hi:[0,0,0]
	v_mfma_scale_f32_16x16x128_f8f6f4 v[86:89], v[26:33], v[198:205], 0, v1, v186 op_sel_hi:[0,0,0]
	v_mfma_scale_f32_16x16x128_f8f6f4 v[78:81], v[18:25], v[206:213], 0, v1, v186 op_sel_hi:[0,0,0]
	v_mfma_scale_f32_16x16x128_f8f6f4 v[70:73], v[26:33], v[206:213], 0, v1, v186 op_sel_hi:[0,0,0]
	v_mfma_scale_f32_16x16x128_f8f6f4 v[62:65], v[18:25], v[214:221], 0, v1, v186 op_sel_hi:[0,0,0]
	v_mfma_scale_f32_16x16x128_f8f6f4 v[54:57], v[26:33], v[214:221], 0, v1, v186 op_sel_hi:[0,0,0]
	v_mfma_scale_f32_16x16x128_f8f6f4 v[46:49], v[18:25], v[222:229], 0, v1, v186 op_sel_hi:[0,0,0]
	v_mfma_scale_f32_16x16x128_f8f6f4 v[38:41], v[26:33], v[222:229], 0, v1, v186 op_sel_hi:[0,0,0]
	s_setprio 0
	s_setprio 1
	v_mfma_scale_f32_16x16x128_f8f6f4 v[90:93], v[2:9], v[198:205], 0, v1, v186 op_sel_hi:[0,0,0]
	v_mfma_scale_f32_16x16x128_f8f6f4 v[82:85], v[10:17], v[198:205], 0, v1, v186 op_sel_hi:[0,0,0]
	v_mfma_scale_f32_16x16x128_f8f6f4 v[74:77], v[2:9], v[206:213], 0, v1, v186 op_sel_hi:[0,0,0]
	v_mfma_scale_f32_16x16x128_f8f6f4 v[66:69], v[10:17], v[206:213], 0, v1, v186 op_sel_hi:[0,0,0]
	v_mfma_scale_f32_16x16x128_f8f6f4 v[58:61], v[2:9], v[214:221], 0, v1, v186 op_sel_hi:[0,0,0]
	v_mfma_scale_f32_16x16x128_f8f6f4 v[50:53], v[10:17], v[214:221], 0, v1, v186 op_sel_hi:[0,0,0]
	v_mfma_scale_f32_16x16x128_f8f6f4 v[42:45], v[2:9], v[222:229], 0, v1, v186 op_sel_hi:[0,0,0]
	v_mfma_scale_f32_16x16x128_f8f6f4 v[34:37], v[10:17], v[222:229], 0, v1, v186 op_sel_hi:[0,0,0]
	s_setprio 0
	s_barrier
; #define PG8_STAGE(bufoff, gbase, voff) do { _Pragma("unroll") for (int _i = 0; _i < 2; ++_i) \
;         __builtin_amdgcn_global_load_lds((const unsigned*)((const char*)(gbase) + (voff)[_i]), (PG8_LAS unsigned*)(lds + (bufoff) + ldsw + _i * 8192), 16, 0, 0); } while (0)
; #define PG8_LDA(dst, b, h) do { _Pragma("unroll") for (int m = 0; m < 4; ++m) _Pragma("unroll") for (int k = 0; k < 2; ++k) dst[m][k] = *(const PG8_LAS bf16x8*)(lds + PG8_SA(b, h) + aoff + m * 2048 + k * 1024); } while (0)
; #define PG8_LDB(dst, b, h) do { _Pragma("unroll") for (int n = 0; n < 2; ++n) _Pragma("unroll") for (int k = 0; k < 2; ++k) dst[n][k] = *(const PG8_LAS bf16x8*)(lds + PG8_SB(b, h) + boff + n * 2048 + k * 1024); } while (0)
; #define PG8_MMA(ai, bj, At, Bt) do { __builtin_amdgcn_s_setprio(1); _Pragma("unroll") for (int m = 0; m < 4; ++m) _Pragma("unroll") for (int n = 0; n < 2; ++n) _Pragma("unroll") for (int k = 0; k < 2; ++k) \
;         acc[ai][bj][m][n] = __builtin_amdgcn_mfma_f32_16x16x32_bf16(Bt[n][k], At[m][k], acc[ai][bj][m][n], 0, 0, 0); __builtin_amdgcn_s_setprio(0); } while (0)
; #define PG8_WAIT_V(n) asm volatile("s_waitcnt vmcnt(" #n ")" ::: "memory")
; #define PG8_WAIT_L(n) asm volatile("s_waitcnt lgkmcnt(" #n ")" ::: "memory")
; #define PG8_BAR __builtin_amdgcn_s_barrier()
; #define PG8_SCHED __builtin_amdgcn_sched_barrier(0)
; #define PG8_STAGE(bufoff, gbase, voff) do { _Pragma("unroll") for (int _i = 0; _i < 2; ++_i) \
;         __builtin_amdgcn_global_load_lds((const unsigned*)((const char*)(gbase) + (voff)[_i]), (PG8_LAS unsigned*)(lds + (bufoff) + ldsw + _i * 8192), 16, 0, 0); } while (0)
; #define PG8_WAIT_V(n) asm volatile("s_waitcnt vmcnt(" #n ")" ::: "memory")
; template <class Epi, class Sched, bool ALIGN_EPI = false>
; __device__ __forceinline__ void gemm_phase8(PG8_LAS unsigned char* lds, const Gemm g, const Sched& S, const Epi& E) {
;     ...
;             PG8_LDB(B0, 1, 0); PG8_LDB(B1, 1, 1); PG8_SCHED; PG8_LDA(At, 1, 0); PG8_STAGE(PG8_SA(0, 1), a2 + hstepA, voffA);
;             PG8_WAIT_V(8); PG8_WAIT_L(0); PG8_BAR; PG8_MMA(0, 0, At, B0); PG8_MMA(0, 1, At, B1); PG8_BAR; PG8_SCHED;
;             PG8_LDA(At, 1, 1); PG8_STAGE(PG8_SB(1, 0), b3, voffB); PG8_STAGE(PG8_SB(1, 1), b3 + hstepB, voffB); PG8_STAGE(PG8_SA(1, 0), a3, voffA);
;             PG8_WAIT_V(8); PG8_WAIT_L(0); PG8_BAR; PG8_MMA(1, 0, At, B0); PG8_MMA(1, 1, At, B1); PG8_BAR; PG8_SCHED;
	s_add_i32 s56, 0, 0x18000
	s_add_i32 s57, 0, 0x1c000
	v_add_u32_e32 v6, s56, v187
	v_add_u32_e32 v14, s56, v188
	v_add_u32_e32 v22, s57, v187
	v_add_u32_e32 v30, s57, v188
	ds_read_b128 v[2:5], v6
	ds_read_b128 v[10:13], v6 offset:2048
	ds_read_b128 v[6:9], v14
	ds_read_b128 v[14:17], v14 offset:2048
	ds_read_b128 v[18:21], v22
	ds_read_b128 v[26:29], v22 offset:2048
	ds_read_b128 v[22:25], v30
	ds_read_b128 v[30:33], v30 offset:2048
	s_add_u32 s24, s24, 0x40000
	s_addc_u32 s25, s25, 0
	s_mov_b32 m0, s35
	ds_read_b128 v[198:201], v195 offset:32768
	ds_read_b128 v[206:209], v195 offset:34816
	ds_read_b128 v[202:205], v196 offset:32768
	ds_read_b128 v[210:213], v196 offset:34816
	ds_read_b128 v[214:217], v195 offset:36864
	ds_read_b128 v[222:225], v195 offset:38912
	ds_read_b128 v[218:221], v196 offset:36864
	ds_read_b128 v[226:229], v196 offset:38912
	global_load_lds_dwordx4 v162, s[24:25]
	s_mov_b32 m0, s36
	s_nop 0
	global_load_lds_dwordx4 v166, s[24:25]
	s_waitcnt vmcnt(8)
	s_waitcnt lgkmcnt(0)
	s_barrier
	s_setprio 1
	s_waitcnt lgkmcnt(0)
	v_mfma_scale_f32_16x16x128_f8f6f4 v[158:161], v[2:9], v[198:205], v[158:161], v1, v186 op_sel_hi:[0,0,0]
	v_mfma_scale_f32_16x16x128_f8f6f4 v[150:153], v[10:17], v[198:205], v[150:153], v1, v186 op_sel_hi:[0,0,0]
	v_mfma_scale_f32_16x16x128_f8f6f4 v[142:145], v[2:9], v[206:213], v[142:145], v1, v186 op_sel_hi:[0,0,0]
	v_mfma_scale_f32_16x16x128_f8f6f4 v[134:137], v[10:17], v[206:213], v[134:137], v1, v186 op_sel_hi:[0,0,0]
	v_mfma_scale_f32_16x16x128_f8f6f4 v[126:129], v[2:9], v[214:221], v[126:129], v1, v186 op_sel_hi:[0,0,0]
	v_mfma_scale_f32_16x16x128_f8f6f4 v[118:121], v[10:17], v[214:221], v[118:121], v1, v186 op_sel_hi:[0,0,0]
	v_mfma_scale_f32_16x16x128_f8f6f4 v[110:113], v[2:9], v[222:229], v[110:113], v1, v186 op_sel_hi:[0,0,0]
	v_mfma_scale_f32_16x16x128_f8f6f4 v[102:105], v[10:17], v[222:229], v[102:105], v1, v186 op_sel_hi:[0,0,0]
	s_setprio 0
	s_setprio 1
	v_mfma_scale_f32_16x16x128_f8f6f4 v[154:157], v[18:25], v[198:205], v[154:157], v1, v186 op_sel_hi:[0,0,0]
	v_mfma_scale_f32_16x16x128_f8f6f4 v[146:149], v[26:33], v[198:205], v[146:149], v1, v186 op_sel_hi:[0,0,0]
	v_mfma_scale_f32_16x16x128_f8f6f4 v[138:141], v[18:25], v[206:213], v[138:141], v1, v186 op_sel_hi:[0,0,0]
	v_mfma_scale_f32_16x16x128_f8f6f4 v[130:133], v[26:33], v[206:213], v[130:133], v1, v186 op_sel_hi:[0,0,0]
	v_mfma_scale_f32_16x16x128_f8f6f4 v[122:125], v[18:25], v[214:221], v[122:125], v1, v186 op_sel_hi:[0,0,0]
	v_mfma_scale_f32_16x16x128_f8f6f4 v[114:117], v[26:33], v[214:221], v[114:117], v1, v186 op_sel_hi:[0,0,0]
	v_mfma_scale_f32_16x16x128_f8f6f4 v[106:109], v[18:25], v[222:229], v[106:109], v1, v186 op_sel_hi:[0,0,0]
	v_mfma_scale_f32_16x16x128_f8f6f4 v[98:101], v[26:33], v[222:229], v[98:101], v1, v186 op_sel_hi:[0,0,0]
	s_setprio 0
	s_barrier
	s_add_i32 s101, s56, s30
	s_add_u32 s98, s22, s6
	s_addc_u32 s99, s23, s7
	s_mov_b32 m0, s101
	ds_read_b128 v[198:201], v195 offset:49152
	ds_read_b128 v[206:209], v195 offset:51200
	ds_read_b128 v[202:205], v196 offset:49152
	ds_read_b128 v[210:213], v196 offset:51200
	ds_read_b128 v[214:217], v195 offset:53248
	ds_read_b128 v[222:225], v195 offset:55296
	ds_read_b128 v[218:221], v196 offset:53248
	ds_read_b128 v[226:229], v196 offset:55296
	global_load_lds_dwordx4 v164, s[98:99]
	s_add_i32 m0, s101, 0x2000
	s_add_u32 s22, s22, 0x40080
	s_addc_u32 s23, s23, 0
	s_add_i32 s101, s57, s30
	global_load_lds_dwordx4 v168, s[98:99]
	s_add_u32 s98, s24, s6
	s_addc_u32 s99, s25, s7
	s_sub_u32 s98, s98, 0x40000
	s_subb_u32 s99, s99, 0
	s_mov_b32 m0, s101
	s_nop 0
	global_load_lds_dwordx4 v164, s[22:23]
	s_add_i32 m0, s101, 0x2000
	s_nop 0
	global_load_lds_dwordx4 v168, s[22:23]
	s_mov_b32 m0, s39
	s_nop 0
	global_load_lds_dwordx4 v162, s[98:99]
	s_mov_b32 m0, s40
	s_nop 0
	global_load_lds_dwordx4 v166, s[98:99]
	s_waitcnt vmcnt(8)
	s_waitcnt lgkmcnt(0)
	s_barrier
	s_setprio 1
	s_waitcnt lgkmcnt(0)
	v_mfma_scale_f32_16x16x128_f8f6f4 v[94:97], v[2:9], v[198:205], v[94:97], v1, v186 op_sel_hi:[0,0,0]
	v_mfma_scale_f32_16x16x128_f8f6f4 v[86:89], v[10:17], v[198:205], v[86:89], v1, v186 op_sel_hi:[0,0,0]
	v_mfma_scale_f32_16x16x128_f8f6f4 v[78:81], v[2:9], v[206:213], v[78:81], v1, v186 op_sel_hi:[0,0,0]
	v_mfma_scale_f32_16x16x128_f8f6f4 v[70:73], v[10:17], v[206:213], v[70:73], v1, v186 op_sel_hi:[0,0,0]
	v_mfma_scale_f32_16x16x128_f8f6f4 v[62:65], v[2:9], v[214:221], v[62:65], v1, v186 op_sel_hi:[0,0,0]
	v_mfma_scale_f32_16x16x128_f8f6f4 v[54:57], v[10:17], v[214:221], v[54:57], v1, v186 op_sel_hi:[0,0,0]
	v_mfma_scale_f32_16x16x128_f8f6f4 v[46:49], v[2:9], v[222:229], v[46:49], v1, v186 op_sel_hi:[0,0,0]
	v_mfma_scale_f32_16x16x128_f8f6f4 v[38:41], v[10:17], v[222:229], v[38:41], v1, v186 op_sel_hi:[0,0,0]
	s_setprio 0
	s_setprio 1
	v_mfma_scale_f32_16x16x128_f8f6f4 v[90:93], v[18:25], v[198:205], v[90:93], v1, v186 op_sel_hi:[0,0,0]
	v_mfma_scale_f32_16x16x128_f8f6f4 v[82:85], v[26:33], v[198:205], v[82:85], v1, v186 op_sel_hi:[0,0,0]
	v_mfma_scale_f32_16x16x128_f8f6f4 v[74:77], v[18:25], v[206:213], v[74:77], v1, v186 op_sel_hi:[0,0,0]
	v_mfma_scale_f32_16x16x128_f8f6f4 v[66:69], v[26:33], v[206:213], v[66:69], v1, v186 op_sel_hi:[0,0,0]
	v_mfma_scale_f32_16x16x128_f8f6f4 v[58:61], v[18:25], v[214:221], v[58:61], v1, v186 op_sel_hi:[0,0,0]
	v_mfma_scale_f32_16x16x128_f8f6f4 v[50:53], v[26:33], v[214:221], v[50:53], v1, v186 op_sel_hi:[0,0,0]
	v_mfma_scale_f32_16x16x128_f8f6f4 v[42:45], v[18:25], v[222:229], v[42:45], v1, v186 op_sel_hi:[0,0,0]
	v_mfma_scale_f32_16x16x128_f8f6f4 v[34:37], v[26:33], v[222:229], v[34:37], v1, v186 op_sel_hi:[0,0,0]
	s_setprio 0
	s_barrier
; #define PG8_STAGE(bufoff, gbase, voff) do { _Pragma("unroll") for (int _i = 0; _i < 2; ++_i) \
;         __builtin_amdgcn_global_load_lds((const unsigned*)((const char*)(gbase) + (voff)[_i]), (PG8_LAS unsigned*)(lds + (bufoff) + ldsw + _i * 8192), 16, 0, 0); } while (0)
; #define PG8_LDA(dst, b, h) do { _Pragma("unroll") for (int m = 0; m < 4; ++m) _Pragma("unroll") for (int k = 0; k < 2; ++k) dst[m][k] = *(const PG8_LAS bf16x8*)(lds + PG8_SA(b, h) + aoff + m * 2048 + k * 1024); } while (0)
; #define PG8_LDB(dst, b, h) do { _Pragma("unroll") for (int n = 0; n < 2; ++n) _Pragma("unroll") for (int k = 0; k < 2; ++k) dst[n][k] = *(const PG8_LAS bf16x8*)(lds + PG8_SB(b, h) + boff + n * 2048 + k * 1024); } while (0)
; #define PG8_MMA(ai, bj, At, Bt) do { __builtin_amdgcn_s_setprio(1); _Pragma("unroll") for (int m = 0; m < 4; ++m) _Pragma("unroll") for (int n = 0; n < 2; ++n) _Pragma("unroll") for (int k = 0; k < 2; ++k) \
;         acc[ai][bj][m][n] = __builtin_amdgcn_mfma_f32_16x16x32_bf16(Bt[n][k], At[m][k], acc[ai][bj][m][n], 0, 0, 0); __builtin_amdgcn_s_setprio(0); } while (0)
; #define PG8_WAIT_V(n) asm volatile("s_waitcnt vmcnt(" #n ")" ::: "memory")
; #define PG8_WAIT_L(n) asm volatile("s_waitcnt lgkmcnt(" #n ")" ::: "memory")
; template <class Epi, class Sched, bool ALIGN_EPI = false>
; __device__ __forceinline__ void gemm_phase8(PG8_LAS unsigned char* lds, const Gemm g, const Sched& S, const Epi& E) {
;     ...
;         for (int t = 0; t < nt; t += 2) {
;             const bool last = (t == nt - 2);
;             const char* a1 = cA + (size_t)(t + 1) * kstep;
;             const char* a2 = last ? nA : cA + (size_t)(t + 2) * kstep; const char* b2 = last ? nB : cB + (size_t)(t + 2) * kstep;
;             const char* a3 = a2 + kstep; const char* b3 = b2 + kstep;
;             if (last && has_next) S.a_ready(nxt);
;             PG8_LDB(B0, 0, 0); PG8_LDB(B1, 0, 1); PG8_SCHED; PG8_LDA(At, 0, 0); PG8_STAGE(PG8_SA(1, 1), a1 + hstepA, voffA);
;             PG8_WAIT_V(8); PG8_WAIT_L(0); PG8_BAR; PG8_MMA(0, 0, At, B0); PG8_MMA(0, 1, At, B1); PG8_BAR; PG8_SCHED;
;             PG8_LDA(At, 0, 1); PG8_STAGE(PG8_SB(0, 0), b2, voffB); PG8_STAGE(PG8_SB(0, 1), b2 + hstepB, voffB); PG8_STAGE(PG8_SA(0, 0), a2, voffA);
;             PG8_WAIT_V(8); PG8_WAIT_L(0); PG8_BAR; PG8_MMA(1, 0, At, B0); PG8_MMA(1, 1, At, B1); PG8_BAR; PG8_SCHED;
	s_add_i32 s55, s55, 2
	s_add_u32 s20, s20, 0x100
	s_addc_u32 s21, s21, 0
	s_add_u32 s53, s53, 0x100
	s_addc_u32 s54, s54, 0
	s_cmp_gt_u32 s55, 13
	ds_read_b128 v[18:21], v191
	ds_read_b128 v[26:29], v191 offset:2048
	ds_read_b128 v[22:25], v192
	ds_read_b128 v[30:33], v192 offset:2048
	ds_read_b128 v[2:5], v193
	ds_read_b128 v[10:13], v193 offset:2048
	ds_read_b128 v[6:9], v194
	ds_read_b128 v[14:17], v194 offset:2048
	s_add_u32 s22, s20, 0xfffc0080
	s_addc_u32 s23, s21, -1
	s_cmp_eq_u32 s55, 12
	s_cselect_b32 s25, s13, s23
	s_cselect_b32 s24, s45, s22
	s_cselect_b32 s23, s11, s54
	s_cselect_b32 s22, s52, s53
	s_add_i32 m0, s19, 0xc000
	ds_read_b128 v[178:181], v195
	ds_read_b128 v[198:201], v195 offset:2048
	ds_read_b128 v[182:185], v196
	ds_read_b128 v[202:205], v196 offset:2048
	ds_read_b128 v[206:209], v195 offset:4096
	ds_read_b128 v[214:217], v195 offset:6144
	ds_read_b128 v[210:213], v196 offset:4096
	ds_read_b128 v[218:221], v196 offset:6144
	global_load_lds_dwordx4 v170, s[20:21]
	s_add_i32 m0, s19, 0xe000
	s_nop 0
	global_load_lds_dwordx4 v172, s[20:21]
	s_waitcnt vmcnt(8)
	s_waitcnt lgkmcnt(0)
	s_barrier
	s_setprio 1
	s_waitcnt lgkmcnt(0)
	v_mfma_scale_f32_16x16x128_f8f6f4 v[158:161], v[18:25], v[178:185], v[158:161], v1, v186 op_sel_hi:[0,0,0]
	v_mfma_scale_f32_16x16x128_f8f6f4 v[150:153], v[26:33], v[178:185], v[150:153], v1, v186 op_sel_hi:[0,0,0]
	v_mfma_scale_f32_16x16x128_f8f6f4 v[142:145], v[18:25], v[198:205], v[142:145], v1, v186 op_sel_hi:[0,0,0]
	v_mfma_scale_f32_16x16x128_f8f6f4 v[134:137], v[26:33], v[198:205], v[134:137], v1, v186 op_sel_hi:[0,0,0]
	v_mfma_scale_f32_16x16x128_f8f6f4 v[126:129], v[18:25], v[206:213], v[126:129], v1, v186 op_sel_hi:[0,0,0]
	v_mfma_scale_f32_16x16x128_f8f6f4 v[118:121], v[26:33], v[206:213], v[118:121], v1, v186 op_sel_hi:[0,0,0]
	v_mfma_scale_f32_16x16x128_f8f6f4 v[110:113], v[18:25], v[214:221], v[110:113], v1, v186 op_sel_hi:[0,0,0]
	v_mfma_scale_f32_16x16x128_f8f6f4 v[102:105], v[26:33], v[214:221], v[102:105], v1, v186 op_sel_hi:[0,0,0]
	s_setprio 0
	s_setprio 1
	v_mfma_scale_f32_16x16x128_f8f6f4 v[154:157], v[2:9], v[178:185], v[154:157], v1, v186 op_sel_hi:[0,0,0]
	v_mfma_scale_f32_16x16x128_f8f6f4 v[146:149], v[10:17], v[178:185], v[146:149], v1, v186 op_sel_hi:[0,0,0]
	v_mfma_scale_f32_16x16x128_f8f6f4 v[138:141], v[2:9], v[198:205], v[138:141], v1, v186 op_sel_hi:[0,0,0]
	v_mfma_scale_f32_16x16x128_f8f6f4 v[130:133], v[10:17], v[198:205], v[130:133], v1, v186 op_sel_hi:[0,0,0]
	v_mfma_scale_f32_16x16x128_f8f6f4 v[122:125], v[2:9], v[206:213], v[122:125], v1, v186 op_sel_hi:[0,0,0]
	v_mfma_scale_f32_16x16x128_f8f6f4 v[114:117], v[10:17], v[206:213], v[114:117], v1, v186 op_sel_hi:[0,0,0]
	v_mfma_scale_f32_16x16x128_f8f6f4 v[106:109], v[2:9], v[214:221], v[106:109], v1, v186 op_sel_hi:[0,0,0]
	v_mfma_scale_f32_16x16x128_f8f6f4 v[98:101], v[10:17], v[214:221], v[98:101], v1, v186 op_sel_hi:[0,0,0]
	s_setprio 0
	s_barrier
	s_add_i32 s56, s41, s30
	s_mov_b32 m0, s56
	ds_read_b128 v[198:201], v195 offset:16384
	ds_read_b128 v[206:209], v195 offset:18432
	ds_read_b128 v[202:205], v196 offset:16384
	ds_read_b128 v[210:213], v196 offset:18432
	ds_read_b128 v[214:217], v195 offset:20480
	ds_read_b128 v[222:225], v195 offset:22528
	ds_read_b128 v[218:221], v196 offset:20480
	ds_read_b128 v[226:229], v196 offset:22528
	global_load_lds_dwordx4 v164, s[22:23]
	s_add_i32 m0, s56, 0x2000
	s_add_u32 s56, s22, 0x40000
	s_addc_u32 s57, s23, 0
	s_add_i32 s58, s42, s30
	global_load_lds_dwordx4 v168, s[22:23]
	s_mov_b32 m0, s58
	s_nop 0
	global_load_lds_dwordx4 v164, s[56:57]
	s_add_i32 m0, s58, 0x2000
	s_nop 0
	global_load_lds_dwordx4 v168, s[56:57]
	s_mov_b32 m0, s19
	s_nop 0
	global_load_lds_dwordx4 v162, s[24:25]
	s_mov_b32 m0, s34
	s_nop 0
	global_load_lds_dwordx4 v166, s[24:25]
	s_waitcnt vmcnt(8)
	s_waitcnt lgkmcnt(0)
	s_barrier
	s_setprio 1
	s_waitcnt lgkmcnt(0)
	v_mfma_scale_f32_16x16x128_f8f6f4 v[94:97], v[18:25], v[198:205], v[94:97], v1, v186 op_sel_hi:[0,0,0]
	v_mfma_scale_f32_16x16x128_f8f6f4 v[86:89], v[26:33], v[198:205], v[86:89], v1, v186 op_sel_hi:[0,0,0]
	v_mfma_scale_f32_16x16x128_f8f6f4 v[78:81], v[18:25], v[206:213], v[78:81], v1, v186 op_sel_hi:[0,0,0]
	v_mfma_scale_f32_16x16x128_f8f6f4 v[70:73], v[26:33], v[206:213], v[70:73], v1, v186 op_sel_hi:[0,0,0]
	v_mfma_scale_f32_16x16x128_f8f6f4 v[62:65], v[18:25], v[214:221], v[62:65], v1, v186 op_sel_hi:[0,0,0]
	v_mfma_scale_f32_16x16x128_f8f6f4 v[54:57], v[26:33], v[214:221], v[54:57], v1, v186 op_sel_hi:[0,0,0]
	v_mfma_scale_f32_16x16x128_f8f6f4 v[46:49], v[18:25], v[222:229], v[46:49], v1, v186 op_sel_hi:[0,0,0]
	v_mfma_scale_f32_16x16x128_f8f6f4 v[38:41], v[26:33], v[222:229], v[38:41], v1, v186 op_sel_hi:[0,0,0]
	s_setprio 0
	s_setprio 1
	v_mfma_scale_f32_16x16x128_f8f6f4 v[90:93], v[2:9], v[198:205], v[90:93], v1, v186 op_sel_hi:[0,0,0]
	v_mfma_scale_f32_16x16x128_f8f6f4 v[82:85], v[10:17], v[198:205], v[82:85], v1, v186 op_sel_hi:[0,0,0]
	v_mfma_scale_f32_16x16x128_f8f6f4 v[74:77], v[2:9], v[206:213], v[74:77], v1, v186 op_sel_hi:[0,0,0]
	v_mfma_scale_f32_16x16x128_f8f6f4 v[66:69], v[10:17], v[206:213], v[66:69], v1, v186 op_sel_hi:[0,0,0]
	v_mfma_scale_f32_16x16x128_f8f6f4 v[58:61], v[2:9], v[214:221], v[58:61], v1, v186 op_sel_hi:[0,0,0]
	v_mfma_scale_f32_16x16x128_f8f6f4 v[50:53], v[10:17], v[214:221], v[50:53], v1, v186 op_sel_hi:[0,0,0]
	v_mfma_scale_f32_16x16x128_f8f6f4 v[42:45], v[2:9], v[222:229], v[42:45], v1, v186 op_sel_hi:[0,0,0]
	v_mfma_scale_f32_16x16x128_f8f6f4 v[34:37], v[10:17], v[222:229], v[34:37], v1, v186 op_sel_hi:[0,0,0]
	s_setprio 0
	s_barrier
; #define PG8_STAGE(bufoff, gbase, voff) do { _Pragma("unroll") for (int _i = 0; _i < 2; ++_i) \
;         __builtin_amdgcn_global_load_lds((const unsigned*)((const char*)(gbase) + (voff)[_i]), (PG8_LAS unsigned*)(lds + (bufoff) + ldsw + _i * 8192), 16, 0, 0); } while (0)
; #define PG8_LDA(dst, b, h) do { _Pragma("unroll") for (int m = 0; m < 4; ++m) _Pragma("unroll") for (int k = 0; k < 2; ++k) dst[m][k] = *(const PG8_LAS bf16x8*)(lds + PG8_SA(b, h) + aoff + m * 2048 + k * 1024); } while (0)
; #define PG8_LDB(dst, b, h) do { _Pragma("unroll") for (int n = 0; n < 2; ++n) _Pragma("unroll") for (int k = 0; k < 2; ++k) dst[n][k] = *(const PG8_LAS bf16x8*)(lds + PG8_SB(b, h) + boff + n * 2048 + k * 1024); } while (0)
; #define PG8_MMA(ai, bj, At, Bt) do { __builtin_amdgcn_s_setprio(1); _Pragma("unroll") for (int m = 0; m < 4; ++m) _Pragma("unroll") for (int n = 0; n < 2; ++n) _Pragma("unroll") for (int k = 0; k < 2; ++k) \
;         acc[ai][bj][m][n] = __builtin_amdgcn_mfma_f32_16x16x32_bf16(Bt[n][k], At[m][k], acc[ai][bj][m][n], 0, 0, 0); __builtin_amdgcn_s_setprio(0); } while (0)
; #define PG8_WAIT_V(n) asm volatile("s_waitcnt vmcnt(" #n ")" ::: "memory")
; #define PG8_WAIT_L(n) asm volatile("s_waitcnt lgkmcnt(" #n ")" ::: "memory")
; #define PG8_BAR __builtin_amdgcn_s_barrier()
; #define PG8_SCHED __builtin_amdgcn_sched_barrier(0)
; #define PG8_STAGE(bufoff, gbase, voff) do { _Pragma("unroll") for (int _i = 0; _i < 2; ++_i) \
;         __builtin_amdgcn_global_load_lds((const unsigned*)((const char*)(gbase) + (voff)[_i]), (PG8_LAS unsigned*)(lds + (bufoff) + ldsw + _i * 8192), 16, 0, 0); } while (0)
; template <class Epi, class Sched, bool ALIGN_EPI = false>
; __device__ __forceinline__ void gemm_phase8(PG8_LAS unsigned char* lds, const Gemm g, const Sched& S, const Epi& E) {
;     ...
;         for (int t = 0; t < nt; t += 2) {
;     ...
;             PG8_LDB(B0, 1, 0); PG8_LDB(B1, 1, 1); PG8_SCHED; PG8_LDA(At, 1, 0); PG8_STAGE(PG8_SA(0, 1), a2 + hstepA, voffA);
;             PG8_WAIT_V(8); PG8_WAIT_L(0); PG8_BAR; PG8_MMA(0, 0, At, B0); PG8_MMA(0, 1, At, B1); PG8_BAR; PG8_SCHED;
;             PG8_LDA(At, 1, 1); PG8_STAGE(PG8_SB(1, 0), b3, voffB); PG8_STAGE(PG8_SB(1, 1), b3 + hstepB, voffB); PG8_STAGE(PG8_SA(1, 0), a3, voffA);
;             PG8_WAIT_V(8); PG8_WAIT_L(0); PG8_BAR; PG8_MMA(1, 0, At, B0); PG8_MMA(1, 1, At, B1); PG8_BAR; PG8_SCHED;
	s_add_i32 s56, 0, 0x18000
	s_add_i32 s57, 0, 0x1c000
	v_add_u32_e32 v6, s56, v187
	v_add_u32_e32 v14, s56, v188
	v_add_u32_e32 v22, s57, v187
	v_add_u32_e32 v30, s57, v188
	ds_read_b128 v[2:5], v6
	ds_read_b128 v[10:13], v6 offset:2048
	ds_read_b128 v[6:9], v14
	ds_read_b128 v[14:17], v14 offset:2048
	ds_read_b128 v[18:21], v22
	ds_read_b128 v[26:29], v22 offset:2048
	ds_read_b128 v[22:25], v30
	ds_read_b128 v[30:33], v30 offset:2048
	s_add_u32 s24, s24, 0x40000
	s_addc_u32 s25, s25, 0
	s_mov_b32 m0, s35
	ds_read_b128 v[198:201], v195 offset:32768
	ds_read_b128 v[206:209], v195 offset:34816
	ds_read_b128 v[202:205], v196 offset:32768
	ds_read_b128 v[210:213], v196 offset:34816
	ds_read_b128 v[214:217], v195 offset:36864
	ds_read_b128 v[222:225], v195 offset:38912
	ds_read_b128 v[218:221], v196 offset:36864
	ds_read_b128 v[226:229], v196 offset:38912
	global_load_lds_dwordx4 v162, s[24:25]
	s_mov_b32 m0, s36
	s_nop 0
	global_load_lds_dwordx4 v166, s[24:25]
	s_waitcnt vmcnt(8)
	s_waitcnt lgkmcnt(0)
	s_barrier
	s_setprio 1
	s_waitcnt lgkmcnt(0)
	v_mfma_scale_f32_16x16x128_f8f6f4 v[158:161], v[2:9], v[198:205], v[158:161], v1, v186 op_sel_hi:[0,0,0]
	v_mfma_scale_f32_16x16x128_f8f6f4 v[150:153], v[10:17], v[198:205], v[150:153], v1, v186 op_sel_hi:[0,0,0]
	v_mfma_scale_f32_16x16x128_f8f6f4 v[142:145], v[2:9], v[206:213], v[142:145], v1, v186 op_sel_hi:[0,0,0]
	v_mfma_scale_f32_16x16x128_f8f6f4 v[134:137], v[10:17], v[206:213], v[134:137], v1, v186 op_sel_hi:[0,0,0]
	v_mfma_scale_f32_16x16x128_f8f6f4 v[126:129], v[2:9], v[214:221], v[126:129], v1, v186 op_sel_hi:[0,0,0]
	v_mfma_scale_f32_16x16x128_f8f6f4 v[118:121], v[10:17], v[214:221], v[118:121], v1, v186 op_sel_hi:[0,0,0]
	v_mfma_scale_f32_16x16x128_f8f6f4 v[110:113], v[2:9], v[222:229], v[110:113], v1, v186 op_sel_hi:[0,0,0]
	v_mfma_scale_f32_16x16x128_f8f6f4 v[102:105], v[10:17], v[222:229], v[102:105], v1, v186 op_sel_hi:[0,0,0]
	s_setprio 0
	s_setprio 1
	v_mfma_scale_f32_16x16x128_f8f6f4 v[154:157], v[18:25], v[198:205], v[154:157], v1, v186 op_sel_hi:[0,0,0]
	v_mfma_scale_f32_16x16x128_f8f6f4 v[146:149], v[26:33], v[198:205], v[146:149], v1, v186 op_sel_hi:[0,0,0]
	v_mfma_scale_f32_16x16x128_f8f6f4 v[138:141], v[18:25], v[206:213], v[138:141], v1, v186 op_sel_hi:[0,0,0]
	v_mfma_scale_f32_16x16x128_f8f6f4 v[130:133], v[26:33], v[206:213], v[130:133], v1, v186 op_sel_hi:[0,0,0]
	v_mfma_scale_f32_16x16x128_f8f6f4 v[122:125], v[18:25], v[214:221], v[122:125], v1, v186 op_sel_hi:[0,0,0]
	v_mfma_scale_f32_16x16x128_f8f6f4 v[114:117], v[26:33], v[214:221], v[114:117], v1, v186 op_sel_hi:[0,0,0]
	v_mfma_scale_f32_16x16x128_f8f6f4 v[106:109], v[18:25], v[222:229], v[106:109], v1, v186 op_sel_hi:[0,0,0]
	v_mfma_scale_f32_16x16x128_f8f6f4 v[98:101], v[26:33], v[222:229], v[98:101], v1, v186 op_sel_hi:[0,0,0]
	s_setprio 0
	s_barrier
	s_add_i32 s101, s56, s30
	s_add_u32 s98, s22, s6
	s_addc_u32 s99, s23, s7
	s_mov_b32 m0, s101
	ds_read_b128 v[198:201], v195 offset:49152
	ds_read_b128 v[206:209], v195 offset:51200
	ds_read_b128 v[202:205], v196 offset:49152
	ds_read_b128 v[210:213], v196 offset:51200
	ds_read_b128 v[214:217], v195 offset:53248
	ds_read_b128 v[222:225], v195 offset:55296
	ds_read_b128 v[218:221], v196 offset:53248
	ds_read_b128 v[226:229], v196 offset:55296
	global_load_lds_dwordx4 v164, s[98:99]
	s_add_i32 m0, s101, 0x2000
	s_add_u32 s22, s22, 0x40080
	s_addc_u32 s23, s23, 0
	s_add_i32 s101, s57, s30
	global_load_lds_dwordx4 v168, s[98:99]
	s_add_u32 s98, s24, s6
	s_addc_u32 s99, s25, s7
	s_sub_u32 s98, s98, 0x40000
	s_subb_u32 s99, s99, 0
	s_mov_b32 m0, s101
	s_nop 0
	global_load_lds_dwordx4 v164, s[22:23]
	s_add_i32 m0, s101, 0x2000
	s_nop 0
	global_load_lds_dwordx4 v168, s[22:23]
	s_mov_b32 m0, s39
	s_nop 0
	global_load_lds_dwordx4 v162, s[98:99]
	s_mov_b32 m0, s40
	s_nop 0
	global_load_lds_dwordx4 v166, s[98:99]
	s_waitcnt vmcnt(8)
	s_waitcnt lgkmcnt(0)
	s_barrier
	s_setprio 1
	s_waitcnt lgkmcnt(0)
	v_mfma_scale_f32_16x16x128_f8f6f4 v[94:97], v[2:9], v[198:205], v[94:97], v1, v186 op_sel_hi:[0,0,0]
	v_mfma_scale_f32_16x16x128_f8f6f4 v[86:89], v[10:17], v[198:205], v[86:89], v1, v186 op_sel_hi:[0,0,0]
	v_mfma_scale_f32_16x16x128_f8f6f4 v[78:81], v[2:9], v[206:213], v[78:81], v1, v186 op_sel_hi:[0,0,0]
	v_mfma_scale_f32_16x16x128_f8f6f4 v[70:73], v[10:17], v[206:213], v[70:73], v1, v186 op_sel_hi:[0,0,0]
	v_mfma_scale_f32_16x16x128_f8f6f4 v[62:65], v[2:9], v[214:221], v[62:65], v1, v186 op_sel_hi:[0,0,0]
	v_mfma_scale_f32_16x16x128_f8f6f4 v[54:57], v[10:17], v[214:221], v[54:57], v1, v186 op_sel_hi:[0,0,0]
	v_mfma_scale_f32_16x16x128_f8f6f4 v[46:49], v[2:9], v[222:229], v[46:49], v1, v186 op_sel_hi:[0,0,0]
	v_mfma_scale_f32_16x16x128_f8f6f4 v[38:41], v[10:17], v[222:229], v[38:41], v1, v186 op_sel_hi:[0,0,0]
	s_setprio 0
	s_setprio 1
	v_mfma_scale_f32_16x16x128_f8f6f4 v[90:93], v[18:25], v[198:205], v[90:93], v1, v186 op_sel_hi:[0,0,0]
	v_mfma_scale_f32_16x16x128_f8f6f4 v[82:85], v[26:33], v[198:205], v[82:85], v1, v186 op_sel_hi:[0,0,0]
	v_mfma_scale_f32_16x16x128_f8f6f4 v[74:77], v[18:25], v[206:213], v[74:77], v1, v186 op_sel_hi:[0,0,0]
	v_mfma_scale_f32_16x16x128_f8f6f4 v[66:69], v[26:33], v[206:213], v[66:69], v1, v186 op_sel_hi:[0,0,0]
	v_mfma_scale_f32_16x16x128_f8f6f4 v[58:61], v[18:25], v[214:221], v[58:61], v1, v186 op_sel_hi:[0,0,0]
	v_mfma_scale_f32_16x16x128_f8f6f4 v[50:53], v[26:33], v[214:221], v[50:53], v1, v186 op_sel_hi:[0,0,0]
	v_mfma_scale_f32_16x16x128_f8f6f4 v[42:45], v[18:25], v[222:229], v[42:45], v1, v186 op_sel_hi:[0,0,0]
	v_mfma_scale_f32_16x16x128_f8f6f4 v[34:37], v[26:33], v[222:229], v[34:37], v1, v186 op_sel_hi:[0,0,0]
	s_setprio 0
	s_barrier
	s_add_i32 s55, s55, 2
	s_add_u32 s20, s20, 0x100
	s_addc_u32 s21, s21, 0
	s_add_u32 s53, s53, 0x100
	s_addc_u32 s54, s54, 0
	s_cmp_gt_u32 s55, 13
	s_cbranch_scc1 .Lpx_4
; #define PG8_STAGE(bufoff, gbase, voff) do { _Pragma("unroll") for (int _i = 0; _i < 2; ++_i) \
;         __builtin_amdgcn_global_load_lds((const unsigned*)((const char*)(gbase) + (voff)[_i]), (PG8_LAS unsigned*)(lds + (bufoff) + ldsw + _i * 8192), 16, 0, 0); } while (0)
; #define PG8_LDA(dst, b, h) do { _Pragma("unroll") for (int m = 0; m < 4; ++m) _Pragma("unroll") for (int k = 0; k < 2; ++k) dst[m][k] = *(const PG8_LAS bf16x8*)(lds + PG8_SA(b, h) + aoff + m * 2048 + k * 1024); } while (0)
; #define PG8_LDB(dst, b, h) do { _Pragma("unroll") for (int n = 0; n < 2; ++n) _Pragma("unroll") for (int k = 0; k < 2; ++k) dst[n][k] = *(const PG8_LAS bf16x8*)(lds + PG8_SB(b, h) + boff + n * 2048 + k * 1024); } while (0)
; #define PG8_MMA(ai, bj, At, Bt) do { __builtin_amdgcn_s_setprio(1); _Pragma("unroll") for (int m = 0; m < 4; ++m) _Pragma("unroll") for (int n = 0; n < 2; ++n) _Pragma("unroll") for (int k = 0; k < 2; ++k) \
;         acc[ai][bj][m][n] = __builtin_amdgcn_mfma_f32_16x16x32_bf16(Bt[n][k], At[m][k], acc[ai][bj][m][n], 0, 0, 0); __builtin_amdgcn_s_setprio(0); } while (0)
; #define PG8_WAIT_V(n) asm volatile("s_waitcnt vmcnt(" #n ")" ::: "memory")
; #define PG8_WAIT_L(n) asm volatile("s_waitcnt lgkmcnt(" #n ")" ::: "memory")
; #define PG8_BAR __builtin_amdgcn_s_barrier()
; template <class Epi, class Sched, bool ALIGN_EPI = false>
; __device__ __forceinline__ void gemm_phase8(PG8_LAS unsigned char* lds, const Gemm g, const Sched& S, const Epi& E) {
;     ...
;             const bool last = (t == nt - 2);
;             const char* a1 = cA + (size_t)(t + 1) * kstep;
;             const char* a2 = last ? nA : cA + (size_t)(t + 2) * kstep; const char* b2 = last ? nB : cB + (size_t)(t + 2) * kstep;
;             const char* a3 = a2 + kstep; const char* b3 = b2 + kstep;
;             if (last && has_next) S.a_ready(nxt);
;             PG8_LDB(B0, 0, 0); PG8_LDB(B1, 0, 1); PG8_SCHED; PG8_LDA(At, 0, 0); PG8_STAGE(PG8_SA(1, 1), a1 + hstepA, voffA);
;             PG8_WAIT_V(8); PG8_WAIT_L(0); PG8_BAR; PG8_MMA(0, 0, At, B0); PG8_MMA(0, 1, At, B1); PG8_BAR; PG8_SCHED;
;             PG8_LDA(At, 0, 1); PG8_STAGE(PG8_SB(0, 0), b2, voffB); PG8_STAGE(PG8_SB(0, 1), b2 + hstepB, voffB); PG8_STAGE(PG8_SA(0, 0), a2, voffA);
;             PG8_WAIT_V(8); PG8_WAIT_L(0); PG8_BAR; PG8_MMA(1, 0, At, B0); PG8_MMA(1, 1, At, B1); PG8_BAR; PG8_SCHED;
.LBB0_1422:
	ds_read_b128 v[18:21], v191
	ds_read_b128 v[26:29], v191 offset:2048
	ds_read_b128 v[22:25], v192
	ds_read_b128 v[30:33], v192 offset:2048
	ds_read_b128 v[2:5], v193
	ds_read_b128 v[10:13], v193 offset:2048
	ds_read_b128 v[6:9], v194
	ds_read_b128 v[14:17], v194 offset:2048
	s_add_u32 s22, s20, 0xfffc0080
	s_addc_u32 s23, s21, -1
	s_cmp_eq_u32 s55, 12
	s_cselect_b32 s25, s13, s23
	s_cselect_b32 s24, s45, s22
	s_cselect_b32 s23, s11, s54
	s_cselect_b32 s22, s52, s53
	s_add_i32 m0, s19, 0xc000
	ds_read_b128 v[178:181], v195
	ds_read_b128 v[198:201], v195 offset:2048
	ds_read_b128 v[182:185], v196
	ds_read_b128 v[202:205], v196 offset:2048
	ds_read_b128 v[206:209], v195 offset:4096
	ds_read_b128 v[214:217], v195 offset:6144
	ds_read_b128 v[210:213], v196 offset:4096
	ds_read_b128 v[218:221], v196 offset:6144
	global_load_lds_dwordx4 v170, s[20:21]
	s_add_i32 m0, s19, 0xe000
	s_nop 0
	global_load_lds_dwordx4 v172, s[20:21]
	s_waitcnt vmcnt(8)
	s_waitcnt lgkmcnt(0)
	s_barrier
	s_setprio 1
	s_waitcnt lgkmcnt(0)
	v_mfma_scale_f32_16x16x128_f8f6f4 v[158:161], v[18:25], v[178:185], v[158:161], v1, v186 op_sel_hi:[0,0,0]
	v_mfma_scale_f32_16x16x128_f8f6f4 v[150:153], v[26:33], v[178:185], v[150:153], v1, v186 op_sel_hi:[0,0,0]
	v_mfma_scale_f32_16x16x128_f8f6f4 v[142:145], v[18:25], v[198:205], v[142:145], v1, v186 op_sel_hi:[0,0,0]
	v_mfma_scale_f32_16x16x128_f8f6f4 v[134:137], v[26:33], v[198:205], v[134:137], v1, v186 op_sel_hi:[0,0,0]
	v_mfma_scale_f32_16x16x128_f8f6f4 v[126:129], v[18:25], v[206:213], v[126:129], v1, v186 op_sel_hi:[0,0,0]
	v_mfma_scale_f32_16x16x128_f8f6f4 v[118:121], v[26:33], v[206:213], v[118:121], v1, v186 op_sel_hi:[0,0,0]
	v_mfma_scale_f32_16x16x128_f8f6f4 v[110:113], v[18:25], v[214:221], v[110:113], v1, v186 op_sel_hi:[0,0,0]
	v_mfma_scale_f32_16x16x128_f8f6f4 v[102:105], v[26:33], v[214:221], v[102:105], v1, v186 op_sel_hi:[0,0,0]
	s_setprio 0
	s_setprio 1
	v_mfma_scale_f32_16x16x128_f8f6f4 v[154:157], v[2:9], v[178:185], v[154:157], v1, v186 op_sel_hi:[0,0,0]
	v_mfma_scale_f32_16x16x128_f8f6f4 v[146:149], v[10:17], v[178:185], v[146:149], v1, v186 op_sel_hi:[0,0,0]
	v_mfma_scale_f32_16x16x128_f8f6f4 v[138:141], v[2:9], v[198:205], v[138:141], v1, v186 op_sel_hi:[0,0,0]
	v_mfma_scale_f32_16x16x128_f8f6f4 v[130:133], v[10:17], v[198:205], v[130:133], v1, v186 op_sel_hi:[0,0,0]
	v_mfma_scale_f32_16x16x128_f8f6f4 v[122:125], v[2:9], v[206:213], v[122:125], v1, v186 op_sel_hi:[0,0,0]
	v_mfma_scale_f32_16x16x128_f8f6f4 v[114:117], v[10:17], v[206:213], v[114:117], v1, v186 op_sel_hi:[0,0,0]
	v_mfma_scale_f32_16x16x128_f8f6f4 v[106:109], v[2:9], v[214:221], v[106:109], v1, v186 op_sel_hi:[0,0,0]
	v_mfma_scale_f32_16x16x128_f8f6f4 v[98:101], v[10:17], v[214:221], v[98:101], v1, v186 op_sel_hi:[0,0,0]
	s_setprio 0
	s_barrier
	s_add_i32 s56, s41, s30
	s_mov_b32 m0, s56
	ds_read_b128 v[198:201], v195 offset:16384
	ds_read_b128 v[206:209], v195 offset:18432
	ds_read_b128 v[202:205], v196 offset:16384
	ds_read_b128 v[210:213], v196 offset:18432
	ds_read_b128 v[214:217], v195 offset:20480
	ds_read_b128 v[222:225], v195 offset:22528
	ds_read_b128 v[218:221], v196 offset:20480
	ds_read_b128 v[226:229], v196 offset:22528
	global_load_lds_dwordx4 v164, s[22:23]
	s_add_i32 m0, s56, 0x2000
	s_add_u32 s56, s22, 0x40000
	s_addc_u32 s57, s23, 0
	s_add_i32 s58, s42, s30
	global_load_lds_dwordx4 v168, s[22:23]
	s_mov_b32 m0, s58
	s_nop 0
	global_load_lds_dwordx4 v164, s[56:57]
	s_add_i32 m0, s58, 0x2000
	s_nop 0
	global_load_lds_dwordx4 v168, s[56:57]
	s_mov_b32 m0, s19
	s_nop 0
	global_load_lds_dwordx4 v162, s[24:25]
	s_mov_b32 m0, s34
	s_nop 0
	global_load_lds_dwordx4 v166, s[24:25]
	s_waitcnt vmcnt(8)
	s_waitcnt lgkmcnt(0)
	s_barrier
	s_setprio 1
	s_waitcnt lgkmcnt(0)
	v_mfma_scale_f32_16x16x128_f8f6f4 v[94:97], v[18:25], v[198:205], v[94:97], v1, v186 op_sel_hi:[0,0,0]
	v_mfma_scale_f32_16x16x128_f8f6f4 v[86:89], v[26:33], v[198:205], v[86:89], v1, v186 op_sel_hi:[0,0,0]
	v_mfma_scale_f32_16x16x128_f8f6f4 v[78:81], v[18:25], v[206:213], v[78:81], v1, v186 op_sel_hi:[0,0,0]
	v_mfma_scale_f32_16x16x128_f8f6f4 v[70:73], v[26:33], v[206:213], v[70:73], v1, v186 op_sel_hi:[0,0,0]
	v_mfma_scale_f32_16x16x128_f8f6f4 v[62:65], v[18:25], v[214:221], v[62:65], v1, v186 op_sel_hi:[0,0,0]
	v_mfma_scale_f32_16x16x128_f8f6f4 v[54:57], v[26:33], v[214:221], v[54:57], v1, v186 op_sel_hi:[0,0,0]
	v_mfma_scale_f32_16x16x128_f8f6f4 v[46:49], v[18:25], v[222:229], v[46:49], v1, v186 op_sel_hi:[0,0,0]
	v_mfma_scale_f32_16x16x128_f8f6f4 v[38:41], v[26:33], v[222:229], v[38:41], v1, v186 op_sel_hi:[0,0,0]
	s_setprio 0
	s_setprio 1
	v_mfma_scale_f32_16x16x128_f8f6f4 v[90:93], v[2:9], v[198:205], v[90:93], v1, v186 op_sel_hi:[0,0,0]
	v_mfma_scale_f32_16x16x128_f8f6f4 v[82:85], v[10:17], v[198:205], v[82:85], v1, v186 op_sel_hi:[0,0,0]
	v_mfma_scale_f32_16x16x128_f8f6f4 v[74:77], v[2:9], v[206:213], v[74:77], v1, v186 op_sel_hi:[0,0,0]
	v_mfma_scale_f32_16x16x128_f8f6f4 v[66:69], v[10:17], v[206:213], v[66:69], v1, v186 op_sel_hi:[0,0,0]
	v_mfma_scale_f32_16x16x128_f8f6f4 v[58:61], v[2:9], v[214:221], v[58:61], v1, v186 op_sel_hi:[0,0,0]
	v_mfma_scale_f32_16x16x128_f8f6f4 v[50:53], v[10:17], v[214:221], v[50:53], v1, v186 op_sel_hi:[0,0,0]
	v_mfma_scale_f32_16x16x128_f8f6f4 v[42:45], v[2:9], v[222:229], v[42:45], v1, v186 op_sel_hi:[0,0,0]
	v_mfma_scale_f32_16x16x128_f8f6f4 v[34:37], v[10:17], v[222:229], v[34:37], v1, v186 op_sel_hi:[0,0,0]
	s_setprio 0
	s_barrier
; #define PG8_STAGE(bufoff, gbase, voff) do { _Pragma("unroll") for (int _i = 0; _i < 2; ++_i) \
;         __builtin_amdgcn_global_load_lds((const unsigned*)((const char*)(gbase) + (voff)[_i]), (PG8_LAS unsigned*)(lds + (bufoff) + ldsw + _i * 8192), 16, 0, 0); } while (0)
; #define PG8_LDA(dst, b, h) do { _Pragma("unroll") for (int m = 0; m < 4; ++m) _Pragma("unroll") for (int k = 0; k < 2; ++k) dst[m][k] = *(const PG8_LAS bf16x8*)(lds + PG8_SA(b, h) + aoff + m * 2048 + k * 1024); } while (0)
; #define PG8_LDB(dst, b, h) do { _Pragma("unroll") for (int n = 0; n < 2; ++n) _Pragma("unroll") for (int k = 0; k < 2; ++k) dst[n][k] = *(const PG8_LAS bf16x8*)(lds + PG8_SB(b, h) + boff + n * 2048 + k * 1024); } while (0)
; #define PG8_MMA(ai, bj, At, Bt) do { __builtin_amdgcn_s_setprio(1); _Pragma("unroll") for (int m = 0; m < 4; ++m) _Pragma("unroll") for (int n = 0; n < 2; ++n) _Pragma("unroll") for (int k = 0; k < 2; ++k) \
;         acc[ai][bj][m][n] = __builtin_amdgcn_mfma_f32_16x16x32_bf16(Bt[n][k], At[m][k], acc[ai][bj][m][n], 0, 0, 0); __builtin_amdgcn_s_setprio(0); } while (0)
; #define PG8_WAIT_V(n) asm volatile("s_waitcnt vmcnt(" #n ")" ::: "memory")
; #define PG8_WAIT_L(n) asm volatile("s_waitcnt lgkmcnt(" #n ")" ::: "memory")
; #define PG8_BAR __builtin_amdgcn_s_barrier()
; #define PG8_SCHED __builtin_amdgcn_sched_barrier(0)
; #define PG8_STAGE(bufoff, gbase, voff) do { _Pragma("unroll") for (int _i = 0; _i < 2; ++_i) \
;         __builtin_amdgcn_global_load_lds((const unsigned*)((const char*)(gbase) + (voff)[_i]), (PG8_LAS unsigned*)(lds + (bufoff) + ldsw + _i * 8192), 16, 0, 0); } while (0)
; #define PG8_WAIT_V(n) asm volatile("s_waitcnt vmcnt(" #n ")" ::: "memory")
; template <class Epi, class Sched, bool ALIGN_EPI = false>
; __device__ __forceinline__ void gemm_phase8(PG8_LAS unsigned char* lds, const Gemm g, const Sched& S, const Epi& E) {
;     ...
;             PG8_LDB(B0, 1, 0); PG8_LDB(B1, 1, 1); PG8_SCHED; PG8_LDA(At, 1, 0); PG8_STAGE(PG8_SA(0, 1), a2 + hstepA, voffA);
;             PG8_WAIT_V(8); PG8_WAIT_L(0); PG8_BAR; PG8_MMA(0, 0, At, B0); PG8_MMA(0, 1, At, B1); PG8_BAR; PG8_SCHED;
;             PG8_LDA(At, 1, 1); PG8_STAGE(PG8_SB(1, 0), b3, voffB); PG8_STAGE(PG8_SB(1, 1), b3 + hstepB, voffB); PG8_STAGE(PG8_SA(1, 0), a3, voffA);
;             PG8_WAIT_V(8); PG8_WAIT_L(0); PG8_BAR; PG8_MMA(1, 0, At, B0); PG8_MMA(1, 1, At, B1); PG8_BAR; PG8_SCHED;
	s_add_i32 s56, 0, 0x18000
	s_add_i32 s57, 0, 0x1c000
	v_add_u32_e32 v6, s56, v187
	v_add_u32_e32 v14, s56, v188
	v_add_u32_e32 v22, s57, v187
	v_add_u32_e32 v30, s57, v188
	ds_read_b128 v[2:5], v6
	ds_read_b128 v[10:13], v6 offset:2048
	ds_read_b128 v[6:9], v14
	ds_read_b128 v[14:17], v14 offset:2048
	ds_read_b128 v[18:21], v22
	ds_read_b128 v[26:29], v22 offset:2048
	ds_read_b128 v[22:25], v30
	ds_read_b128 v[30:33], v30 offset:2048
	s_add_u32 s24, s24, 0x40000
	s_addc_u32 s25, s25, 0
	s_mov_b32 m0, s35
	ds_read_b128 v[198:201], v195 offset:32768
	ds_read_b128 v[206:209], v195 offset:34816
	ds_read_b128 v[202:205], v196 offset:32768
	ds_read_b128 v[210:213], v196 offset:34816
	ds_read_b128 v[214:217], v195 offset:36864
	ds_read_b128 v[222:225], v195 offset:38912
	ds_read_b128 v[218:221], v196 offset:36864
	ds_read_b128 v[226:229], v196 offset:38912
	global_load_lds_dwordx4 v162, s[24:25]
	s_mov_b32 m0, s36
	s_nop 0
	global_load_lds_dwordx4 v166, s[24:25]
	s_waitcnt vmcnt(8)
	s_waitcnt lgkmcnt(0)
	s_barrier
	s_setprio 1
	s_waitcnt lgkmcnt(0)
	v_mfma_scale_f32_16x16x128_f8f6f4 v[158:161], v[2:9], v[198:205], v[158:161], v1, v186 op_sel_hi:[0,0,0]
	v_mfma_scale_f32_16x16x128_f8f6f4 v[150:153], v[10:17], v[198:205], v[150:153], v1, v186 op_sel_hi:[0,0,0]
	v_mfma_scale_f32_16x16x128_f8f6f4 v[142:145], v[2:9], v[206:213], v[142:145], v1, v186 op_sel_hi:[0,0,0]
	v_mfma_scale_f32_16x16x128_f8f6f4 v[134:137], v[10:17], v[206:213], v[134:137], v1, v186 op_sel_hi:[0,0,0]
	v_mfma_scale_f32_16x16x128_f8f6f4 v[126:129], v[2:9], v[214:221], v[126:129], v1, v186 op_sel_hi:[0,0,0]
	v_mfma_scale_f32_16x16x128_f8f6f4 v[118:121], v[10:17], v[214:221], v[118:121], v1, v186 op_sel_hi:[0,0,0]
	v_mfma_scale_f32_16x16x128_f8f6f4 v[110:113], v[2:9], v[222:229], v[110:113], v1, v186 op_sel_hi:[0,0,0]
	v_mfma_scale_f32_16x16x128_f8f6f4 v[102:105], v[10:17], v[222:229], v[102:105], v1, v186 op_sel_hi:[0,0,0]
	s_setprio 0
	s_setprio 1
	v_mfma_scale_f32_16x16x128_f8f6f4 v[154:157], v[18:25], v[198:205], v[154:157], v1, v186 op_sel_hi:[0,0,0]
	v_mfma_scale_f32_16x16x128_f8f6f4 v[146:149], v[26:33], v[198:205], v[146:149], v1, v186 op_sel_hi:[0,0,0]
	v_mfma_scale_f32_16x16x128_f8f6f4 v[138:141], v[18:25], v[206:213], v[138:141], v1, v186 op_sel_hi:[0,0,0]
	v_mfma_scale_f32_16x16x128_f8f6f4 v[130:133], v[26:33], v[206:213], v[130:133], v1, v186 op_sel_hi:[0,0,0]
	v_mfma_scale_f32_16x16x128_f8f6f4 v[122:125], v[18:25], v[214:221], v[122:125], v1, v186 op_sel_hi:[0,0,0]
	v_mfma_scale_f32_16x16x128_f8f6f4 v[114:117], v[26:33], v[214:221], v[114:117], v1, v186 op_sel_hi:[0,0,0]
	v_mfma_scale_f32_16x16x128_f8f6f4 v[106:109], v[18:25], v[222:229], v[106:109], v1, v186 op_sel_hi:[0,0,0]
	v_mfma_scale_f32_16x16x128_f8f6f4 v[98:101], v[26:33], v[222:229], v[98:101], v1, v186 op_sel_hi:[0,0,0]
	s_setprio 0
	s_barrier
	s_add_i32 s101, s56, s30
	s_add_u32 s98, s22, s6
	s_addc_u32 s99, s23, s7
	s_mov_b32 m0, s101
	ds_read_b128 v[198:201], v195 offset:49152
	ds_read_b128 v[206:209], v195 offset:51200
	ds_read_b128 v[202:205], v196 offset:49152
	ds_read_b128 v[210:213], v196 offset:51200
	ds_read_b128 v[214:217], v195 offset:53248
	ds_read_b128 v[222:225], v195 offset:55296
	ds_read_b128 v[218:221], v196 offset:53248
	ds_read_b128 v[226:229], v196 offset:55296
	global_load_lds_dwordx4 v164, s[98:99]
	s_add_i32 m0, s101, 0x2000
	s_add_u32 s22, s22, 0x40080
	s_addc_u32 s23, s23, 0
	s_add_i32 s101, s57, s30
	global_load_lds_dwordx4 v168, s[98:99]
	s_add_u32 s98, s24, s6
	s_addc_u32 s99, s25, s7
	s_sub_u32 s98, s98, 0x40000
	s_subb_u32 s99, s99, 0
	s_mov_b32 m0, s101
	s_nop 0
	global_load_lds_dwordx4 v164, s[22:23]
	s_add_i32 m0, s101, 0x2000
	s_nop 0
	global_load_lds_dwordx4 v168, s[22:23]
	s_mov_b32 m0, s39
	s_nop 0
	global_load_lds_dwordx4 v162, s[98:99]
	s_mov_b32 m0, s40
	s_nop 0
	global_load_lds_dwordx4 v166, s[98:99]
	s_waitcnt vmcnt(8)
	s_waitcnt lgkmcnt(0)
	s_barrier
	s_setprio 1
	s_waitcnt lgkmcnt(0)
	v_mfma_scale_f32_16x16x128_f8f6f4 v[94:97], v[2:9], v[198:205], v[94:97], v1, v186 op_sel_hi:[0,0,0]
	v_mfma_scale_f32_16x16x128_f8f6f4 v[86:89], v[10:17], v[198:205], v[86:89], v1, v186 op_sel_hi:[0,0,0]
	v_mfma_scale_f32_16x16x128_f8f6f4 v[78:81], v[2:9], v[206:213], v[78:81], v1, v186 op_sel_hi:[0,0,0]
	v_mfma_scale_f32_16x16x128_f8f6f4 v[70:73], v[10:17], v[206:213], v[70:73], v1, v186 op_sel_hi:[0,0,0]
	v_mfma_scale_f32_16x16x128_f8f6f4 v[62:65], v[2:9], v[214:221], v[62:65], v1, v186 op_sel_hi:[0,0,0]
	v_mfma_scale_f32_16x16x128_f8f6f4 v[54:57], v[10:17], v[214:221], v[54:57], v1, v186 op_sel_hi:[0,0,0]
	v_mfma_scale_f32_16x16x128_f8f6f4 v[46:49], v[2:9], v[222:229], v[46:49], v1, v186 op_sel_hi:[0,0,0]
	v_mfma_scale_f32_16x16x128_f8f6f4 v[38:41], v[10:17], v[222:229], v[38:41], v1, v186 op_sel_hi:[0,0,0]
	s_setprio 0
	s_setprio 1
	v_mfma_scale_f32_16x16x128_f8f6f4 v[90:93], v[18:25], v[198:205], v[90:93], v1, v186 op_sel_hi:[0,0,0]
	v_mfma_scale_f32_16x16x128_f8f6f4 v[82:85], v[26:33], v[198:205], v[82:85], v1, v186 op_sel_hi:[0,0,0]
	v_mfma_scale_f32_16x16x128_f8f6f4 v[74:77], v[18:25], v[206:213], v[74:77], v1, v186 op_sel_hi:[0,0,0]
	v_mfma_scale_f32_16x16x128_f8f6f4 v[66:69], v[26:33], v[206:213], v[66:69], v1, v186 op_sel_hi:[0,0,0]
	v_mfma_scale_f32_16x16x128_f8f6f4 v[58:61], v[18:25], v[214:221], v[58:61], v1, v186 op_sel_hi:[0,0,0]
	v_mfma_scale_f32_16x16x128_f8f6f4 v[50:53], v[26:33], v[214:221], v[50:53], v1, v186 op_sel_hi:[0,0,0]
	v_mfma_scale_f32_16x16x128_f8f6f4 v[42:45], v[18:25], v[222:229], v[42:45], v1, v186 op_sel_hi:[0,0,0]
	v_mfma_scale_f32_16x16x128_f8f6f4 v[34:37], v[26:33], v[222:229], v[34:37], v1, v186 op_sel_hi:[0,0,0]
	s_setprio 0
	s_barrier
; #define PG8_STAGE(bufoff, gbase, voff) do { _Pragma("unroll") for (int _i = 0; _i < 2; ++_i) \
;         __builtin_amdgcn_global_load_lds((const unsigned*)((const char*)(gbase) + (voff)[_i]), (PG8_LAS unsigned*)(lds + (bufoff) + ldsw + _i * 8192), 16, 0, 0); } while (0)
; #define PG8_LDA(dst, b, h) do { _Pragma("unroll") for (int m = 0; m < 4; ++m) _Pragma("unroll") for (int k = 0; k < 2; ++k) dst[m][k] = *(const PG8_LAS bf16x8*)(lds + PG8_SA(b, h) + aoff + m * 2048 + k * 1024); } while (0)
; #define PG8_LDB(dst, b, h) do { _Pragma("unroll") for (int n = 0; n < 2; ++n) _Pragma("unroll") for (int k = 0; k < 2; ++k) dst[n][k] = *(const PG8_LAS bf16x8*)(lds + PG8_SB(b, h) + boff + n * 2048 + k * 1024); } while (0)
; #define PG8_MMA(ai, bj, At, Bt) do { __builtin_amdgcn_s_setprio(1); _Pragma("unroll") for (int m = 0; m < 4; ++m) _Pragma("unroll") for (int n = 0; n < 2; ++n) _Pragma("unroll") for (int k = 0; k < 2; ++k) \
;         acc[ai][bj][m][n] = __builtin_amdgcn_mfma_f32_16x16x32_bf16(Bt[n][k], At[m][k], acc[ai][bj][m][n], 0, 0, 0); __builtin_amdgcn_s_setprio(0); } while (0)
; #define PG8_WAIT_V(n) asm volatile("s_waitcnt vmcnt(" #n ")" ::: "memory")
; #define PG8_WAIT_L(n) asm volatile("s_waitcnt lgkmcnt(" #n ")" ::: "memory")
; template <class Epi, class Sched, bool ALIGN_EPI = false>
; __device__ __forceinline__ void gemm_phase8(PG8_LAS unsigned char* lds, const Gemm g, const Sched& S, const Epi& E) {
;     ...
;         for (int t = 0; t < nt; t += 2) {
;             const bool last = (t == nt - 2);
;             const char* a1 = cA + (size_t)(t + 1) * kstep;
;             const char* a2 = last ? nA : cA + (size_t)(t + 2) * kstep; const char* b2 = last ? nB : cB + (size_t)(t + 2) * kstep;
;             const char* a3 = a2 + kstep; const char* b3 = b2 + kstep;
;             if (last && has_next) S.a_ready(nxt);
;             PG8_LDB(B0, 0, 0); PG8_LDB(B1, 0, 1); PG8_SCHED; PG8_LDA(At, 0, 0); PG8_STAGE(PG8_SA(1, 1), a1 + hstepA, voffA);
;             PG8_WAIT_V(8); PG8_WAIT_L(0); PG8_BAR; PG8_MMA(0, 0, At, B0); PG8_MMA(0, 1, At, B1); PG8_BAR; PG8_SCHED;
;             PG8_LDA(At, 0, 1); PG8_STAGE(PG8_SB(0, 0), b2, voffB); PG8_STAGE(PG8_SB(0, 1), b2 + hstepB, voffB); PG8_STAGE(PG8_SA(0, 0), a2, voffA);
;             PG8_WAIT_V(8); PG8_WAIT_L(0); PG8_BAR; PG8_MMA(1, 0, At, B0); PG8_MMA(1, 1, At, B1); PG8_BAR; PG8_SCHED;
	s_add_i32 s55, s55, 2
	s_add_u32 s20, s20, 0x100
	s_addc_u32 s21, s21, 0
	s_add_u32 s53, s53, 0x100
	s_addc_u32 s54, s54, 0
	s_cmp_gt_u32 s55, 13
	ds_read_b128 v[18:21], v191
	ds_read_b128 v[26:29], v191 offset:2048
	ds_read_b128 v[22:25], v192
	ds_read_b128 v[30:33], v192 offset:2048
	ds_read_b128 v[2:5], v193
	ds_read_b128 v[10:13], v193 offset:2048
	ds_read_b128 v[6:9], v194
	ds_read_b128 v[14:17], v194 offset:2048
	s_add_u32 s22, s20, 0xfffc0080
	s_addc_u32 s23, s21, -1
	s_cmp_eq_u32 s55, 12
	s_cselect_b32 s25, s13, s23
	s_cselect_b32 s24, s45, s22
	s_cselect_b32 s23, s11, s54
	s_cselect_b32 s22, s52, s53
	s_add_i32 m0, s19, 0xc000
	ds_read_b128 v[178:181], v195
	ds_read_b128 v[198:201], v195 offset:2048
	ds_read_b128 v[182:185], v196
	ds_read_b128 v[202:205], v196 offset:2048
	ds_read_b128 v[206:209], v195 offset:4096
	ds_read_b128 v[214:217], v195 offset:6144
	ds_read_b128 v[210:213], v196 offset:4096
	ds_read_b128 v[218:221], v196 offset:6144
	global_load_lds_dwordx4 v170, s[20:21]
	s_add_i32 m0, s19, 0xe000
	s_nop 0
	global_load_lds_dwordx4 v172, s[20:21]
	s_waitcnt vmcnt(8)
	s_waitcnt lgkmcnt(0)
	s_barrier
	s_setprio 1
	s_waitcnt lgkmcnt(0)
	v_mfma_scale_f32_16x16x128_f8f6f4 v[158:161], v[18:25], v[178:185], v[158:161], v1, v186 op_sel_hi:[0,0,0]
	v_mfma_scale_f32_16x16x128_f8f6f4 v[150:153], v[26:33], v[178:185], v[150:153], v1, v186 op_sel_hi:[0,0,0]
	v_mfma_scale_f32_16x16x128_f8f6f4 v[142:145], v[18:25], v[198:205], v[142:145], v1, v186 op_sel_hi:[0,0,0]
	v_mfma_scale_f32_16x16x128_f8f6f4 v[134:137], v[26:33], v[198:205], v[134:137], v1, v186 op_sel_hi:[0,0,0]
	v_mfma_scale_f32_16x16x128_f8f6f4 v[126:129], v[18:25], v[206:213], v[126:129], v1, v186 op_sel_hi:[0,0,0]
	v_mfma_scale_f32_16x16x128_f8f6f4 v[118:121], v[26:33], v[206:213], v[118:121], v1, v186 op_sel_hi:[0,0,0]
	v_mfma_scale_f32_16x16x128_f8f6f4 v[110:113], v[18:25], v[214:221], v[110:113], v1, v186 op_sel_hi:[0,0,0]
	v_mfma_scale_f32_16x16x128_f8f6f4 v[102:105], v[26:33], v[214:221], v[102:105], v1, v186 op_sel_hi:[0,0,0]
	s_setprio 0
	s_setprio 1
	v_mfma_scale_f32_16x16x128_f8f6f4 v[154:157], v[2:9], v[178:185], v[154:157], v1, v186 op_sel_hi:[0,0,0]
	v_mfma_scale_f32_16x16x128_f8f6f4 v[146:149], v[10:17], v[178:185], v[146:149], v1, v186 op_sel_hi:[0,0,0]
	v_mfma_scale_f32_16x16x128_f8f6f4 v[138:141], v[2:9], v[198:205], v[138:141], v1, v186 op_sel_hi:[0,0,0]
	v_mfma_scale_f32_16x16x128_f8f6f4 v[130:133], v[10:17], v[198:205], v[130:133], v1, v186 op_sel_hi:[0,0,0]
	v_mfma_scale_f32_16x16x128_f8f6f4 v[122:125], v[2:9], v[206:213], v[122:125], v1, v186 op_sel_hi:[0,0,0]
	v_mfma_scale_f32_16x16x128_f8f6f4 v[114:117], v[10:17], v[206:213], v[114:117], v1, v186 op_sel_hi:[0,0,0]
	v_mfma_scale_f32_16x16x128_f8f6f4 v[106:109], v[2:9], v[214:221], v[106:109], v1, v186 op_sel_hi:[0,0,0]
	v_mfma_scale_f32_16x16x128_f8f6f4 v[98:101], v[10:17], v[214:221], v[98:101], v1, v186 op_sel_hi:[0,0,0]
	s_setprio 0
	s_barrier
	s_add_i32 s56, s41, s30
	s_mov_b32 m0, s56
	ds_read_b128 v[198:201], v195 offset:16384
	ds_read_b128 v[206:209], v195 offset:18432
	ds_read_b128 v[202:205], v196 offset:16384
	ds_read_b128 v[210:213], v196 offset:18432
	ds_read_b128 v[214:217], v195 offset:20480
	ds_read_b128 v[222:225], v195 offset:22528
	ds_read_b128 v[218:221], v196 offset:20480
	ds_read_b128 v[226:229], v196 offset:22528
	global_load_lds_dwordx4 v164, s[22:23]
	s_add_i32 m0, s56, 0x2000
	s_add_u32 s56, s22, 0x40000
	s_addc_u32 s57, s23, 0
	s_add_i32 s58, s42, s30
	global_load_lds_dwordx4 v168, s[22:23]
	s_mov_b32 m0, s58
	s_nop 0
	global_load_lds_dwordx4 v164, s[56:57]
	s_add_i32 m0, s58, 0x2000
	s_nop 0
	global_load_lds_dwordx4 v168, s[56:57]
	s_mov_b32 m0, s19
	s_nop 0
	global_load_lds_dwordx4 v162, s[24:25]
	s_mov_b32 m0, s34
	s_nop 0
	global_load_lds_dwordx4 v166, s[24:25]
	s_waitcnt vmcnt(8)
	s_waitcnt lgkmcnt(0)
	s_barrier
	s_setprio 1
	s_waitcnt lgkmcnt(0)
	v_mfma_scale_f32_16x16x128_f8f6f4 v[94:97], v[18:25], v[198:205], v[94:97], v1, v186 op_sel_hi:[0,0,0]
	v_mfma_scale_f32_16x16x128_f8f6f4 v[86:89], v[26:33], v[198:205], v[86:89], v1, v186 op_sel_hi:[0,0,0]
	v_mfma_scale_f32_16x16x128_f8f6f4 v[78:81], v[18:25], v[206:213], v[78:81], v1, v186 op_sel_hi:[0,0,0]
	v_mfma_scale_f32_16x16x128_f8f6f4 v[70:73], v[26:33], v[206:213], v[70:73], v1, v186 op_sel_hi:[0,0,0]
	v_mfma_scale_f32_16x16x128_f8f6f4 v[62:65], v[18:25], v[214:221], v[62:65], v1, v186 op_sel_hi:[0,0,0]
	v_mfma_scale_f32_16x16x128_f8f6f4 v[54:57], v[26:33], v[214:221], v[54:57], v1, v186 op_sel_hi:[0,0,0]
	v_mfma_scale_f32_16x16x128_f8f6f4 v[46:49], v[18:25], v[222:229], v[46:49], v1, v186 op_sel_hi:[0,0,0]
	v_mfma_scale_f32_16x16x128_f8f6f4 v[38:41], v[26:33], v[222:229], v[38:41], v1, v186 op_sel_hi:[0,0,0]
	s_setprio 0
	s_setprio 1
	v_mfma_scale_f32_16x16x128_f8f6f4 v[90:93], v[2:9], v[198:205], v[90:93], v1, v186 op_sel_hi:[0,0,0]
	v_mfma_scale_f32_16x16x128_f8f6f4 v[82:85], v[10:17], v[198:205], v[82:85], v1, v186 op_sel_hi:[0,0,0]
	v_mfma_scale_f32_16x16x128_f8f6f4 v[74:77], v[2:9], v[206:213], v[74:77], v1, v186 op_sel_hi:[0,0,0]
	v_mfma_scale_f32_16x16x128_f8f6f4 v[66:69], v[10:17], v[206:213], v[66:69], v1, v186 op_sel_hi:[0,0,0]
	v_mfma_scale_f32_16x16x128_f8f6f4 v[58:61], v[2:9], v[214:221], v[58:61], v1, v186 op_sel_hi:[0,0,0]
	v_mfma_scale_f32_16x16x128_f8f6f4 v[50:53], v[10:17], v[214:221], v[50:53], v1, v186 op_sel_hi:[0,0,0]
	v_mfma_scale_f32_16x16x128_f8f6f4 v[42:45], v[2:9], v[222:229], v[42:45], v1, v186 op_sel_hi:[0,0,0]
	v_mfma_scale_f32_16x16x128_f8f6f4 v[34:37], v[10:17], v[222:229], v[34:37], v1, v186 op_sel_hi:[0,0,0]
	s_setprio 0
	s_barrier
; #define PG8_STAGE(bufoff, gbase, voff) do { _Pragma("unroll") for (int _i = 0; _i < 2; ++_i) \
;         __builtin_amdgcn_global_load_lds((const unsigned*)((const char*)(gbase) + (voff)[_i]), (PG8_LAS unsigned*)(lds + (bufoff) + ldsw + _i * 8192), 16, 0, 0); } while (0)
; #define PG8_LDA(dst, b, h) do { _Pragma("unroll") for (int m = 0; m < 4; ++m) _Pragma("unroll") for (int k = 0; k < 2; ++k) dst[m][k] = *(const PG8_LAS bf16x8*)(lds + PG8_SA(b, h) + aoff + m * 2048 + k * 1024); } while (0)
; #define PG8_LDB(dst, b, h) do { _Pragma("unroll") for (int n = 0; n < 2; ++n) _Pragma("unroll") for (int k = 0; k < 2; ++k) dst[n][k] = *(const PG8_LAS bf16x8*)(lds + PG8_SB(b, h) + boff + n * 2048 + k * 1024); } while (0)
; #define PG8_MMA(ai, bj, At, Bt) do { __builtin_amdgcn_s_setprio(1); _Pragma("unroll") for (int m = 0; m < 4; ++m) _Pragma("unroll") for (int n = 0; n < 2; ++n) _Pragma("unroll") for (int k = 0; k < 2; ++k) \
;         acc[ai][bj][m][n] = __builtin_amdgcn_mfma_f32_16x16x32_bf16(Bt[n][k], At[m][k], acc[ai][bj][m][n], 0, 0, 0); __builtin_amdgcn_s_setprio(0); } while (0)
; #define PG8_WAIT_V(n) asm volatile("s_waitcnt vmcnt(" #n ")" ::: "memory")
; #define PG8_WAIT_L(n) asm volatile("s_waitcnt lgkmcnt(" #n ")" ::: "memory")
; #define PG8_BAR __builtin_amdgcn_s_barrier()
; #define PG8_SCHED __builtin_amdgcn_sched_barrier(0)
; #define PG8_STAGE(bufoff, gbase, voff) do { _Pragma("unroll") for (int _i = 0; _i < 2; ++_i) \
;         __builtin_amdgcn_global_load_lds((const unsigned*)((const char*)(gbase) + (voff)[_i]), (PG8_LAS unsigned*)(lds + (bufoff) + ldsw + _i * 8192), 16, 0, 0); } while (0)
; template <class Epi, class Sched, bool ALIGN_EPI = false>
; __device__ __forceinline__ void gemm_phase8(PG8_LAS unsigned char* lds, const Gemm g, const Sched& S, const Epi& E) {
;     ...
;             PG8_LDB(B0, 1, 0); PG8_LDB(B1, 1, 1); PG8_SCHED; PG8_LDA(At, 1, 0); PG8_STAGE(PG8_SA(0, 1), a2 + hstepA, voffA);
;             PG8_WAIT_V(8); PG8_WAIT_L(0); PG8_BAR; PG8_MMA(0, 0, At, B0); PG8_MMA(0, 1, At, B1); PG8_BAR; PG8_SCHED;
;             PG8_LDA(At, 1, 1); PG8_STAGE(PG8_SB(1, 0), b3, voffB); PG8_STAGE(PG8_SB(1, 1), b3 + hstepB, voffB); PG8_STAGE(PG8_SA(1, 0), a3, voffA);
;             PG8_WAIT_V(8); PG8_WAIT_L(0); PG8_BAR; PG8_MMA(1, 0, At, B0); PG8_MMA(1, 1, At, B1); PG8_BAR; PG8_SCHED;
;         }
;         if constexpr (ALIGN_EPI) { if (wr == 0) PG8_BAR; }
	s_add_i32 s56, 0, 0x18000
	s_add_i32 s57, 0, 0x1c000
	v_add_u32_e32 v6, s56, v187
	v_add_u32_e32 v14, s56, v188
	v_add_u32_e32 v22, s57, v187
	v_add_u32_e32 v30, s57, v188
	ds_read_b128 v[2:5], v6
	ds_read_b128 v[10:13], v6 offset:2048
	ds_read_b128 v[6:9], v14
	ds_read_b128 v[14:17], v14 offset:2048
	ds_read_b128 v[18:21], v22
	ds_read_b128 v[26:29], v22 offset:2048
	ds_read_b128 v[22:25], v30
	ds_read_b128 v[30:33], v30 offset:2048
	s_add_u32 s24, s24, 0x40000
	s_addc_u32 s25, s25, 0
	s_mov_b32 m0, s35
	ds_read_b128 v[198:201], v195 offset:32768
	ds_read_b128 v[206:209], v195 offset:34816
	ds_read_b128 v[202:205], v196 offset:32768
	ds_read_b128 v[210:213], v196 offset:34816
	ds_read_b128 v[214:217], v195 offset:36864
	ds_read_b128 v[222:225], v195 offset:38912
	ds_read_b128 v[218:221], v196 offset:36864
	ds_read_b128 v[226:229], v196 offset:38912
	global_load_lds_dwordx4 v162, s[24:25]
	s_mov_b32 m0, s36
	s_nop 0
	global_load_lds_dwordx4 v166, s[24:25]
	s_waitcnt vmcnt(8)
	s_waitcnt lgkmcnt(0)
	s_barrier
	s_setprio 1
	s_waitcnt lgkmcnt(0)
	v_mfma_scale_f32_16x16x128_f8f6f4 v[158:161], v[2:9], v[198:205], v[158:161], v1, v186 op_sel_hi:[0,0,0]
	v_mfma_scale_f32_16x16x128_f8f6f4 v[150:153], v[10:17], v[198:205], v[150:153], v1, v186 op_sel_hi:[0,0,0]
	v_mfma_scale_f32_16x16x128_f8f6f4 v[142:145], v[2:9], v[206:213], v[142:145], v1, v186 op_sel_hi:[0,0,0]
	v_mfma_scale_f32_16x16x128_f8f6f4 v[134:137], v[10:17], v[206:213], v[134:137], v1, v186 op_sel_hi:[0,0,0]
	v_mfma_scale_f32_16x16x128_f8f6f4 v[126:129], v[2:9], v[214:221], v[126:129], v1, v186 op_sel_hi:[0,0,0]
	v_mfma_scale_f32_16x16x128_f8f6f4 v[118:121], v[10:17], v[214:221], v[118:121], v1, v186 op_sel_hi:[0,0,0]
	v_mfma_scale_f32_16x16x128_f8f6f4 v[110:113], v[2:9], v[222:229], v[110:113], v1, v186 op_sel_hi:[0,0,0]
	v_mfma_scale_f32_16x16x128_f8f6f4 v[102:105], v[10:17], v[222:229], v[102:105], v1, v186 op_sel_hi:[0,0,0]
	s_setprio 0
	s_setprio 1
	v_mfma_scale_f32_16x16x128_f8f6f4 v[154:157], v[18:25], v[198:205], v[154:157], v1, v186 op_sel_hi:[0,0,0]
	v_mfma_scale_f32_16x16x128_f8f6f4 v[146:149], v[26:33], v[198:205], v[146:149], v1, v186 op_sel_hi:[0,0,0]
	v_mfma_scale_f32_16x16x128_f8f6f4 v[138:141], v[18:25], v[206:213], v[138:141], v1, v186 op_sel_hi:[0,0,0]
	v_mfma_scale_f32_16x16x128_f8f6f4 v[130:133], v[26:33], v[206:213], v[130:133], v1, v186 op_sel_hi:[0,0,0]
	v_mfma_scale_f32_16x16x128_f8f6f4 v[122:125], v[18:25], v[214:221], v[122:125], v1, v186 op_sel_hi:[0,0,0]
	v_mfma_scale_f32_16x16x128_f8f6f4 v[114:117], v[26:33], v[214:221], v[114:117], v1, v186 op_sel_hi:[0,0,0]
	v_mfma_scale_f32_16x16x128_f8f6f4 v[106:109], v[18:25], v[222:229], v[106:109], v1, v186 op_sel_hi:[0,0,0]
	v_mfma_scale_f32_16x16x128_f8f6f4 v[98:101], v[26:33], v[222:229], v[98:101], v1, v186 op_sel_hi:[0,0,0]
	s_setprio 0
	s_barrier
	s_add_i32 s101, s56, s30
	s_add_u32 s98, s22, s6
	s_addc_u32 s99, s23, s7
	s_mov_b32 m0, s101
	ds_read_b128 v[198:201], v195 offset:49152
	ds_read_b128 v[206:209], v195 offset:51200
	ds_read_b128 v[202:205], v196 offset:49152
	ds_read_b128 v[210:213], v196 offset:51200
	ds_read_b128 v[214:217], v195 offset:53248
	ds_read_b128 v[222:225], v195 offset:55296
	ds_read_b128 v[218:221], v196 offset:53248
	ds_read_b128 v[226:229], v196 offset:55296
	global_load_lds_dwordx4 v164, s[98:99]
	s_add_i32 m0, s101, 0x2000
	s_add_u32 s22, s22, 0x40080
	s_addc_u32 s23, s23, 0
	s_add_i32 s101, s57, s30
	global_load_lds_dwordx4 v168, s[98:99]
	s_add_u32 s98, s24, s6
	s_addc_u32 s99, s25, s7
	s_sub_u32 s98, s98, 0x40000
	s_subb_u32 s99, s99, 0
	s_mov_b32 m0, s101
	s_nop 0
	global_load_lds_dwordx4 v164, s[22:23]
	s_add_i32 m0, s101, 0x2000
	s_nop 0
	global_load_lds_dwordx4 v168, s[22:23]
	s_mov_b32 m0, s39
	s_nop 0
	global_load_lds_dwordx4 v162, s[98:99]
	s_mov_b32 m0, s40
	s_nop 0
	global_load_lds_dwordx4 v166, s[98:99]
	s_waitcnt vmcnt(8)
	s_waitcnt lgkmcnt(0)
	s_barrier
	s_setprio 1
	s_waitcnt lgkmcnt(0)
	v_mfma_scale_f32_16x16x128_f8f6f4 v[94:97], v[2:9], v[198:205], v[94:97], v1, v186 op_sel_hi:[0,0,0]
	v_mfma_scale_f32_16x16x128_f8f6f4 v[86:89], v[10:17], v[198:205], v[86:89], v1, v186 op_sel_hi:[0,0,0]
	v_mfma_scale_f32_16x16x128_f8f6f4 v[78:81], v[2:9], v[206:213], v[78:81], v1, v186 op_sel_hi:[0,0,0]
	v_mfma_scale_f32_16x16x128_f8f6f4 v[70:73], v[10:17], v[206:213], v[70:73], v1, v186 op_sel_hi:[0,0,0]
	v_mfma_scale_f32_16x16x128_f8f6f4 v[62:65], v[2:9], v[214:221], v[62:65], v1, v186 op_sel_hi:[0,0,0]
	v_mfma_scale_f32_16x16x128_f8f6f4 v[54:57], v[10:17], v[214:221], v[54:57], v1, v186 op_sel_hi:[0,0,0]
	v_mfma_scale_f32_16x16x128_f8f6f4 v[46:49], v[2:9], v[222:229], v[46:49], v1, v186 op_sel_hi:[0,0,0]
	v_mfma_scale_f32_16x16x128_f8f6f4 v[38:41], v[10:17], v[222:229], v[38:41], v1, v186 op_sel_hi:[0,0,0]
	s_setprio 0
	s_setprio 1
	v_mfma_scale_f32_16x16x128_f8f6f4 v[90:93], v[18:25], v[198:205], v[90:93], v1, v186 op_sel_hi:[0,0,0]
	v_mfma_scale_f32_16x16x128_f8f6f4 v[82:85], v[26:33], v[198:205], v[82:85], v1, v186 op_sel_hi:[0,0,0]
	v_mfma_scale_f32_16x16x128_f8f6f4 v[74:77], v[18:25], v[206:213], v[74:77], v1, v186 op_sel_hi:[0,0,0]
	v_mfma_scale_f32_16x16x128_f8f6f4 v[66:69], v[26:33], v[206:213], v[66:69], v1, v186 op_sel_hi:[0,0,0]
	v_mfma_scale_f32_16x16x128_f8f6f4 v[58:61], v[18:25], v[214:221], v[58:61], v1, v186 op_sel_hi:[0,0,0]
	v_mfma_scale_f32_16x16x128_f8f6f4 v[50:53], v[26:33], v[214:221], v[50:53], v1, v186 op_sel_hi:[0,0,0]
	v_mfma_scale_f32_16x16x128_f8f6f4 v[42:45], v[18:25], v[222:229], v[42:45], v1, v186 op_sel_hi:[0,0,0]
	v_mfma_scale_f32_16x16x128_f8f6f4 v[34:37], v[26:33], v[222:229], v[34:37], v1, v186 op_sel_hi:[0,0,0]
	s_setprio 0
	s_barrier
	s_add_i32 s55, s55, 2
	s_add_u32 s20, s20, 0x100
	s_addc_u32 s21, s21, 0
	s_add_u32 s53, s53, 0x100
	s_addc_u32 s54, s54, 0
	s_cmp_gt_u32 s55, 13
	s_cbranch_scc0 .LBB0_1422
.Lpx_4:
	s_and_b64 vcc, exec, s[8:9]
	s_cbranch_vccz .LBB0_1425
	s_barrier

; #define PG8_STAGE(bufoff, gbase, voff) do { _Pragma("unroll") for (int _i = 0; _i < 2; ++_i) \
;         __builtin_amdgcn_global_load_lds((const unsigned*)((const char*)(gbase) + (voff)[_i]), (PG8_LAS unsigned*)(lds + (bufoff) + ldsw + _i * 8192), 16, 0, 0); } while (0)
; #define PG8_LDA(dst, b, h) do { _Pragma("unroll") for (int m = 0; m < 4; ++m) _Pragma("unroll") for (int k = 0; k < 2; ++k) dst[m][k] = *(const PG8_LAS bf16x8*)(lds + PG8_SA(b, h) + aoff + m * 2048 + k * 1024); } while (0)
; #define PG8_LDB(dst, b, h) do { _Pragma("unroll") for (int n = 0; n < 2; ++n) _Pragma("unroll") for (int k = 0; k < 2; ++k) dst[n][k] = *(const PG8_LAS bf16x8*)(lds + PG8_SB(b, h) + boff + n * 2048 + k * 1024); } while (0)
; #define PG8_WAIT_V(n) asm volatile("s_waitcnt vmcnt(" #n ")" ::: "memory")
; #define PG8_WAIT_L(n) asm volatile("s_waitcnt lgkmcnt(" #n ")" ::: "memory")
; template <class Epi, class Sched, bool ALIGN_EPI = false>
; __device__ __forceinline__ void gemm_phase8(PG8_LAS unsigned char* lds, const Gemm g, const Sched& S, const Epi& E) {
;     ...
;         const bool has_next = S.next(ui + 1, nxt);
;         const size_t nko = (has_next && nxt.kp > 0) ? (size_t)nxt.kp * g.kpiece : 0;
;         const char* nA = has_next ? (const char*)g.A + (size_t)nxt.pm * tstepA + (size_t)nxt.pn * astep + nko : cA; const char* nB = has_next ? (const char*)g.Bt + (size_t)nxt.pn * tstepB + nko : cB;
;         const int nt = (cur.kp < 0 ? g.K : g.kpiece) / 128;
;         for (int t = 0; t < nt; t += 2) {
;             const bool last = (t == nt - 2);
;             const char* a1 = cA + (size_t)(t + 1) * kstep;
;             const char* a2 = last ? nA : cA + (size_t)(t + 2) * kstep; const char* b2 = last ? nB : cB + (size_t)(t + 2) * kstep;
;             const char* a3 = a2 + kstep; const char* b3 = b2 + kstep;
;             if (last && has_next) S.a_ready(nxt);
;             PG8_LDB(B0, 0, 0); PG8_LDB(B1, 0, 1); PG8_SCHED; PG8_LDA(At, 0, 0); PG8_STAGE(PG8_SA(1, 1), a1 + hstepA, voffA);
;             PG8_WAIT_V(8); PG8_WAIT_L(0); PG8_BAR; PG8_MMA(0, 0, At, B0); PG8_MMA(0, 1, At, B1); PG8_BAR; PG8_SCHED;
;             PG8_LDA(At, 0, 1); PG8_STAGE(PG8_SB(0, 0), b2, voffB); PG8_STAGE(PG8_SB(0, 1), b2 + hstepB, voffB); PG8_STAGE(PG8_SA(0, 0), a2, voffA);
;             PG8_WAIT_V(8); PG8_WAIT_L(0); PG8_BAR; PG8_MMA(1, 0, At, B0); PG8_MMA(1, 1, At, B1); PG8_BAR; PG8_SCHED;
.LBB0_1510:
	s_cmp_gt_i32 s30, -1
	s_cselect_b64 s[36:37], -1, 0
	s_cmp_lt_i32 s30, 0
	s_cselect_b32 s31, 44, 4
	s_add_i32 s79, s31, -2
	s_add_u32 s38, s38, 0xb0080
	s_addc_u32 s39, s39, 0
	s_add_u32 s80, s34, 0x100
	s_mov_b32 s40, 0
	s_addc_u32 s81, s35, 0
	ds_read_b128 v[18:21], v187
	ds_read_b128 v[26:29], v187 offset:2048
	ds_read_b128 v[22:25], v188
	ds_read_b128 v[30:33], v188 offset:2048
	ds_read_b128 v[2:5], v189
	ds_read_b128 v[10:13], v189 offset:2048
	ds_read_b128 v[6:9], v190
	ds_read_b128 v[14:17], v190 offset:2048
	s_add_i32 s82, s40, 2
	s_add_u32 s34, s38, 0xfff50080
	s_addc_u32 s35, s39, -1
	s_cmp_eq_u32 s79, s40
	s_cselect_b32 s40, s26, s34
	s_cselect_b32 s41, s27, s35
	s_cselect_b32 s35, s29, s81
	s_cselect_b32 s34, s28, s80
	s_add_i32 m0, s52, 0xc000
	ds_read_b128 v[174:177], v191
	ds_read_b128 v[194:197], v191 offset:2048
	ds_read_b128 v[178:181], v192
	ds_read_b128 v[198:201], v192 offset:2048
	ds_read_b128 v[202:205], v191 offset:4096
	ds_read_b128 v[210:213], v191 offset:6144
	ds_read_b128 v[206:209], v192 offset:4096
	ds_read_b128 v[214:217], v192 offset:6144
	global_load_lds_dwordx4 v170, s[38:39]
	s_add_i32 m0, s52, 0xe000
	s_nop 0
	global_load_lds_dwordx4 v172, s[38:39]
	s_waitcnt vmcnt(8)
	s_waitcnt lgkmcnt(0)
	s_barrier
	s_setprio 1
	s_waitcnt lgkmcnt(0)
	v_mfma_scale_f32_16x16x128_f8f6f4 v[158:161], v[18:25], v[174:181], 0, v1, v182 op_sel_hi:[0,0,0]
	v_mfma_scale_f32_16x16x128_f8f6f4 v[154:157], v[26:33], v[174:181], 0, v1, v182 op_sel_hi:[0,0,0]
	v_mfma_scale_f32_16x16x128_f8f6f4 v[150:153], v[18:25], v[194:201], 0, v1, v182 op_sel_hi:[0,0,0]
	v_mfma_scale_f32_16x16x128_f8f6f4 v[138:141], v[26:33], v[194:201], 0, v1, v182 op_sel_hi:[0,0,0]
	v_mfma_scale_f32_16x16x128_f8f6f4 v[130:133], v[18:25], v[202:209], 0, v1, v182 op_sel_hi:[0,0,0]
	v_mfma_scale_f32_16x16x128_f8f6f4 v[122:125], v[26:33], v[202:209], 0, v1, v182 op_sel_hi:[0,0,0]
	v_mfma_scale_f32_16x16x128_f8f6f4 v[118:121], v[18:25], v[210:217], 0, v1, v182 op_sel_hi:[0,0,0]
	v_mfma_scale_f32_16x16x128_f8f6f4 v[106:109], v[26:33], v[210:217], 0, v1, v182 op_sel_hi:[0,0,0]
	s_setprio 0
	s_setprio 1
	v_mfma_scale_f32_16x16x128_f8f6f4 v[146:149], v[2:9], v[174:181], 0, v1, v182 op_sel_hi:[0,0,0]
	v_mfma_scale_f32_16x16x128_f8f6f4 v[142:145], v[10:17], v[174:181], 0, v1, v182 op_sel_hi:[0,0,0]
	v_mfma_scale_f32_16x16x128_f8f6f4 v[134:137], v[2:9], v[194:201], 0, v1, v182 op_sel_hi:[0,0,0]
	v_mfma_scale_f32_16x16x128_f8f6f4 v[126:129], v[10:17], v[194:201], 0, v1, v182 op_sel_hi:[0,0,0]
	v_mfma_scale_f32_16x16x128_f8f6f4 v[114:117], v[2:9], v[202:209], 0, v1, v182 op_sel_hi:[0,0,0]
	v_mfma_scale_f32_16x16x128_f8f6f4 v[110:113], v[10:17], v[202:209], 0, v1, v182 op_sel_hi:[0,0,0]
	v_mfma_scale_f32_16x16x128_f8f6f4 v[102:105], v[2:9], v[210:217], 0, v1, v182 op_sel_hi:[0,0,0]
	v_mfma_scale_f32_16x16x128_f8f6f4 v[98:101], v[10:17], v[210:217], 0, v1, v182 op_sel_hi:[0,0,0]
	s_setprio 0
	s_barrier
	s_add_i32 s83, s63, s45
	s_mov_b32 m0, s83
	ds_read_b128 v[194:197], v191 offset:16384
	ds_read_b128 v[202:205], v191 offset:18432
	ds_read_b128 v[198:201], v192 offset:16384
	ds_read_b128 v[206:209], v192 offset:18432
	ds_read_b128 v[210:213], v191 offset:20480
	ds_read_b128 v[218:221], v191 offset:22528
	ds_read_b128 v[214:217], v192 offset:20480
	ds_read_b128 v[222:225], v192 offset:22528
	global_load_lds_dwordx4 v164, s[34:35]
	s_add_i32 m0, s83, 0x2000
	s_add_u32 s84, s34, 0xb0000
	s_addc_u32 s85, s35, 0
	s_add_i32 s83, s64, s45
	global_load_lds_dwordx4 v168, s[34:35]
	s_mov_b32 m0, s83
	s_nop 0
	global_load_lds_dwordx4 v164, s[84:85]
	s_add_i32 m0, s83, 0x2000
	s_nop 0
	global_load_lds_dwordx4 v168, s[84:85]
	s_mov_b32 m0, s52
	s_nop 0
	global_load_lds_dwordx4 v162, s[40:41]
	s_mov_b32 m0, s53
	s_nop 0
	global_load_lds_dwordx4 v166, s[40:41]
	s_waitcnt vmcnt(8)
	s_waitcnt lgkmcnt(0)
	s_barrier
	s_setprio 1
	s_waitcnt lgkmcnt(0)
	v_mfma_scale_f32_16x16x128_f8f6f4 v[94:97], v[18:25], v[194:201], 0, v1, v182 op_sel_hi:[0,0,0]
	v_mfma_scale_f32_16x16x128_f8f6f4 v[90:93], v[26:33], v[194:201], 0, v1, v182 op_sel_hi:[0,0,0]
	v_mfma_scale_f32_16x16x128_f8f6f4 v[82:85], v[18:25], v[202:209], 0, v1, v182 op_sel_hi:[0,0,0]
	v_mfma_scale_f32_16x16x128_f8f6f4 v[74:77], v[26:33], v[202:209], 0, v1, v182 op_sel_hi:[0,0,0]
	v_mfma_scale_f32_16x16x128_f8f6f4 v[66:69], v[18:25], v[210:217], 0, v1, v182 op_sel_hi:[0,0,0]
	v_mfma_scale_f32_16x16x128_f8f6f4 v[58:61], v[26:33], v[210:217], 0, v1, v182 op_sel_hi:[0,0,0]
	v_mfma_scale_f32_16x16x128_f8f6f4 v[50:53], v[18:25], v[218:225], 0, v1, v182 op_sel_hi:[0,0,0]
	v_mfma_scale_f32_16x16x128_f8f6f4 v[42:45], v[26:33], v[218:225], 0, v1, v182 op_sel_hi:[0,0,0]
	s_setprio 0
	s_setprio 1
	v_mfma_scale_f32_16x16x128_f8f6f4 v[86:89], v[2:9], v[194:201], 0, v1, v182 op_sel_hi:[0,0,0]
	v_mfma_scale_f32_16x16x128_f8f6f4 v[78:81], v[10:17], v[194:201], 0, v1, v182 op_sel_hi:[0,0,0]
	v_mfma_scale_f32_16x16x128_f8f6f4 v[70:73], v[2:9], v[202:209], 0, v1, v182 op_sel_hi:[0,0,0]
	v_mfma_scale_f32_16x16x128_f8f6f4 v[62:65], v[10:17], v[202:209], 0, v1, v182 op_sel_hi:[0,0,0]
	v_mfma_scale_f32_16x16x128_f8f6f4 v[54:57], v[2:9], v[210:217], 0, v1, v182 op_sel_hi:[0,0,0]
	v_mfma_scale_f32_16x16x128_f8f6f4 v[46:49], v[10:17], v[210:217], 0, v1, v182 op_sel_hi:[0,0,0]
	v_mfma_scale_f32_16x16x128_f8f6f4 v[38:41], v[2:9], v[218:225], 0, v1, v182 op_sel_hi:[0,0,0]
	v_mfma_scale_f32_16x16x128_f8f6f4 v[34:37], v[10:17], v[218:225], 0, v1, v182 op_sel_hi:[0,0,0]
	s_setprio 0
	s_barrier
; #define PG8_STAGE(bufoff, gbase, voff) do { _Pragma("unroll") for (int _i = 0; _i < 2; ++_i) \
;         __builtin_amdgcn_global_load_lds((const unsigned*)((const char*)(gbase) + (voff)[_i]), (PG8_LAS unsigned*)(lds + (bufoff) + ldsw + _i * 8192), 16, 0, 0); } while (0)
; #define PG8_LDA(dst, b, h) do { _Pragma("unroll") for (int m = 0; m < 4; ++m) _Pragma("unroll") for (int k = 0; k < 2; ++k) dst[m][k] = *(const PG8_LAS bf16x8*)(lds + PG8_SA(b, h) + aoff + m * 2048 + k * 1024); } while (0)
; #define PG8_LDB(dst, b, h) do { _Pragma("unroll") for (int n = 0; n < 2; ++n) _Pragma("unroll") for (int k = 0; k < 2; ++k) dst[n][k] = *(const PG8_LAS bf16x8*)(lds + PG8_SB(b, h) + boff + n * 2048 + k * 1024); } while (0)
; #define PG8_MMA(ai, bj, At, Bt) do { __builtin_amdgcn_s_setprio(1); _Pragma("unroll") for (int m = 0; m < 4; ++m) _Pragma("unroll") for (int n = 0; n < 2; ++n) _Pragma("unroll") for (int k = 0; k < 2; ++k) \
;         acc[ai][bj][m][n] = __builtin_amdgcn_mfma_f32_16x16x32_bf16(Bt[n][k], At[m][k], acc[ai][bj][m][n], 0, 0, 0); __builtin_amdgcn_s_setprio(0); } while (0)
; #define PG8_WAIT_V(n) asm volatile("s_waitcnt vmcnt(" #n ")" ::: "memory")
; #define PG8_WAIT_L(n) asm volatile("s_waitcnt lgkmcnt(" #n ")" ::: "memory")
; #define PG8_BAR __builtin_amdgcn_s_barrier()
; #define PG8_SCHED __builtin_amdgcn_sched_barrier(0)
; #define PG8_STAGE(bufoff, gbase, voff) do { _Pragma("unroll") for (int _i = 0; _i < 2; ++_i) \
;         __builtin_amdgcn_global_load_lds((const unsigned*)((const char*)(gbase) + (voff)[_i]), (PG8_LAS unsigned*)(lds + (bufoff) + ldsw + _i * 8192), 16, 0, 0); } while (0)
; #define PG8_WAIT_V(n) asm volatile("s_waitcnt vmcnt(" #n ")" ::: "memory")
; template <class Epi, class Sched, bool ALIGN_EPI = false>
; __device__ __forceinline__ void gemm_phase8(PG8_LAS unsigned char* lds, const Gemm g, const Sched& S, const Epi& E) {
;     ...
;             PG8_LDB(B0, 1, 0); PG8_LDB(B1, 1, 1); PG8_SCHED; PG8_LDA(At, 1, 0); PG8_STAGE(PG8_SA(0, 1), a2 + hstepA, voffA);
;             PG8_WAIT_V(8); PG8_WAIT_L(0); PG8_BAR; PG8_MMA(0, 0, At, B0); PG8_MMA(0, 1, At, B1); PG8_BAR; PG8_SCHED;
;             PG8_LDA(At, 1, 1); PG8_STAGE(PG8_SB(1, 0), b3, voffB); PG8_STAGE(PG8_SB(1, 1), b3 + hstepB, voffB); PG8_STAGE(PG8_SA(1, 0), a3, voffA);
;             PG8_WAIT_V(8); PG8_WAIT_L(0); PG8_BAR; PG8_MMA(1, 0, At, B0); PG8_MMA(1, 1, At, B1); PG8_BAR; PG8_SCHED;
	s_add_i32 s83, 0, 0x18000
	s_add_i32 s84, 0, 0x1c000
	v_add_u32_e32 v6, s83, v184
	v_add_u32_e32 v14, s83, v185
	v_add_u32_e32 v22, s84, v184
	v_add_u32_e32 v30, s84, v185
	ds_read_b128 v[2:5], v6
	ds_read_b128 v[10:13], v6 offset:2048
	ds_read_b128 v[6:9], v14
	ds_read_b128 v[14:17], v14 offset:2048
	ds_read_b128 v[18:21], v22
	ds_read_b128 v[26:29], v22 offset:2048
	ds_read_b128 v[22:25], v30
	ds_read_b128 v[30:33], v30 offset:2048
	s_add_u32 s40, s40, 0xb0000
	s_addc_u32 s41, s41, 0
	s_mov_b32 m0, s54
	ds_read_b128 v[194:197], v191 offset:32768
	ds_read_b128 v[202:205], v191 offset:34816
	ds_read_b128 v[198:201], v192 offset:32768
	ds_read_b128 v[206:209], v192 offset:34816
	ds_read_b128 v[210:213], v191 offset:36864
	ds_read_b128 v[218:221], v191 offset:38912
	ds_read_b128 v[214:217], v192 offset:36864
	ds_read_b128 v[222:225], v192 offset:38912
	global_load_lds_dwordx4 v162, s[40:41]
	s_mov_b32 m0, s55
	s_nop 0
	global_load_lds_dwordx4 v166, s[40:41]
	s_waitcnt vmcnt(8)
	s_waitcnt lgkmcnt(0)
	s_barrier
	s_setprio 1
	s_waitcnt lgkmcnt(0)
	v_mfma_scale_f32_16x16x128_f8f6f4 v[158:161], v[2:9], v[194:201], v[158:161], v1, v182 op_sel_hi:[0,0,0]
	v_mfma_scale_f32_16x16x128_f8f6f4 v[154:157], v[10:17], v[194:201], v[154:157], v1, v182 op_sel_hi:[0,0,0]
	v_mfma_scale_f32_16x16x128_f8f6f4 v[150:153], v[2:9], v[202:209], v[150:153], v1, v182 op_sel_hi:[0,0,0]
	v_mfma_scale_f32_16x16x128_f8f6f4 v[138:141], v[10:17], v[202:209], v[138:141], v1, v182 op_sel_hi:[0,0,0]
	v_mfma_scale_f32_16x16x128_f8f6f4 v[130:133], v[2:9], v[210:217], v[130:133], v1, v182 op_sel_hi:[0,0,0]
	v_mfma_scale_f32_16x16x128_f8f6f4 v[122:125], v[10:17], v[210:217], v[122:125], v1, v182 op_sel_hi:[0,0,0]
	v_mfma_scale_f32_16x16x128_f8f6f4 v[118:121], v[2:9], v[218:225], v[118:121], v1, v182 op_sel_hi:[0,0,0]
	v_mfma_scale_f32_16x16x128_f8f6f4 v[106:109], v[10:17], v[218:225], v[106:109], v1, v182 op_sel_hi:[0,0,0]
	s_setprio 0
	s_setprio 1
	v_mfma_scale_f32_16x16x128_f8f6f4 v[146:149], v[18:25], v[194:201], v[146:149], v1, v182 op_sel_hi:[0,0,0]
	v_mfma_scale_f32_16x16x128_f8f6f4 v[142:145], v[26:33], v[194:201], v[142:145], v1, v182 op_sel_hi:[0,0,0]
	v_mfma_scale_f32_16x16x128_f8f6f4 v[134:137], v[18:25], v[202:209], v[134:137], v1, v182 op_sel_hi:[0,0,0]
	v_mfma_scale_f32_16x16x128_f8f6f4 v[126:129], v[26:33], v[202:209], v[126:129], v1, v182 op_sel_hi:[0,0,0]
	v_mfma_scale_f32_16x16x128_f8f6f4 v[114:117], v[18:25], v[210:217], v[114:117], v1, v182 op_sel_hi:[0,0,0]
	v_mfma_scale_f32_16x16x128_f8f6f4 v[110:113], v[26:33], v[210:217], v[110:113], v1, v182 op_sel_hi:[0,0,0]
	v_mfma_scale_f32_16x16x128_f8f6f4 v[102:105], v[18:25], v[218:225], v[102:105], v1, v182 op_sel_hi:[0,0,0]
	v_mfma_scale_f32_16x16x128_f8f6f4 v[98:101], v[26:33], v[218:225], v[98:101], v1, v182 op_sel_hi:[0,0,0]
	s_setprio 0
	s_barrier
	s_add_i32 s101, s83, s45
	s_add_u32 s98, s34, s12
	s_addc_u32 s99, s35, s13
	s_mov_b32 m0, s101
	ds_read_b128 v[194:197], v191 offset:49152
	ds_read_b128 v[202:205], v191 offset:51200
	ds_read_b128 v[198:201], v192 offset:49152
	ds_read_b128 v[206:209], v192 offset:51200
	ds_read_b128 v[210:213], v191 offset:53248
	ds_read_b128 v[218:221], v191 offset:55296
	ds_read_b128 v[214:217], v192 offset:53248
	ds_read_b128 v[222:225], v192 offset:55296
	global_load_lds_dwordx4 v164, s[98:99]
	s_add_i32 m0, s101, 0x2000
	s_add_u32 s34, s34, 0xb0080
	s_addc_u32 s35, s35, 0
	s_add_i32 s101, s84, s45
	global_load_lds_dwordx4 v168, s[98:99]
	s_add_u32 s98, s40, s12
	s_addc_u32 s99, s41, s13
	s_sub_u32 s98, s98, 0xb0000
	s_subb_u32 s99, s99, 0
	s_mov_b32 m0, s101
	s_nop 0
	global_load_lds_dwordx4 v164, s[34:35]
	s_add_i32 m0, s101, 0x2000
	s_nop 0
	global_load_lds_dwordx4 v168, s[34:35]
	s_mov_b32 m0, s61
	s_nop 0
	global_load_lds_dwordx4 v162, s[98:99]
	s_mov_b32 m0, s62
	s_nop 0
	global_load_lds_dwordx4 v166, s[98:99]
	s_waitcnt vmcnt(8)
	s_waitcnt lgkmcnt(0)
	s_barrier
	s_setprio 1
	s_waitcnt lgkmcnt(0)
	v_mfma_scale_f32_16x16x128_f8f6f4 v[94:97], v[2:9], v[194:201], v[94:97], v1, v182 op_sel_hi:[0,0,0]
	v_mfma_scale_f32_16x16x128_f8f6f4 v[90:93], v[10:17], v[194:201], v[90:93], v1, v182 op_sel_hi:[0,0,0]
	v_mfma_scale_f32_16x16x128_f8f6f4 v[82:85], v[2:9], v[202:209], v[82:85], v1, v182 op_sel_hi:[0,0,0]
	v_mfma_scale_f32_16x16x128_f8f6f4 v[74:77], v[10:17], v[202:209], v[74:77], v1, v182 op_sel_hi:[0,0,0]
	v_mfma_scale_f32_16x16x128_f8f6f4 v[66:69], v[2:9], v[210:217], v[66:69], v1, v182 op_sel_hi:[0,0,0]
	v_mfma_scale_f32_16x16x128_f8f6f4 v[58:61], v[10:17], v[210:217], v[58:61], v1, v182 op_sel_hi:[0,0,0]
	v_mfma_scale_f32_16x16x128_f8f6f4 v[50:53], v[2:9], v[218:225], v[50:53], v1, v182 op_sel_hi:[0,0,0]
	v_mfma_scale_f32_16x16x128_f8f6f4 v[42:45], v[10:17], v[218:225], v[42:45], v1, v182 op_sel_hi:[0,0,0]
	s_setprio 0
	s_setprio 1
	v_mfma_scale_f32_16x16x128_f8f6f4 v[86:89], v[18:25], v[194:201], v[86:89], v1, v182 op_sel_hi:[0,0,0]
	v_mfma_scale_f32_16x16x128_f8f6f4 v[78:81], v[26:33], v[194:201], v[78:81], v1, v182 op_sel_hi:[0,0,0]
	v_mfma_scale_f32_16x16x128_f8f6f4 v[70:73], v[18:25], v[202:209], v[70:73], v1, v182 op_sel_hi:[0,0,0]
	v_mfma_scale_f32_16x16x128_f8f6f4 v[62:65], v[26:33], v[202:209], v[62:65], v1, v182 op_sel_hi:[0,0,0]
	v_mfma_scale_f32_16x16x128_f8f6f4 v[54:57], v[18:25], v[210:217], v[54:57], v1, v182 op_sel_hi:[0,0,0]
	v_mfma_scale_f32_16x16x128_f8f6f4 v[46:49], v[26:33], v[210:217], v[46:49], v1, v182 op_sel_hi:[0,0,0]
	v_mfma_scale_f32_16x16x128_f8f6f4 v[38:41], v[18:25], v[218:225], v[38:41], v1, v182 op_sel_hi:[0,0,0]
	v_mfma_scale_f32_16x16x128_f8f6f4 v[34:37], v[26:33], v[218:225], v[34:37], v1, v182 op_sel_hi:[0,0,0]
	s_setprio 0
	s_barrier
; #define PG8_STAGE(bufoff, gbase, voff) do { _Pragma("unroll") for (int _i = 0; _i < 2; ++_i) \
;         __builtin_amdgcn_global_load_lds((const unsigned*)((const char*)(gbase) + (voff)[_i]), (PG8_LAS unsigned*)(lds + (bufoff) + ldsw + _i * 8192), 16, 0, 0); } while (0)
; #define PG8_LDA(dst, b, h) do { _Pragma("unroll") for (int m = 0; m < 4; ++m) _Pragma("unroll") for (int k = 0; k < 2; ++k) dst[m][k] = *(const PG8_LAS bf16x8*)(lds + PG8_SA(b, h) + aoff + m * 2048 + k * 1024); } while (0)
; #define PG8_LDB(dst, b, h) do { _Pragma("unroll") for (int n = 0; n < 2; ++n) _Pragma("unroll") for (int k = 0; k < 2; ++k) dst[n][k] = *(const PG8_LAS bf16x8*)(lds + PG8_SB(b, h) + boff + n * 2048 + k * 1024); } while (0)
; #define PG8_MMA(ai, bj, At, Bt) do { __builtin_amdgcn_s_setprio(1); _Pragma("unroll") for (int m = 0; m < 4; ++m) _Pragma("unroll") for (int n = 0; n < 2; ++n) _Pragma("unroll") for (int k = 0; k < 2; ++k) \
;         acc[ai][bj][m][n] = __builtin_amdgcn_mfma_f32_16x16x32_bf16(Bt[n][k], At[m][k], acc[ai][bj][m][n], 0, 0, 0); __builtin_amdgcn_s_setprio(0); } while (0)
; #define PG8_WAIT_V(n) asm volatile("s_waitcnt vmcnt(" #n ")" ::: "memory")
; #define PG8_WAIT_L(n) asm volatile("s_waitcnt lgkmcnt(" #n ")" ::: "memory")
; template <class Epi, class Sched, bool ALIGN_EPI = false>
; __device__ __forceinline__ void gemm_phase8(PG8_LAS unsigned char* lds, const Gemm g, const Sched& S, const Epi& E) {
;     ...
;         for (int t = 0; t < nt; t += 2) {
;             const bool last = (t == nt - 2);
;             const char* a1 = cA + (size_t)(t + 1) * kstep;
;             const char* a2 = last ? nA : cA + (size_t)(t + 2) * kstep; const char* b2 = last ? nB : cB + (size_t)(t + 2) * kstep;
;             const char* a3 = a2 + kstep; const char* b3 = b2 + kstep;
;             if (last && has_next) S.a_ready(nxt);
;             PG8_LDB(B0, 0, 0); PG8_LDB(B1, 0, 1); PG8_SCHED; PG8_LDA(At, 0, 0); PG8_STAGE(PG8_SA(1, 1), a1 + hstepA, voffA);
;             PG8_WAIT_V(8); PG8_WAIT_L(0); PG8_BAR; PG8_MMA(0, 0, At, B0); PG8_MMA(0, 1, At, B1); PG8_BAR; PG8_SCHED;
;             PG8_LDA(At, 0, 1); PG8_STAGE(PG8_SB(0, 0), b2, voffB); PG8_STAGE(PG8_SB(0, 1), b2 + hstepB, voffB); PG8_STAGE(PG8_SA(0, 0), a2, voffA);
;             PG8_WAIT_V(8); PG8_WAIT_L(0); PG8_BAR; PG8_MMA(1, 0, At, B0); PG8_MMA(1, 1, At, B1); PG8_BAR; PG8_SCHED;
	s_add_u32 s38, s38, 0x100
	s_addc_u32 s39, s39, 0
	s_add_u32 s80, s80, 0x100
	s_addc_u32 s81, s81, 0
	s_cmp_ge_u32 s82, s31
	s_mov_b32 s40, s82
	ds_read_b128 v[18:21], v187
	ds_read_b128 v[26:29], v187 offset:2048
	ds_read_b128 v[22:25], v188
	ds_read_b128 v[30:33], v188 offset:2048
	ds_read_b128 v[2:5], v189
	ds_read_b128 v[10:13], v189 offset:2048
	ds_read_b128 v[6:9], v190
	ds_read_b128 v[14:17], v190 offset:2048
	s_add_i32 s82, s40, 2
	s_add_u32 s34, s38, 0xfff50080
	s_addc_u32 s35, s39, -1
	s_cmp_eq_u32 s79, s40
	s_cselect_b32 s40, s26, s34
	s_cselect_b32 s41, s27, s35
	s_cselect_b32 s35, s29, s81
	s_cselect_b32 s34, s28, s80
	s_add_i32 m0, s52, 0xc000
	ds_read_b128 v[174:177], v191
	ds_read_b128 v[194:197], v191 offset:2048
	ds_read_b128 v[178:181], v192
	ds_read_b128 v[198:201], v192 offset:2048
	ds_read_b128 v[202:205], v191 offset:4096
	ds_read_b128 v[210:213], v191 offset:6144
	ds_read_b128 v[206:209], v192 offset:4096
	ds_read_b128 v[214:217], v192 offset:6144
	global_load_lds_dwordx4 v170, s[38:39]
	s_add_i32 m0, s52, 0xe000
	s_nop 0
	global_load_lds_dwordx4 v172, s[38:39]
	s_waitcnt vmcnt(8)
	s_waitcnt lgkmcnt(0)
	s_barrier
	s_setprio 1
	s_waitcnt lgkmcnt(0)
	v_mfma_scale_f32_16x16x128_f8f6f4 v[158:161], v[18:25], v[174:181], v[158:161], v1, v182 op_sel_hi:[0,0,0]
	v_mfma_scale_f32_16x16x128_f8f6f4 v[154:157], v[26:33], v[174:181], v[154:157], v1, v182 op_sel_hi:[0,0,0]
	v_mfma_scale_f32_16x16x128_f8f6f4 v[150:153], v[18:25], v[194:201], v[150:153], v1, v182 op_sel_hi:[0,0,0]
	v_mfma_scale_f32_16x16x128_f8f6f4 v[138:141], v[26:33], v[194:201], v[138:141], v1, v182 op_sel_hi:[0,0,0]
	v_mfma_scale_f32_16x16x128_f8f6f4 v[130:133], v[18:25], v[202:209], v[130:133], v1, v182 op_sel_hi:[0,0,0]
	v_mfma_scale_f32_16x16x128_f8f6f4 v[122:125], v[26:33], v[202:209], v[122:125], v1, v182 op_sel_hi:[0,0,0]
	v_mfma_scale_f32_16x16x128_f8f6f4 v[118:121], v[18:25], v[210:217], v[118:121], v1, v182 op_sel_hi:[0,0,0]
	v_mfma_scale_f32_16x16x128_f8f6f4 v[106:109], v[26:33], v[210:217], v[106:109], v1, v182 op_sel_hi:[0,0,0]
	s_setprio 0
	s_setprio 1
	v_mfma_scale_f32_16x16x128_f8f6f4 v[146:149], v[2:9], v[174:181], v[146:149], v1, v182 op_sel_hi:[0,0,0]
	v_mfma_scale_f32_16x16x128_f8f6f4 v[142:145], v[10:17], v[174:181], v[142:145], v1, v182 op_sel_hi:[0,0,0]
	v_mfma_scale_f32_16x16x128_f8f6f4 v[134:137], v[2:9], v[194:201], v[134:137], v1, v182 op_sel_hi:[0,0,0]
	v_mfma_scale_f32_16x16x128_f8f6f4 v[126:129], v[10:17], v[194:201], v[126:129], v1, v182 op_sel_hi:[0,0,0]
	v_mfma_scale_f32_16x16x128_f8f6f4 v[114:117], v[2:9], v[202:209], v[114:117], v1, v182 op_sel_hi:[0,0,0]
	v_mfma_scale_f32_16x16x128_f8f6f4 v[110:113], v[10:17], v[202:209], v[110:113], v1, v182 op_sel_hi:[0,0,0]
	v_mfma_scale_f32_16x16x128_f8f6f4 v[102:105], v[2:9], v[210:217], v[102:105], v1, v182 op_sel_hi:[0,0,0]
	v_mfma_scale_f32_16x16x128_f8f6f4 v[98:101], v[10:17], v[210:217], v[98:101], v1, v182 op_sel_hi:[0,0,0]
	s_setprio 0
	s_barrier
	s_add_i32 s83, s63, s45
	s_mov_b32 m0, s83
	ds_read_b128 v[194:197], v191 offset:16384
	ds_read_b128 v[202:205], v191 offset:18432
	ds_read_b128 v[198:201], v192 offset:16384
	ds_read_b128 v[206:209], v192 offset:18432
	ds_read_b128 v[210:213], v191 offset:20480
	ds_read_b128 v[218:221], v191 offset:22528
	ds_read_b128 v[214:217], v192 offset:20480
	ds_read_b128 v[222:225], v192 offset:22528
	global_load_lds_dwordx4 v164, s[34:35]
	s_add_i32 m0, s83, 0x2000
	s_add_u32 s84, s34, 0xb0000
	s_addc_u32 s85, s35, 0
	s_add_i32 s83, s64, s45
	global_load_lds_dwordx4 v168, s[34:35]
	s_mov_b32 m0, s83
	s_nop 0
	global_load_lds_dwordx4 v164, s[84:85]
	s_add_i32 m0, s83, 0x2000
	s_nop 0
	global_load_lds_dwordx4 v168, s[84:85]
	s_mov_b32 m0, s52
	s_nop 0
	global_load_lds_dwordx4 v162, s[40:41]
	s_mov_b32 m0, s53
	s_nop 0
	global_load_lds_dwordx4 v166, s[40:41]
	s_waitcnt vmcnt(8)
	s_waitcnt lgkmcnt(0)
	s_barrier
	s_setprio 1
	s_waitcnt lgkmcnt(0)
	v_mfma_scale_f32_16x16x128_f8f6f4 v[94:97], v[18:25], v[194:201], v[94:97], v1, v182 op_sel_hi:[0,0,0]
	v_mfma_scale_f32_16x16x128_f8f6f4 v[90:93], v[26:33], v[194:201], v[90:93], v1, v182 op_sel_hi:[0,0,0]
	v_mfma_scale_f32_16x16x128_f8f6f4 v[82:85], v[18:25], v[202:209], v[82:85], v1, v182 op_sel_hi:[0,0,0]
	v_mfma_scale_f32_16x16x128_f8f6f4 v[74:77], v[26:33], v[202:209], v[74:77], v1, v182 op_sel_hi:[0,0,0]
	v_mfma_scale_f32_16x16x128_f8f6f4 v[66:69], v[18:25], v[210:217], v[66:69], v1, v182 op_sel_hi:[0,0,0]
	v_mfma_scale_f32_16x16x128_f8f6f4 v[58:61], v[26:33], v[210:217], v[58:61], v1, v182 op_sel_hi:[0,0,0]
	v_mfma_scale_f32_16x16x128_f8f6f4 v[50:53], v[18:25], v[218:225], v[50:53], v1, v182 op_sel_hi:[0,0,0]
	v_mfma_scale_f32_16x16x128_f8f6f4 v[42:45], v[26:33], v[218:225], v[42:45], v1, v182 op_sel_hi:[0,0,0]
	s_setprio 0
	s_setprio 1
	v_mfma_scale_f32_16x16x128_f8f6f4 v[86:89], v[2:9], v[194:201], v[86:89], v1, v182 op_sel_hi:[0,0,0]
	v_mfma_scale_f32_16x16x128_f8f6f4 v[78:81], v[10:17], v[194:201], v[78:81], v1, v182 op_sel_hi:[0,0,0]
	v_mfma_scale_f32_16x16x128_f8f6f4 v[70:73], v[2:9], v[202:209], v[70:73], v1, v182 op_sel_hi:[0,0,0]
	v_mfma_scale_f32_16x16x128_f8f6f4 v[62:65], v[10:17], v[202:209], v[62:65], v1, v182 op_sel_hi:[0,0,0]
	v_mfma_scale_f32_16x16x128_f8f6f4 v[54:57], v[2:9], v[210:217], v[54:57], v1, v182 op_sel_hi:[0,0,0]
	v_mfma_scale_f32_16x16x128_f8f6f4 v[46:49], v[10:17], v[210:217], v[46:49], v1, v182 op_sel_hi:[0,0,0]
	v_mfma_scale_f32_16x16x128_f8f6f4 v[38:41], v[2:9], v[218:225], v[38:41], v1, v182 op_sel_hi:[0,0,0]
	v_mfma_scale_f32_16x16x128_f8f6f4 v[34:37], v[10:17], v[218:225], v[34:37], v1, v182 op_sel_hi:[0,0,0]
	s_setprio 0
	s_barrier
; #define PG8_STAGE(bufoff, gbase, voff) do { _Pragma("unroll") for (int _i = 0; _i < 2; ++_i) \
;         __builtin_amdgcn_global_load_lds((const unsigned*)((const char*)(gbase) + (voff)[_i]), (PG8_LAS unsigned*)(lds + (bufoff) + ldsw + _i * 8192), 16, 0, 0); } while (0)
; #define PG8_LDA(dst, b, h) do { _Pragma("unroll") for (int m = 0; m < 4; ++m) _Pragma("unroll") for (int k = 0; k < 2; ++k) dst[m][k] = *(const PG8_LAS bf16x8*)(lds + PG8_SA(b, h) + aoff + m * 2048 + k * 1024); } while (0)
; #define PG8_LDB(dst, b, h) do { _Pragma("unroll") for (int n = 0; n < 2; ++n) _Pragma("unroll") for (int k = 0; k < 2; ++k) dst[n][k] = *(const PG8_LAS bf16x8*)(lds + PG8_SB(b, h) + boff + n * 2048 + k * 1024); } while (0)
; #define PG8_MMA(ai, bj, At, Bt) do { __builtin_amdgcn_s_setprio(1); _Pragma("unroll") for (int m = 0; m < 4; ++m) _Pragma("unroll") for (int n = 0; n < 2; ++n) _Pragma("unroll") for (int k = 0; k < 2; ++k) \
;         acc[ai][bj][m][n] = __builtin_amdgcn_mfma_f32_16x16x32_bf16(Bt[n][k], At[m][k], acc[ai][bj][m][n], 0, 0, 0); __builtin_amdgcn_s_setprio(0); } while (0)
; #define PG8_WAIT_V(n) asm volatile("s_waitcnt vmcnt(" #n ")" ::: "memory")
; #define PG8_WAIT_L(n) asm volatile("s_waitcnt lgkmcnt(" #n ")" ::: "memory")
; #define PG8_BAR __builtin_amdgcn_s_barrier()
; #define PG8_SCHED __builtin_amdgcn_sched_barrier(0)
; #define PG8_STAGE(bufoff, gbase, voff) do { _Pragma("unroll") for (int _i = 0; _i < 2; ++_i) \
;         __builtin_amdgcn_global_load_lds((const unsigned*)((const char*)(gbase) + (voff)[_i]), (PG8_LAS unsigned*)(lds + (bufoff) + ldsw + _i * 8192), 16, 0, 0); } while (0)
; template <class Epi, class Sched, bool ALIGN_EPI = false>
; __device__ __forceinline__ void gemm_phase8(PG8_LAS unsigned char* lds, const Gemm g, const Sched& S, const Epi& E) {
;     ...
;         for (int t = 0; t < nt; t += 2) {
;     ...
;             PG8_LDB(B0, 1, 0); PG8_LDB(B1, 1, 1); PG8_SCHED; PG8_LDA(At, 1, 0); PG8_STAGE(PG8_SA(0, 1), a2 + hstepA, voffA);
;             PG8_WAIT_V(8); PG8_WAIT_L(0); PG8_BAR; PG8_MMA(0, 0, At, B0); PG8_MMA(0, 1, At, B1); PG8_BAR; PG8_SCHED;
;             PG8_LDA(At, 1, 1); PG8_STAGE(PG8_SB(1, 0), b3, voffB); PG8_STAGE(PG8_SB(1, 1), b3 + hstepB, voffB); PG8_STAGE(PG8_SA(1, 0), a3, voffA);
;             PG8_WAIT_V(8); PG8_WAIT_L(0); PG8_BAR; PG8_MMA(1, 0, At, B0); PG8_MMA(1, 1, At, B1); PG8_BAR; PG8_SCHED;
	s_add_i32 s83, 0, 0x18000
	s_add_i32 s84, 0, 0x1c000
	v_add_u32_e32 v6, s83, v184
	v_add_u32_e32 v14, s83, v185
	v_add_u32_e32 v22, s84, v184
	v_add_u32_e32 v30, s84, v185
	ds_read_b128 v[2:5], v6
	ds_read_b128 v[10:13], v6 offset:2048
	ds_read_b128 v[6:9], v14
	ds_read_b128 v[14:17], v14 offset:2048
	ds_read_b128 v[18:21], v22
	ds_read_b128 v[26:29], v22 offset:2048
	ds_read_b128 v[22:25], v30
	ds_read_b128 v[30:33], v30 offset:2048
	s_add_u32 s40, s40, 0xb0000
	s_addc_u32 s41, s41, 0
	s_mov_b32 m0, s54
	ds_read_b128 v[194:197], v191 offset:32768
	ds_read_b128 v[202:205], v191 offset:34816
	ds_read_b128 v[198:201], v192 offset:32768
	ds_read_b128 v[206:209], v192 offset:34816
	ds_read_b128 v[210:213], v191 offset:36864
	ds_read_b128 v[218:221], v191 offset:38912
	ds_read_b128 v[214:217], v192 offset:36864
	ds_read_b128 v[222:225], v192 offset:38912
	global_load_lds_dwordx4 v162, s[40:41]
	s_mov_b32 m0, s55
	s_nop 0
	global_load_lds_dwordx4 v166, s[40:41]
	s_waitcnt vmcnt(8)
	s_waitcnt lgkmcnt(0)
	s_barrier
	s_setprio 1
	s_waitcnt lgkmcnt(0)
	v_mfma_scale_f32_16x16x128_f8f6f4 v[158:161], v[2:9], v[194:201], v[158:161], v1, v182 op_sel_hi:[0,0,0]
	v_mfma_scale_f32_16x16x128_f8f6f4 v[154:157], v[10:17], v[194:201], v[154:157], v1, v182 op_sel_hi:[0,0,0]
	v_mfma_scale_f32_16x16x128_f8f6f4 v[150:153], v[2:9], v[202:209], v[150:153], v1, v182 op_sel_hi:[0,0,0]
	v_mfma_scale_f32_16x16x128_f8f6f4 v[138:141], v[10:17], v[202:209], v[138:141], v1, v182 op_sel_hi:[0,0,0]
	v_mfma_scale_f32_16x16x128_f8f6f4 v[130:133], v[2:9], v[210:217], v[130:133], v1, v182 op_sel_hi:[0,0,0]
	v_mfma_scale_f32_16x16x128_f8f6f4 v[122:125], v[10:17], v[210:217], v[122:125], v1, v182 op_sel_hi:[0,0,0]
	v_mfma_scale_f32_16x16x128_f8f6f4 v[118:121], v[2:9], v[218:225], v[118:121], v1, v182 op_sel_hi:[0,0,0]
	v_mfma_scale_f32_16x16x128_f8f6f4 v[106:109], v[10:17], v[218:225], v[106:109], v1, v182 op_sel_hi:[0,0,0]
	s_setprio 0
	s_setprio 1
	v_mfma_scale_f32_16x16x128_f8f6f4 v[146:149], v[18:25], v[194:201], v[146:149], v1, v182 op_sel_hi:[0,0,0]
	v_mfma_scale_f32_16x16x128_f8f6f4 v[142:145], v[26:33], v[194:201], v[142:145], v1, v182 op_sel_hi:[0,0,0]
	v_mfma_scale_f32_16x16x128_f8f6f4 v[134:137], v[18:25], v[202:209], v[134:137], v1, v182 op_sel_hi:[0,0,0]
	v_mfma_scale_f32_16x16x128_f8f6f4 v[126:129], v[26:33], v[202:209], v[126:129], v1, v182 op_sel_hi:[0,0,0]
	v_mfma_scale_f32_16x16x128_f8f6f4 v[114:117], v[18:25], v[210:217], v[114:117], v1, v182 op_sel_hi:[0,0,0]
	v_mfma_scale_f32_16x16x128_f8f6f4 v[110:113], v[26:33], v[210:217], v[110:113], v1, v182 op_sel_hi:[0,0,0]
	v_mfma_scale_f32_16x16x128_f8f6f4 v[102:105], v[18:25], v[218:225], v[102:105], v1, v182 op_sel_hi:[0,0,0]
	v_mfma_scale_f32_16x16x128_f8f6f4 v[98:101], v[26:33], v[218:225], v[98:101], v1, v182 op_sel_hi:[0,0,0]
	s_setprio 0
	s_barrier
	s_add_i32 s101, s83, s45
	s_add_u32 s98, s34, s12
	s_addc_u32 s99, s35, s13
	s_mov_b32 m0, s101
	ds_read_b128 v[194:197], v191 offset:49152
	ds_read_b128 v[202:205], v191 offset:51200
	ds_read_b128 v[198:201], v192 offset:49152
	ds_read_b128 v[206:209], v192 offset:51200
	ds_read_b128 v[210:213], v191 offset:53248
	ds_read_b128 v[218:221], v191 offset:55296
	ds_read_b128 v[214:217], v192 offset:53248
	ds_read_b128 v[222:225], v192 offset:55296
	global_load_lds_dwordx4 v164, s[98:99]
	s_add_i32 m0, s101, 0x2000
	s_add_u32 s34, s34, 0xb0080
	s_addc_u32 s35, s35, 0
	s_add_i32 s101, s84, s45
	global_load_lds_dwordx4 v168, s[98:99]
	s_add_u32 s98, s40, s12
	s_addc_u32 s99, s41, s13
	s_sub_u32 s98, s98, 0xb0000
	s_subb_u32 s99, s99, 0
	s_mov_b32 m0, s101
	s_nop 0
	global_load_lds_dwordx4 v164, s[34:35]
	s_add_i32 m0, s101, 0x2000
	s_nop 0
	global_load_lds_dwordx4 v168, s[34:35]
	s_mov_b32 m0, s61
	s_nop 0
	global_load_lds_dwordx4 v162, s[98:99]
	s_mov_b32 m0, s62
	s_nop 0
	global_load_lds_dwordx4 v166, s[98:99]
	s_waitcnt vmcnt(8)
	s_waitcnt lgkmcnt(0)
	s_barrier
	s_setprio 1
	s_waitcnt lgkmcnt(0)
	v_mfma_scale_f32_16x16x128_f8f6f4 v[94:97], v[2:9], v[194:201], v[94:97], v1, v182 op_sel_hi:[0,0,0]
	v_mfma_scale_f32_16x16x128_f8f6f4 v[90:93], v[10:17], v[194:201], v[90:93], v1, v182 op_sel_hi:[0,0,0]
	v_mfma_scale_f32_16x16x128_f8f6f4 v[82:85], v[2:9], v[202:209], v[82:85], v1, v182 op_sel_hi:[0,0,0]
	v_mfma_scale_f32_16x16x128_f8f6f4 v[74:77], v[10:17], v[202:209], v[74:77], v1, v182 op_sel_hi:[0,0,0]
	v_mfma_scale_f32_16x16x128_f8f6f4 v[66:69], v[2:9], v[210:217], v[66:69], v1, v182 op_sel_hi:[0,0,0]
	v_mfma_scale_f32_16x16x128_f8f6f4 v[58:61], v[10:17], v[210:217], v[58:61], v1, v182 op_sel_hi:[0,0,0]
	v_mfma_scale_f32_16x16x128_f8f6f4 v[50:53], v[2:9], v[218:225], v[50:53], v1, v182 op_sel_hi:[0,0,0]
	v_mfma_scale_f32_16x16x128_f8f6f4 v[42:45], v[10:17], v[218:225], v[42:45], v1, v182 op_sel_hi:[0,0,0]
	s_setprio 0
	s_setprio 1
	v_mfma_scale_f32_16x16x128_f8f6f4 v[86:89], v[18:25], v[194:201], v[86:89], v1, v182 op_sel_hi:[0,0,0]
	v_mfma_scale_f32_16x16x128_f8f6f4 v[78:81], v[26:33], v[194:201], v[78:81], v1, v182 op_sel_hi:[0,0,0]
	v_mfma_scale_f32_16x16x128_f8f6f4 v[70:73], v[18:25], v[202:209], v[70:73], v1, v182 op_sel_hi:[0,0,0]
	v_mfma_scale_f32_16x16x128_f8f6f4 v[62:65], v[26:33], v[202:209], v[62:65], v1, v182 op_sel_hi:[0,0,0]
	v_mfma_scale_f32_16x16x128_f8f6f4 v[54:57], v[18:25], v[210:217], v[54:57], v1, v182 op_sel_hi:[0,0,0]
	v_mfma_scale_f32_16x16x128_f8f6f4 v[46:49], v[26:33], v[210:217], v[46:49], v1, v182 op_sel_hi:[0,0,0]
	v_mfma_scale_f32_16x16x128_f8f6f4 v[38:41], v[18:25], v[218:225], v[38:41], v1, v182 op_sel_hi:[0,0,0]
	v_mfma_scale_f32_16x16x128_f8f6f4 v[34:37], v[26:33], v[218:225], v[34:37], v1, v182 op_sel_hi:[0,0,0]
	s_setprio 0
	s_barrier
	s_add_u32 s38, s38, 0x100
	s_addc_u32 s39, s39, 0
	s_add_u32 s80, s80, 0x100
	s_addc_u32 s81, s81, 0
	s_cmp_ge_u32 s82, s31
	s_mov_b32 s40, s82
	s_cbranch_scc1 .Lpx_5
; #define PG8_STAGE(bufoff, gbase, voff) do { _Pragma("unroll") for (int _i = 0; _i < 2; ++_i) \
;         __builtin_amdgcn_global_load_lds((const unsigned*)((const char*)(gbase) + (voff)[_i]), (PG8_LAS unsigned*)(lds + (bufoff) + ldsw + _i * 8192), 16, 0, 0); } while (0)
; #define PG8_LDA(dst, b, h) do { _Pragma("unroll") for (int m = 0; m < 4; ++m) _Pragma("unroll") for (int k = 0; k < 2; ++k) dst[m][k] = *(const PG8_LAS bf16x8*)(lds + PG8_SA(b, h) + aoff + m * 2048 + k * 1024); } while (0)
; #define PG8_LDB(dst, b, h) do { _Pragma("unroll") for (int n = 0; n < 2; ++n) _Pragma("unroll") for (int k = 0; k < 2; ++k) dst[n][k] = *(const PG8_LAS bf16x8*)(lds + PG8_SB(b, h) + boff + n * 2048 + k * 1024); } while (0)
; #define PG8_MMA(ai, bj, At, Bt) do { __builtin_amdgcn_s_setprio(1); _Pragma("unroll") for (int m = 0; m < 4; ++m) _Pragma("unroll") for (int n = 0; n < 2; ++n) _Pragma("unroll") for (int k = 0; k < 2; ++k) \
;         acc[ai][bj][m][n] = __builtin_amdgcn_mfma_f32_16x16x32_bf16(Bt[n][k], At[m][k], acc[ai][bj][m][n], 0, 0, 0); __builtin_amdgcn_s_setprio(0); } while (0)
; #define PG8_WAIT_V(n) asm volatile("s_waitcnt vmcnt(" #n ")" ::: "memory")
; #define PG8_WAIT_L(n) asm volatile("s_waitcnt lgkmcnt(" #n ")" ::: "memory")
; #define PG8_BAR __builtin_amdgcn_s_barrier()
; template <class Epi, class Sched, bool ALIGN_EPI = false>
; __device__ __forceinline__ void gemm_phase8(PG8_LAS unsigned char* lds, const Gemm g, const Sched& S, const Epi& E) {
;     ...
;             const bool last = (t == nt - 2);
;             const char* a1 = cA + (size_t)(t + 1) * kstep;
;             const char* a2 = last ? nA : cA + (size_t)(t + 2) * kstep; const char* b2 = last ? nB : cB + (size_t)(t + 2) * kstep;
;             const char* a3 = a2 + kstep; const char* b3 = b2 + kstep;
;             if (last && has_next) S.a_ready(nxt);
;             PG8_LDB(B0, 0, 0); PG8_LDB(B1, 0, 1); PG8_SCHED; PG8_LDA(At, 0, 0); PG8_STAGE(PG8_SA(1, 1), a1 + hstepA, voffA);
;             PG8_WAIT_V(8); PG8_WAIT_L(0); PG8_BAR; PG8_MMA(0, 0, At, B0); PG8_MMA(0, 1, At, B1); PG8_BAR; PG8_SCHED;
;             PG8_LDA(At, 0, 1); PG8_STAGE(PG8_SB(0, 0), b2, voffB); PG8_STAGE(PG8_SB(0, 1), b2 + hstepB, voffB); PG8_STAGE(PG8_SA(0, 0), a2, voffA);
;             PG8_WAIT_V(8); PG8_WAIT_L(0); PG8_BAR; PG8_MMA(1, 0, At, B0); PG8_MMA(1, 1, At, B1); PG8_BAR; PG8_SCHED;
.LBB0_1511:
	ds_read_b128 v[18:21], v187
	ds_read_b128 v[26:29], v187 offset:2048
	ds_read_b128 v[22:25], v188
	ds_read_b128 v[30:33], v188 offset:2048
	ds_read_b128 v[2:5], v189
	ds_read_b128 v[10:13], v189 offset:2048
	ds_read_b128 v[6:9], v190
	ds_read_b128 v[14:17], v190 offset:2048
	s_add_i32 s82, s40, 2
	s_add_u32 s34, s38, 0xfff50080
	s_addc_u32 s35, s39, -1
	s_cmp_eq_u32 s79, s40
	s_cselect_b32 s40, s26, s34
	s_cselect_b32 s41, s27, s35
	s_cselect_b32 s35, s29, s81
	s_cselect_b32 s34, s28, s80
	s_add_i32 m0, s52, 0xc000
	ds_read_b128 v[174:177], v191
	ds_read_b128 v[194:197], v191 offset:2048
	ds_read_b128 v[178:181], v192
	ds_read_b128 v[198:201], v192 offset:2048
	ds_read_b128 v[202:205], v191 offset:4096
	ds_read_b128 v[210:213], v191 offset:6144
	ds_read_b128 v[206:209], v192 offset:4096
	ds_read_b128 v[214:217], v192 offset:6144
	global_load_lds_dwordx4 v170, s[38:39]
	s_add_i32 m0, s52, 0xe000
	s_nop 0
	global_load_lds_dwordx4 v172, s[38:39]
	s_waitcnt vmcnt(8)
	s_waitcnt lgkmcnt(0)
	s_barrier
	s_setprio 1
	s_waitcnt lgkmcnt(0)
	v_mfma_scale_f32_16x16x128_f8f6f4 v[158:161], v[18:25], v[174:181], v[158:161], v1, v182 op_sel_hi:[0,0,0]
	v_mfma_scale_f32_16x16x128_f8f6f4 v[154:157], v[26:33], v[174:181], v[154:157], v1, v182 op_sel_hi:[0,0,0]
	v_mfma_scale_f32_16x16x128_f8f6f4 v[150:153], v[18:25], v[194:201], v[150:153], v1, v182 op_sel_hi:[0,0,0]
	v_mfma_scale_f32_16x16x128_f8f6f4 v[138:141], v[26:33], v[194:201], v[138:141], v1, v182 op_sel_hi:[0,0,0]
	v_mfma_scale_f32_16x16x128_f8f6f4 v[130:133], v[18:25], v[202:209], v[130:133], v1, v182 op_sel_hi:[0,0,0]
	v_mfma_scale_f32_16x16x128_f8f6f4 v[122:125], v[26:33], v[202:209], v[122:125], v1, v182 op_sel_hi:[0,0,0]
	v_mfma_scale_f32_16x16x128_f8f6f4 v[118:121], v[18:25], v[210:217], v[118:121], v1, v182 op_sel_hi:[0,0,0]
	v_mfma_scale_f32_16x16x128_f8f6f4 v[106:109], v[26:33], v[210:217], v[106:109], v1, v182 op_sel_hi:[0,0,0]
	s_setprio 0
	s_setprio 1
	v_mfma_scale_f32_16x16x128_f8f6f4 v[146:149], v[2:9], v[174:181], v[146:149], v1, v182 op_sel_hi:[0,0,0]
	v_mfma_scale_f32_16x16x128_f8f6f4 v[142:145], v[10:17], v[174:181], v[142:145], v1, v182 op_sel_hi:[0,0,0]
	v_mfma_scale_f32_16x16x128_f8f6f4 v[134:137], v[2:9], v[194:201], v[134:137], v1, v182 op_sel_hi:[0,0,0]
	v_mfma_scale_f32_16x16x128_f8f6f4 v[126:129], v[10:17], v[194:201], v[126:129], v1, v182 op_sel_hi:[0,0,0]
	v_mfma_scale_f32_16x16x128_f8f6f4 v[114:117], v[2:9], v[202:209], v[114:117], v1, v182 op_sel_hi:[0,0,0]
	v_mfma_scale_f32_16x16x128_f8f6f4 v[110:113], v[10:17], v[202:209], v[110:113], v1, v182 op_sel_hi:[0,0,0]
	v_mfma_scale_f32_16x16x128_f8f6f4 v[102:105], v[2:9], v[210:217], v[102:105], v1, v182 op_sel_hi:[0,0,0]
	v_mfma_scale_f32_16x16x128_f8f6f4 v[98:101], v[10:17], v[210:217], v[98:101], v1, v182 op_sel_hi:[0,0,0]
	s_setprio 0
	s_barrier
	s_add_i32 s83, s63, s45
	s_mov_b32 m0, s83
	ds_read_b128 v[194:197], v191 offset:16384
	ds_read_b128 v[202:205], v191 offset:18432
	ds_read_b128 v[198:201], v192 offset:16384
	ds_read_b128 v[206:209], v192 offset:18432
	ds_read_b128 v[210:213], v191 offset:20480
	ds_read_b128 v[218:221], v191 offset:22528
	ds_read_b128 v[214:217], v192 offset:20480
	ds_read_b128 v[222:225], v192 offset:22528
	global_load_lds_dwordx4 v164, s[34:35]
	s_add_i32 m0, s83, 0x2000
	s_add_u32 s84, s34, 0xb0000
	s_addc_u32 s85, s35, 0
	s_add_i32 s83, s64, s45
	global_load_lds_dwordx4 v168, s[34:35]
	s_mov_b32 m0, s83
	s_nop 0
	global_load_lds_dwordx4 v164, s[84:85]
	s_add_i32 m0, s83, 0x2000
	s_nop 0
	global_load_lds_dwordx4 v168, s[84:85]
	s_mov_b32 m0, s52
	s_nop 0
	global_load_lds_dwordx4 v162, s[40:41]
	s_mov_b32 m0, s53
	s_nop 0
	global_load_lds_dwordx4 v166, s[40:41]
	s_waitcnt vmcnt(8)
	s_waitcnt lgkmcnt(0)
	s_barrier
	s_setprio 1
	s_waitcnt lgkmcnt(0)
	v_mfma_scale_f32_16x16x128_f8f6f4 v[94:97], v[18:25], v[194:201], v[94:97], v1, v182 op_sel_hi:[0,0,0]
	v_mfma_scale_f32_16x16x128_f8f6f4 v[90:93], v[26:33], v[194:201], v[90:93], v1, v182 op_sel_hi:[0,0,0]
	v_mfma_scale_f32_16x16x128_f8f6f4 v[82:85], v[18:25], v[202:209], v[82:85], v1, v182 op_sel_hi:[0,0,0]
	v_mfma_scale_f32_16x16x128_f8f6f4 v[74:77], v[26:33], v[202:209], v[74:77], v1, v182 op_sel_hi:[0,0,0]
	v_mfma_scale_f32_16x16x128_f8f6f4 v[66:69], v[18:25], v[210:217], v[66:69], v1, v182 op_sel_hi:[0,0,0]
	v_mfma_scale_f32_16x16x128_f8f6f4 v[58:61], v[26:33], v[210:217], v[58:61], v1, v182 op_sel_hi:[0,0,0]
	v_mfma_scale_f32_16x16x128_f8f6f4 v[50:53], v[18:25], v[218:225], v[50:53], v1, v182 op_sel_hi:[0,0,0]
	v_mfma_scale_f32_16x16x128_f8f6f4 v[42:45], v[26:33], v[218:225], v[42:45], v1, v182 op_sel_hi:[0,0,0]
	s_setprio 0
	s_setprio 1
	v_mfma_scale_f32_16x16x128_f8f6f4 v[86:89], v[2:9], v[194:201], v[86:89], v1, v182 op_sel_hi:[0,0,0]
	v_mfma_scale_f32_16x16x128_f8f6f4 v[78:81], v[10:17], v[194:201], v[78:81], v1, v182 op_sel_hi:[0,0,0]
	v_mfma_scale_f32_16x16x128_f8f6f4 v[70:73], v[2:9], v[202:209], v[70:73], v1, v182 op_sel_hi:[0,0,0]
	v_mfma_scale_f32_16x16x128_f8f6f4 v[62:65], v[10:17], v[202:209], v[62:65], v1, v182 op_sel_hi:[0,0,0]
	v_mfma_scale_f32_16x16x128_f8f6f4 v[54:57], v[2:9], v[210:217], v[54:57], v1, v182 op_sel_hi:[0,0,0]
	v_mfma_scale_f32_16x16x128_f8f6f4 v[46:49], v[10:17], v[210:217], v[46:49], v1, v182 op_sel_hi:[0,0,0]
	v_mfma_scale_f32_16x16x128_f8f6f4 v[38:41], v[2:9], v[218:225], v[38:41], v1, v182 op_sel_hi:[0,0,0]
	v_mfma_scale_f32_16x16x128_f8f6f4 v[34:37], v[10:17], v[218:225], v[34:37], v1, v182 op_sel_hi:[0,0,0]
	s_setprio 0
	s_barrier
; #define PG8_STAGE(bufoff, gbase, voff) do { _Pragma("unroll") for (int _i = 0; _i < 2; ++_i) \
;         __builtin_amdgcn_global_load_lds((const unsigned*)((const char*)(gbase) + (voff)[_i]), (PG8_LAS unsigned*)(lds + (bufoff) + ldsw + _i * 8192), 16, 0, 0); } while (0)
; #define PG8_LDA(dst, b, h) do { _Pragma("unroll") for (int m = 0; m < 4; ++m) _Pragma("unroll") for (int k = 0; k < 2; ++k) dst[m][k] = *(const PG8_LAS bf16x8*)(lds + PG8_SA(b, h) + aoff + m * 2048 + k * 1024); } while (0)
; #define PG8_LDB(dst, b, h) do { _Pragma("unroll") for (int n = 0; n < 2; ++n) _Pragma("unroll") for (int k = 0; k < 2; ++k) dst[n][k] = *(const PG8_LAS bf16x8*)(lds + PG8_SB(b, h) + boff + n * 2048 + k * 1024); } while (0)
; #define PG8_MMA(ai, bj, At, Bt) do { __builtin_amdgcn_s_setprio(1); _Pragma("unroll") for (int m = 0; m < 4; ++m) _Pragma("unroll") for (int n = 0; n < 2; ++n) _Pragma("unroll") for (int k = 0; k < 2; ++k) \
;         acc[ai][bj][m][n] = __builtin_amdgcn_mfma_f32_16x16x32_bf16(Bt[n][k], At[m][k], acc[ai][bj][m][n], 0, 0, 0); __builtin_amdgcn_s_setprio(0); } while (0)
; #define PG8_WAIT_V(n) asm volatile("s_waitcnt vmcnt(" #n ")" ::: "memory")
; #define PG8_WAIT_L(n) asm volatile("s_waitcnt lgkmcnt(" #n ")" ::: "memory")
; #define PG8_BAR __builtin_amdgcn_s_barrier()
; #define PG8_SCHED __builtin_amdgcn_sched_barrier(0)
; #define PG8_STAGE(bufoff, gbase, voff) do { _Pragma("unroll") for (int _i = 0; _i < 2; ++_i) \
;         __builtin_amdgcn_global_load_lds((const unsigned*)((const char*)(gbase) + (voff)[_i]), (PG8_LAS unsigned*)(lds + (bufoff) + ldsw + _i * 8192), 16, 0, 0); } while (0)
; #define PG8_WAIT_V(n) asm volatile("s_waitcnt vmcnt(" #n ")" ::: "memory")
; template <class Epi, class Sched, bool ALIGN_EPI = false>
; __device__ __forceinline__ void gemm_phase8(PG8_LAS unsigned char* lds, const Gemm g, const Sched& S, const Epi& E) {
;     ...
;             PG8_LDB(B0, 1, 0); PG8_LDB(B1, 1, 1); PG8_SCHED; PG8_LDA(At, 1, 0); PG8_STAGE(PG8_SA(0, 1), a2 + hstepA, voffA);
;             PG8_WAIT_V(8); PG8_WAIT_L(0); PG8_BAR; PG8_MMA(0, 0, At, B0); PG8_MMA(0, 1, At, B1); PG8_BAR; PG8_SCHED;
;             PG8_LDA(At, 1, 1); PG8_STAGE(PG8_SB(1, 0), b3, voffB); PG8_STAGE(PG8_SB(1, 1), b3 + hstepB, voffB); PG8_STAGE(PG8_SA(1, 0), a3, voffA);
;             PG8_WAIT_V(8); PG8_WAIT_L(0); PG8_BAR; PG8_MMA(1, 0, At, B0); PG8_MMA(1, 1, At, B1); PG8_BAR; PG8_SCHED;
	s_add_i32 s83, 0, 0x18000
	s_add_i32 s84, 0, 0x1c000
	v_add_u32_e32 v6, s83, v184
	v_add_u32_e32 v14, s83, v185
	v_add_u32_e32 v22, s84, v184
	v_add_u32_e32 v30, s84, v185
	ds_read_b128 v[2:5], v6
	ds_read_b128 v[10:13], v6 offset:2048
	ds_read_b128 v[6:9], v14
	ds_read_b128 v[14:17], v14 offset:2048
	ds_read_b128 v[18:21], v22
	ds_read_b128 v[26:29], v22 offset:2048
	ds_read_b128 v[22:25], v30
	ds_read_b128 v[30:33], v30 offset:2048
	s_add_u32 s40, s40, 0xb0000
	s_addc_u32 s41, s41, 0
	s_mov_b32 m0, s54
	ds_read_b128 v[194:197], v191 offset:32768
	ds_read_b128 v[202:205], v191 offset:34816
	ds_read_b128 v[198:201], v192 offset:32768
	ds_read_b128 v[206:209], v192 offset:34816
	ds_read_b128 v[210:213], v191 offset:36864
	ds_read_b128 v[218:221], v191 offset:38912
	ds_read_b128 v[214:217], v192 offset:36864
	ds_read_b128 v[222:225], v192 offset:38912
	global_load_lds_dwordx4 v162, s[40:41]
	s_mov_b32 m0, s55
	s_nop 0
	global_load_lds_dwordx4 v166, s[40:41]
	s_waitcnt vmcnt(8)
	s_waitcnt lgkmcnt(0)
	s_barrier
	s_setprio 1
	s_waitcnt lgkmcnt(0)
	v_mfma_scale_f32_16x16x128_f8f6f4 v[158:161], v[2:9], v[194:201], v[158:161], v1, v182 op_sel_hi:[0,0,0]
	v_mfma_scale_f32_16x16x128_f8f6f4 v[154:157], v[10:17], v[194:201], v[154:157], v1, v182 op_sel_hi:[0,0,0]
	v_mfma_scale_f32_16x16x128_f8f6f4 v[150:153], v[2:9], v[202:209], v[150:153], v1, v182 op_sel_hi:[0,0,0]
	v_mfma_scale_f32_16x16x128_f8f6f4 v[138:141], v[10:17], v[202:209], v[138:141], v1, v182 op_sel_hi:[0,0,0]
	v_mfma_scale_f32_16x16x128_f8f6f4 v[130:133], v[2:9], v[210:217], v[130:133], v1, v182 op_sel_hi:[0,0,0]
	v_mfma_scale_f32_16x16x128_f8f6f4 v[122:125], v[10:17], v[210:217], v[122:125], v1, v182 op_sel_hi:[0,0,0]
	v_mfma_scale_f32_16x16x128_f8f6f4 v[118:121], v[2:9], v[218:225], v[118:121], v1, v182 op_sel_hi:[0,0,0]
	v_mfma_scale_f32_16x16x128_f8f6f4 v[106:109], v[10:17], v[218:225], v[106:109], v1, v182 op_sel_hi:[0,0,0]
	s_setprio 0
	s_setprio 1
	v_mfma_scale_f32_16x16x128_f8f6f4 v[146:149], v[18:25], v[194:201], v[146:149], v1, v182 op_sel_hi:[0,0,0]
	v_mfma_scale_f32_16x16x128_f8f6f4 v[142:145], v[26:33], v[194:201], v[142:145], v1, v182 op_sel_hi:[0,0,0]
	v_mfma_scale_f32_16x16x128_f8f6f4 v[134:137], v[18:25], v[202:209], v[134:137], v1, v182 op_sel_hi:[0,0,0]
	v_mfma_scale_f32_16x16x128_f8f6f4 v[126:129], v[26:33], v[202:209], v[126:129], v1, v182 op_sel_hi:[0,0,0]
	v_mfma_scale_f32_16x16x128_f8f6f4 v[114:117], v[18:25], v[210:217], v[114:117], v1, v182 op_sel_hi:[0,0,0]
	v_mfma_scale_f32_16x16x128_f8f6f4 v[110:113], v[26:33], v[210:217], v[110:113], v1, v182 op_sel_hi:[0,0,0]
	v_mfma_scale_f32_16x16x128_f8f6f4 v[102:105], v[18:25], v[218:225], v[102:105], v1, v182 op_sel_hi:[0,0,0]
	v_mfma_scale_f32_16x16x128_f8f6f4 v[98:101], v[26:33], v[218:225], v[98:101], v1, v182 op_sel_hi:[0,0,0]
	s_setprio 0
	s_barrier
	s_add_i32 s101, s83, s45
	s_add_u32 s98, s34, s12
	s_addc_u32 s99, s35, s13
	s_mov_b32 m0, s101
	ds_read_b128 v[194:197], v191 offset:49152
	ds_read_b128 v[202:205], v191 offset:51200
	ds_read_b128 v[198:201], v192 offset:49152
	ds_read_b128 v[206:209], v192 offset:51200
	ds_read_b128 v[210:213], v191 offset:53248
	ds_read_b128 v[218:221], v191 offset:55296
	ds_read_b128 v[214:217], v192 offset:53248
	ds_read_b128 v[222:225], v192 offset:55296
	global_load_lds_dwordx4 v164, s[98:99]
	s_add_i32 m0, s101, 0x2000
	s_add_u32 s34, s34, 0xb0080
	s_addc_u32 s35, s35, 0
	s_add_i32 s101, s84, s45
	global_load_lds_dwordx4 v168, s[98:99]
	s_add_u32 s98, s40, s12
	s_addc_u32 s99, s41, s13
	s_sub_u32 s98, s98, 0xb0000
	s_subb_u32 s99, s99, 0
	s_mov_b32 m0, s101
	s_nop 0
	global_load_lds_dwordx4 v164, s[34:35]
	s_add_i32 m0, s101, 0x2000
	s_nop 0
	global_load_lds_dwordx4 v168, s[34:35]
	s_mov_b32 m0, s61
	s_nop 0
	global_load_lds_dwordx4 v162, s[98:99]
	s_mov_b32 m0, s62
	s_nop 0
	global_load_lds_dwordx4 v166, s[98:99]
	s_waitcnt vmcnt(8)
	s_waitcnt lgkmcnt(0)
	s_barrier
	s_setprio 1
	s_waitcnt lgkmcnt(0)
	v_mfma_scale_f32_16x16x128_f8f6f4 v[94:97], v[2:9], v[194:201], v[94:97], v1, v182 op_sel_hi:[0,0,0]
	v_mfma_scale_f32_16x16x128_f8f6f4 v[90:93], v[10:17], v[194:201], v[90:93], v1, v182 op_sel_hi:[0,0,0]
	v_mfma_scale_f32_16x16x128_f8f6f4 v[82:85], v[2:9], v[202:209], v[82:85], v1, v182 op_sel_hi:[0,0,0]
	v_mfma_scale_f32_16x16x128_f8f6f4 v[74:77], v[10:17], v[202:209], v[74:77], v1, v182 op_sel_hi:[0,0,0]
	v_mfma_scale_f32_16x16x128_f8f6f4 v[66:69], v[2:9], v[210:217], v[66:69], v1, v182 op_sel_hi:[0,0,0]
	v_mfma_scale_f32_16x16x128_f8f6f4 v[58:61], v[10:17], v[210:217], v[58:61], v1, v182 op_sel_hi:[0,0,0]
	v_mfma_scale_f32_16x16x128_f8f6f4 v[50:53], v[2:9], v[218:225], v[50:53], v1, v182 op_sel_hi:[0,0,0]
	v_mfma_scale_f32_16x16x128_f8f6f4 v[42:45], v[10:17], v[218:225], v[42:45], v1, v182 op_sel_hi:[0,0,0]
	s_setprio 0
	s_setprio 1
	v_mfma_scale_f32_16x16x128_f8f6f4 v[86:89], v[18:25], v[194:201], v[86:89], v1, v182 op_sel_hi:[0,0,0]
	v_mfma_scale_f32_16x16x128_f8f6f4 v[78:81], v[26:33], v[194:201], v[78:81], v1, v182 op_sel_hi:[0,0,0]
	v_mfma_scale_f32_16x16x128_f8f6f4 v[70:73], v[18:25], v[202:209], v[70:73], v1, v182 op_sel_hi:[0,0,0]
	v_mfma_scale_f32_16x16x128_f8f6f4 v[62:65], v[26:33], v[202:209], v[62:65], v1, v182 op_sel_hi:[0,0,0]
	v_mfma_scale_f32_16x16x128_f8f6f4 v[54:57], v[18:25], v[210:217], v[54:57], v1, v182 op_sel_hi:[0,0,0]
	v_mfma_scale_f32_16x16x128_f8f6f4 v[46:49], v[26:33], v[210:217], v[46:49], v1, v182 op_sel_hi:[0,0,0]
	v_mfma_scale_f32_16x16x128_f8f6f4 v[38:41], v[18:25], v[218:225], v[38:41], v1, v182 op_sel_hi:[0,0,0]
	v_mfma_scale_f32_16x16x128_f8f6f4 v[34:37], v[26:33], v[218:225], v[34:37], v1, v182 op_sel_hi:[0,0,0]
	s_setprio 0
	s_barrier
; #define PG8_STAGE(bufoff, gbase, voff) do { _Pragma("unroll") for (int _i = 0; _i < 2; ++_i) \
;         __builtin_amdgcn_global_load_lds((const unsigned*)((const char*)(gbase) + (voff)[_i]), (PG8_LAS unsigned*)(lds + (bufoff) + ldsw + _i * 8192), 16, 0, 0); } while (0)
; #define PG8_LDA(dst, b, h) do { _Pragma("unroll") for (int m = 0; m < 4; ++m) _Pragma("unroll") for (int k = 0; k < 2; ++k) dst[m][k] = *(const PG8_LAS bf16x8*)(lds + PG8_SA(b, h) + aoff + m * 2048 + k * 1024); } while (0)
; #define PG8_LDB(dst, b, h) do { _Pragma("unroll") for (int n = 0; n < 2; ++n) _Pragma("unroll") for (int k = 0; k < 2; ++k) dst[n][k] = *(const PG8_LAS bf16x8*)(lds + PG8_SB(b, h) + boff + n * 2048 + k * 1024); } while (0)
; #define PG8_MMA(ai, bj, At, Bt) do { __builtin_amdgcn_s_setprio(1); _Pragma("unroll") for (int m = 0; m < 4; ++m) _Pragma("unroll") for (int n = 0; n < 2; ++n) _Pragma("unroll") for (int k = 0; k < 2; ++k) \
;         acc[ai][bj][m][n] = __builtin_amdgcn_mfma_f32_16x16x32_bf16(Bt[n][k], At[m][k], acc[ai][bj][m][n], 0, 0, 0); __builtin_amdgcn_s_setprio(0); } while (0)
; #define PG8_WAIT_V(n) asm volatile("s_waitcnt vmcnt(" #n ")" ::: "memory")
; #define PG8_WAIT_L(n) asm volatile("s_waitcnt lgkmcnt(" #n ")" ::: "memory")
; template <class Epi, class Sched, bool ALIGN_EPI = false>
; __device__ __forceinline__ void gemm_phase8(PG8_LAS unsigned char* lds, const Gemm g, const Sched& S, const Epi& E) {
;     ...
;         for (int t = 0; t < nt; t += 2) {
;             const bool last = (t == nt - 2);
;             const char* a1 = cA + (size_t)(t + 1) * kstep;
;             const char* a2 = last ? nA : cA + (size_t)(t + 2) * kstep; const char* b2 = last ? nB : cB + (size_t)(t + 2) * kstep;
;             const char* a3 = a2 + kstep; const char* b3 = b2 + kstep;
;             if (last && has_next) S.a_ready(nxt);
;             PG8_LDB(B0, 0, 0); PG8_LDB(B1, 0, 1); PG8_SCHED; PG8_LDA(At, 0, 0); PG8_STAGE(PG8_SA(1, 1), a1 + hstepA, voffA);
;             PG8_WAIT_V(8); PG8_WAIT_L(0); PG8_BAR; PG8_MMA(0, 0, At, B0); PG8_MMA(0, 1, At, B1); PG8_BAR; PG8_SCHED;
;             PG8_LDA(At, 0, 1); PG8_STAGE(PG8_SB(0, 0), b2, voffB); PG8_STAGE(PG8_SB(0, 1), b2 + hstepB, voffB); PG8_STAGE(PG8_SA(0, 0), a2, voffA);
;             PG8_WAIT_V(8); PG8_WAIT_L(0); PG8_BAR; PG8_MMA(1, 0, At, B0); PG8_MMA(1, 1, At, B1); PG8_BAR; PG8_SCHED;
	s_add_u32 s38, s38, 0x100
	s_addc_u32 s39, s39, 0
	s_add_u32 s80, s80, 0x100
	s_addc_u32 s81, s81, 0
	s_cmp_ge_u32 s82, s31
	s_mov_b32 s40, s82
	ds_read_b128 v[18:21], v187
	ds_read_b128 v[26:29], v187 offset:2048
	ds_read_b128 v[22:25], v188
	ds_read_b128 v[30:33], v188 offset:2048
	ds_read_b128 v[2:5], v189
	ds_read_b128 v[10:13], v189 offset:2048
	ds_read_b128 v[6:9], v190
	ds_read_b128 v[14:17], v190 offset:2048
	s_add_i32 s82, s40, 2
	s_add_u32 s34, s38, 0xfff50080
	s_addc_u32 s35, s39, -1
	s_cmp_eq_u32 s79, s40
	s_cselect_b32 s40, s26, s34
	s_cselect_b32 s41, s27, s35
	s_cselect_b32 s35, s29, s81
	s_cselect_b32 s34, s28, s80
	s_add_i32 m0, s52, 0xc000
	ds_read_b128 v[174:177], v191
	ds_read_b128 v[194:197], v191 offset:2048
	ds_read_b128 v[178:181], v192
	ds_read_b128 v[198:201], v192 offset:2048
	ds_read_b128 v[202:205], v191 offset:4096
	ds_read_b128 v[210:213], v191 offset:6144
	ds_read_b128 v[206:209], v192 offset:4096
	ds_read_b128 v[214:217], v192 offset:6144
	global_load_lds_dwordx4 v170, s[38:39]
	s_add_i32 m0, s52, 0xe000
	s_nop 0
	global_load_lds_dwordx4 v172, s[38:39]
	s_waitcnt vmcnt(8)
	s_waitcnt lgkmcnt(0)
	s_barrier
	s_setprio 1
	s_waitcnt lgkmcnt(0)
	v_mfma_scale_f32_16x16x128_f8f6f4 v[158:161], v[18:25], v[174:181], v[158:161], v1, v182 op_sel_hi:[0,0,0]
	v_mfma_scale_f32_16x16x128_f8f6f4 v[154:157], v[26:33], v[174:181], v[154:157], v1, v182 op_sel_hi:[0,0,0]
	v_mfma_scale_f32_16x16x128_f8f6f4 v[150:153], v[18:25], v[194:201], v[150:153], v1, v182 op_sel_hi:[0,0,0]
	v_mfma_scale_f32_16x16x128_f8f6f4 v[138:141], v[26:33], v[194:201], v[138:141], v1, v182 op_sel_hi:[0,0,0]
	v_mfma_scale_f32_16x16x128_f8f6f4 v[130:133], v[18:25], v[202:209], v[130:133], v1, v182 op_sel_hi:[0,0,0]
	v_mfma_scale_f32_16x16x128_f8f6f4 v[122:125], v[26:33], v[202:209], v[122:125], v1, v182 op_sel_hi:[0,0,0]
	v_mfma_scale_f32_16x16x128_f8f6f4 v[118:121], v[18:25], v[210:217], v[118:121], v1, v182 op_sel_hi:[0,0,0]
	v_mfma_scale_f32_16x16x128_f8f6f4 v[106:109], v[26:33], v[210:217], v[106:109], v1, v182 op_sel_hi:[0,0,0]
	s_setprio 0
	s_setprio 1
	v_mfma_scale_f32_16x16x128_f8f6f4 v[146:149], v[2:9], v[174:181], v[146:149], v1, v182 op_sel_hi:[0,0,0]
	v_mfma_scale_f32_16x16x128_f8f6f4 v[142:145], v[10:17], v[174:181], v[142:145], v1, v182 op_sel_hi:[0,0,0]
	v_mfma_scale_f32_16x16x128_f8f6f4 v[134:137], v[2:9], v[194:201], v[134:137], v1, v182 op_sel_hi:[0,0,0]
	v_mfma_scale_f32_16x16x128_f8f6f4 v[126:129], v[10:17], v[194:201], v[126:129], v1, v182 op_sel_hi:[0,0,0]
	v_mfma_scale_f32_16x16x128_f8f6f4 v[114:117], v[2:9], v[202:209], v[114:117], v1, v182 op_sel_hi:[0,0,0]
	v_mfma_scale_f32_16x16x128_f8f6f4 v[110:113], v[10:17], v[202:209], v[110:113], v1, v182 op_sel_hi:[0,0,0]
	v_mfma_scale_f32_16x16x128_f8f6f4 v[102:105], v[2:9], v[210:217], v[102:105], v1, v182 op_sel_hi:[0,0,0]
	v_mfma_scale_f32_16x16x128_f8f6f4 v[98:101], v[10:17], v[210:217], v[98:101], v1, v182 op_sel_hi:[0,0,0]
	s_setprio 0
	s_barrier
	s_add_i32 s83, s63, s45
	s_mov_b32 m0, s83
	ds_read_b128 v[194:197], v191 offset:16384
	ds_read_b128 v[202:205], v191 offset:18432
	ds_read_b128 v[198:201], v192 offset:16384
	ds_read_b128 v[206:209], v192 offset:18432
	ds_read_b128 v[210:213], v191 offset:20480
	ds_read_b128 v[218:221], v191 offset:22528
	ds_read_b128 v[214:217], v192 offset:20480
	ds_read_b128 v[222:225], v192 offset:22528
	global_load_lds_dwordx4 v164, s[34:35]
	s_add_i32 m0, s83, 0x2000
	s_add_u32 s84, s34, 0xb0000
	s_addc_u32 s85, s35, 0
	s_add_i32 s83, s64, s45
	global_load_lds_dwordx4 v168, s[34:35]
	s_mov_b32 m0, s83
	s_nop 0
	global_load_lds_dwordx4 v164, s[84:85]
	s_add_i32 m0, s83, 0x2000
	s_nop 0
	global_load_lds_dwordx4 v168, s[84:85]
	s_mov_b32 m0, s52
	s_nop 0
	global_load_lds_dwordx4 v162, s[40:41]
	s_mov_b32 m0, s53
	s_nop 0
	global_load_lds_dwordx4 v166, s[40:41]
	s_waitcnt vmcnt(8)
	s_waitcnt lgkmcnt(0)
	s_barrier
	s_setprio 1
	s_waitcnt lgkmcnt(0)
	v_mfma_scale_f32_16x16x128_f8f6f4 v[94:97], v[18:25], v[194:201], v[94:97], v1, v182 op_sel_hi:[0,0,0]
	v_mfma_scale_f32_16x16x128_f8f6f4 v[90:93], v[26:33], v[194:201], v[90:93], v1, v182 op_sel_hi:[0,0,0]
	v_mfma_scale_f32_16x16x128_f8f6f4 v[82:85], v[18:25], v[202:209], v[82:85], v1, v182 op_sel_hi:[0,0,0]
	v_mfma_scale_f32_16x16x128_f8f6f4 v[74:77], v[26:33], v[202:209], v[74:77], v1, v182 op_sel_hi:[0,0,0]
	v_mfma_scale_f32_16x16x128_f8f6f4 v[66:69], v[18:25], v[210:217], v[66:69], v1, v182 op_sel_hi:[0,0,0]
	v_mfma_scale_f32_16x16x128_f8f6f4 v[58:61], v[26:33], v[210:217], v[58:61], v1, v182 op_sel_hi:[0,0,0]
	v_mfma_scale_f32_16x16x128_f8f6f4 v[50:53], v[18:25], v[218:225], v[50:53], v1, v182 op_sel_hi:[0,0,0]
	v_mfma_scale_f32_16x16x128_f8f6f4 v[42:45], v[26:33], v[218:225], v[42:45], v1, v182 op_sel_hi:[0,0,0]
	s_setprio 0
	s_setprio 1
	v_mfma_scale_f32_16x16x128_f8f6f4 v[86:89], v[2:9], v[194:201], v[86:89], v1, v182 op_sel_hi:[0,0,0]
	v_mfma_scale_f32_16x16x128_f8f6f4 v[78:81], v[10:17], v[194:201], v[78:81], v1, v182 op_sel_hi:[0,0,0]
	v_mfma_scale_f32_16x16x128_f8f6f4 v[70:73], v[2:9], v[202:209], v[70:73], v1, v182 op_sel_hi:[0,0,0]
	v_mfma_scale_f32_16x16x128_f8f6f4 v[62:65], v[10:17], v[202:209], v[62:65], v1, v182 op_sel_hi:[0,0,0]
	v_mfma_scale_f32_16x16x128_f8f6f4 v[54:57], v[2:9], v[210:217], v[54:57], v1, v182 op_sel_hi:[0,0,0]
	v_mfma_scale_f32_16x16x128_f8f6f4 v[46:49], v[10:17], v[210:217], v[46:49], v1, v182 op_sel_hi:[0,0,0]
	v_mfma_scale_f32_16x16x128_f8f6f4 v[38:41], v[2:9], v[218:225], v[38:41], v1, v182 op_sel_hi:[0,0,0]
	v_mfma_scale_f32_16x16x128_f8f6f4 v[34:37], v[10:17], v[218:225], v[34:37], v1, v182 op_sel_hi:[0,0,0]
	s_setprio 0
	s_barrier
; #define PG8_STAGE(bufoff, gbase, voff) do { _Pragma("unroll") for (int _i = 0; _i < 2; ++_i) \
;         __builtin_amdgcn_global_load_lds((const unsigned*)((const char*)(gbase) + (voff)[_i]), (PG8_LAS unsigned*)(lds + (bufoff) + ldsw + _i * 8192), 16, 0, 0); } while (0)
; #define PG8_LDA(dst, b, h) do { _Pragma("unroll") for (int m = 0; m < 4; ++m) _Pragma("unroll") for (int k = 0; k < 2; ++k) dst[m][k] = *(const PG8_LAS bf16x8*)(lds + PG8_SA(b, h) + aoff + m * 2048 + k * 1024); } while (0)
; #define PG8_LDB(dst, b, h) do { _Pragma("unroll") for (int n = 0; n < 2; ++n) _Pragma("unroll") for (int k = 0; k < 2; ++k) dst[n][k] = *(const PG8_LAS bf16x8*)(lds + PG8_SB(b, h) + boff + n * 2048 + k * 1024); } while (0)
; #define PG8_MMA(ai, bj, At, Bt) do { __builtin_amdgcn_s_setprio(1); _Pragma("unroll") for (int m = 0; m < 4; ++m) _Pragma("unroll") for (int n = 0; n < 2; ++n) _Pragma("unroll") for (int k = 0; k < 2; ++k) \
;         acc[ai][bj][m][n] = __builtin_amdgcn_mfma_f32_16x16x32_bf16(Bt[n][k], At[m][k], acc[ai][bj][m][n], 0, 0, 0); __builtin_amdgcn_s_setprio(0); } while (0)
; #define PG8_WAIT_V(n) asm volatile("s_waitcnt vmcnt(" #n ")" ::: "memory")
; #define PG8_WAIT_L(n) asm volatile("s_waitcnt lgkmcnt(" #n ")" ::: "memory")
; #define PG8_BAR __builtin_amdgcn_s_barrier()
; #define PG8_SCHED __builtin_amdgcn_sched_barrier(0)
; #define PG8_STAGE(bufoff, gbase, voff) do { _Pragma("unroll") for (int _i = 0; _i < 2; ++_i) \
;         __builtin_amdgcn_global_load_lds((const unsigned*)((const char*)(gbase) + (voff)[_i]), (PG8_LAS unsigned*)(lds + (bufoff) + ldsw + _i * 8192), 16, 0, 0); } while (0)
; #define PG8_WAIT_V(n) asm volatile("s_waitcnt vmcnt(" #n ")" ::: "memory")
; template <class Epi, class Sched, bool ALIGN_EPI = false>
; __device__ __forceinline__ void gemm_phase8(PG8_LAS unsigned char* lds, const Gemm g, const Sched& S, const Epi& E) {
;     ...
;             PG8_LDB(B0, 1, 0); PG8_LDB(B1, 1, 1); PG8_SCHED; PG8_LDA(At, 1, 0); PG8_STAGE(PG8_SA(0, 1), a2 + hstepA, voffA);
;             PG8_WAIT_V(8); PG8_WAIT_L(0); PG8_BAR; PG8_MMA(0, 0, At, B0); PG8_MMA(0, 1, At, B1); PG8_BAR; PG8_SCHED;
;             PG8_LDA(At, 1, 1); PG8_STAGE(PG8_SB(1, 0), b3, voffB); PG8_STAGE(PG8_SB(1, 1), b3 + hstepB, voffB); PG8_STAGE(PG8_SA(1, 0), a3, voffA);
;             PG8_WAIT_V(8); PG8_WAIT_L(0); PG8_BAR; PG8_MMA(1, 0, At, B0); PG8_MMA(1, 1, At, B1); PG8_BAR; PG8_SCHED;
	s_add_i32 s83, 0, 0x18000
	s_add_i32 s84, 0, 0x1c000
	v_add_u32_e32 v6, s83, v184
	v_add_u32_e32 v14, s83, v185
	v_add_u32_e32 v22, s84, v184
	v_add_u32_e32 v30, s84, v185
	ds_read_b128 v[2:5], v6
	ds_read_b128 v[10:13], v6 offset:2048
	ds_read_b128 v[6:9], v14
	ds_read_b128 v[14:17], v14 offset:2048
	ds_read_b128 v[18:21], v22
	ds_read_b128 v[26:29], v22 offset:2048
	ds_read_b128 v[22:25], v30
	ds_read_b128 v[30:33], v30 offset:2048
	s_add_u32 s40, s40, 0xb0000
	s_addc_u32 s41, s41, 0
	s_mov_b32 m0, s54
	ds_read_b128 v[194:197], v191 offset:32768
	ds_read_b128 v[202:205], v191 offset:34816
	ds_read_b128 v[198:201], v192 offset:32768
	ds_read_b128 v[206:209], v192 offset:34816
	ds_read_b128 v[210:213], v191 offset:36864
	ds_read_b128 v[218:221], v191 offset:38912
	ds_read_b128 v[214:217], v192 offset:36864
	ds_read_b128 v[222:225], v192 offset:38912
	global_load_lds_dwordx4 v162, s[40:41]
	s_mov_b32 m0, s55
	s_nop 0
	global_load_lds_dwordx4 v166, s[40:41]
	s_waitcnt vmcnt(8)
	s_waitcnt lgkmcnt(0)
	s_barrier
	s_setprio 1
	s_waitcnt lgkmcnt(0)
	v_mfma_scale_f32_16x16x128_f8f6f4 v[158:161], v[2:9], v[194:201], v[158:161], v1, v182 op_sel_hi:[0,0,0]
	v_mfma_scale_f32_16x16x128_f8f6f4 v[154:157], v[10:17], v[194:201], v[154:157], v1, v182 op_sel_hi:[0,0,0]
	v_mfma_scale_f32_16x16x128_f8f6f4 v[150:153], v[2:9], v[202:209], v[150:153], v1, v182 op_sel_hi:[0,0,0]
	v_mfma_scale_f32_16x16x128_f8f6f4 v[138:141], v[10:17], v[202:209], v[138:141], v1, v182 op_sel_hi:[0,0,0]
	v_mfma_scale_f32_16x16x128_f8f6f4 v[130:133], v[2:9], v[210:217], v[130:133], v1, v182 op_sel_hi:[0,0,0]
	v_mfma_scale_f32_16x16x128_f8f6f4 v[122:125], v[10:17], v[210:217], v[122:125], v1, v182 op_sel_hi:[0,0,0]
	v_mfma_scale_f32_16x16x128_f8f6f4 v[118:121], v[2:9], v[218:225], v[118:121], v1, v182 op_sel_hi:[0,0,0]
	v_mfma_scale_f32_16x16x128_f8f6f4 v[106:109], v[10:17], v[218:225], v[106:109], v1, v182 op_sel_hi:[0,0,0]
	s_setprio 0
	s_setprio 1
	v_mfma_scale_f32_16x16x128_f8f6f4 v[146:149], v[18:25], v[194:201], v[146:149], v1, v182 op_sel_hi:[0,0,0]
	v_mfma_scale_f32_16x16x128_f8f6f4 v[142:145], v[26:33], v[194:201], v[142:145], v1, v182 op_sel_hi:[0,0,0]
	v_mfma_scale_f32_16x16x128_f8f6f4 v[134:137], v[18:25], v[202:209], v[134:137], v1, v182 op_sel_hi:[0,0,0]
	v_mfma_scale_f32_16x16x128_f8f6f4 v[126:129], v[26:33], v[202:209], v[126:129], v1, v182 op_sel_hi:[0,0,0]
	v_mfma_scale_f32_16x16x128_f8f6f4 v[114:117], v[18:25], v[210:217], v[114:117], v1, v182 op_sel_hi:[0,0,0]
	v_mfma_scale_f32_16x16x128_f8f6f4 v[110:113], v[26:33], v[210:217], v[110:113], v1, v182 op_sel_hi:[0,0,0]
	v_mfma_scale_f32_16x16x128_f8f6f4 v[102:105], v[18:25], v[218:225], v[102:105], v1, v182 op_sel_hi:[0,0,0]
	v_mfma_scale_f32_16x16x128_f8f6f4 v[98:101], v[26:33], v[218:225], v[98:101], v1, v182 op_sel_hi:[0,0,0]
	s_setprio 0
	s_barrier
	s_add_i32 s101, s83, s45
	s_add_u32 s98, s34, s12
	s_addc_u32 s99, s35, s13
	s_mov_b32 m0, s101
	ds_read_b128 v[194:197], v191 offset:49152
	ds_read_b128 v[202:205], v191 offset:51200
	ds_read_b128 v[198:201], v192 offset:49152
	ds_read_b128 v[206:209], v192 offset:51200
	ds_read_b128 v[210:213], v191 offset:53248
	ds_read_b128 v[218:221], v191 offset:55296
	ds_read_b128 v[214:217], v192 offset:53248
	ds_read_b128 v[222:225], v192 offset:55296
	global_load_lds_dwordx4 v164, s[98:99]
	s_add_i32 m0, s101, 0x2000
	s_add_u32 s34, s34, 0xb0080
	s_addc_u32 s35, s35, 0
	s_add_i32 s101, s84, s45
	global_load_lds_dwordx4 v168, s[98:99]
	s_add_u32 s98, s40, s12
	s_addc_u32 s99, s41, s13
	s_sub_u32 s98, s98, 0xb0000
	s_subb_u32 s99, s99, 0
	s_mov_b32 m0, s101
	s_nop 0
	global_load_lds_dwordx4 v164, s[34:35]
	s_add_i32 m0, s101, 0x2000
	s_nop 0
	global_load_lds_dwordx4 v168, s[34:35]
	s_mov_b32 m0, s61
	s_nop 0
	global_load_lds_dwordx4 v162, s[98:99]
	s_mov_b32 m0, s62
	s_nop 0
	global_load_lds_dwordx4 v166, s[98:99]
	s_waitcnt vmcnt(8)
	s_waitcnt lgkmcnt(0)
	s_barrier
	s_setprio 1
	s_waitcnt lgkmcnt(0)
	v_mfma_scale_f32_16x16x128_f8f6f4 v[94:97], v[2:9], v[194:201], v[94:97], v1, v182 op_sel_hi:[0,0,0]
	v_mfma_scale_f32_16x16x128_f8f6f4 v[90:93], v[10:17], v[194:201], v[90:93], v1, v182 op_sel_hi:[0,0,0]
	v_mfma_scale_f32_16x16x128_f8f6f4 v[82:85], v[2:9], v[202:209], v[82:85], v1, v182 op_sel_hi:[0,0,0]
	v_mfma_scale_f32_16x16x128_f8f6f4 v[74:77], v[10:17], v[202:209], v[74:77], v1, v182 op_sel_hi:[0,0,0]
	v_mfma_scale_f32_16x16x128_f8f6f4 v[66:69], v[2:9], v[210:217], v[66:69], v1, v182 op_sel_hi:[0,0,0]
	v_mfma_scale_f32_16x16x128_f8f6f4 v[58:61], v[10:17], v[210:217], v[58:61], v1, v182 op_sel_hi:[0,0,0]
	v_mfma_scale_f32_16x16x128_f8f6f4 v[50:53], v[2:9], v[218:225], v[50:53], v1, v182 op_sel_hi:[0,0,0]
	v_mfma_scale_f32_16x16x128_f8f6f4 v[42:45], v[10:17], v[218:225], v[42:45], v1, v182 op_sel_hi:[0,0,0]
	s_setprio 0
	s_setprio 1
	v_mfma_scale_f32_16x16x128_f8f6f4 v[86:89], v[18:25], v[194:201], v[86:89], v1, v182 op_sel_hi:[0,0,0]
	v_mfma_scale_f32_16x16x128_f8f6f4 v[78:81], v[26:33], v[194:201], v[78:81], v1, v182 op_sel_hi:[0,0,0]
	v_mfma_scale_f32_16x16x128_f8f6f4 v[70:73], v[18:25], v[202:209], v[70:73], v1, v182 op_sel_hi:[0,0,0]
	v_mfma_scale_f32_16x16x128_f8f6f4 v[62:65], v[26:33], v[202:209], v[62:65], v1, v182 op_sel_hi:[0,0,0]
	v_mfma_scale_f32_16x16x128_f8f6f4 v[54:57], v[18:25], v[210:217], v[54:57], v1, v182 op_sel_hi:[0,0,0]
	v_mfma_scale_f32_16x16x128_f8f6f4 v[46:49], v[26:33], v[210:217], v[46:49], v1, v182 op_sel_hi:[0,0,0]
	v_mfma_scale_f32_16x16x128_f8f6f4 v[38:41], v[18:25], v[218:225], v[38:41], v1, v182 op_sel_hi:[0,0,0]
	v_mfma_scale_f32_16x16x128_f8f6f4 v[34:37], v[26:33], v[218:225], v[34:37], v1, v182 op_sel_hi:[0,0,0]
	s_setprio 0
	s_barrier
	s_add_u32 s38, s38, 0x100
	s_addc_u32 s39, s39, 0
	s_add_u32 s80, s80, 0x100
	s_addc_u32 s81, s81, 0
	s_cmp_ge_u32 s82, s31
	s_mov_b32 s40, s82
	s_cbranch_scc0 .LBB0_1511
